# half-barrier K-loop (complementary barrier placement for the two wave halves, alignment barriers removed) in 7 multi-tile GEMM phases, on top of MFMA reorder + P14/P0 edits
# baseline (speedup 1.0000x reference)
; #define PG8_STAGE(bufoff, gbase, voff) do { _Pragma("unroll") for (int _i = 0; _i < 2; ++_i) \
;         __builtin_amdgcn_global_load_lds((const unsigned*)((const char*)(gbase) + (voff)[_i]), (LAS unsigned*)(lds + (bufoff) + ldsw + _i * 8192), 16, 0, 0); } while (0)
; #define PG8_WAIT_V(n) asm volatile("s_waitcnt vmcnt(" #n ")" ::: "memory")
; #define PG8_BAR __builtin_amdgcn_s_barrier()
; template <bool ALIGN_EPI, class Epi, class Sched>
; __device__ __forceinline__ void gemm_phase(LAS unsigned char* lds, const int lda, const int ldb, const int K, const Sched& S, const Epi& E, const size_t kstepA = (size_t)(BK * 2), const size_t kstepB = (size_t)(BK * 2)) {
;     int tid = threadIdx.x; asm volatile("" : "+v"(tid));
;     const int wid = __builtin_amdgcn_readfirstlane(tid >> 6), lane = tid & 63, wr = wid >> 2, wc = wid & 3, fr = lane & 15, fq = lane >> 4;
;     const int nt = K / BK;
;     unsigned voffA[2], voffB[2];
; #pragma unroll
;     for (int i = 0; i < 2; ++i) { int R, C; stage_rc(tid * 16 + i * 8192, R, C); const int Rb = (R & ~31) + perm32(R & 31);
;         voffA[i] = (unsigned)(R * lda + C) * 2u; voffB[i] = (unsigned)(Rb * ldb + C) * 2u; }
;     const size_t kstep = kstepB;
;     const size_t hstepA = (size_t)HALF * lda * 2, hstepB = (size_t)HALF * ldb * 2;
;     const unsigned ldsw = (unsigned)wid * 1024u;
;     const int aoff = lds_byte(wr * 64 + fr, fq * 8), boff = lds_byte(wc * 32 + fr, fq * 8);
;     ...
;     Unit cur, nxt; int ui = 0;
;     if (!S.next(0, cur)) return;
;     f32x4 acc[2][2][4][2];
; #pragma unroll
;     for (int a = 0; a < 2; ++a)
; #pragma unroll
;         for (int b = 0; b < 2; ++b)
; #pragma unroll
;             for (int m = 0; m < 4; ++m)
; #pragma unroll
;                 for (int n = 0; n < 2; ++n) acc[a][b][m][n] = (f32x4){0.f, 0.f, 0.f, 0.f};
;     bf16x8 At[4][2], B0[2][2], B1[2][2];
;     const char* cA = cur.a; const char* cB = cur.b;
;     PG8_STAGE(PG8_SB(0, 0), cB, voffB); PG8_STAGE(PG8_SB(0, 1), cB + hstepB, voffB); PG8_STAGE(PG8_SA(0, 0), cA, voffA); PG8_STAGE(PG8_SA(0, 1), cA + hstepA, voffA);
;     if (wr == 1) PG8_BAR;
;     PG8_WAIT_V(2); PG8_BAR;
;     PG8_STAGE(PG8_SB(1, 0), cB + kstep, voffB); PG8_STAGE(PG8_SA(1, 0), cA + kstepA, voffA); PG8_STAGE(PG8_SB(1, 1), cB + hstepB + kstep, voffB);
;     PG8_WAIT_V(6); PG8_BAR;
.LBB0_130:
	s_or_b64 exec, exec, s[4:5]
	s_add_u32 s36, s26, 0xcc14000
	s_addc_u32 s37, s27, 0
	s_add_u32 s38, s26, 0x10c14000
	s_addc_u32 s39, s27, 0
	s_cmp_lt_i32 s2, s34
	s_cselect_b64 s[44:45], -1, 0
	s_cmpk_lt_i32 s2, 0xb00
	s_cselect_b64 s[4:5], -1, 0
	s_and_b64 s[4:5], s[4:5], s[44:45]
	v_cndmask_b32_e64 v1, 0, 1, s[4:5]
	s_waitcnt lgkmcnt(0)
	v_mov_b32_e32 v0, v184
	v_cmp_ne_u32_e64 s[6:7], 1, v1
	s_barrier
	s_nop 0
	v_writelane_b32 v250, s6, 4
	s_andn2_b64 vcc, exec, s[4:5]
	v_readfirstlane_b32 s5, v0
	v_writelane_b32 v250, s7, 5
	s_cbranch_vccnz .LBB0_146
	v_lshlrev_b32_e32 v4, 4, v0
	v_add_u32_e32 v2, 0x2000, v4
	v_ashrrev_i32_e32 v1, 31, v2
	v_lshrrev_b32_e32 v1, 22, v1
	v_add_u32_e32 v1, v2, v1
	v_ashrrev_i32_e32 v1, 10, v1
	v_mul_i32_i24_e32 v3, 0x400, v1
	v_sub_u32_e32 v2, v2, v3
	v_lshrrev_b32_e32 v3, 4, v2
	v_bitop3_b32 v3, v3, v2, 32 bitop3:0x6c
	v_ashrrev_i32_e32 v2, 31, v3
	v_lshrrev_b32_e32 v2, 26, v2
	v_add_u32_e32 v5, v3, v2
	v_lshlrev_b32_e32 v6, 3, v1
	v_ashrrev_i32_e32 v2, 6, v5
	v_and_b32_e32 v6, -16, v6
	v_add_u32_e32 v6, v2, v6
	v_and_b32_e32 v7, 3, v2
	s_mov_b32 s4, 0x1ffffe0
	v_lshrrev_b32_e32 v8, 2, v6
	v_lshlrev_b32_e32 v9, 1, v6
	v_and_or_b32 v7, v6, s4, v7
	v_and_b32_e32 v8, 4, v8
	v_and_b32_e32 v9, 24, v9
	v_and_b32_e32 v5, 0xc0, v5
	v_or3_b32 v7, v7, v8, v9
	v_sub_u32_e32 v3, v3, v5
	v_mov_b32_e32 v9, 1
	v_lshlrev_b32_e32 v8, 5, v1
	v_ashrrev_i16_sdwa v3, v9, sext(v3) dst_sel:DWORD dst_unused:UNUSED_PAD src0_sel:DWORD src1_sel:BYTE_0
	v_and_b32_e32 v8, 32, v8
	v_bfe_i32 v3, v3, 0, 16
	v_add_lshl_u32 v5, v8, v3, 1
	v_lshl_add_u32 v128, v7, 7, v5
	v_lshl_add_u32 v130, v6, 7, v5
	v_bfe_i32 v5, v0, 27, 1
	v_lshrrev_b32_e32 v5, 22, v5
	v_add_u32_e32 v5, v4, v5
	v_and_b32_e32 v5, 0xfffffc00, v5
	v_sub_u32_e32 v4, v4, v5
	v_lshrrev_b32_e32 v5, 4, v4
	v_bitop3_b32 v6, v5, v4, 32 bitop3:0x6c
	v_ashrrev_i32_e32 v5, 31, v0
	v_lshrrev_b32_e32 v5, 26, v5
	v_ashrrev_i32_e32 v4, 31, v6
	v_add_u32_e32 v5, v0, v5
	v_lshrrev_b32_e32 v4, 26, v4
	v_ashrrev_i32_e32 v5, 6, v5
	v_add_u32_e32 v7, v6, v4
	v_lshlrev_b32_e32 v8, 3, v5
	v_ashrrev_i32_e32 v4, 6, v7
	v_and_b32_e32 v8, -16, v8
	v_add_u32_e32 v8, v4, v8
	v_and_b32_e32 v10, 3, v4
	v_and_or_b32 v10, v8, s4, v10
	s_lshr_b32 s4, s3, 29
	s_add_i32 s4, s2, s4
	s_ashr_i32 s7, s5, 6
	s_ashr_i32 s10, s4, 3
	s_and_b32 s4, s4, -8
	s_ashr_i32 s6, s5, 8
	s_lshl_b32 s18, s7, 10
	s_sub_i32 s4, s2, s4
	s_cmp_lt_i32 s4, 0
	s_movk_i32 s19, 0x161
	s_cselect_b32 s11, s19, 0x160
	s_mul_i32 s4, s4, s11
	s_add_i32 s4, s4, s10
	s_mul_hi_i32 s10, s4, 0x2e8ba2e9
	s_lshr_b32 s11, s10, 31
	s_ashr_i32 s10, s10, 6
	s_add_i32 s10, s10, s11
	s_lshl_b32 s11, s10, 3
	s_mulk_i32 s10, 0x160
	s_sub_i32 s10, s4, s10
	s_sext_i32_i16 s4, s10
	s_bfe_u32 s4, s4, 0x3001c
	s_add_i32 s12, s10, s4
	s_sext_i32_i16 s4, s12
	s_and_b32 s12, s12, 0xfff8
	s_sub_i32 s10, s10, s12
	s_sext_i32_i16 s10, s10
	s_add_i32 s66, s11, s10
	s_ashr_i32 s67, s66, 31
	s_lshr_b32 s4, s4, 3
	s_lshl_b64 s[10:11], s[66:67], 15
	v_lshrrev_b32_e32 v11, 2, v8
	v_lshlrev_b32_e32 v12, 1, v8
	v_and_b32_e32 v7, 0xc0, v7
	s_add_u32 s70, s36, s10
	v_and_b32_e32 v11, 4, v11
	v_and_b32_e32 v12, 24, v12
	v_sub_u32_e32 v6, v6, v7
	s_addc_u32 s71, s37, s11
	s_bfe_i64 s[10:11], s[4:5], 0x100000
	v_or3_b32 v10, v10, v11, v12
	v_lshlrev_b32_e32 v11, 5, v5
	v_ashrrev_i16_sdwa v6, v9, sext(v6) dst_sel:DWORD dst_unused:UNUSED_PAD src0_sel:DWORD src1_sel:BYTE_0
	s_lshl_b64 s[10:11], s[10:11], 15
	v_and_b32_e32 v11, 32, v11
	v_bfe_i32 v6, v6, 0, 16
	s_add_u32 s74, s8, s10
	v_add_lshl_u32 v7, v11, v6, 1
	s_addc_u32 s75, s9, s11
	s_add_i32 s20, s18, 0
	v_lshl_add_u32 v132, v10, 7, v7
	s_add_i32 m0, s20, 0x10000
	v_lshl_add_u32 v134, v8, 7, v7
	global_load_lds_dwordx4 v132, s[74:75]
	s_add_i32 m0, s20, 0x12000
	s_add_u32 s10, s74, 0x4000
	global_load_lds_dwordx4 v128, s[74:75]
	s_addc_u32 s11, s75, 0
	s_add_i32 m0, s20, 0x14000
	s_add_i32 s21, s20, 0x2000
	global_load_lds_dwordx4 v132, s[10:11]
	s_add_i32 m0, s20, 0x16000
	v_mov_b32_e32 v137, 0
	global_load_lds_dwordx4 v128, s[10:11]
	s_mov_b32 m0, s20
	s_add_u32 s10, s70, 0x4000
	global_load_lds_dwordx4 v134, s[70:71]
	s_mov_b32 m0, s21
	s_addc_u32 s11, s71, 0
	s_add_i32 s22, s20, 0x4000
	global_load_lds_dwordx4 v130, s[70:71]
	s_mov_b32 m0, s22
	s_add_i32 s23, s20, 0x6000
	global_load_lds_dwordx4 v134, s[10:11]
	s_mov_b32 m0, s23
	s_cmp_eq_u32 s6, 1
	global_load_lds_dwordx4 v130, s[10:11]
	s_mov_b32 s29, 0
	v_mov_b32_e32 v133, v137
	v_mov_b32_e32 v129, v137
	v_mov_b32_e32 v135, v137
	s_cselect_b64 s[10:11], -1, 0
	s_cmp_lg_u32 s6, 1
	v_mov_b32_e32 v131, v137
	s_cbranch_scc1 .LBB0_133
.LBB0_133:
	s_lshl_b32 s7, s7, 5
	s_and_b32 s30, s7, 0x60
	s_lshl_b32 s40, s6, 13
	s_lshl_b32 s41, s30, 7
	s_add_u32 s12, s74, 0x160000
	s_addc_u32 s13, s75, 0
	s_add_i32 m0, s20, 0x18000
	v_lshl_add_u64 v[8:9], s[12:13], 0, v[132:133]
	s_waitcnt vmcnt(2)
	s_barrier
	global_load_lds_dwordx4 v[8:9], off
	s_add_i32 m0, s20, 0x1a000
	v_lshl_add_u64 v[8:9], s[12:13], 0, v[128:129]
	s_add_u32 s12, s70, 0x200000
	s_addc_u32 s13, s71, 0
	s_add_i32 s31, s20, 0x8000
	global_load_lds_dwordx4 v[8:9], off
	v_lshl_add_u64 v[8:9], s[12:13], 0, v[134:135]
	s_mov_b32 m0, s31
	s_add_i32 s33, s20, 0xa000
	global_load_lds_dwordx4 v[8:9], off
	v_lshl_add_u64 v[8:9], s[12:13], 0, v[130:131]
	s_add_u32 s12, s74, 0x164000
	s_mov_b32 m0, s33
	s_addc_u32 s13, s75, 0
	global_load_lds_dwordx4 v[8:9], off
	s_add_i32 m0, s20, 0x1c000
	v_lshl_add_u64 v[8:9], s[12:13], 0, v[132:133]
	global_load_lds_dwordx4 v[8:9], off
	v_lshl_add_u64 v[8:9], s[12:13], 0, v[128:129]
	s_add_i32 m0, s20, 0x1e000
	v_and_b32_e32 v7, 15, v0
	global_load_lds_dwordx4 v[8:9], off
	v_lshrrev_b32_e32 v8, 1, v0
	v_and_b32_e32 v8, 24, v8
	v_lshlrev_b32_e32 v9, 1, v8
	v_lshlrev_b32_e32 v0, 2, v0
	v_lshl_or_b32 v148, s6, 6, v7
	v_lshl_or_b32 v7, v7, 6, v9
	v_and_b32_e32 v0, 32, v0
	v_bitop3_b32 v9, v7, s40, v0 bitop3:0xde
	v_bitop3_b32 v149, v7, s41, v0 bitop3:0xde
	v_lshlrev_b32_e32 v7, 10, v5
	v_and_b32_e32 v7, 0xfffff800, v7
	v_lshl_add_u32 v4, v4, 7, v7
	v_and_b32_e32 v5, 1, v5
	v_lshl_or_b32 v4, v5, 6, v4
	v_lshl_add_u32 v138, v6, 1, v4
	v_lshlrev_b32_e32 v4, 10, v1
	v_and_b32_e32 v4, 0xfffff800, v4
	s_waitcnt vmcnt(6)
	s_cmpk_lt_u32 s5, 0x100
	v_lshl_add_u32 v2, v2, 7, v4
	v_and_b32_e32 v1, 1, v1
	s_cselect_b64 s[12:13], -1, 0
	v_and_or_b32 v0, s7, 32, v8
	v_lshl_or_b32 v1, v1, 6, v2
	s_add_i32 s42, 0, 0x10000
	s_add_i32 s43, 0, 0x14000
	s_sext_i32_i16 s50, s4
	v_mov_b32_e32 v139, v137
	v_lshl_add_u32 v140, v3, 1, v1
	v_mov_b32_e32 v141, v137
	v_mov_b64_e32 v[142:143], 0xb00
	v_mov_b64_e32 v[144:145], 0xaff
	v_add_u32_e32 v150, s42, v149
	v_add_u32_e32 v151, s43, v149
	v_add_u32_e32 v152, 0, v9
	v_lshlrev_b32_e32 v136, 1, v0
	s_barrier
	s_branch .LBB0_136

; #define PG8_STAGE(bufoff, gbase, voff) do { _Pragma("unroll") for (int _i = 0; _i < 2; ++_i) \
;         __builtin_amdgcn_global_load_lds((const unsigned*)((const char*)(gbase) + (voff)[_i]), (LAS unsigned*)(lds + (bufoff) + ldsw + _i * 8192), 16, 0, 0); } while (0)
; #define PG8_LDA(dst, b, h) do { _Pragma("unroll") for (int m = 0; m < 4; ++m) _Pragma("unroll") for (int k = 0; k < 2; ++k) dst[m][k] = *(const LAS bf16x8*)(lds + PG8_SA(b, h) + aoff + m * 2048 + k * 1024); } while (0)
; #define PG8_LDB(dst, b, h) do { _Pragma("unroll") for (int n = 0; n < 2; ++n) _Pragma("unroll") for (int k = 0; k < 2; ++k) dst[n][k] = *(const LAS bf16x8*)(lds + PG8_SB(b, h) + boff + n * 2048 + k * 1024); } while (0)
; #define PG8_WAIT_V(n) asm volatile("s_waitcnt vmcnt(" #n ")" ::: "memory")
; #define PG8_WAIT_L(n) asm volatile("s_waitcnt lgkmcnt(" #n ")" ::: "memory")
; #define PG8_BAR __builtin_amdgcn_s_barrier()
; #define PG8_SCHED __builtin_amdgcn_sched_barrier(0)
; template <bool ALIGN_EPI, class Epi, class Sched>
; __device__ __forceinline__ void gemm_phase(LAS unsigned char* lds, const int lda, const int ldb, const int K, const Sched& S, const Epi& E, const size_t kstepA = (size_t)(BK * 2), const size_t kstepB = (size_t)(BK * 2)) {
;     ...
;     for (;;) {
;         const bool has_next = S.next(ui + 1, nxt);
;         const char* nA = has_next ? nxt.a : cA; const char* nB = has_next ? nxt.b : cB;
; #pragma unroll 1
;         for (int t = 0; t < nt; t += 2) {
;             const bool last = (t == nt - 2);
;             const char* a1 = cA + (size_t)(t + 1) * kstepA;
;             const char* a2 = last ? nA : cA + (size_t)(t + 2) * kstepA; const char* b2 = last ? nB : cB + (size_t)(t + 2) * kstep;
;             const char* a3 = a2 + kstepA; const char* b3 = b2 + kstep;
;             PG8_LDB(B0, 0, 0); PG8_LDB(B1, 0, 1); PG8_SCHED; PG8_LDA(At, 0, 0); PG8_STAGE(PG8_SA(1, 1), a1 + hstepA, voffA);
;             PG8_WAIT_V(8); PG8_WAIT_L(0); PG8_BAR; PG8_MMA(0, 0, At, B0); PG8_MMA(0, 1, At, B1); PG8_BAR; PG8_SCHED;
;     ...
; #pragma unroll
;         for (int a = 0; a < 2; ++a)
; #pragma unroll
;             for (int b = 0; b < 2; ++b)
; #pragma unroll
;                 for (int m = 0; m < 4; ++m)
; #pragma unroll
;                     for (int n = 0; n < 2; ++n) acc[a][b][m][n] = (f32x4){0.f, 0.f, 0.f, 0.f};
;         cur = nxt; cA = nA; cB = nB; ++ui;
.LBB0_138:
	s_add_u32 s41, s74, 0x2c0000
	s_addc_u32 s49, s75, 0
	s_add_u32 s70, s70, 0x204000
	v_mov_b32_e32 v0, 0
	s_addc_u32 s71, s71, 0
	s_mov_b32 s51, -2
	v_mov_b32_e32 v1, v0
	v_mov_b32_e32 v2, v0
	v_mov_b32_e32 v3, v0
	v_mov_b32_e32 v8, v0
	v_mov_b32_e32 v9, v0
	v_mov_b32_e32 v10, v0
	v_mov_b32_e32 v11, v0
	v_mov_b32_e32 v16, v0
	v_mov_b32_e32 v17, v0
	v_mov_b32_e32 v18, v0
	v_mov_b32_e32 v19, v0
	v_mov_b32_e32 v24, v0
	v_mov_b32_e32 v25, v0
	v_mov_b32_e32 v26, v0
	v_mov_b32_e32 v27, v0
	v_mov_b32_e32 v32, v0
	v_mov_b32_e32 v33, v0
	v_mov_b32_e32 v34, v0
	v_mov_b32_e32 v35, v0
	v_mov_b32_e32 v40, v0
	v_mov_b32_e32 v41, v0
	v_mov_b32_e32 v42, v0
	v_mov_b32_e32 v43, v0
	v_mov_b32_e32 v48, v0
	v_mov_b32_e32 v49, v0
	v_mov_b32_e32 v50, v0
	v_mov_b32_e32 v51, v0
	v_mov_b32_e32 v56, v0
	v_mov_b32_e32 v57, v0
	v_mov_b32_e32 v58, v0
	v_mov_b32_e32 v59, v0
	v_mov_b32_e32 v4, v0
	v_mov_b32_e32 v5, v0
	v_mov_b32_e32 v6, v0
	v_mov_b32_e32 v7, v0
	v_mov_b32_e32 v12, v0
	v_mov_b32_e32 v13, v0
	v_mov_b32_e32 v14, v0
	v_mov_b32_e32 v15, v0
	v_mov_b32_e32 v20, v0
	v_mov_b32_e32 v21, v0
	v_mov_b32_e32 v22, v0
	v_mov_b32_e32 v23, v0
	v_mov_b32_e32 v28, v0
	v_mov_b32_e32 v29, v0
	v_mov_b32_e32 v30, v0
	v_mov_b32_e32 v31, v0
	v_mov_b32_e32 v36, v0
	v_mov_b32_e32 v37, v0
	v_mov_b32_e32 v38, v0
	v_mov_b32_e32 v39, v0
	v_mov_b32_e32 v44, v0
	v_mov_b32_e32 v45, v0
	v_mov_b32_e32 v46, v0
	v_mov_b32_e32 v47, v0
	v_mov_b32_e32 v52, v0
	v_mov_b32_e32 v53, v0
	v_mov_b32_e32 v54, v0
	v_mov_b32_e32 v55, v0
	v_mov_b32_e32 v60, v0
	v_mov_b32_e32 v61, v0
	v_mov_b32_e32 v62, v0
	v_mov_b32_e32 v63, v0
	v_mov_b32_e32 v64, v0
	v_mov_b32_e32 v65, v0
	v_mov_b32_e32 v66, v0
	v_mov_b32_e32 v67, v0
	v_mov_b32_e32 v72, v0
	v_mov_b32_e32 v73, v0
	v_mov_b32_e32 v74, v0
	v_mov_b32_e32 v75, v0
	v_mov_b32_e32 v80, v0
	v_mov_b32_e32 v81, v0
	v_mov_b32_e32 v82, v0
	v_mov_b32_e32 v83, v0
	v_mov_b32_e32 v88, v0
	v_mov_b32_e32 v89, v0
	v_mov_b32_e32 v90, v0
	v_mov_b32_e32 v91, v0
	v_mov_b32_e32 v96, v0
	v_mov_b32_e32 v97, v0
	v_mov_b32_e32 v98, v0
	v_mov_b32_e32 v99, v0
	v_mov_b32_e32 v104, v0
	v_mov_b32_e32 v105, v0
	v_mov_b32_e32 v106, v0
	v_mov_b32_e32 v107, v0
	v_mov_b32_e32 v112, v0
	v_mov_b32_e32 v113, v0
	v_mov_b32_e32 v114, v0
	v_mov_b32_e32 v115, v0
	v_mov_b32_e32 v120, v0
	v_mov_b32_e32 v121, v0
	v_mov_b32_e32 v122, v0
	v_mov_b32_e32 v123, v0
	v_mov_b32_e32 v68, v0
	v_mov_b32_e32 v69, v0
	v_mov_b32_e32 v70, v0
	v_mov_b32_e32 v71, v0
	v_mov_b32_e32 v76, v0
	v_mov_b32_e32 v77, v0
	v_mov_b32_e32 v78, v0
	v_mov_b32_e32 v79, v0
	v_mov_b32_e32 v84, v0
	v_mov_b32_e32 v85, v0
	v_mov_b32_e32 v86, v0
	v_mov_b32_e32 v87, v0
	v_mov_b32_e32 v92, v0
	v_mov_b32_e32 v93, v0
	v_mov_b32_e32 v94, v0
	v_mov_b32_e32 v95, v0
	v_mov_b32_e32 v100, v0
	v_mov_b32_e32 v101, v0
	v_mov_b32_e32 v102, v0
	v_mov_b32_e32 v103, v0
	v_mov_b32_e32 v108, v0
	v_mov_b32_e32 v109, v0
	v_mov_b32_e32 v110, v0
	v_mov_b32_e32 v111, v0
	v_mov_b32_e32 v116, v0
	v_mov_b32_e32 v117, v0
	v_mov_b32_e32 v118, v0
	v_mov_b32_e32 v119, v0
	v_mov_b32_e32 v124, v0
	v_mov_b32_e32 v125, v0
	v_mov_b32_e32 v126, v0
	v_mov_b32_e32 v127, v0
	s_cmp_lg_u64 s[12:13], 0
	s_cbranch_scc0 .Lp1_kloop_y
.LBB0_139:
	ds_read_b128 v[154:157], v150
	ds_read_b128 v[158:161], v150 offset:1024
	ds_read_b128 v[162:165], v150 offset:2048
	ds_read_b128 v[166:169], v150 offset:3072
	ds_read_b128 v[170:173], v151
	ds_read_b128 v[174:177], v151 offset:1024
	ds_read_b128 v[178:181], v151 offset:2048
	ds_read_b128 v[194:197], v151 offset:3072
	s_add_u32 s54, s70, 0x1fc000
	s_addc_u32 s55, s71, 0
	s_cmp_eq_u32 s51, 28
	s_cselect_b32 s78, s6, s54
	s_cselect_b32 s79, s7, s55
	s_cselect_b32 s76, s68, s41
	s_cselect_b32 s77, s69, s49
	s_add_u32 s74, s78, 0x200000
	s_addc_u32 s75, s79, 0
	v_lshl_add_u64 v[146:147], s[70:71], 0, v[138:139]
	s_add_i32 m0, s20, 0xc000
	ds_read_b128 v[198:201], v152
	ds_read_b128 v[202:205], v152 offset:1024
	ds_read_b128 v[206:209], v152 offset:2048
	ds_read_b128 v[210:213], v152 offset:3072
	ds_read_b128 v[214:217], v152 offset:4096
	ds_read_b128 v[218:221], v152 offset:5120
	ds_read_b128 v[222:225], v152 offset:6144
	ds_read_b128 v[226:229], v152 offset:7168
	global_load_lds_dwordx4 v[146:147], off
	v_lshl_add_u64 v[146:147], s[70:71], 0, v[140:141]
	s_add_i32 m0, s20, 0xe000
	s_nop 0
	global_load_lds_dwordx4 v[146:147], off
	s_waitcnt vmcnt(8)
	s_waitcnt lgkmcnt(0)
	s_setprio 1
	s_waitcnt lgkmcnt(0)
	v_mfma_f32_16x16x32_bf16 v[124:127], v[154:157], v[198:201], v[124:127]
	v_mfma_f32_16x16x32_bf16 v[124:127], v[158:161], v[202:205], v[124:127]
	v_mfma_f32_16x16x32_bf16 v[116:119], v[162:165], v[198:201], v[116:119]
	v_mfma_f32_16x16x32_bf16 v[116:119], v[166:169], v[202:205], v[116:119]
	v_mfma_f32_16x16x32_bf16 v[108:111], v[154:157], v[206:209], v[108:111]
	v_mfma_f32_16x16x32_bf16 v[108:111], v[158:161], v[210:213], v[108:111]
	v_mfma_f32_16x16x32_bf16 v[100:103], v[162:165], v[206:209], v[100:103]
	v_mfma_f32_16x16x32_bf16 v[100:103], v[166:169], v[210:213], v[100:103]
	v_mfma_f32_16x16x32_bf16 v[92:95], v[154:157], v[214:217], v[92:95]
	v_mfma_f32_16x16x32_bf16 v[92:95], v[158:161], v[218:221], v[92:95]
	v_mfma_f32_16x16x32_bf16 v[84:87], v[162:165], v[214:217], v[84:87]
	v_mfma_f32_16x16x32_bf16 v[84:87], v[166:169], v[218:221], v[84:87]
	v_mfma_f32_16x16x32_bf16 v[76:79], v[154:157], v[222:225], v[76:79]
	v_mfma_f32_16x16x32_bf16 v[76:79], v[158:161], v[226:229], v[76:79]
	v_mfma_f32_16x16x32_bf16 v[68:71], v[162:165], v[222:225], v[68:71]
	v_mfma_f32_16x16x32_bf16 v[68:71], v[166:169], v[226:229], v[68:71]
	s_setprio 0
	s_setprio 1
	v_mfma_f32_16x16x32_bf16 v[120:123], v[170:173], v[198:201], v[120:123]
	v_mfma_f32_16x16x32_bf16 v[120:123], v[174:177], v[202:205], v[120:123]
	v_mfma_f32_16x16x32_bf16 v[112:115], v[178:181], v[198:201], v[112:115]
	v_mfma_f32_16x16x32_bf16 v[112:115], v[194:197], v[202:205], v[112:115]
	v_mfma_f32_16x16x32_bf16 v[104:107], v[170:173], v[206:209], v[104:107]
	v_mfma_f32_16x16x32_bf16 v[104:107], v[174:177], v[210:213], v[104:107]
	v_mfma_f32_16x16x32_bf16 v[96:99], v[178:181], v[206:209], v[96:99]
	v_mfma_f32_16x16x32_bf16 v[96:99], v[194:197], v[210:213], v[96:99]
	v_mfma_f32_16x16x32_bf16 v[88:91], v[170:173], v[214:217], v[88:91]
	v_mfma_f32_16x16x32_bf16 v[88:91], v[174:177], v[218:221], v[88:91]
	v_mfma_f32_16x16x32_bf16 v[80:83], v[178:181], v[214:217], v[80:83]
	v_mfma_f32_16x16x32_bf16 v[80:83], v[194:197], v[218:221], v[80:83]
	v_mfma_f32_16x16x32_bf16 v[72:75], v[170:173], v[222:225], v[72:75]
	v_mfma_f32_16x16x32_bf16 v[72:75], v[174:177], v[226:229], v[72:75]
	v_mfma_f32_16x16x32_bf16 v[64:67], v[178:181], v[222:225], v[64:67]
	v_mfma_f32_16x16x32_bf16 v[64:67], v[194:197], v[226:229], v[64:67]
	s_setprio 0
	s_barrier
; #define PG8_STAGE(bufoff, gbase, voff) do { _Pragma("unroll") for (int _i = 0; _i < 2; ++_i) \
;         __builtin_amdgcn_global_load_lds((const unsigned*)((const char*)(gbase) + (voff)[_i]), (LAS unsigned*)(lds + (bufoff) + ldsw + _i * 8192), 16, 0, 0); } while (0)
; #define PG8_LDA(dst, b, h) do { _Pragma("unroll") for (int m = 0; m < 4; ++m) _Pragma("unroll") for (int k = 0; k < 2; ++k) dst[m][k] = *(const LAS bf16x8*)(lds + PG8_SA(b, h) + aoff + m * 2048 + k * 1024); } while (0)
; #define PG8_LDB(dst, b, h) do { _Pragma("unroll") for (int n = 0; n < 2; ++n) _Pragma("unroll") for (int k = 0; k < 2; ++k) dst[n][k] = *(const LAS bf16x8*)(lds + PG8_SB(b, h) + boff + n * 2048 + k * 1024); } while (0)
; #define PG8_MMA(ai, bj, At, Bt) do { __builtin_amdgcn_s_setprio(1); _Pragma("unroll") for (int m = 0; m < 4; ++m) _Pragma("unroll") for (int n = 0; n < 2; ++n) _Pragma("unroll") for (int k = 0; k < 2; ++k) \
;         acc[ai][bj][m][n] = __builtin_amdgcn_mfma_f32_16x16x32_bf16(Bt[n][k], At[m][k], acc[ai][bj][m][n], 0, 0, 0); __builtin_amdgcn_s_setprio(0); } while (0)
; #define PG8_WAIT_V(n) asm volatile("s_waitcnt vmcnt(" #n ")" ::: "memory")
; #define PG8_WAIT_L(n) asm volatile("s_waitcnt lgkmcnt(" #n ")" ::: "memory")
; #define PG8_BAR __builtin_amdgcn_s_barrier()
; #define PG8_SCHED __builtin_amdgcn_sched_barrier(0)
; template <bool ALIGN_EPI, class Epi, class Sched>
; __device__ __forceinline__ void gemm_phase(LAS unsigned char* lds, const int lda, const int ldb, const int K, const Sched& S, const Epi& E, const size_t kstepA = (size_t)(BK * 2), const size_t kstepB = (size_t)(BK * 2)) {
;     ...
;             PG8_LDA(At, 0, 1); PG8_STAGE(PG8_SB(0, 0), b2, voffB); PG8_STAGE(PG8_SB(0, 1), b2 + hstepB, voffB); PG8_STAGE(PG8_SA(0, 0), a2, voffA);
;             PG8_WAIT_V(8); PG8_WAIT_L(0); PG8_BAR; PG8_MMA(1, 0, At, B0); PG8_MMA(1, 1, At, B1); PG8_BAR; PG8_SCHED;
;             PG8_LDB(B0, 1, 0); PG8_LDB(B1, 1, 1); PG8_SCHED; PG8_LDA(At, 1, 0); PG8_STAGE(PG8_SA(0, 1), a2 + hstepA, voffA);
;             PG8_WAIT_V(8); PG8_WAIT_L(0); PG8_BAR; PG8_MMA(0, 0, At, B0); PG8_MMA(0, 1, At, B1); PG8_BAR; PG8_SCHED;
	s_add_i32 s54, s42, s18
	v_lshl_add_u64 v[146:147], s[76:77], 0, v[132:133]
	s_mov_b32 m0, s54
	ds_read_b128 v[198:201], v152 offset:16384
	ds_read_b128 v[202:205], v152 offset:17408
	ds_read_b128 v[206:209], v152 offset:18432
	ds_read_b128 v[210:213], v152 offset:19456
	ds_read_b128 v[214:217], v152 offset:20480
	ds_read_b128 v[218:221], v152 offset:21504
	ds_read_b128 v[222:225], v152 offset:22528
	ds_read_b128 v[226:229], v152 offset:23552
	global_load_lds_dwordx4 v[146:147], off
	s_add_i32 m0, s54, 0x2000
	s_add_u32 s54, s76, 0x4000
	v_lshl_add_u64 v[146:147], s[76:77], 0, v[128:129]
	s_addc_u32 s55, s77, 0
	s_add_i32 s56, s43, s18
	global_load_lds_dwordx4 v[146:147], off
	v_lshl_add_u64 v[146:147], s[54:55], 0, v[132:133]
	s_mov_b32 m0, s56
	s_nop 0
	global_load_lds_dwordx4 v[146:147], off
	v_lshl_add_u64 v[146:147], s[54:55], 0, v[128:129]
	s_add_i32 m0, s56, 0x2000
	s_nop 0
	global_load_lds_dwordx4 v[146:147], off
	v_lshl_add_u64 v[146:147], s[78:79], 0, v[134:135]
	s_mov_b32 m0, s20
	s_nop 0
	global_load_lds_dwordx4 v[146:147], off
	v_lshl_add_u64 v[146:147], s[78:79], 0, v[130:131]
	s_mov_b32 m0, s21
	s_nop 0
	global_load_lds_dwordx4 v[146:147], off
	s_waitcnt vmcnt(8)
	s_waitcnt lgkmcnt(0)
	s_setprio 1
	s_waitcnt lgkmcnt(0)
	v_mfma_f32_16x16x32_bf16 v[60:63], v[154:157], v[198:201], v[60:63]
	v_mfma_f32_16x16x32_bf16 v[60:63], v[158:161], v[202:205], v[60:63]
	v_mfma_f32_16x16x32_bf16 v[52:55], v[162:165], v[198:201], v[52:55]
	v_mfma_f32_16x16x32_bf16 v[52:55], v[166:169], v[202:205], v[52:55]
	v_mfma_f32_16x16x32_bf16 v[44:47], v[154:157], v[206:209], v[44:47]
	v_mfma_f32_16x16x32_bf16 v[44:47], v[158:161], v[210:213], v[44:47]
	v_mfma_f32_16x16x32_bf16 v[36:39], v[162:165], v[206:209], v[36:39]
	v_mfma_f32_16x16x32_bf16 v[36:39], v[166:169], v[210:213], v[36:39]
	v_mfma_f32_16x16x32_bf16 v[28:31], v[154:157], v[214:217], v[28:31]
	v_mfma_f32_16x16x32_bf16 v[28:31], v[158:161], v[218:221], v[28:31]
	v_mfma_f32_16x16x32_bf16 v[20:23], v[162:165], v[214:217], v[20:23]
	v_mfma_f32_16x16x32_bf16 v[20:23], v[166:169], v[218:221], v[20:23]
	v_mfma_f32_16x16x32_bf16 v[12:15], v[154:157], v[222:225], v[12:15]
	v_mfma_f32_16x16x32_bf16 v[12:15], v[158:161], v[226:229], v[12:15]
	v_mfma_f32_16x16x32_bf16 v[4:7], v[162:165], v[222:225], v[4:7]
	v_mfma_f32_16x16x32_bf16 v[4:7], v[166:169], v[226:229], v[4:7]
	s_setprio 0
	s_setprio 1
	v_mfma_f32_16x16x32_bf16 v[56:59], v[170:173], v[198:201], v[56:59]
	v_mfma_f32_16x16x32_bf16 v[56:59], v[174:177], v[202:205], v[56:59]
	v_mfma_f32_16x16x32_bf16 v[48:51], v[178:181], v[198:201], v[48:51]
	v_mfma_f32_16x16x32_bf16 v[48:51], v[194:197], v[202:205], v[48:51]
	v_mfma_f32_16x16x32_bf16 v[40:43], v[170:173], v[206:209], v[40:43]
	v_mfma_f32_16x16x32_bf16 v[40:43], v[174:177], v[210:213], v[40:43]
	v_mfma_f32_16x16x32_bf16 v[32:35], v[178:181], v[206:209], v[32:35]
	v_mfma_f32_16x16x32_bf16 v[32:35], v[194:197], v[210:213], v[32:35]
	v_mfma_f32_16x16x32_bf16 v[24:27], v[170:173], v[214:217], v[24:27]
	v_mfma_f32_16x16x32_bf16 v[24:27], v[174:177], v[218:221], v[24:27]
	v_mfma_f32_16x16x32_bf16 v[16:19], v[178:181], v[214:217], v[16:19]
	v_mfma_f32_16x16x32_bf16 v[16:19], v[194:197], v[218:221], v[16:19]
	v_mfma_f32_16x16x32_bf16 v[8:11], v[170:173], v[222:225], v[8:11]
	v_mfma_f32_16x16x32_bf16 v[8:11], v[174:177], v[226:229], v[8:11]
	v_mfma_f32_16x16x32_bf16 v[0:3], v[178:181], v[222:225], v[0:3]
	v_mfma_f32_16x16x32_bf16 v[0:3], v[194:197], v[226:229], v[0:3]
	s_setprio 0
	s_barrier
	s_add_i32 s56, 0, 0x18000
	v_add_u32_e32 v146, s56, v149
	s_add_i32 s57, 0, 0x1c000
	ds_read_b128 v[154:157], v146
	ds_read_b128 v[158:161], v146 offset:1024
	ds_read_b128 v[162:165], v146 offset:2048
	ds_read_b128 v[166:169], v146 offset:3072
	v_add_u32_e32 v146, s57, v149
	ds_read_b128 v[170:173], v146
	ds_read_b128 v[174:177], v146 offset:1024
	ds_read_b128 v[178:181], v146 offset:2048
	ds_read_b128 v[194:197], v146 offset:3072
	s_add_u32 s54, s78, 0x4000
	s_addc_u32 s55, s79, 0
	s_mov_b32 m0, s22
	v_lshl_add_u64 v[146:147], s[54:55], 0, v[134:135]
	ds_read_b128 v[198:201], v152 offset:32768
	ds_read_b128 v[202:205], v152 offset:33792
	ds_read_b128 v[206:209], v152 offset:34816
	ds_read_b128 v[210:213], v152 offset:35840
	ds_read_b128 v[214:217], v152 offset:36864
	ds_read_b128 v[218:221], v152 offset:37888
	ds_read_b128 v[222:225], v152 offset:38912
	ds_read_b128 v[226:229], v152 offset:39936
	global_load_lds_dwordx4 v[146:147], off
	v_lshl_add_u64 v[146:147], s[54:55], 0, v[130:131]
	s_mov_b32 m0, s23
	s_nop 0
	global_load_lds_dwordx4 v[146:147], off
	s_waitcnt vmcnt(8)
	s_waitcnt lgkmcnt(0)
	s_setprio 1
	s_waitcnt lgkmcnt(0)
	v_mfma_f32_16x16x32_bf16 v[124:127], v[154:157], v[198:201], v[124:127]
	v_mfma_f32_16x16x32_bf16 v[124:127], v[158:161], v[202:205], v[124:127]
	v_mfma_f32_16x16x32_bf16 v[116:119], v[162:165], v[198:201], v[116:119]
	v_mfma_f32_16x16x32_bf16 v[116:119], v[166:169], v[202:205], v[116:119]
	v_mfma_f32_16x16x32_bf16 v[108:111], v[154:157], v[206:209], v[108:111]
	v_mfma_f32_16x16x32_bf16 v[108:111], v[158:161], v[210:213], v[108:111]
	v_mfma_f32_16x16x32_bf16 v[100:103], v[162:165], v[206:209], v[100:103]
	v_mfma_f32_16x16x32_bf16 v[100:103], v[166:169], v[210:213], v[100:103]
	v_mfma_f32_16x16x32_bf16 v[92:95], v[154:157], v[214:217], v[92:95]
	v_mfma_f32_16x16x32_bf16 v[92:95], v[158:161], v[218:221], v[92:95]
	v_mfma_f32_16x16x32_bf16 v[84:87], v[162:165], v[214:217], v[84:87]
	v_mfma_f32_16x16x32_bf16 v[84:87], v[166:169], v[218:221], v[84:87]
	v_mfma_f32_16x16x32_bf16 v[76:79], v[154:157], v[222:225], v[76:79]
	v_mfma_f32_16x16x32_bf16 v[76:79], v[158:161], v[226:229], v[76:79]
	v_mfma_f32_16x16x32_bf16 v[68:71], v[162:165], v[222:225], v[68:71]
	v_mfma_f32_16x16x32_bf16 v[68:71], v[166:169], v[226:229], v[68:71]
	s_setprio 0
	s_setprio 1
	v_mfma_f32_16x16x32_bf16 v[120:123], v[170:173], v[198:201], v[120:123]
	v_mfma_f32_16x16x32_bf16 v[120:123], v[174:177], v[202:205], v[120:123]
	v_mfma_f32_16x16x32_bf16 v[112:115], v[178:181], v[198:201], v[112:115]
	v_mfma_f32_16x16x32_bf16 v[112:115], v[194:197], v[202:205], v[112:115]
	v_mfma_f32_16x16x32_bf16 v[104:107], v[170:173], v[206:209], v[104:107]
	v_mfma_f32_16x16x32_bf16 v[104:107], v[174:177], v[210:213], v[104:107]
	v_mfma_f32_16x16x32_bf16 v[96:99], v[178:181], v[206:209], v[96:99]
	v_mfma_f32_16x16x32_bf16 v[96:99], v[194:197], v[210:213], v[96:99]
	v_mfma_f32_16x16x32_bf16 v[88:91], v[170:173], v[214:217], v[88:91]
	v_mfma_f32_16x16x32_bf16 v[88:91], v[174:177], v[218:221], v[88:91]
	v_mfma_f32_16x16x32_bf16 v[80:83], v[178:181], v[214:217], v[80:83]
	v_mfma_f32_16x16x32_bf16 v[80:83], v[194:197], v[218:221], v[80:83]
	v_mfma_f32_16x16x32_bf16 v[72:75], v[170:173], v[222:225], v[72:75]
	v_mfma_f32_16x16x32_bf16 v[72:75], v[174:177], v[226:229], v[72:75]
	v_mfma_f32_16x16x32_bf16 v[64:67], v[178:181], v[222:225], v[64:67]
	v_mfma_f32_16x16x32_bf16 v[64:67], v[194:197], v[226:229], v[64:67]
	s_setprio 0
	s_barrier
; #define PG8_STAGE(bufoff, gbase, voff) do { _Pragma("unroll") for (int _i = 0; _i < 2; ++_i) \
;         __builtin_amdgcn_global_load_lds((const unsigned*)((const char*)(gbase) + (voff)[_i]), (LAS unsigned*)(lds + (bufoff) + ldsw + _i * 8192), 16, 0, 0); } while (0)
; #define PG8_LDA(dst, b, h) do { _Pragma("unroll") for (int m = 0; m < 4; ++m) _Pragma("unroll") for (int k = 0; k < 2; ++k) dst[m][k] = *(const LAS bf16x8*)(lds + PG8_SA(b, h) + aoff + m * 2048 + k * 1024); } while (0)
; #define PG8_LDB(dst, b, h) do { _Pragma("unroll") for (int n = 0; n < 2; ++n) _Pragma("unroll") for (int k = 0; k < 2; ++k) dst[n][k] = *(const LAS bf16x8*)(lds + PG8_SB(b, h) + boff + n * 2048 + k * 1024); } while (0)
; #define PG8_MMA(ai, bj, At, Bt) do { __builtin_amdgcn_s_setprio(1); _Pragma("unroll") for (int m = 0; m < 4; ++m) _Pragma("unroll") for (int n = 0; n < 2; ++n) _Pragma("unroll") for (int k = 0; k < 2; ++k) \
;         acc[ai][bj][m][n] = __builtin_amdgcn_mfma_f32_16x16x32_bf16(Bt[n][k], At[m][k], acc[ai][bj][m][n], 0, 0, 0); __builtin_amdgcn_s_setprio(0); } while (0)
; #define PG8_WAIT_V(n) asm volatile("s_waitcnt vmcnt(" #n ")" ::: "memory")
; #define PG8_WAIT_L(n) asm volatile("s_waitcnt lgkmcnt(" #n ")" ::: "memory")
; #define PG8_BAR __builtin_amdgcn_s_barrier()
; #define PG8_SCHED __builtin_amdgcn_sched_barrier(0)
; template <bool ALIGN_EPI, class Epi, class Sched>
; __device__ __forceinline__ void gemm_phase(LAS unsigned char* lds, const int lda, const int ldb, const int K, const Sched& S, const Epi& E, const size_t kstepA = (size_t)(BK * 2), const size_t kstepB = (size_t)(BK * 2)) {
;     ...
;             PG8_LDB(B0, 0, 0); PG8_LDB(B1, 0, 1); PG8_SCHED; PG8_LDA(At, 0, 0); PG8_STAGE(PG8_SA(1, 1), a1 + hstepA, voffA);
;             PG8_WAIT_V(8); PG8_WAIT_L(0); PG8_BAR; PG8_MMA(0, 0, At, B0); PG8_MMA(0, 1, At, B1); PG8_BAR; PG8_SCHED;
;     ...
;             PG8_LDA(At, 1, 1); PG8_STAGE(PG8_SB(1, 0), b3, voffB); PG8_STAGE(PG8_SB(1, 1), b3 + hstepB, voffB); PG8_STAGE(PG8_SA(1, 0), a3, voffA);
;             PG8_WAIT_V(8); PG8_WAIT_L(0); PG8_BAR; PG8_MMA(1, 0, At, B0); PG8_MMA(1, 1, At, B1); PG8_BAR; PG8_SCHED;
;         }
	s_add_u32 s54, s76, 0x160000
	s_addc_u32 s55, s77, 0
	s_add_i32 s56, s56, s18
	v_lshl_add_u64 v[146:147], s[54:55], 0, v[132:133]
	s_mov_b32 m0, s56
	ds_read_b128 v[198:201], v152 offset:49152
	ds_read_b128 v[202:205], v152 offset:50176
	ds_read_b128 v[206:209], v152 offset:51200
	ds_read_b128 v[210:213], v152 offset:52224
	ds_read_b128 v[214:217], v152 offset:53248
	ds_read_b128 v[218:221], v152 offset:54272
	ds_read_b128 v[222:225], v152 offset:55296
	ds_read_b128 v[226:229], v152 offset:56320
	global_load_lds_dwordx4 v[146:147], off
	s_add_i32 m0, s56, 0x2000
	v_lshl_add_u64 v[146:147], s[54:55], 0, v[128:129]
	s_add_u32 s54, s76, 0x164000
	s_addc_u32 s55, s77, 0
	s_add_i32 s56, s57, s18
	global_load_lds_dwordx4 v[146:147], off
	v_lshl_add_u64 v[146:147], s[54:55], 0, v[132:133]
	s_mov_b32 m0, s56
	s_nop 0
	global_load_lds_dwordx4 v[146:147], off
	v_lshl_add_u64 v[146:147], s[54:55], 0, v[128:129]
	s_add_i32 m0, s56, 0x2000
	s_nop 0
	global_load_lds_dwordx4 v[146:147], off
	v_lshl_add_u64 v[146:147], s[74:75], 0, v[134:135]
	s_mov_b32 m0, s31
	s_nop 0
	global_load_lds_dwordx4 v[146:147], off
	v_lshl_add_u64 v[146:147], s[74:75], 0, v[130:131]
	s_mov_b32 m0, s33
	s_nop 0
	global_load_lds_dwordx4 v[146:147], off
	s_waitcnt vmcnt(8)
	s_waitcnt lgkmcnt(0)
	s_setprio 1
	s_waitcnt lgkmcnt(0)
	v_mfma_f32_16x16x32_bf16 v[60:63], v[154:157], v[198:201], v[60:63]
	v_mfma_f32_16x16x32_bf16 v[60:63], v[158:161], v[202:205], v[60:63]
	v_mfma_f32_16x16x32_bf16 v[52:55], v[162:165], v[198:201], v[52:55]
	v_mfma_f32_16x16x32_bf16 v[52:55], v[166:169], v[202:205], v[52:55]
	v_mfma_f32_16x16x32_bf16 v[44:47], v[154:157], v[206:209], v[44:47]
	v_mfma_f32_16x16x32_bf16 v[44:47], v[158:161], v[210:213], v[44:47]
	v_mfma_f32_16x16x32_bf16 v[36:39], v[162:165], v[206:209], v[36:39]
	v_mfma_f32_16x16x32_bf16 v[36:39], v[166:169], v[210:213], v[36:39]
	v_mfma_f32_16x16x32_bf16 v[28:31], v[154:157], v[214:217], v[28:31]
	v_mfma_f32_16x16x32_bf16 v[28:31], v[158:161], v[218:221], v[28:31]
	v_mfma_f32_16x16x32_bf16 v[20:23], v[162:165], v[214:217], v[20:23]
	v_mfma_f32_16x16x32_bf16 v[20:23], v[166:169], v[218:221], v[20:23]
	v_mfma_f32_16x16x32_bf16 v[12:15], v[154:157], v[222:225], v[12:15]
	v_mfma_f32_16x16x32_bf16 v[12:15], v[158:161], v[226:229], v[12:15]
	v_mfma_f32_16x16x32_bf16 v[4:7], v[162:165], v[222:225], v[4:7]
	v_mfma_f32_16x16x32_bf16 v[4:7], v[166:169], v[226:229], v[4:7]
	s_setprio 0
	s_setprio 1
	v_mfma_f32_16x16x32_bf16 v[56:59], v[170:173], v[198:201], v[56:59]
	v_mfma_f32_16x16x32_bf16 v[56:59], v[174:177], v[202:205], v[56:59]
	v_mfma_f32_16x16x32_bf16 v[48:51], v[178:181], v[198:201], v[48:51]
	v_mfma_f32_16x16x32_bf16 v[48:51], v[194:197], v[202:205], v[48:51]
	v_mfma_f32_16x16x32_bf16 v[40:43], v[170:173], v[206:209], v[40:43]
	v_mfma_f32_16x16x32_bf16 v[40:43], v[174:177], v[210:213], v[40:43]
	v_mfma_f32_16x16x32_bf16 v[32:35], v[178:181], v[206:209], v[32:35]
	v_mfma_f32_16x16x32_bf16 v[32:35], v[194:197], v[210:213], v[32:35]
	v_mfma_f32_16x16x32_bf16 v[24:27], v[170:173], v[214:217], v[24:27]
	v_mfma_f32_16x16x32_bf16 v[24:27], v[174:177], v[218:221], v[24:27]
	v_mfma_f32_16x16x32_bf16 v[16:19], v[178:181], v[214:217], v[16:19]
	v_mfma_f32_16x16x32_bf16 v[16:19], v[194:197], v[218:221], v[16:19]
	v_mfma_f32_16x16x32_bf16 v[8:11], v[170:173], v[222:225], v[8:11]
	v_mfma_f32_16x16x32_bf16 v[8:11], v[174:177], v[226:229], v[8:11]
	v_mfma_f32_16x16x32_bf16 v[0:3], v[178:181], v[222:225], v[0:3]
	v_mfma_f32_16x16x32_bf16 v[0:3], v[194:197], v[226:229], v[0:3]
	s_setprio 0
	s_barrier
	s_add_i32 s51, s51, 2
	s_add_u32 s41, s41, 0x2c0000
	s_addc_u32 s49, s49, 0
	s_add_u32 s70, s70, 0x400000
	s_addc_u32 s71, s71, 0
	s_cmp_gt_u32 s51, 29
	s_cbranch_scc0 .LBB0_139
	s_branch .Lp1_kloop_done
.Lp1_kloop_y:
	ds_read_b128 v[154:157], v150
	ds_read_b128 v[158:161], v150 offset:1024
	ds_read_b128 v[162:165], v150 offset:2048
	ds_read_b128 v[166:169], v150 offset:3072
	ds_read_b128 v[170:173], v151
	ds_read_b128 v[174:177], v151 offset:1024
	ds_read_b128 v[178:181], v151 offset:2048
	ds_read_b128 v[194:197], v151 offset:3072
	s_add_u32 s54, s70, 0x1fc000
	s_addc_u32 s55, s71, 0
	s_cmp_eq_u32 s51, 28
	s_cselect_b32 s78, s6, s54
	s_cselect_b32 s79, s7, s55
	s_cselect_b32 s76, s68, s41
	s_cselect_b32 s77, s69, s49
	s_add_u32 s74, s78, 0x200000
	s_addc_u32 s75, s79, 0
	v_lshl_add_u64 v[146:147], s[70:71], 0, v[138:139]
	s_add_i32 m0, s20, 0xc000
	ds_read_b128 v[198:201], v152
	ds_read_b128 v[202:205], v152 offset:1024
	ds_read_b128 v[206:209], v152 offset:2048
	ds_read_b128 v[210:213], v152 offset:3072
	ds_read_b128 v[214:217], v152 offset:4096
	ds_read_b128 v[218:221], v152 offset:5120
	ds_read_b128 v[222:225], v152 offset:6144
	ds_read_b128 v[226:229], v152 offset:7168
	global_load_lds_dwordx4 v[146:147], off
	v_lshl_add_u64 v[146:147], s[70:71], 0, v[140:141]
	s_add_i32 m0, s20, 0xe000
	s_nop 0
	global_load_lds_dwordx4 v[146:147], off
	s_waitcnt vmcnt(8)
	s_waitcnt lgkmcnt(0)
	s_barrier
; #define PG8_STAGE(bufoff, gbase, voff) do { _Pragma("unroll") for (int _i = 0; _i < 2; ++_i) \
;         __builtin_amdgcn_global_load_lds((const unsigned*)((const char*)(gbase) + (voff)[_i]), (LAS unsigned*)(lds + (bufoff) + ldsw + _i * 8192), 16, 0, 0); } while (0)
; #define PG8_LDA(dst, b, h) do { _Pragma("unroll") for (int m = 0; m < 4; ++m) _Pragma("unroll") for (int k = 0; k < 2; ++k) dst[m][k] = *(const LAS bf16x8*)(lds + PG8_SA(b, h) + aoff + m * 2048 + k * 1024); } while (0)
; #define PG8_LDB(dst, b, h) do { _Pragma("unroll") for (int n = 0; n < 2; ++n) _Pragma("unroll") for (int k = 0; k < 2; ++k) dst[n][k] = *(const LAS bf16x8*)(lds + PG8_SB(b, h) + boff + n * 2048 + k * 1024); } while (0)
; #define PG8_MMA(ai, bj, At, Bt) do { __builtin_amdgcn_s_setprio(1); _Pragma("unroll") for (int m = 0; m < 4; ++m) _Pragma("unroll") for (int n = 0; n < 2; ++n) _Pragma("unroll") for (int k = 0; k < 2; ++k) \
;         acc[ai][bj][m][n] = __builtin_amdgcn_mfma_f32_16x16x32_bf16(Bt[n][k], At[m][k], acc[ai][bj][m][n], 0, 0, 0); __builtin_amdgcn_s_setprio(0); } while (0)
; #define PG8_WAIT_V(n) asm volatile("s_waitcnt vmcnt(" #n ")" ::: "memory")
; #define PG8_WAIT_L(n) asm volatile("s_waitcnt lgkmcnt(" #n ")" ::: "memory")
; #define PG8_BAR __builtin_amdgcn_s_barrier()
; #define PG8_SCHED __builtin_amdgcn_sched_barrier(0)
; template <bool ALIGN_EPI, class Epi, class Sched>
; __device__ __forceinline__ void gemm_phase(LAS unsigned char* lds, const int lda, const int ldb, const int K, const Sched& S, const Epi& E, const size_t kstepA = (size_t)(BK * 2), const size_t kstepB = (size_t)(BK * 2)) {
;     ...
;             PG8_WAIT_V(8); PG8_WAIT_L(0); PG8_BAR; PG8_MMA(0, 0, At, B0); PG8_MMA(0, 1, At, B1); PG8_BAR; PG8_SCHED;
;             PG8_LDA(At, 0, 1); PG8_STAGE(PG8_SB(0, 0), b2, voffB); PG8_STAGE(PG8_SB(0, 1), b2 + hstepB, voffB); PG8_STAGE(PG8_SA(0, 0), a2, voffA);
;             PG8_WAIT_V(8); PG8_WAIT_L(0); PG8_BAR; PG8_MMA(1, 0, At, B0); PG8_MMA(1, 1, At, B1); PG8_BAR; PG8_SCHED;
;             PG8_LDB(B0, 1, 0); PG8_LDB(B1, 1, 1); PG8_SCHED; PG8_LDA(At, 1, 0); PG8_STAGE(PG8_SA(0, 1), a2 + hstepA, voffA);
;             PG8_WAIT_V(8); PG8_WAIT_L(0); PG8_BAR; PG8_MMA(0, 0, At, B0); PG8_MMA(0, 1, At, B1); PG8_BAR; PG8_SCHED;
	s_setprio 2
	s_waitcnt lgkmcnt(0)
	v_mfma_f32_16x16x32_bf16 v[124:127], v[154:157], v[198:201], v[124:127]
	v_mfma_f32_16x16x32_bf16 v[124:127], v[158:161], v[202:205], v[124:127]
	v_mfma_f32_16x16x32_bf16 v[116:119], v[162:165], v[198:201], v[116:119]
	v_mfma_f32_16x16x32_bf16 v[116:119], v[166:169], v[202:205], v[116:119]
	v_mfma_f32_16x16x32_bf16 v[108:111], v[154:157], v[206:209], v[108:111]
	v_mfma_f32_16x16x32_bf16 v[108:111], v[158:161], v[210:213], v[108:111]
	v_mfma_f32_16x16x32_bf16 v[100:103], v[162:165], v[206:209], v[100:103]
	v_mfma_f32_16x16x32_bf16 v[100:103], v[166:169], v[210:213], v[100:103]
	v_mfma_f32_16x16x32_bf16 v[92:95], v[154:157], v[214:217], v[92:95]
	v_mfma_f32_16x16x32_bf16 v[92:95], v[158:161], v[218:221], v[92:95]
	v_mfma_f32_16x16x32_bf16 v[84:87], v[162:165], v[214:217], v[84:87]
	v_mfma_f32_16x16x32_bf16 v[84:87], v[166:169], v[218:221], v[84:87]
	v_mfma_f32_16x16x32_bf16 v[76:79], v[154:157], v[222:225], v[76:79]
	v_mfma_f32_16x16x32_bf16 v[76:79], v[158:161], v[226:229], v[76:79]
	v_mfma_f32_16x16x32_bf16 v[68:71], v[162:165], v[222:225], v[68:71]
	v_mfma_f32_16x16x32_bf16 v[68:71], v[166:169], v[226:229], v[68:71]
	s_setprio 0
	s_setprio 2
	v_mfma_f32_16x16x32_bf16 v[120:123], v[170:173], v[198:201], v[120:123]
	v_mfma_f32_16x16x32_bf16 v[120:123], v[174:177], v[202:205], v[120:123]
	v_mfma_f32_16x16x32_bf16 v[112:115], v[178:181], v[198:201], v[112:115]
	v_mfma_f32_16x16x32_bf16 v[112:115], v[194:197], v[202:205], v[112:115]
	v_mfma_f32_16x16x32_bf16 v[104:107], v[170:173], v[206:209], v[104:107]
	v_mfma_f32_16x16x32_bf16 v[104:107], v[174:177], v[210:213], v[104:107]
	v_mfma_f32_16x16x32_bf16 v[96:99], v[178:181], v[206:209], v[96:99]
	v_mfma_f32_16x16x32_bf16 v[96:99], v[194:197], v[210:213], v[96:99]
	v_mfma_f32_16x16x32_bf16 v[88:91], v[170:173], v[214:217], v[88:91]
	v_mfma_f32_16x16x32_bf16 v[88:91], v[174:177], v[218:221], v[88:91]
	v_mfma_f32_16x16x32_bf16 v[80:83], v[178:181], v[214:217], v[80:83]
	v_mfma_f32_16x16x32_bf16 v[80:83], v[194:197], v[218:221], v[80:83]
	v_mfma_f32_16x16x32_bf16 v[72:75], v[170:173], v[222:225], v[72:75]
	v_mfma_f32_16x16x32_bf16 v[72:75], v[174:177], v[226:229], v[72:75]
	v_mfma_f32_16x16x32_bf16 v[64:67], v[178:181], v[222:225], v[64:67]
	v_mfma_f32_16x16x32_bf16 v[64:67], v[194:197], v[226:229], v[64:67]
	s_setprio 0
	s_add_i32 s54, s42, s18
	v_lshl_add_u64 v[146:147], s[76:77], 0, v[132:133]
	s_mov_b32 m0, s54
	ds_read_b128 v[198:201], v152 offset:16384
	ds_read_b128 v[202:205], v152 offset:17408
	ds_read_b128 v[206:209], v152 offset:18432
	ds_read_b128 v[210:213], v152 offset:19456
	ds_read_b128 v[214:217], v152 offset:20480
	ds_read_b128 v[218:221], v152 offset:21504
	ds_read_b128 v[222:225], v152 offset:22528
	ds_read_b128 v[226:229], v152 offset:23552
	global_load_lds_dwordx4 v[146:147], off
	s_add_i32 m0, s54, 0x2000
	s_add_u32 s54, s76, 0x4000
	v_lshl_add_u64 v[146:147], s[76:77], 0, v[128:129]
	s_addc_u32 s55, s77, 0
	s_add_i32 s56, s43, s18
	global_load_lds_dwordx4 v[146:147], off
	v_lshl_add_u64 v[146:147], s[54:55], 0, v[132:133]
	s_mov_b32 m0, s56
	s_nop 0
	global_load_lds_dwordx4 v[146:147], off
	v_lshl_add_u64 v[146:147], s[54:55], 0, v[128:129]
	s_add_i32 m0, s56, 0x2000
	s_nop 0
	global_load_lds_dwordx4 v[146:147], off
	v_lshl_add_u64 v[146:147], s[78:79], 0, v[134:135]
	s_mov_b32 m0, s20
	s_nop 0
	global_load_lds_dwordx4 v[146:147], off
	v_lshl_add_u64 v[146:147], s[78:79], 0, v[130:131]
	s_mov_b32 m0, s21
	s_nop 0
	global_load_lds_dwordx4 v[146:147], off
	s_waitcnt vmcnt(8)
	s_waitcnt lgkmcnt(0)
	s_barrier
	s_setprio 2
	s_waitcnt lgkmcnt(0)
	v_mfma_f32_16x16x32_bf16 v[60:63], v[154:157], v[198:201], v[60:63]
	v_mfma_f32_16x16x32_bf16 v[60:63], v[158:161], v[202:205], v[60:63]
	v_mfma_f32_16x16x32_bf16 v[52:55], v[162:165], v[198:201], v[52:55]
	v_mfma_f32_16x16x32_bf16 v[52:55], v[166:169], v[202:205], v[52:55]
	v_mfma_f32_16x16x32_bf16 v[44:47], v[154:157], v[206:209], v[44:47]
	v_mfma_f32_16x16x32_bf16 v[44:47], v[158:161], v[210:213], v[44:47]
	v_mfma_f32_16x16x32_bf16 v[36:39], v[162:165], v[206:209], v[36:39]
	v_mfma_f32_16x16x32_bf16 v[36:39], v[166:169], v[210:213], v[36:39]
	v_mfma_f32_16x16x32_bf16 v[28:31], v[154:157], v[214:217], v[28:31]
	v_mfma_f32_16x16x32_bf16 v[28:31], v[158:161], v[218:221], v[28:31]
	v_mfma_f32_16x16x32_bf16 v[20:23], v[162:165], v[214:217], v[20:23]
	v_mfma_f32_16x16x32_bf16 v[20:23], v[166:169], v[218:221], v[20:23]
	v_mfma_f32_16x16x32_bf16 v[12:15], v[154:157], v[222:225], v[12:15]
	v_mfma_f32_16x16x32_bf16 v[12:15], v[158:161], v[226:229], v[12:15]
	v_mfma_f32_16x16x32_bf16 v[4:7], v[162:165], v[222:225], v[4:7]
	v_mfma_f32_16x16x32_bf16 v[4:7], v[166:169], v[226:229], v[4:7]
	s_setprio 0
	s_setprio 2
	v_mfma_f32_16x16x32_bf16 v[56:59], v[170:173], v[198:201], v[56:59]
	v_mfma_f32_16x16x32_bf16 v[56:59], v[174:177], v[202:205], v[56:59]
	v_mfma_f32_16x16x32_bf16 v[48:51], v[178:181], v[198:201], v[48:51]
	v_mfma_f32_16x16x32_bf16 v[48:51], v[194:197], v[202:205], v[48:51]
	v_mfma_f32_16x16x32_bf16 v[40:43], v[170:173], v[206:209], v[40:43]
	v_mfma_f32_16x16x32_bf16 v[40:43], v[174:177], v[210:213], v[40:43]
	v_mfma_f32_16x16x32_bf16 v[32:35], v[178:181], v[206:209], v[32:35]
	v_mfma_f32_16x16x32_bf16 v[32:35], v[194:197], v[210:213], v[32:35]
	v_mfma_f32_16x16x32_bf16 v[24:27], v[170:173], v[214:217], v[24:27]
	v_mfma_f32_16x16x32_bf16 v[24:27], v[174:177], v[218:221], v[24:27]
	v_mfma_f32_16x16x32_bf16 v[16:19], v[178:181], v[214:217], v[16:19]
	v_mfma_f32_16x16x32_bf16 v[16:19], v[194:197], v[218:221], v[16:19]
	v_mfma_f32_16x16x32_bf16 v[8:11], v[170:173], v[222:225], v[8:11]
	v_mfma_f32_16x16x32_bf16 v[8:11], v[174:177], v[226:229], v[8:11]
	v_mfma_f32_16x16x32_bf16 v[0:3], v[178:181], v[222:225], v[0:3]
	v_mfma_f32_16x16x32_bf16 v[0:3], v[194:197], v[226:229], v[0:3]
	s_setprio 0
	s_add_i32 s56, 0, 0x18000
	v_add_u32_e32 v146, s56, v149
	s_add_i32 s57, 0, 0x1c000
	ds_read_b128 v[154:157], v146
	ds_read_b128 v[158:161], v146 offset:1024
	ds_read_b128 v[162:165], v146 offset:2048
	ds_read_b128 v[166:169], v146 offset:3072
	v_add_u32_e32 v146, s57, v149
	ds_read_b128 v[170:173], v146
	ds_read_b128 v[174:177], v146 offset:1024
	ds_read_b128 v[178:181], v146 offset:2048
	ds_read_b128 v[194:197], v146 offset:3072
	s_add_u32 s54, s78, 0x4000
	s_addc_u32 s55, s79, 0
	s_mov_b32 m0, s22
	v_lshl_add_u64 v[146:147], s[54:55], 0, v[134:135]
	ds_read_b128 v[198:201], v152 offset:32768
	ds_read_b128 v[202:205], v152 offset:33792
	ds_read_b128 v[206:209], v152 offset:34816
	ds_read_b128 v[210:213], v152 offset:35840
	ds_read_b128 v[214:217], v152 offset:36864
	ds_read_b128 v[218:221], v152 offset:37888
	ds_read_b128 v[222:225], v152 offset:38912
	ds_read_b128 v[226:229], v152 offset:39936
	global_load_lds_dwordx4 v[146:147], off
	v_lshl_add_u64 v[146:147], s[54:55], 0, v[130:131]
	s_mov_b32 m0, s23
	s_nop 0
	global_load_lds_dwordx4 v[146:147], off
	s_waitcnt vmcnt(8)
	s_waitcnt lgkmcnt(0)
	s_barrier
; #define PG8_STAGE(bufoff, gbase, voff) do { _Pragma("unroll") for (int _i = 0; _i < 2; ++_i) \
;         __builtin_amdgcn_global_load_lds((const unsigned*)((const char*)(gbase) + (voff)[_i]), (LAS unsigned*)(lds + (bufoff) + ldsw + _i * 8192), 16, 0, 0); } while (0)
; #define PG8_LDA(dst, b, h) do { _Pragma("unroll") for (int m = 0; m < 4; ++m) _Pragma("unroll") for (int k = 0; k < 2; ++k) dst[m][k] = *(const LAS bf16x8*)(lds + PG8_SA(b, h) + aoff + m * 2048 + k * 1024); } while (0)
; #define PG8_MMA(ai, bj, At, Bt) do { __builtin_amdgcn_s_setprio(1); _Pragma("unroll") for (int m = 0; m < 4; ++m) _Pragma("unroll") for (int n = 0; n < 2; ++n) _Pragma("unroll") for (int k = 0; k < 2; ++k) \
;         acc[ai][bj][m][n] = __builtin_amdgcn_mfma_f32_16x16x32_bf16(Bt[n][k], At[m][k], acc[ai][bj][m][n], 0, 0, 0); __builtin_amdgcn_s_setprio(0); } while (0)
; #define PG8_WAIT_V(n) asm volatile("s_waitcnt vmcnt(" #n ")" ::: "memory")
; #define PG8_WAIT_L(n) asm volatile("s_waitcnt lgkmcnt(" #n ")" ::: "memory")
; #define PG8_BAR __builtin_amdgcn_s_barrier()
; #define PG8_SCHED __builtin_amdgcn_sched_barrier(0)
; template <bool ALIGN_EPI, class Epi, class Sched>
; __device__ __forceinline__ void gemm_phase(LAS unsigned char* lds, const int lda, const int ldb, const int K, const Sched& S, const Epi& E, const size_t kstepA = (size_t)(BK * 2), const size_t kstepB = (size_t)(BK * 2)) {
;     ...
;             PG8_WAIT_V(8); PG8_WAIT_L(0); PG8_BAR; PG8_MMA(0, 0, At, B0); PG8_MMA(0, 1, At, B1); PG8_BAR; PG8_SCHED;
;             PG8_LDA(At, 1, 1); PG8_STAGE(PG8_SB(1, 0), b3, voffB); PG8_STAGE(PG8_SB(1, 1), b3 + hstepB, voffB); PG8_STAGE(PG8_SA(1, 0), a3, voffA);
;             PG8_WAIT_V(8); PG8_WAIT_L(0); PG8_BAR; PG8_MMA(1, 0, At, B0); PG8_MMA(1, 1, At, B1); PG8_BAR; PG8_SCHED;
;         }
	s_setprio 2
	s_waitcnt lgkmcnt(0)
	v_mfma_f32_16x16x32_bf16 v[124:127], v[154:157], v[198:201], v[124:127]
	v_mfma_f32_16x16x32_bf16 v[124:127], v[158:161], v[202:205], v[124:127]
	v_mfma_f32_16x16x32_bf16 v[116:119], v[162:165], v[198:201], v[116:119]
	v_mfma_f32_16x16x32_bf16 v[116:119], v[166:169], v[202:205], v[116:119]
	v_mfma_f32_16x16x32_bf16 v[108:111], v[154:157], v[206:209], v[108:111]
	v_mfma_f32_16x16x32_bf16 v[108:111], v[158:161], v[210:213], v[108:111]
	v_mfma_f32_16x16x32_bf16 v[100:103], v[162:165], v[206:209], v[100:103]
	v_mfma_f32_16x16x32_bf16 v[100:103], v[166:169], v[210:213], v[100:103]
	v_mfma_f32_16x16x32_bf16 v[92:95], v[154:157], v[214:217], v[92:95]
	v_mfma_f32_16x16x32_bf16 v[92:95], v[158:161], v[218:221], v[92:95]
	v_mfma_f32_16x16x32_bf16 v[84:87], v[162:165], v[214:217], v[84:87]
	v_mfma_f32_16x16x32_bf16 v[84:87], v[166:169], v[218:221], v[84:87]
	v_mfma_f32_16x16x32_bf16 v[76:79], v[154:157], v[222:225], v[76:79]
	v_mfma_f32_16x16x32_bf16 v[76:79], v[158:161], v[226:229], v[76:79]
	v_mfma_f32_16x16x32_bf16 v[68:71], v[162:165], v[222:225], v[68:71]
	v_mfma_f32_16x16x32_bf16 v[68:71], v[166:169], v[226:229], v[68:71]
	s_setprio 0
	s_setprio 2
	v_mfma_f32_16x16x32_bf16 v[120:123], v[170:173], v[198:201], v[120:123]
	v_mfma_f32_16x16x32_bf16 v[120:123], v[174:177], v[202:205], v[120:123]
	v_mfma_f32_16x16x32_bf16 v[112:115], v[178:181], v[198:201], v[112:115]
	v_mfma_f32_16x16x32_bf16 v[112:115], v[194:197], v[202:205], v[112:115]
	v_mfma_f32_16x16x32_bf16 v[104:107], v[170:173], v[206:209], v[104:107]
	v_mfma_f32_16x16x32_bf16 v[104:107], v[174:177], v[210:213], v[104:107]
	v_mfma_f32_16x16x32_bf16 v[96:99], v[178:181], v[206:209], v[96:99]
	v_mfma_f32_16x16x32_bf16 v[96:99], v[194:197], v[210:213], v[96:99]
	v_mfma_f32_16x16x32_bf16 v[88:91], v[170:173], v[214:217], v[88:91]
	v_mfma_f32_16x16x32_bf16 v[88:91], v[174:177], v[218:221], v[88:91]
	v_mfma_f32_16x16x32_bf16 v[80:83], v[178:181], v[214:217], v[80:83]
	v_mfma_f32_16x16x32_bf16 v[80:83], v[194:197], v[218:221], v[80:83]
	v_mfma_f32_16x16x32_bf16 v[72:75], v[170:173], v[222:225], v[72:75]
	v_mfma_f32_16x16x32_bf16 v[72:75], v[174:177], v[226:229], v[72:75]
	v_mfma_f32_16x16x32_bf16 v[64:67], v[178:181], v[222:225], v[64:67]
	v_mfma_f32_16x16x32_bf16 v[64:67], v[194:197], v[226:229], v[64:67]
	s_setprio 0
	s_add_u32 s54, s76, 0x160000
	s_addc_u32 s55, s77, 0
	s_add_i32 s56, s56, s18
	v_lshl_add_u64 v[146:147], s[54:55], 0, v[132:133]
	s_mov_b32 m0, s56
	ds_read_b128 v[198:201], v152 offset:49152
	ds_read_b128 v[202:205], v152 offset:50176
	ds_read_b128 v[206:209], v152 offset:51200
	ds_read_b128 v[210:213], v152 offset:52224
	ds_read_b128 v[214:217], v152 offset:53248
	ds_read_b128 v[218:221], v152 offset:54272
	ds_read_b128 v[222:225], v152 offset:55296
	ds_read_b128 v[226:229], v152 offset:56320
	global_load_lds_dwordx4 v[146:147], off
	s_add_i32 m0, s56, 0x2000
	v_lshl_add_u64 v[146:147], s[54:55], 0, v[128:129]
	s_add_u32 s54, s76, 0x164000
	s_addc_u32 s55, s77, 0
	s_add_i32 s56, s57, s18
	global_load_lds_dwordx4 v[146:147], off
	v_lshl_add_u64 v[146:147], s[54:55], 0, v[132:133]
	s_mov_b32 m0, s56
	s_nop 0
	global_load_lds_dwordx4 v[146:147], off
	v_lshl_add_u64 v[146:147], s[54:55], 0, v[128:129]
	s_add_i32 m0, s56, 0x2000
	s_nop 0
	global_load_lds_dwordx4 v[146:147], off
	v_lshl_add_u64 v[146:147], s[74:75], 0, v[134:135]
	s_mov_b32 m0, s31
	s_nop 0
	global_load_lds_dwordx4 v[146:147], off
	v_lshl_add_u64 v[146:147], s[74:75], 0, v[130:131]
	s_mov_b32 m0, s33
	s_nop 0
	global_load_lds_dwordx4 v[146:147], off
	s_waitcnt vmcnt(8)
	s_waitcnt lgkmcnt(0)
	s_barrier
	s_setprio 2
	s_waitcnt lgkmcnt(0)
	v_mfma_f32_16x16x32_bf16 v[60:63], v[154:157], v[198:201], v[60:63]
	v_mfma_f32_16x16x32_bf16 v[60:63], v[158:161], v[202:205], v[60:63]
	v_mfma_f32_16x16x32_bf16 v[52:55], v[162:165], v[198:201], v[52:55]
	v_mfma_f32_16x16x32_bf16 v[52:55], v[166:169], v[202:205], v[52:55]
	v_mfma_f32_16x16x32_bf16 v[44:47], v[154:157], v[206:209], v[44:47]
	v_mfma_f32_16x16x32_bf16 v[44:47], v[158:161], v[210:213], v[44:47]
	v_mfma_f32_16x16x32_bf16 v[36:39], v[162:165], v[206:209], v[36:39]
	v_mfma_f32_16x16x32_bf16 v[36:39], v[166:169], v[210:213], v[36:39]
	v_mfma_f32_16x16x32_bf16 v[28:31], v[154:157], v[214:217], v[28:31]
	v_mfma_f32_16x16x32_bf16 v[28:31], v[158:161], v[218:221], v[28:31]
	v_mfma_f32_16x16x32_bf16 v[20:23], v[162:165], v[214:217], v[20:23]
	v_mfma_f32_16x16x32_bf16 v[20:23], v[166:169], v[218:221], v[20:23]
	v_mfma_f32_16x16x32_bf16 v[12:15], v[154:157], v[222:225], v[12:15]
	v_mfma_f32_16x16x32_bf16 v[12:15], v[158:161], v[226:229], v[12:15]
	v_mfma_f32_16x16x32_bf16 v[4:7], v[162:165], v[222:225], v[4:7]
	v_mfma_f32_16x16x32_bf16 v[4:7], v[166:169], v[226:229], v[4:7]
	s_setprio 0
	s_setprio 2
	v_mfma_f32_16x16x32_bf16 v[56:59], v[170:173], v[198:201], v[56:59]
	v_mfma_f32_16x16x32_bf16 v[56:59], v[174:177], v[202:205], v[56:59]
	v_mfma_f32_16x16x32_bf16 v[48:51], v[178:181], v[198:201], v[48:51]
	v_mfma_f32_16x16x32_bf16 v[48:51], v[194:197], v[202:205], v[48:51]
	v_mfma_f32_16x16x32_bf16 v[40:43], v[170:173], v[206:209], v[40:43]
	v_mfma_f32_16x16x32_bf16 v[40:43], v[174:177], v[210:213], v[40:43]
	v_mfma_f32_16x16x32_bf16 v[32:35], v[178:181], v[206:209], v[32:35]
	v_mfma_f32_16x16x32_bf16 v[32:35], v[194:197], v[210:213], v[32:35]
	v_mfma_f32_16x16x32_bf16 v[24:27], v[170:173], v[214:217], v[24:27]
	v_mfma_f32_16x16x32_bf16 v[24:27], v[174:177], v[218:221], v[24:27]
	v_mfma_f32_16x16x32_bf16 v[16:19], v[178:181], v[214:217], v[16:19]
	v_mfma_f32_16x16x32_bf16 v[16:19], v[194:197], v[218:221], v[16:19]
	v_mfma_f32_16x16x32_bf16 v[8:11], v[170:173], v[222:225], v[8:11]
	v_mfma_f32_16x16x32_bf16 v[8:11], v[174:177], v[226:229], v[8:11]
	v_mfma_f32_16x16x32_bf16 v[0:3], v[178:181], v[222:225], v[0:3]
	v_mfma_f32_16x16x32_bf16 v[0:3], v[194:197], v[226:229], v[0:3]
	s_setprio 0
	s_add_i32 s51, s51, 2
	s_add_u32 s41, s41, 0x2c0000
	s_addc_u32 s49, s49, 0
	s_add_u32 s70, s70, 0x400000
	s_addc_u32 s71, s71, 0
	s_cmp_gt_u32 s51, 29
	s_cbranch_scc0 .Lp1_kloop_y
; __device__ __forceinline__ unsigned cvt_pk_bf16(float lo, float hi) { const f32x2 v = {lo, hi}; const bf16x2_t r = __builtin_convertvector(v, bf16x2_t); return __builtin_bit_cast(unsigned, r); }
; __device__ __forceinline__ float silu_f(float g) { return g * __builtin_amdgcn_rcpf(1.0f + __builtin_amdgcn_exp2f(-1.44269504f * g)); }
; __device__ __forceinline__ float row_rs(const RowScale& R, int pm, int lr) { return (R.rsl && pm == R.pm0) ? R.rsl[lr] : rstd_of(R.ss, pm * 256 + lr); }
; #define PG8_BAR __builtin_amdgcn_s_barrier()
; template <bool ALIGN_EPI, class Epi, class Sched>
; __device__ __forceinline__ void gemm_phase(LAS unsigned char* lds, const int lda, const int ldb, const int K, const Sched& S, const Epi& E, const size_t kstepA = (size_t)(BK * 2), const size_t kstepB = (size_t)(BK * 2)) {
;     ...
;         if constexpr (ALIGN_EPI) { if (wr == 0) PG8_BAR; }
;         if constexpr (!Epi::AFTER_DRAIN) { E(acc, cur, wr, wc, fr, fq); }
;     __device__ __forceinline__ void operator()(const Acc& acc, const Unit& u, int wr, int wc, int fr, int fq) const {
;         const int row0 = u.pm * BM + wr * 64 + fr, col0 = u.pn * 128 + wc * 32 + 8 * fq;
; #pragma unroll
;         for (int ai = 0; ai < 2; ++ai)
; #pragma unroll
;             for (int m = 0; m < 4; ++m) { const int row = row0 + ai * HALF + m * 16; const float rs = scaled ? row_rs(R, u.pm, ai * HALF + wr * 64 + m * 16 + fr) : 1.0f;
;                 const f32x4 g0 = acc[ai][0][m][0] * rs, g1 = acc[ai][0][m][1] * rs, u0 = acc[ai][1][m][0] * rs, u1 = acc[ai][1][m][1] * rs;
;                 u32x4 w; w.x = cvt_pk_bf16(silu_f(g0[0]) * u0[0], silu_f(g0[1]) * u0[1]); w.y = cvt_pk_bf16(silu_f(g0[2]) * u0[2], silu_f(g0[3]) * u0[3]);
;                 w.z = cvt_pk_bf16(silu_f(g1[0]) * u1[0], silu_f(g1[1]) * u1[1]); w.w = cvt_pk_bf16(silu_f(g1[2]) * u1[2], silu_f(g1[3]) * u1[3]);
;                 *(u32x4*)(O + ((size_t)(col0 >> 6) * T + row) * 64 + (col0 & 63)) = w; }
.Lp1_kloop_done:
	s_and_b64 vcc, exec, s[12:13]
	s_cbranch_vccz .LBB0_142
.LBB0_142:
	v_mul_f32_e32 v147, 0xbfb8aa3b, v124
	v_exp_f32_e32 v147, v147
	v_mul_f32_e32 v153, 0xbfb8aa3b, v125
	v_exp_f32_e32 v153, v153
	v_mul_f32_e32 v155, 0xbfb8aa3b, v127
	v_add_f32_e32 v147, 1.0, v147
	v_rcp_f32_e32 v154, v147
	v_add_f32_e32 v147, 1.0, v153
	v_mul_f32_e32 v153, 0xbfb8aa3b, v126
	v_exp_f32_e32 v153, v153
	v_exp_f32_e32 v157, v155
	v_rcp_f32_e32 v155, v147
	s_lshl_b32 s6, s50, 7
	v_add_f32_e32 v147, 1.0, v153
	v_rcp_f32_e32 v156, v147
	v_add_f32_e32 v147, 1.0, v157
	v_rcp_f32_e32 v157, v147
	v_pk_mul_f32 v[124:125], v[124:125], v[154:155]
	s_or_b32 s6, s6, s30
	v_pk_mul_f32 v[120:121], v[124:125], v[120:121]
	v_pk_mul_f32 v[124:125], v[126:127], v[156:157]
	v_cvt_pk_bf16_f32 v120, v120, v121
	v_mul_f32_e32 v121, 0xbfb8aa3b, v116
	v_pk_mul_f32 v[122:123], v[124:125], v[122:123]
	v_exp_f32_e32 v124, v121
	v_mul_f32_e32 v121, 0xbfb8aa3b, v117
	v_exp_f32_e32 v125, v121
	v_cvt_pk_bf16_f32 v121, v122, v123
	v_add_f32_e32 v122, 1.0, v124
	v_mul_f32_e32 v124, 0xbfb8aa3b, v118
	v_add_f32_e32 v123, 1.0, v125
	v_mul_f32_e32 v125, 0xbfb8aa3b, v119
	v_exp_f32_e32 v124, v124
	v_exp_f32_e32 v125, v125
	v_rcp_f32_e32 v122, v122
	v_rcp_f32_e32 v123, v123
	v_add_f32_e32 v124, 1.0, v124
	v_add_f32_e32 v125, 1.0, v125
	v_rcp_f32_e32 v124, v124
	v_rcp_f32_e32 v125, v125
	v_pk_mul_f32 v[116:117], v[116:117], v[122:123]
	s_ashr_i32 s6, s6, 6
	v_pk_mul_f32 v[112:113], v[116:117], v[112:113]
	v_lshl_add_u32 v146, s66, 8, v148
	v_cvt_pk_bf16_f32 v122, v112, v113
	v_pk_mul_f32 v[112:113], v[118:119], v[124:125]
	s_ashr_i32 s7, s6, 31
	v_pk_mul_f32 v[112:113], v[112:113], v[114:115]
	v_mul_f32_e32 v114, 0xbfb8aa3b, v108
	v_exp_f32_e32 v115, v114
	v_mul_f32_e32 v114, 0xbfb8aa3b, v109
	v_exp_f32_e32 v117, v114
	s_lshl_b64 s[6:7], s[6:7], 21
	v_add_f32_e32 v115, 1.0, v115
	v_rcp_f32_e32 v116, v115
	v_add_f32_e32 v115, 1.0, v117
	v_mul_f32_e32 v117, 0xbfb8aa3b, v110
	v_exp_f32_e32 v118, v117
	v_mul_f32_e32 v117, 0xbfb8aa3b, v111
	v_exp_f32_e32 v119, v117
	v_rcp_f32_e32 v117, v115
	v_add_f32_e32 v115, 1.0, v118
	v_rcp_f32_e32 v118, v115
	v_add_f32_e32 v115, 1.0, v119
	v_rcp_f32_e32 v119, v115
	v_pk_mul_f32 v[108:109], v[108:109], v[116:117]
	v_or_b32_e32 v114, 16, v146
	v_pk_mul_f32 v[104:105], v[108:109], v[104:105]
	v_pk_mul_f32 v[108:109], v[110:111], v[118:119]
	v_cvt_pk_bf16_f32 v104, v104, v105
	v_mul_f32_e32 v105, 0xbfb8aa3b, v100
	v_pk_mul_f32 v[106:107], v[108:109], v[106:107]
	v_exp_f32_e32 v108, v105
	v_mul_f32_e32 v105, 0xbfb8aa3b, v101
	v_exp_f32_e32 v109, v105
	v_cvt_pk_bf16_f32 v105, v106, v107
	v_add_f32_e32 v106, 1.0, v108
	v_mul_f32_e32 v108, 0xbfb8aa3b, v102
	v_add_f32_e32 v107, 1.0, v109
	v_mul_f32_e32 v109, 0xbfb8aa3b, v103
	v_exp_f32_e32 v108, v108
	v_exp_f32_e32 v109, v109
	v_rcp_f32_e32 v106, v106
	v_rcp_f32_e32 v107, v107
	v_add_f32_e32 v108, 1.0, v108
	v_add_f32_e32 v109, 1.0, v109
	v_rcp_f32_e32 v108, v108
	v_rcp_f32_e32 v109, v109
	v_pk_mul_f32 v[100:101], v[100:101], v[106:107]
	s_add_u32 s6, s38, s6
	v_pk_mul_f32 v[96:97], v[100:101], v[96:97]
	v_ashrrev_i32_e32 v115, 31, v114
	v_cvt_pk_bf16_f32 v106, v96, v97
	v_pk_mul_f32 v[96:97], v[102:103], v[108:109]
	s_addc_u32 s7, s39, s7
	v_pk_mul_f32 v[96:97], v[96:97], v[98:99]
	v_ashrrev_i32_e32 v147, 31, v146
	v_cvt_pk_bf16_f32 v107, v96, v97
	v_lshlrev_b64 v[96:97], 7, v[114:115]
	v_lshl_add_u64 v[96:97], s[6:7], 0, v[96:97]
	v_lshl_add_u64 v[96:97], v[96:97], 0, v[136:137]
	global_store_dwordx4 v[96:97], v[104:107], off
	v_mul_f32_e32 v96, 0xbfb8aa3b, v92
	v_exp_f32_e32 v97, v96
	v_mul_f32_e32 v96, 0xbfb8aa3b, v93
	v_exp_f32_e32 v99, v96
	v_or_b32_e32 v96, 32, v146
	v_add_f32_e32 v97, 1.0, v97
	v_rcp_f32_e32 v98, v97
	v_add_f32_e32 v97, 1.0, v99
	v_mul_f32_e32 v99, 0xbfb8aa3b, v94
	v_exp_f32_e32 v100, v99
	v_mul_f32_e32 v99, 0xbfb8aa3b, v95
	v_exp_f32_e32 v101, v99
	v_rcp_f32_e32 v99, v97
	v_add_f32_e32 v97, 1.0, v100
	v_rcp_f32_e32 v100, v97
	v_add_f32_e32 v97, 1.0, v101
	v_rcp_f32_e32 v101, v97
	v_pk_mul_f32 v[92:93], v[92:93], v[98:99]
	v_ashrrev_i32_e32 v97, 31, v96
	v_pk_mul_f32 v[88:89], v[92:93], v[88:89]
	v_pk_mul_f32 v[92:93], v[94:95], v[100:101]
	v_cvt_pk_bf16_f32 v88, v88, v89
	v_mul_f32_e32 v89, 0xbfb8aa3b, v84
	v_pk_mul_f32 v[90:91], v[92:93], v[90:91]
	v_exp_f32_e32 v92, v89
	v_mul_f32_e32 v89, 0xbfb8aa3b, v85
	v_exp_f32_e32 v93, v89
	v_cvt_pk_bf16_f32 v89, v90, v91
	v_add_f32_e32 v90, 1.0, v92
	v_mul_f32_e32 v92, 0xbfb8aa3b, v86
	v_add_f32_e32 v91, 1.0, v93
	v_mul_f32_e32 v93, 0xbfb8aa3b, v87
	v_exp_f32_e32 v92, v92
	v_exp_f32_e32 v93, v93
	v_rcp_f32_e32 v90, v90
	v_rcp_f32_e32 v91, v91
	v_add_f32_e32 v92, 1.0, v92
	v_add_f32_e32 v93, 1.0, v93
	v_rcp_f32_e32 v92, v92
	v_rcp_f32_e32 v93, v93
	v_pk_mul_f32 v[84:85], v[84:85], v[90:91]
	v_cvt_pk_bf16_f32 v123, v112, v113
	v_pk_mul_f32 v[80:81], v[84:85], v[80:81]
	v_lshlrev_b64 v[112:113], 7, v[146:147]
	v_cvt_pk_bf16_f32 v90, v80, v81
	v_pk_mul_f32 v[80:81], v[86:87], v[92:93]
	v_lshl_add_u64 v[112:113], s[6:7], 0, v[112:113]
	v_pk_mul_f32 v[80:81], v[80:81], v[82:83]
	v_lshl_add_u64 v[112:113], v[112:113], 0, v[136:137]
	v_cvt_pk_bf16_f32 v91, v80, v81
	v_lshlrev_b64 v[80:81], 7, v[96:97]
	v_lshl_add_u64 v[80:81], s[6:7], 0, v[80:81]
	v_lshl_add_u64 v[80:81], v[80:81], 0, v[136:137]
	global_store_dwordx4 v[80:81], v[88:91], off
	v_mul_f32_e32 v80, 0xbfb8aa3b, v76
	v_exp_f32_e32 v81, v80
	v_mul_f32_e32 v80, 0xbfb8aa3b, v77
	v_exp_f32_e32 v83, v80
	v_or_b32_e32 v80, 48, v146
	v_add_f32_e32 v81, 1.0, v81
	v_rcp_f32_e32 v82, v81
	v_add_f32_e32 v81, 1.0, v83
	v_mul_f32_e32 v83, 0xbfb8aa3b, v78
	v_exp_f32_e32 v84, v83
; __device__ __forceinline__ unsigned cvt_pk_bf16(float lo, float hi) { const f32x2 v = {lo, hi}; const bf16x2_t r = __builtin_convertvector(v, bf16x2_t); return __builtin_bit_cast(unsigned, r); }
; __device__ __forceinline__ float silu_f(float g) { return g * __builtin_amdgcn_rcpf(1.0f + __builtin_amdgcn_exp2f(-1.44269504f * g)); }
; __device__ __forceinline__ float row_rs(const RowScale& R, int pm, int lr) { return (R.rsl && pm == R.pm0) ? R.rsl[lr] : rstd_of(R.ss, pm * 256 + lr); }
;     __device__ __forceinline__ void operator()(const Acc& acc, const Unit& u, int wr, int wc, int fr, int fq) const {
;     ...
;             for (int m = 0; m < 4; ++m) { const int row = row0 + ai * HALF + m * 16; const float rs = scaled ? row_rs(R, u.pm, ai * HALF + wr * 64 + m * 16 + fr) : 1.0f;
;                 const f32x4 g0 = acc[ai][0][m][0] * rs, g1 = acc[ai][0][m][1] * rs, u0 = acc[ai][1][m][0] * rs, u1 = acc[ai][1][m][1] * rs;
;                 u32x4 w; w.x = cvt_pk_bf16(silu_f(g0[0]) * u0[0], silu_f(g0[1]) * u0[1]); w.y = cvt_pk_bf16(silu_f(g0[2]) * u0[2], silu_f(g0[3]) * u0[3]);
;                 w.z = cvt_pk_bf16(silu_f(g1[0]) * u1[0], silu_f(g1[1]) * u1[1]); w.w = cvt_pk_bf16(silu_f(g1[2]) * u1[2], silu_f(g1[3]) * u1[3]);
;                 *(u32x4*)(O + ((size_t)(col0 >> 6) * T + row) * 64 + (col0 & 63)) = w; }
	v_mul_f32_e32 v83, 0xbfb8aa3b, v79
	v_exp_f32_e32 v85, v83
	v_rcp_f32_e32 v83, v81
	v_add_f32_e32 v81, 1.0, v84
	v_rcp_f32_e32 v84, v81
	v_add_f32_e32 v81, 1.0, v85
	v_rcp_f32_e32 v85, v81
	v_pk_mul_f32 v[76:77], v[76:77], v[82:83]
	v_ashrrev_i32_e32 v81, 31, v80
	v_pk_mul_f32 v[72:73], v[76:77], v[72:73]
	v_pk_mul_f32 v[76:77], v[78:79], v[84:85]
	v_cvt_pk_bf16_f32 v72, v72, v73
	v_mul_f32_e32 v73, 0xbfb8aa3b, v68
	v_pk_mul_f32 v[74:75], v[76:77], v[74:75]
	v_exp_f32_e32 v76, v73
	v_mul_f32_e32 v73, 0xbfb8aa3b, v69
	v_exp_f32_e32 v77, v73
	v_cvt_pk_bf16_f32 v73, v74, v75
	v_add_f32_e32 v74, 1.0, v76
	v_mul_f32_e32 v76, 0xbfb8aa3b, v70
	v_add_f32_e32 v75, 1.0, v77
	v_mul_f32_e32 v77, 0xbfb8aa3b, v71
	v_exp_f32_e32 v76, v76
	v_exp_f32_e32 v77, v77
	v_rcp_f32_e32 v74, v74
	v_rcp_f32_e32 v75, v75
	v_add_f32_e32 v76, 1.0, v76
	v_add_f32_e32 v77, 1.0, v77
	v_rcp_f32_e32 v76, v76
	v_rcp_f32_e32 v77, v77
	v_pk_mul_f32 v[68:69], v[68:69], v[74:75]
	global_store_dwordx4 v[112:113], v[120:123], off
	v_pk_mul_f32 v[64:65], v[68:69], v[64:65]
	s_nop 0
	v_cvt_pk_bf16_f32 v74, v64, v65
	v_pk_mul_f32 v[64:65], v[70:71], v[76:77]
	s_nop 0
	v_pk_mul_f32 v[64:65], v[64:65], v[66:67]
	v_mul_f32_e32 v66, 0xbfb8aa3b, v60
	v_mul_f32_e32 v67, 0xbfb8aa3b, v61
	v_exp_f32_e32 v66, v66
	v_exp_f32_e32 v67, v67
	v_cvt_pk_bf16_f32 v75, v64, v65
	v_lshlrev_b64 v[64:65], 7, v[80:81]
	v_lshl_add_u64 v[64:65], s[6:7], 0, v[64:65]
	v_lshl_add_u64 v[64:65], v[64:65], 0, v[136:137]
	global_store_dwordx4 v[64:65], v[72:75], off
	v_add_f32_e32 v64, 1.0, v66
	v_add_f32_e32 v65, 1.0, v67
	v_mul_f32_e32 v66, 0xbfb8aa3b, v62
	v_mul_f32_e32 v67, 0xbfb8aa3b, v63
	v_exp_f32_e32 v66, v66
	v_exp_f32_e32 v67, v67
	v_rcp_f32_e32 v64, v64
	v_rcp_f32_e32 v65, v65
	v_add_f32_e32 v66, 1.0, v66
	v_add_f32_e32 v67, 1.0, v67
	v_rcp_f32_e32 v66, v66
	v_rcp_f32_e32 v67, v67
	v_pk_mul_f32 v[60:61], v[60:61], v[64:65]
	s_movk_i32 s6, 0x4000
	v_pk_mul_f32 v[56:57], v[60:61], v[56:57]
	v_pk_mul_f32 v[60:61], v[62:63], v[66:67]
	v_cvt_pk_bf16_f32 v56, v56, v57
	v_mul_f32_e32 v57, 0xbfb8aa3b, v52
	v_pk_mul_f32 v[58:59], v[60:61], v[58:59]
	v_exp_f32_e32 v60, v57
	v_mul_f32_e32 v57, 0xbfb8aa3b, v53
	v_exp_f32_e32 v61, v57
	v_cvt_pk_bf16_f32 v57, v58, v59
	v_add_f32_e32 v58, 1.0, v60
	v_mul_f32_e32 v60, 0xbfb8aa3b, v54
	v_add_f32_e32 v59, 1.0, v61
	v_mul_f32_e32 v61, 0xbfb8aa3b, v55
	v_exp_f32_e32 v60, v60
	v_exp_f32_e32 v61, v61
	v_rcp_f32_e32 v58, v58
	v_rcp_f32_e32 v59, v59
	v_add_f32_e32 v60, 1.0, v60
	v_add_f32_e32 v61, 1.0, v61
	v_rcp_f32_e32 v60, v60
	v_rcp_f32_e32 v61, v61
	v_pk_mul_f32 v[52:53], v[52:53], v[58:59]
	s_nop 0
	v_pk_mul_f32 v[48:49], v[52:53], v[48:49]
	v_mul_f32_e32 v52, 0xbfb8aa3b, v44
	v_mul_f32_e32 v53, 0xbfb8aa3b, v45
	v_exp_f32_e32 v52, v52
	v_exp_f32_e32 v53, v53
	v_cvt_pk_bf16_f32 v58, v48, v49
	v_pk_mul_f32 v[48:49], v[54:55], v[60:61]
	v_mul_f32_e32 v54, 0xbfb8aa3b, v46
	v_mul_f32_e32 v55, 0xbfb8aa3b, v47
	v_exp_f32_e32 v54, v54
	v_exp_f32_e32 v55, v55
	v_add_f32_e32 v52, 1.0, v52
	v_add_f32_e32 v53, 1.0, v53
	v_rcp_f32_e32 v52, v52
	v_rcp_f32_e32 v53, v53
	v_add_f32_e32 v54, 1.0, v54
	v_add_f32_e32 v55, 1.0, v55
	v_rcp_f32_e32 v54, v54
	v_rcp_f32_e32 v55, v55
	v_pk_mul_f32 v[44:45], v[44:45], v[52:53]
	v_pk_mul_f32 v[48:49], v[48:49], v[50:51]
	v_pk_mul_f32 v[40:41], v[44:45], v[40:41]
	v_pk_mul_f32 v[44:45], v[46:47], v[54:55]
	v_cvt_pk_bf16_f32 v40, v40, v41
	v_mul_f32_e32 v41, 0xbfb8aa3b, v36
	v_pk_mul_f32 v[42:43], v[44:45], v[42:43]
	v_exp_f32_e32 v44, v41
	v_mul_f32_e32 v41, 0xbfb8aa3b, v37
	v_exp_f32_e32 v45, v41
	v_cvt_pk_bf16_f32 v41, v42, v43
	v_add_f32_e32 v42, 1.0, v44
	v_mul_f32_e32 v44, 0xbfb8aa3b, v38
	v_add_f32_e32 v43, 1.0, v45
	v_mul_f32_e32 v45, 0xbfb8aa3b, v39
	v_exp_f32_e32 v44, v44
; __device__ __forceinline__ unsigned cvt_pk_bf16(float lo, float hi) { const f32x2 v = {lo, hi}; const bf16x2_t r = __builtin_convertvector(v, bf16x2_t); return __builtin_bit_cast(unsigned, r); }
; __device__ __forceinline__ float silu_f(float g) { return g * __builtin_amdgcn_rcpf(1.0f + __builtin_amdgcn_exp2f(-1.44269504f * g)); }
; __device__ __forceinline__ float row_rs(const RowScale& R, int pm, int lr) { return (R.rsl && pm == R.pm0) ? R.rsl[lr] : rstd_of(R.ss, pm * 256 + lr); }
; #define PG8_BAR __builtin_amdgcn_s_barrier()
; template <bool ALIGN_EPI, class Epi, class Sched>
; __device__ __forceinline__ void gemm_phase(LAS unsigned char* lds, const int lda, const int ldb, const int K, const Sched& S, const Epi& E, const size_t kstepA = (size_t)(BK * 2), const size_t kstepB = (size_t)(BK * 2)) {
;     ...
;         if (!has_next) break;
; #pragma unroll
;         for (int a = 0; a < 2; ++a)
; #pragma unroll
;             for (int b = 0; b < 2; ++b)
; #pragma unroll
;                 for (int m = 0; m < 4; ++m)
; #pragma unroll
;                     for (int n = 0; n < 2; ++n) acc[a][b][m][n] = (f32x4){0.f, 0.f, 0.f, 0.f};
;         cur = nxt; cA = nA; cB = nB; ++ui;
;         if constexpr (ALIGN_EPI) { if (wr == 1) PG8_BAR; }
;     __device__ __forceinline__ void operator()(const Acc& acc, const Unit& u, int wr, int wc, int fr, int fq) const {
;     ...
;             for (int m = 0; m < 4; ++m) { const int row = row0 + ai * HALF + m * 16; const float rs = scaled ? row_rs(R, u.pm, ai * HALF + wr * 64 + m * 16 + fr) : 1.0f;
;                 const f32x4 g0 = acc[ai][0][m][0] * rs, g1 = acc[ai][0][m][1] * rs, u0 = acc[ai][1][m][0] * rs, u1 = acc[ai][1][m][1] * rs;
;                 u32x4 w; w.x = cvt_pk_bf16(silu_f(g0[0]) * u0[0], silu_f(g0[1]) * u0[1]); w.y = cvt_pk_bf16(silu_f(g0[2]) * u0[2], silu_f(g0[3]) * u0[3]);
;                 w.z = cvt_pk_bf16(silu_f(g1[0]) * u1[0], silu_f(g1[1]) * u1[1]); w.w = cvt_pk_bf16(silu_f(g1[2]) * u1[2], silu_f(g1[3]) * u1[3]);
;                 *(u32x4*)(O + ((size_t)(col0 >> 6) * T + row) * 64 + (col0 & 63)) = w; }
	v_exp_f32_e32 v45, v45
	v_rcp_f32_e32 v42, v42
	v_rcp_f32_e32 v43, v43
	v_add_f32_e32 v44, 1.0, v44
	v_add_f32_e32 v45, 1.0, v45
	v_rcp_f32_e32 v44, v44
	v_rcp_f32_e32 v45, v45
	v_pk_mul_f32 v[36:37], v[36:37], v[42:43]
	v_cvt_pk_bf16_f32 v59, v48, v49
	v_pk_mul_f32 v[32:33], v[36:37], v[32:33]
	v_add_co_u32_e32 v48, vcc, s6, v112
	v_cvt_pk_bf16_f32 v42, v32, v33
	v_pk_mul_f32 v[32:33], v[38:39], v[44:45]
	v_addc_co_u32_e32 v49, vcc, 0, v113, vcc
	v_pk_mul_f32 v[32:33], v[32:33], v[34:35]
	v_mul_f32_e32 v34, 0xbfb8aa3b, v30
	v_cvt_pk_bf16_f32 v43, v32, v33
	v_mul_f32_e32 v32, 0xbfb8aa3b, v28
	v_mul_f32_e32 v33, 0xbfb8aa3b, v29
	v_exp_f32_e32 v32, v32
	v_exp_f32_e32 v33, v33
	v_mul_f32_e32 v35, 0xbfb8aa3b, v31
	v_exp_f32_e32 v34, v34
	v_exp_f32_e32 v35, v35
	v_add_f32_e32 v32, 1.0, v32
	v_add_f32_e32 v33, 1.0, v33
	v_rcp_f32_e32 v32, v32
	v_rcp_f32_e32 v33, v33
	v_add_f32_e32 v34, 1.0, v34
	v_add_f32_e32 v35, 1.0, v35
	v_rcp_f32_e32 v34, v34
	v_rcp_f32_e32 v35, v35
	v_pk_mul_f32 v[28:29], v[28:29], v[32:33]
	s_movk_i32 s6, 0x5000
	v_pk_mul_f32 v[24:25], v[28:29], v[24:25]
	v_pk_mul_f32 v[28:29], v[30:31], v[34:35]
	v_cvt_pk_bf16_f32 v24, v24, v25
	v_mul_f32_e32 v25, 0xbfb8aa3b, v20
	v_pk_mul_f32 v[26:27], v[28:29], v[26:27]
	v_exp_f32_e32 v28, v25
	v_mul_f32_e32 v25, 0xbfb8aa3b, v21
	v_exp_f32_e32 v29, v25
	v_cvt_pk_bf16_f32 v25, v26, v27
	v_add_f32_e32 v26, 1.0, v28
	v_mul_f32_e32 v28, 0xbfb8aa3b, v22
	v_add_f32_e32 v27, 1.0, v29
	v_mul_f32_e32 v29, 0xbfb8aa3b, v23
	v_exp_f32_e32 v28, v28
	v_exp_f32_e32 v29, v29
	v_rcp_f32_e32 v26, v26
	v_rcp_f32_e32 v27, v27
	v_add_f32_e32 v28, 1.0, v28
	v_add_f32_e32 v29, 1.0, v29
	v_rcp_f32_e32 v28, v28
	v_rcp_f32_e32 v29, v29
	v_pk_mul_f32 v[20:21], v[20:21], v[26:27]
	v_add_co_u32_e32 v50, vcc, s6, v112
	v_pk_mul_f32 v[16:17], v[20:21], v[16:17]
	s_nop 0
	v_addc_co_u32_e32 v51, vcc, 0, v113, vcc
	v_cvt_pk_bf16_f32 v26, v16, v17
	v_pk_mul_f32 v[16:17], v[22:23], v[28:29]
	s_andn2_b64 vcc, exec, s[4:5]
	v_pk_mul_f32 v[16:17], v[16:17], v[18:19]
	v_mul_f32_e32 v18, 0xbfb8aa3b, v14
	v_cvt_pk_bf16_f32 v27, v16, v17
	v_mul_f32_e32 v16, 0xbfb8aa3b, v12
	v_mul_f32_e32 v17, 0xbfb8aa3b, v13
	v_exp_f32_e32 v16, v16
	v_exp_f32_e32 v17, v17
	v_mul_f32_e32 v19, 0xbfb8aa3b, v15
	v_exp_f32_e32 v18, v18
	v_exp_f32_e32 v19, v19
	v_add_f32_e32 v16, 1.0, v16
	v_add_f32_e32 v17, 1.0, v17
	v_rcp_f32_e32 v16, v16
	v_rcp_f32_e32 v17, v17
	v_add_f32_e32 v18, 1.0, v18
	v_add_f32_e32 v19, 1.0, v19
	v_rcp_f32_e32 v18, v18
	v_rcp_f32_e32 v19, v19
	v_pk_mul_f32 v[12:13], v[12:13], v[16:17]
	s_mov_b64 s[4:5], -1
	v_pk_mul_f32 v[8:9], v[12:13], v[8:9]
	v_pk_mul_f32 v[12:13], v[14:15], v[18:19]
	v_cvt_pk_bf16_f32 v8, v8, v9
	v_mul_f32_e32 v9, 0xbfb8aa3b, v4
	v_pk_mul_f32 v[10:11], v[12:13], v[10:11]
	v_exp_f32_e32 v12, v9
	v_mul_f32_e32 v9, 0xbfb8aa3b, v5
	v_exp_f32_e32 v13, v9
	v_cvt_pk_bf16_f32 v9, v10, v11
	v_add_f32_e32 v10, 1.0, v12
	v_mul_f32_e32 v12, 0xbfb8aa3b, v6
	v_add_f32_e32 v11, 1.0, v13
	v_mul_f32_e32 v13, 0xbfb8aa3b, v7
	v_exp_f32_e32 v12, v12
	v_exp_f32_e32 v13, v13
	v_rcp_f32_e32 v10, v10
	v_rcp_f32_e32 v11, v11
	v_add_f32_e32 v12, 1.0, v12
	v_add_f32_e32 v13, 1.0, v13
	v_rcp_f32_e32 v12, v12
	v_rcp_f32_e32 v13, v13
	v_pk_mul_f32 v[4:5], v[4:5], v[10:11]
	global_store_dwordx4 v[50:51], v[56:59], off offset:-4096
	v_pk_mul_f32 v[0:1], v[4:5], v[0:1]
	global_store_dwordx4 v[48:49], v[40:43], off offset:2048
	v_cvt_pk_bf16_f32 v10, v0, v1
	v_pk_mul_f32 v[0:1], v[6:7], v[12:13]
	global_store_dwordx4 v[50:51], v[24:27], off
	v_pk_mul_f32 v[0:1], v[0:1], v[2:3]
	s_nop 0
	v_cvt_pk_bf16_f32 v11, v0, v1
	global_store_dwordx4 v[50:51], v[8:11], off offset:2048
	s_cbranch_vccnz .LBB0_135
	s_andn2_b64 vcc, exec, s[10:11]
	s_cbranch_vccnz .LBB0_134
	s_branch .LBB0_134

; #define PG8_STAGE(bufoff, gbase, voff) do { _Pragma("unroll") for (int _i = 0; _i < 2; ++_i) \
;         __builtin_amdgcn_global_load_lds((const unsigned*)((const char*)(gbase) + (voff)[_i]), (LAS unsigned*)(lds + (bufoff) + ldsw + _i * 8192), 16, 0, 0); } while (0)
; #define PG8_WAIT_V(n) asm volatile("s_waitcnt vmcnt(" #n ")" ::: "memory")
; #define PG8_BAR __builtin_amdgcn_s_barrier()
; template <bool ALIGN_EPI, class Epi, class Sched>
; __device__ __forceinline__ void gemm_phase(LAS unsigned char* lds, const int lda, const int ldb, const int K, const Sched& S, const Epi& E, const size_t kstepA = (size_t)(BK * 2), const size_t kstepB = (size_t)(BK * 2)) {
;     int tid = threadIdx.x; asm volatile("" : "+v"(tid));
;     const int wid = __builtin_amdgcn_readfirstlane(tid >> 6), lane = tid & 63, wr = wid >> 2, wc = wid & 3, fr = lane & 15, fq = lane >> 4;
;     const int nt = K / BK;
;     unsigned voffA[2], voffB[2];
; #pragma unroll
;     for (int i = 0; i < 2; ++i) { int R, C; stage_rc(tid * 16 + i * 8192, R, C); const int Rb = (R & ~31) + perm32(R & 31);
;         voffA[i] = (unsigned)(R * lda + C) * 2u; voffB[i] = (unsigned)(Rb * ldb + C) * 2u; }
;     const size_t kstep = kstepB;
;     const size_t hstepA = (size_t)HALF * lda * 2, hstepB = (size_t)HALF * ldb * 2;
;     const unsigned ldsw = (unsigned)wid * 1024u;
;     const int aoff = lds_byte(wr * 64 + fr, fq * 8), boff = lds_byte(wc * 32 + fr, fq * 8);
;     ...
;     Unit cur, nxt; int ui = 0;
;     if (!S.next(0, cur)) return;
;     f32x4 acc[2][2][4][2];
; #pragma unroll
;     for (int a = 0; a < 2; ++a)
; #pragma unroll
;         for (int b = 0; b < 2; ++b)
; #pragma unroll
;             for (int m = 0; m < 4; ++m)
; #pragma unroll
;                 for (int n = 0; n < 2; ++n) acc[a][b][m][n] = (f32x4){0.f, 0.f, 0.f, 0.f};
;     bf16x8 At[4][2], B0[2][2], B1[2][2];
;     const char* cA = cur.a; const char* cB = cur.b;
;     PG8_STAGE(PG8_SB(0, 0), cB, voffB); PG8_STAGE(PG8_SB(0, 1), cB + hstepB, voffB); PG8_STAGE(PG8_SA(0, 0), cA, voffA); PG8_STAGE(PG8_SA(0, 1), cA + hstepA, voffA);
;     if (wr == 1) PG8_BAR;
;     PG8_WAIT_V(2); PG8_BAR;
;     PG8_STAGE(PG8_SB(1, 0), cB + kstep, voffB); PG8_STAGE(PG8_SA(1, 0), cA + kstepA, voffA); PG8_STAGE(PG8_SB(1, 1), cB + hstepB + kstep, voffB);
;     PG8_WAIT_V(6); PG8_BAR;
.LBB0_205:
	s_mov_b32 s86, s80
	s_add_u32 s80, s26, 0x4000
	s_mov_b32 s87, s81
	s_addc_u32 s81, s27, 0
	s_and_b64 vcc, exec, s[4:5]
	s_cbranch_vccnz .LBB0_257
	v_bfe_i32 v2, v0, 27, 1
	v_lshlrev_b32_e32 v4, 4, v0
	v_lshrrev_b32_e32 v2, 22, v2
	v_ashrrev_i32_e32 v1, 31, v0
	v_add_u32_e32 v2, v4, v2
	v_lshrrev_b32_e32 v1, 26, v1
	v_and_b32_e32 v2, 0xfffffc00, v2
	v_add_u32_e32 v1, v0, v1
	v_sub_u32_e32 v2, v4, v2
	v_ashrrev_i32_e32 v1, 6, v1
	v_lshrrev_b32_e32 v3, 4, v2
	v_bitop3_b32 v3, v3, v2, 32 bitop3:0x6c
	v_lshlrev_b32_e32 v2, 3, v1
	v_and_b32_e32 v5, -16, v2
	v_ashrrev_i32_e32 v2, 31, v3
	v_lshrrev_b32_e32 v2, 26, v2
	v_add_u32_e32 v6, v3, v2
	v_ashrrev_i32_e32 v2, 6, v6
	v_and_b32_e32 v6, 0xc0, v6
	v_sub_u32_e32 v3, v3, v6
	v_mov_b32_e32 v6, 1
	v_lshlrev_b32_e32 v7, 5, v1
	v_ashrrev_i16_sdwa v3, v6, sext(v3) dst_sel:DWORD dst_unused:UNUSED_PAD src0_sel:DWORD src1_sel:BYTE_0
	v_and_b32_e32 v7, 32, v7
	v_bfe_i32 v3, v3, 0, 16
	v_add_u32_e32 v5, v2, v5
	v_and_b32_e32 v10, 3, v2
	s_mov_b32 s7, 0x1ffffe0
	v_add_lshl_u32 v7, v7, v3, 1
	v_lshlrev_b32_e32 v8, 1, v5
	v_lshrrev_b32_e32 v9, 2, v5
	v_and_or_b32 v10, v5, s7, v10
	v_lshl_add_u32 v194, v5, 7, v7
	v_add_u32_e32 v5, 0x2000, v4
	v_ashrrev_i32_e32 v4, 31, v5
	v_lshrrev_b32_e32 v4, 22, v4
	v_and_b32_e32 v8, 24, v8
	v_and_b32_e32 v9, 4, v9
	v_add_u32_e32 v4, v5, v4
	v_or3_b32 v8, v10, v9, v8
	v_ashrrev_i32_e32 v4, 10, v4
	v_lshl_add_u32 v196, v8, 7, v7
	v_mul_i32_i24_e32 v7, 0x400, v4
	v_sub_u32_e32 v5, v5, v7
	v_lshrrev_b32_e32 v7, 4, v5
	v_bitop3_b32 v7, v7, v5, 32 bitop3:0x6c
	v_lshlrev_b32_e32 v5, 3, v4
	v_and_b32_e32 v8, -16, v5
	v_ashrrev_i32_e32 v5, 31, v7
	v_lshrrev_b32_e32 v5, 26, v5
	v_add_u32_e32 v9, v7, v5
	s_ashr_i32 s6, s8, 6
	v_ashrrev_i32_e32 v5, 6, v9
	v_and_b32_e32 v9, 0xc0, v9
	v_add_u32_e32 v8, v5, v8
	v_sub_u32_e32 v7, v7, v9
	s_lshl_b32 s18, s6, 10
	v_lshlrev_b32_e32 v10, 5, v4
	v_ashrrev_i16_sdwa v6, v6, sext(v7) dst_sel:DWORD dst_unused:UNUSED_PAD src0_sel:DWORD src1_sel:BYTE_0
	v_lshlrev_b32_e32 v7, 1, v8
	v_lshrrev_b32_e32 v9, 2, v8
	v_and_b32_e32 v11, 3, v5
	s_add_i32 s19, s18, 0
	v_and_b32_e32 v10, 32, v10
	v_bfe_i32 v6, v6, 0, 16
	v_and_b32_e32 v7, 24, v7
	v_and_b32_e32 v9, 4, v9
	v_and_or_b32 v11, v8, s7, v11
	s_add_i32 m0, s19, 0x10000
	v_or3_b32 v7, v11, v9, v7
	v_add_lshl_u32 v9, v10, v6, 1
	s_ashr_i32 s7, s8, 8
	global_load_lds_dwordx4 v196, s[94:95]
	s_add_i32 m0, s19, 0x12000
	v_lshl_add_u32 v200, v7, 7, v9
	s_add_u32 s10, s94, 0x4000
	global_load_lds_dwordx4 v200, s[94:95]
	s_addc_u32 s11, s95, 0
	s_add_i32 m0, s19, 0x14000
	s_add_i32 s20, s19, 0x2000
	global_load_lds_dwordx4 v196, s[10:11]
	s_add_i32 m0, s19, 0x16000
	v_lshl_add_u32 v198, v8, 7, v9
	global_load_lds_dwordx4 v200, s[10:11]
	s_mov_b32 m0, s19
	s_add_u32 s10, s82, 0x4000
	global_load_lds_dwordx4 v194, s[82:83]
	s_mov_b32 m0, s20
	s_addc_u32 s11, s83, 0
	s_add_i32 s21, s19, 0x4000
	global_load_lds_dwordx4 v198, s[82:83]
	s_mov_b32 m0, s21
	s_add_i32 s22, s19, 0x6000
	global_load_lds_dwordx4 v194, s[10:11]
	s_mov_b32 m0, s22
	v_mov_b32_e32 v203, 0
	global_load_lds_dwordx4 v198, s[10:11]
	s_cmp_eq_u32 s7, 1
	s_mov_b32 s41, 0
	v_mov_b32_e32 v197, v203
	v_mov_b32_e32 v201, v203
	v_mov_b32_e32 v195, v203
	s_cselect_b64 s[48:49], -1, 0
	s_cmp_lg_u32 s7, 1
	v_mov_b32_e32 v199, v203
	s_cbranch_scc1 .LBB0_208
.LBB0_208:
	s_and_b32 s23, s6, 3
	s_lshl_b32 s6, s7, 13
	s_lshl_b32 s29, s23, 5
	s_lshl_b32 s9, s23, 12
	s_add_u32 s72, s26, 0x1fc14000
	s_addc_u32 s73, s27, 0
	s_add_u32 s10, s94, 0x40000
	s_addc_u32 s11, s95, 0
	s_add_i32 m0, s19, 0x18000
	v_lshl_add_u64 v[8:9], s[10:11], 0, v[196:197]
	s_waitcnt vmcnt(2)
	s_barrier
	global_load_lds_dwordx4 v[8:9], off
	s_add_i32 m0, s19, 0x1a000
	v_lshl_add_u64 v[8:9], s[10:11], 0, v[200:201]
	s_add_u32 s10, s82, 0x200000
	s_addc_u32 s11, s83, 0
	s_add_i32 s30, s19, 0x8000
	global_load_lds_dwordx4 v[8:9], off
	v_lshl_add_u64 v[8:9], s[10:11], 0, v[194:195]
	s_mov_b32 m0, s30
	s_add_i32 s31, s19, 0xa000
	global_load_lds_dwordx4 v[8:9], off
	v_lshl_add_u64 v[8:9], s[10:11], 0, v[198:199]
	s_add_u32 s10, s94, 0x44000
	s_mov_b32 m0, s31
	s_addc_u32 s11, s95, 0
	global_load_lds_dwordx4 v[8:9], off
	s_add_i32 m0, s19, 0x1c000
	v_lshl_add_u64 v[8:9], s[10:11], 0, v[196:197]
	global_load_lds_dwordx4 v[8:9], off
	v_lshl_add_u64 v[8:9], s[10:11], 0, v[200:201]
	s_add_i32 m0, s19, 0x1e000
	v_bfe_u32 v7, v0, 4, 2
	global_load_lds_dwordx4 v[8:9], off
	v_and_b32_e32 v8, 15, v0
	v_lshlrev_b32_e32 v9, 4, v7
	v_lshlrev_b32_e32 v0, 2, v0
	v_lshl_or_b32 v187, s7, 6, v8
	v_lshl_or_b32 v8, v8, 6, v9
	v_and_b32_e32 v0, 32, v0
	v_bitop3_b32 v9, v8, s6, v0 bitop3:0xde
	v_bitop3_b32 v191, v8, s9, v0 bitop3:0xde
	v_lshlrev_b32_e32 v0, 10, v1
	v_and_b32_e32 v0, 0xfffff800, v0
	v_lshl_add_u32 v0, v2, 7, v0
	v_and_b32_e32 v1, 1, v1
	v_lshl_or_b32 v0, v1, 6, v0
	v_lshl_add_u32 v204, v3, 1, v0
	v_lshlrev_b32_e32 v0, 10, v4
	v_and_b32_e32 v0, 0xfffff800, v0
	s_waitcnt vmcnt(6)
	s_cmpk_lt_u32 s8, 0x100
	v_lshl_add_u32 v0, v5, 7, v0
	v_and_b32_e32 v1, 1, v4
	s_cselect_b64 s[84:85], -1, 0
	v_lshl_or_b32 v0, v1, 6, v0
	s_add_i32 s33, 0, 0x10000
	s_add_i32 s42, 0, 0x14000
	v_lshlrev_b32_e32 v189, 3, v7
	v_cmp_eq_u32_e64 s[8:9], 0, v7
	v_mov_b32_e32 v205, v203
	v_lshl_add_u32 v206, v6, 1, v0
	v_mov_b32_e32 v207, v203
	v_mov_b64_e32 v[208:209], 0x200
	v_mov_b64_e32 v[210:211], 0x1ff
	v_add_u32_e32 v193, s33, v191
	v_add_u32_e32 v232, s42, v191
	v_add_u32_e32 v233, 0, v9
	v_mbcnt_hi_u32_b32 v234, -1, v185
	s_mov_b32 s43, 0
	s_barrier
	s_branch .LBB0_211

; #define PG8_STAGE(bufoff, gbase, voff) do { _Pragma("unroll") for (int _i = 0; _i < 2; ++_i) \
;         __builtin_amdgcn_global_load_lds((const unsigned*)((const char*)(gbase) + (voff)[_i]), (LAS unsigned*)(lds + (bufoff) + ldsw + _i * 8192), 16, 0, 0); } while (0)
; #define PG8_LDA(dst, b, h) do { _Pragma("unroll") for (int m = 0; m < 4; ++m) _Pragma("unroll") for (int k = 0; k < 2; ++k) dst[m][k] = *(const LAS bf16x8*)(lds + PG8_SA(b, h) + aoff + m * 2048 + k * 1024); } while (0)
; #define PG8_LDB(dst, b, h) do { _Pragma("unroll") for (int n = 0; n < 2; ++n) _Pragma("unroll") for (int k = 0; k < 2; ++k) dst[n][k] = *(const LAS bf16x8*)(lds + PG8_SB(b, h) + boff + n * 2048 + k * 1024); } while (0)
; #define PG8_WAIT_V(n) asm volatile("s_waitcnt vmcnt(" #n ")" ::: "memory")
; #define PG8_WAIT_L(n) asm volatile("s_waitcnt lgkmcnt(" #n ")" ::: "memory")
; #define PG8_BAR __builtin_amdgcn_s_barrier()
; #define PG8_SCHED __builtin_amdgcn_sched_barrier(0)
; template <bool ALIGN_EPI, class Epi, class Sched>
; __device__ __forceinline__ void gemm_phase(LAS unsigned char* lds, const int lda, const int ldb, const int K, const Sched& S, const Epi& E, const size_t kstepA = (size_t)(BK * 2), const size_t kstepB = (size_t)(BK * 2)) {
;     ...
;     for (;;) {
;         const bool has_next = S.next(ui + 1, nxt);
;         const char* nA = has_next ? nxt.a : cA; const char* nB = has_next ? nxt.b : cB;
; #pragma unroll 1
;         for (int t = 0; t < nt; t += 2) {
;             const bool last = (t == nt - 2);
;             const char* a1 = cA + (size_t)(t + 1) * kstepA;
;             const char* a2 = last ? nA : cA + (size_t)(t + 2) * kstepA; const char* b2 = last ? nB : cB + (size_t)(t + 2) * kstep;
;             const char* a3 = a2 + kstepA; const char* b3 = b2 + kstep;
;             PG8_LDB(B0, 0, 0); PG8_LDB(B1, 0, 1); PG8_SCHED; PG8_LDA(At, 0, 0); PG8_STAGE(PG8_SA(1, 1), a1 + hstepA, voffA);
;             PG8_WAIT_V(8); PG8_WAIT_L(0); PG8_BAR; PG8_MMA(0, 0, At, B0); PG8_MMA(0, 1, At, B1); PG8_BAR; PG8_SCHED;
;     ...
; #pragma unroll
;         for (int a = 0; a < 2; ++a)
; #pragma unroll
;             for (int b = 0; b < 2; ++b)
; #pragma unroll
;                 for (int m = 0; m < 4; ++m)
; #pragma unroll
;                     for (int n = 0; n < 2; ++n) acc[a][b][m][n] = (f32x4){0.f, 0.f, 0.f, 0.f};
;         cur = nxt; cA = nA; cB = nB; ++ui;
.LBB0_217:
	s_add_u32 s13, s94, 0x80000
	s_addc_u32 s50, s95, 0
	s_add_u32 s82, s82, 0x204000
	v_mov_b32_e32 v0, 0
	s_addc_u32 s83, s83, 0
	s_mov_b32 s51, -2
	s_waitcnt lgkmcnt(0)
	v_mov_b32_e32 v1, v0
	v_mov_b32_e32 v2, v0
	v_mov_b32_e32 v3, v0
	v_mov_b32_e32 v4, v0
	v_mov_b32_e32 v5, v0
	v_mov_b32_e32 v6, v0
	v_mov_b32_e32 v7, v0
	v_mov_b32_e32 v16, v0
	v_mov_b32_e32 v17, v0
	v_mov_b32_e32 v18, v0
	v_mov_b32_e32 v19, v0
	v_mov_b32_e32 v20, v0
	v_mov_b32_e32 v21, v0
	v_mov_b32_e32 v22, v0
	v_mov_b32_e32 v23, v0
	v_mov_b32_e32 v32, v0
	v_mov_b32_e32 v33, v0
	v_mov_b32_e32 v34, v0
	v_mov_b32_e32 v35, v0
	v_mov_b32_e32 v36, v0
	v_mov_b32_e32 v37, v0
	v_mov_b32_e32 v38, v0
	v_mov_b32_e32 v39, v0
	v_mov_b32_e32 v48, v0
	v_mov_b32_e32 v49, v0
	v_mov_b32_e32 v50, v0
	v_mov_b32_e32 v51, v0
	v_mov_b32_e32 v52, v0
	v_mov_b32_e32 v53, v0
	v_mov_b32_e32 v54, v0
	v_mov_b32_e32 v55, v0
	v_mov_b32_e32 v8, v0
	v_mov_b32_e32 v9, v0
	v_mov_b32_e32 v10, v0
	v_mov_b32_e32 v11, v0
	v_mov_b32_e32 v12, v0
	v_mov_b32_e32 v13, v0
	v_mov_b32_e32 v14, v0
	v_mov_b32_e32 v15, v0
	v_mov_b32_e32 v24, v0
	v_mov_b32_e32 v25, v0
	v_mov_b32_e32 v26, v0
	v_mov_b32_e32 v27, v0
	v_mov_b32_e32 v28, v0
	v_mov_b32_e32 v29, v0
	v_mov_b32_e32 v30, v0
	v_mov_b32_e32 v31, v0
	v_mov_b32_e32 v40, v0
	v_mov_b32_e32 v41, v0
	v_mov_b32_e32 v42, v0
	v_mov_b32_e32 v43, v0
	v_mov_b32_e32 v44, v0
	v_mov_b32_e32 v45, v0
	v_mov_b32_e32 v46, v0
	v_mov_b32_e32 v47, v0
	v_mov_b32_e32 v56, v0
	v_mov_b32_e32 v57, v0
	v_mov_b32_e32 v58, v0
	v_mov_b32_e32 v59, v0
	v_mov_b32_e32 v60, v0
	v_mov_b32_e32 v61, v0
	v_mov_b32_e32 v62, v0
	v_mov_b32_e32 v63, v0
	v_mov_b32_e32 v72, v0
	v_mov_b32_e32 v73, v0
	v_mov_b32_e32 v74, v0
	v_mov_b32_e32 v75, v0
	v_mov_b32_e32 v76, v0
	v_mov_b32_e32 v77, v0
	v_mov_b32_e32 v78, v0
	v_mov_b32_e32 v79, v0
	v_mov_b32_e32 v96, v0
	v_mov_b32_e32 v97, v0
	v_mov_b32_e32 v98, v0
	v_mov_b32_e32 v99, v0
	v_mov_b32_e32 v100, v0
	v_mov_b32_e32 v101, v0
	v_mov_b32_e32 v102, v0
	v_mov_b32_e32 v103, v0
	v_mov_b32_e32 v112, v0
	v_mov_b32_e32 v113, v0
	v_mov_b32_e32 v114, v0
	v_mov_b32_e32 v115, v0
	v_mov_b32_e32 v116, v0
	v_mov_b32_e32 v117, v0
	v_mov_b32_e32 v118, v0
	v_mov_b32_e32 v119, v0
	v_mov_b32_e32 v128, v0
	v_mov_b32_e32 v129, v0
	v_mov_b32_e32 v130, v0
	v_mov_b32_e32 v131, v0
	v_mov_b32_e32 v132, v0
	v_mov_b32_e32 v133, v0
	v_mov_b32_e32 v134, v0
	v_mov_b32_e32 v135, v0
	v_mov_b32_e32 v88, v0
	v_mov_b32_e32 v89, v0
	v_mov_b32_e32 v90, v0
	v_mov_b32_e32 v91, v0
	v_mov_b32_e32 v92, v0
	v_mov_b32_e32 v93, v0
	v_mov_b32_e32 v94, v0
	v_mov_b32_e32 v95, v0
	v_mov_b32_e32 v104, v0
	v_mov_b32_e32 v105, v0
	v_mov_b32_e32 v106, v0
	v_mov_b32_e32 v107, v0
	v_mov_b32_e32 v108, v0
	v_mov_b32_e32 v109, v0
	v_mov_b32_e32 v110, v0
	v_mov_b32_e32 v111, v0
	v_mov_b32_e32 v120, v0
	v_mov_b32_e32 v121, v0
	v_mov_b32_e32 v122, v0
	v_mov_b32_e32 v123, v0
	v_mov_b32_e32 v124, v0
	v_mov_b32_e32 v125, v0
	v_mov_b32_e32 v126, v0
	v_mov_b32_e32 v127, v0
	v_mov_b32_e32 v136, v0
	v_mov_b32_e32 v137, v0
	v_mov_b32_e32 v138, v0
	v_mov_b32_e32 v139, v0
	v_mov_b32_e32 v140, v0
	v_mov_b32_e32 v141, v0
	v_mov_b32_e32 v142, v0
	v_mov_b32_e32 v143, v0
	s_cmp_lg_u64 s[84:85], 0
	s_cbranch_scc0 .Lp2_kloop_y
.LBB0_218:
	ds_read_b128 v[64:67], v193
	ds_read_b128 v[68:71], v193 offset:1024
	ds_read_b128 v[80:83], v193 offset:2048
	ds_read_b128 v[84:87], v193 offset:3072
	ds_read_b128 v[144:147], v232
	ds_read_b128 v[148:151], v232 offset:1024
	ds_read_b128 v[152:155], v232 offset:2048
	ds_read_b128 v[156:159], v232 offset:3072
	s_add_u32 s54, s82, 0x1fc000
	s_addc_u32 s55, s83, 0
	s_cmpk_eq_i32 s51, 0x54
	s_cselect_b32 vcc_lo, s6, s54
	s_cselect_b32 vcc_hi, s7, s55
	s_cselect_b32 s96, s78, s13
	s_cselect_b32 s97, s79, s50
	s_add_u32 s94, vcc_lo, 0x200000
	s_addc_u32 s95, vcc_hi, 0
	v_lshl_add_u64 v[220:221], s[82:83], 0, v[204:205]
	s_add_i32 m0, s19, 0xc000
	ds_read_b128 v[160:163], v233
	ds_read_b128 v[164:167], v233 offset:1024
	ds_read_b128 v[168:171], v233 offset:2048
	ds_read_b128 v[172:175], v233 offset:3072
	ds_read_b128 v[176:179], v233 offset:4096
	ds_read_b128 v[180:183], v233 offset:5120
	ds_read_b128 v[212:215], v233 offset:6144
	ds_read_b128 v[216:219], v233 offset:7168
	global_load_lds_dwordx4 v[220:221], off
	v_lshl_add_u64 v[220:221], s[82:83], 0, v[206:207]
	s_add_i32 m0, s19, 0xe000
	s_nop 0
	global_load_lds_dwordx4 v[220:221], off
	s_waitcnt vmcnt(8)
	s_waitcnt lgkmcnt(0)
	s_setprio 1
	s_waitcnt lgkmcnt(0)
	v_mfma_f32_16x16x32_bf16 v[140:143], v[64:67], v[160:163], v[140:143]
	v_mfma_f32_16x16x32_bf16 v[140:143], v[68:71], v[164:167], v[140:143]
	v_mfma_f32_16x16x32_bf16 v[136:139], v[80:83], v[160:163], v[136:139]
	v_mfma_f32_16x16x32_bf16 v[136:139], v[84:87], v[164:167], v[136:139]
	v_mfma_f32_16x16x32_bf16 v[124:127], v[64:67], v[168:171], v[124:127]
	v_mfma_f32_16x16x32_bf16 v[124:127], v[68:71], v[172:175], v[124:127]
	v_mfma_f32_16x16x32_bf16 v[120:123], v[80:83], v[168:171], v[120:123]
	v_mfma_f32_16x16x32_bf16 v[120:123], v[84:87], v[172:175], v[120:123]
	v_mfma_f32_16x16x32_bf16 v[108:111], v[64:67], v[176:179], v[108:111]
	v_mfma_f32_16x16x32_bf16 v[108:111], v[68:71], v[180:183], v[108:111]
	v_mfma_f32_16x16x32_bf16 v[104:107], v[80:83], v[176:179], v[104:107]
	v_mfma_f32_16x16x32_bf16 v[104:107], v[84:87], v[180:183], v[104:107]
	v_mfma_f32_16x16x32_bf16 v[92:95], v[64:67], v[212:215], v[92:95]
	v_mfma_f32_16x16x32_bf16 v[92:95], v[68:71], v[216:219], v[92:95]
	v_mfma_f32_16x16x32_bf16 v[88:91], v[80:83], v[212:215], v[88:91]
	v_mfma_f32_16x16x32_bf16 v[88:91], v[84:87], v[216:219], v[88:91]
	s_setprio 0
	s_setprio 1
	v_mfma_f32_16x16x32_bf16 v[132:135], v[144:147], v[160:163], v[132:135]
	v_mfma_f32_16x16x32_bf16 v[132:135], v[148:151], v[164:167], v[132:135]
	v_mfma_f32_16x16x32_bf16 v[128:131], v[152:155], v[160:163], v[128:131]
	v_mfma_f32_16x16x32_bf16 v[128:131], v[156:159], v[164:167], v[128:131]
	v_mfma_f32_16x16x32_bf16 v[116:119], v[144:147], v[168:171], v[116:119]
	v_mfma_f32_16x16x32_bf16 v[116:119], v[148:151], v[172:175], v[116:119]
	v_mfma_f32_16x16x32_bf16 v[112:115], v[152:155], v[168:171], v[112:115]
	v_mfma_f32_16x16x32_bf16 v[112:115], v[156:159], v[172:175], v[112:115]
	v_mfma_f32_16x16x32_bf16 v[100:103], v[144:147], v[176:179], v[100:103]
	v_mfma_f32_16x16x32_bf16 v[100:103], v[148:151], v[180:183], v[100:103]
	v_mfma_f32_16x16x32_bf16 v[96:99], v[152:155], v[176:179], v[96:99]
	v_mfma_f32_16x16x32_bf16 v[96:99], v[156:159], v[180:183], v[96:99]
	v_mfma_f32_16x16x32_bf16 v[76:79], v[144:147], v[212:215], v[76:79]
	v_mfma_f32_16x16x32_bf16 v[76:79], v[148:151], v[216:219], v[76:79]
	v_mfma_f32_16x16x32_bf16 v[72:75], v[152:155], v[212:215], v[72:75]
	v_mfma_f32_16x16x32_bf16 v[72:75], v[156:159], v[216:219], v[72:75]
	s_setprio 0
	s_barrier
; #define PG8_STAGE(bufoff, gbase, voff) do { _Pragma("unroll") for (int _i = 0; _i < 2; ++_i) \
;         __builtin_amdgcn_global_load_lds((const unsigned*)((const char*)(gbase) + (voff)[_i]), (LAS unsigned*)(lds + (bufoff) + ldsw + _i * 8192), 16, 0, 0); } while (0)
; #define PG8_LDA(dst, b, h) do { _Pragma("unroll") for (int m = 0; m < 4; ++m) _Pragma("unroll") for (int k = 0; k < 2; ++k) dst[m][k] = *(const LAS bf16x8*)(lds + PG8_SA(b, h) + aoff + m * 2048 + k * 1024); } while (0)
; #define PG8_LDB(dst, b, h) do { _Pragma("unroll") for (int n = 0; n < 2; ++n) _Pragma("unroll") for (int k = 0; k < 2; ++k) dst[n][k] = *(const LAS bf16x8*)(lds + PG8_SB(b, h) + boff + n * 2048 + k * 1024); } while (0)
; #define PG8_MMA(ai, bj, At, Bt) do { __builtin_amdgcn_s_setprio(1); _Pragma("unroll") for (int m = 0; m < 4; ++m) _Pragma("unroll") for (int n = 0; n < 2; ++n) _Pragma("unroll") for (int k = 0; k < 2; ++k) \
;         acc[ai][bj][m][n] = __builtin_amdgcn_mfma_f32_16x16x32_bf16(Bt[n][k], At[m][k], acc[ai][bj][m][n], 0, 0, 0); __builtin_amdgcn_s_setprio(0); } while (0)
; #define PG8_WAIT_V(n) asm volatile("s_waitcnt vmcnt(" #n ")" ::: "memory")
; #define PG8_WAIT_L(n) asm volatile("s_waitcnt lgkmcnt(" #n ")" ::: "memory")
; #define PG8_BAR __builtin_amdgcn_s_barrier()
; #define PG8_SCHED __builtin_amdgcn_sched_barrier(0)
; template <bool ALIGN_EPI, class Epi, class Sched>
; __device__ __forceinline__ void gemm_phase(LAS unsigned char* lds, const int lda, const int ldb, const int K, const Sched& S, const Epi& E, const size_t kstepA = (size_t)(BK * 2), const size_t kstepB = (size_t)(BK * 2)) {
;     ...
;             PG8_LDA(At, 0, 1); PG8_STAGE(PG8_SB(0, 0), b2, voffB); PG8_STAGE(PG8_SB(0, 1), b2 + hstepB, voffB); PG8_STAGE(PG8_SA(0, 0), a2, voffA);
;             PG8_WAIT_V(8); PG8_WAIT_L(0); PG8_BAR; PG8_MMA(1, 0, At, B0); PG8_MMA(1, 1, At, B1); PG8_BAR; PG8_SCHED;
;             PG8_LDB(B0, 1, 0); PG8_LDB(B1, 1, 1); PG8_SCHED; PG8_LDA(At, 1, 0); PG8_STAGE(PG8_SA(0, 1), a2 + hstepA, voffA);
;             PG8_WAIT_V(8); PG8_WAIT_L(0); PG8_BAR; PG8_MMA(0, 0, At, B0); PG8_MMA(0, 1, At, B1); PG8_BAR; PG8_SCHED;
	s_add_i32 s54, s33, s18
	v_lshl_add_u64 v[220:221], s[96:97], 0, v[196:197]
	s_mov_b32 m0, s54
	ds_read_b128 v[160:163], v233 offset:16384
	ds_read_b128 v[164:167], v233 offset:17408
	ds_read_b128 v[168:171], v233 offset:18432
	ds_read_b128 v[172:175], v233 offset:19456
	ds_read_b128 v[176:179], v233 offset:20480
	ds_read_b128 v[180:183], v233 offset:21504
	ds_read_b128 v[212:215], v233 offset:22528
	ds_read_b128 v[216:219], v233 offset:23552
	global_load_lds_dwordx4 v[220:221], off
	s_add_i32 m0, s54, 0x2000
	s_add_u32 s54, s96, 0x4000
	v_lshl_add_u64 v[220:221], s[96:97], 0, v[200:201]
	s_addc_u32 s55, s97, 0
	s_add_i32 s56, s42, s18
	global_load_lds_dwordx4 v[220:221], off
	v_lshl_add_u64 v[220:221], s[54:55], 0, v[196:197]
	s_mov_b32 m0, s56
	s_nop 0
	global_load_lds_dwordx4 v[220:221], off
	v_lshl_add_u64 v[220:221], s[54:55], 0, v[200:201]
	s_add_i32 m0, s56, 0x2000
	s_nop 0
	global_load_lds_dwordx4 v[220:221], off
	v_lshl_add_u64 v[220:221], vcc, 0, v[194:195]
	s_mov_b32 m0, s19
	s_nop 0
	global_load_lds_dwordx4 v[220:221], off
	v_lshl_add_u64 v[220:221], vcc, 0, v[198:199]
	s_mov_b32 m0, s20
	s_nop 0
	global_load_lds_dwordx4 v[220:221], off
	s_waitcnt vmcnt(8)
	s_waitcnt lgkmcnt(0)
	s_setprio 1
	s_waitcnt lgkmcnt(0)
	v_mfma_f32_16x16x32_bf16 v[60:63], v[64:67], v[160:163], v[60:63]
	v_mfma_f32_16x16x32_bf16 v[60:63], v[68:71], v[164:167], v[60:63]
	v_mfma_f32_16x16x32_bf16 v[56:59], v[80:83], v[160:163], v[56:59]
	v_mfma_f32_16x16x32_bf16 v[56:59], v[84:87], v[164:167], v[56:59]
	v_mfma_f32_16x16x32_bf16 v[44:47], v[64:67], v[168:171], v[44:47]
	v_mfma_f32_16x16x32_bf16 v[44:47], v[68:71], v[172:175], v[44:47]
	v_mfma_f32_16x16x32_bf16 v[40:43], v[80:83], v[168:171], v[40:43]
	v_mfma_f32_16x16x32_bf16 v[40:43], v[84:87], v[172:175], v[40:43]
	v_mfma_f32_16x16x32_bf16 v[28:31], v[64:67], v[176:179], v[28:31]
	v_mfma_f32_16x16x32_bf16 v[28:31], v[68:71], v[180:183], v[28:31]
	v_mfma_f32_16x16x32_bf16 v[24:27], v[80:83], v[176:179], v[24:27]
	v_mfma_f32_16x16x32_bf16 v[24:27], v[84:87], v[180:183], v[24:27]
	v_mfma_f32_16x16x32_bf16 v[12:15], v[64:67], v[212:215], v[12:15]
	v_mfma_f32_16x16x32_bf16 v[12:15], v[68:71], v[216:219], v[12:15]
	v_mfma_f32_16x16x32_bf16 v[8:11], v[80:83], v[212:215], v[8:11]
	v_mfma_f32_16x16x32_bf16 v[8:11], v[84:87], v[216:219], v[8:11]
	s_setprio 0
	s_setprio 1
	v_mfma_f32_16x16x32_bf16 v[52:55], v[144:147], v[160:163], v[52:55]
	v_mfma_f32_16x16x32_bf16 v[52:55], v[148:151], v[164:167], v[52:55]
	v_mfma_f32_16x16x32_bf16 v[48:51], v[152:155], v[160:163], v[48:51]
	v_mfma_f32_16x16x32_bf16 v[48:51], v[156:159], v[164:167], v[48:51]
	v_mfma_f32_16x16x32_bf16 v[36:39], v[144:147], v[168:171], v[36:39]
	v_mfma_f32_16x16x32_bf16 v[36:39], v[148:151], v[172:175], v[36:39]
	v_mfma_f32_16x16x32_bf16 v[32:35], v[152:155], v[168:171], v[32:35]
	v_mfma_f32_16x16x32_bf16 v[32:35], v[156:159], v[172:175], v[32:35]
	v_mfma_f32_16x16x32_bf16 v[20:23], v[144:147], v[176:179], v[20:23]
	v_mfma_f32_16x16x32_bf16 v[20:23], v[148:151], v[180:183], v[20:23]
	v_mfma_f32_16x16x32_bf16 v[16:19], v[152:155], v[176:179], v[16:19]
	v_mfma_f32_16x16x32_bf16 v[16:19], v[156:159], v[180:183], v[16:19]
	v_mfma_f32_16x16x32_bf16 v[4:7], v[144:147], v[212:215], v[4:7]
	v_mfma_f32_16x16x32_bf16 v[4:7], v[148:151], v[216:219], v[4:7]
	v_mfma_f32_16x16x32_bf16 v[0:3], v[152:155], v[212:215], v[0:3]
	v_mfma_f32_16x16x32_bf16 v[0:3], v[156:159], v[216:219], v[0:3]
	s_setprio 0
	s_barrier
	s_add_i32 s56, 0, 0x18000
	s_add_i32 s57, 0, 0x1c000
	v_add_u32_e32 v84, s56, v191
	v_add_u32_e32 v156, s57, v191
	ds_read_b128 v[64:67], v84
	ds_read_b128 v[68:71], v84 offset:1024
	ds_read_b128 v[80:83], v84 offset:2048
	ds_read_b128 v[84:87], v84 offset:3072
	ds_read_b128 v[144:147], v156
	ds_read_b128 v[148:151], v156 offset:1024
	ds_read_b128 v[152:155], v156 offset:2048
	ds_read_b128 v[156:159], v156 offset:3072
	s_add_u32 s54, vcc_lo, 0x4000
	s_addc_u32 s55, vcc_hi, 0
	s_mov_b32 m0, s21
	v_lshl_add_u64 v[220:221], s[54:55], 0, v[194:195]
	ds_read_b128 v[160:163], v233 offset:32768
	ds_read_b128 v[164:167], v233 offset:33792
	ds_read_b128 v[168:171], v233 offset:34816
	ds_read_b128 v[172:175], v233 offset:35840
	ds_read_b128 v[176:179], v233 offset:36864
	ds_read_b128 v[180:183], v233 offset:37888
	ds_read_b128 v[212:215], v233 offset:38912
	ds_read_b128 v[216:219], v233 offset:39936
	global_load_lds_dwordx4 v[220:221], off
	v_lshl_add_u64 v[220:221], s[54:55], 0, v[198:199]
	s_mov_b32 m0, s22
	s_nop 0
	global_load_lds_dwordx4 v[220:221], off
	s_waitcnt vmcnt(8)
	s_waitcnt lgkmcnt(0)
	s_setprio 1
	s_waitcnt lgkmcnt(0)
	v_mfma_f32_16x16x32_bf16 v[140:143], v[64:67], v[160:163], v[140:143]
	v_mfma_f32_16x16x32_bf16 v[140:143], v[68:71], v[164:167], v[140:143]
	v_mfma_f32_16x16x32_bf16 v[136:139], v[80:83], v[160:163], v[136:139]
	v_mfma_f32_16x16x32_bf16 v[136:139], v[84:87], v[164:167], v[136:139]
	v_mfma_f32_16x16x32_bf16 v[124:127], v[64:67], v[168:171], v[124:127]
	v_mfma_f32_16x16x32_bf16 v[124:127], v[68:71], v[172:175], v[124:127]
	v_mfma_f32_16x16x32_bf16 v[120:123], v[80:83], v[168:171], v[120:123]
	v_mfma_f32_16x16x32_bf16 v[120:123], v[84:87], v[172:175], v[120:123]
	v_mfma_f32_16x16x32_bf16 v[108:111], v[64:67], v[176:179], v[108:111]
	v_mfma_f32_16x16x32_bf16 v[108:111], v[68:71], v[180:183], v[108:111]
	v_mfma_f32_16x16x32_bf16 v[104:107], v[80:83], v[176:179], v[104:107]
	v_mfma_f32_16x16x32_bf16 v[104:107], v[84:87], v[180:183], v[104:107]
	v_mfma_f32_16x16x32_bf16 v[92:95], v[64:67], v[212:215], v[92:95]
	v_mfma_f32_16x16x32_bf16 v[92:95], v[68:71], v[216:219], v[92:95]
	v_mfma_f32_16x16x32_bf16 v[88:91], v[80:83], v[212:215], v[88:91]
	v_mfma_f32_16x16x32_bf16 v[88:91], v[84:87], v[216:219], v[88:91]
	s_setprio 0
	s_setprio 1
	v_mfma_f32_16x16x32_bf16 v[132:135], v[144:147], v[160:163], v[132:135]
	v_mfma_f32_16x16x32_bf16 v[132:135], v[148:151], v[164:167], v[132:135]
	v_mfma_f32_16x16x32_bf16 v[128:131], v[152:155], v[160:163], v[128:131]
	v_mfma_f32_16x16x32_bf16 v[128:131], v[156:159], v[164:167], v[128:131]
	v_mfma_f32_16x16x32_bf16 v[116:119], v[144:147], v[168:171], v[116:119]
	v_mfma_f32_16x16x32_bf16 v[116:119], v[148:151], v[172:175], v[116:119]
	v_mfma_f32_16x16x32_bf16 v[112:115], v[152:155], v[168:171], v[112:115]
	v_mfma_f32_16x16x32_bf16 v[112:115], v[156:159], v[172:175], v[112:115]
	v_mfma_f32_16x16x32_bf16 v[100:103], v[144:147], v[176:179], v[100:103]
	v_mfma_f32_16x16x32_bf16 v[100:103], v[148:151], v[180:183], v[100:103]
	v_mfma_f32_16x16x32_bf16 v[96:99], v[152:155], v[176:179], v[96:99]
	v_mfma_f32_16x16x32_bf16 v[96:99], v[156:159], v[180:183], v[96:99]
	v_mfma_f32_16x16x32_bf16 v[76:79], v[144:147], v[212:215], v[76:79]
	v_mfma_f32_16x16x32_bf16 v[76:79], v[148:151], v[216:219], v[76:79]
	v_mfma_f32_16x16x32_bf16 v[72:75], v[152:155], v[212:215], v[72:75]
	v_mfma_f32_16x16x32_bf16 v[72:75], v[156:159], v[216:219], v[72:75]
	s_setprio 0
	s_barrier
; #define PG8_STAGE(bufoff, gbase, voff) do { _Pragma("unroll") for (int _i = 0; _i < 2; ++_i) \
;         __builtin_amdgcn_global_load_lds((const unsigned*)((const char*)(gbase) + (voff)[_i]), (LAS unsigned*)(lds + (bufoff) + ldsw + _i * 8192), 16, 0, 0); } while (0)
; #define PG8_LDA(dst, b, h) do { _Pragma("unroll") for (int m = 0; m < 4; ++m) _Pragma("unroll") for (int k = 0; k < 2; ++k) dst[m][k] = *(const LAS bf16x8*)(lds + PG8_SA(b, h) + aoff + m * 2048 + k * 1024); } while (0)
; #define PG8_LDB(dst, b, h) do { _Pragma("unroll") for (int n = 0; n < 2; ++n) _Pragma("unroll") for (int k = 0; k < 2; ++k) dst[n][k] = *(const LAS bf16x8*)(lds + PG8_SB(b, h) + boff + n * 2048 + k * 1024); } while (0)
; #define PG8_MMA(ai, bj, At, Bt) do { __builtin_amdgcn_s_setprio(1); _Pragma("unroll") for (int m = 0; m < 4; ++m) _Pragma("unroll") for (int n = 0; n < 2; ++n) _Pragma("unroll") for (int k = 0; k < 2; ++k) \
;         acc[ai][bj][m][n] = __builtin_amdgcn_mfma_f32_16x16x32_bf16(Bt[n][k], At[m][k], acc[ai][bj][m][n], 0, 0, 0); __builtin_amdgcn_s_setprio(0); } while (0)
; #define PG8_WAIT_V(n) asm volatile("s_waitcnt vmcnt(" #n ")" ::: "memory")
; #define PG8_WAIT_L(n) asm volatile("s_waitcnt lgkmcnt(" #n ")" ::: "memory")
; #define PG8_BAR __builtin_amdgcn_s_barrier()
; #define PG8_SCHED __builtin_amdgcn_sched_barrier(0)
; template <bool ALIGN_EPI, class Epi, class Sched>
; __device__ __forceinline__ void gemm_phase(LAS unsigned char* lds, const int lda, const int ldb, const int K, const Sched& S, const Epi& E, const size_t kstepA = (size_t)(BK * 2), const size_t kstepB = (size_t)(BK * 2)) {
;     ...
;             PG8_LDB(B0, 0, 0); PG8_LDB(B1, 0, 1); PG8_SCHED; PG8_LDA(At, 0, 0); PG8_STAGE(PG8_SA(1, 1), a1 + hstepA, voffA);
;             PG8_WAIT_V(8); PG8_WAIT_L(0); PG8_BAR; PG8_MMA(0, 0, At, B0); PG8_MMA(0, 1, At, B1); PG8_BAR; PG8_SCHED;
;     ...
;             PG8_LDA(At, 1, 1); PG8_STAGE(PG8_SB(1, 0), b3, voffB); PG8_STAGE(PG8_SB(1, 1), b3 + hstepB, voffB); PG8_STAGE(PG8_SA(1, 0), a3, voffA);
;             PG8_WAIT_V(8); PG8_WAIT_L(0); PG8_BAR; PG8_MMA(1, 0, At, B0); PG8_MMA(1, 1, At, B1); PG8_BAR; PG8_SCHED;
;         }
	s_add_u32 s54, s96, 0x40000
	s_addc_u32 s55, s97, 0
	s_add_i32 s56, s56, s18
	v_lshl_add_u64 v[220:221], s[54:55], 0, v[196:197]
	s_mov_b32 m0, s56
	ds_read_b128 v[160:163], v233 offset:49152
	ds_read_b128 v[164:167], v233 offset:50176
	ds_read_b128 v[168:171], v233 offset:51200
	ds_read_b128 v[172:175], v233 offset:52224
	ds_read_b128 v[176:179], v233 offset:53248
	ds_read_b128 v[180:183], v233 offset:54272
	ds_read_b128 v[212:215], v233 offset:55296
	ds_read_b128 v[216:219], v233 offset:56320
	global_load_lds_dwordx4 v[220:221], off
	s_add_i32 m0, s56, 0x2000
	v_lshl_add_u64 v[220:221], s[54:55], 0, v[200:201]
	s_add_u32 s54, s96, 0x44000
	s_addc_u32 s55, s97, 0
	s_add_i32 s56, s57, s18
	global_load_lds_dwordx4 v[220:221], off
	v_lshl_add_u64 v[220:221], s[54:55], 0, v[196:197]
	s_mov_b32 m0, s56
	s_nop 0
	global_load_lds_dwordx4 v[220:221], off
	v_lshl_add_u64 v[220:221], s[54:55], 0, v[200:201]
	s_add_i32 m0, s56, 0x2000
	s_nop 0
	global_load_lds_dwordx4 v[220:221], off
	v_lshl_add_u64 v[220:221], s[94:95], 0, v[194:195]
	s_mov_b32 m0, s30
	s_nop 0
	global_load_lds_dwordx4 v[220:221], off
	v_lshl_add_u64 v[220:221], s[94:95], 0, v[198:199]
	s_mov_b32 m0, s31
	s_nop 0
	global_load_lds_dwordx4 v[220:221], off
	s_waitcnt vmcnt(8)
	s_waitcnt lgkmcnt(0)
	s_setprio 1
	s_waitcnt lgkmcnt(0)
	v_mfma_f32_16x16x32_bf16 v[60:63], v[64:67], v[160:163], v[60:63]
	v_mfma_f32_16x16x32_bf16 v[60:63], v[68:71], v[164:167], v[60:63]
	v_mfma_f32_16x16x32_bf16 v[56:59], v[80:83], v[160:163], v[56:59]
	v_mfma_f32_16x16x32_bf16 v[56:59], v[84:87], v[164:167], v[56:59]
	v_mfma_f32_16x16x32_bf16 v[44:47], v[64:67], v[168:171], v[44:47]
	v_mfma_f32_16x16x32_bf16 v[44:47], v[68:71], v[172:175], v[44:47]
	v_mfma_f32_16x16x32_bf16 v[40:43], v[80:83], v[168:171], v[40:43]
	v_mfma_f32_16x16x32_bf16 v[40:43], v[84:87], v[172:175], v[40:43]
	v_mfma_f32_16x16x32_bf16 v[28:31], v[64:67], v[176:179], v[28:31]
	v_mfma_f32_16x16x32_bf16 v[28:31], v[68:71], v[180:183], v[28:31]
	v_mfma_f32_16x16x32_bf16 v[24:27], v[80:83], v[176:179], v[24:27]
	v_mfma_f32_16x16x32_bf16 v[24:27], v[84:87], v[180:183], v[24:27]
	v_mfma_f32_16x16x32_bf16 v[12:15], v[64:67], v[212:215], v[12:15]
	v_mfma_f32_16x16x32_bf16 v[12:15], v[68:71], v[216:219], v[12:15]
	v_mfma_f32_16x16x32_bf16 v[8:11], v[80:83], v[212:215], v[8:11]
	v_mfma_f32_16x16x32_bf16 v[8:11], v[84:87], v[216:219], v[8:11]
	s_setprio 0
	s_setprio 1
	v_mfma_f32_16x16x32_bf16 v[52:55], v[144:147], v[160:163], v[52:55]
	v_mfma_f32_16x16x32_bf16 v[52:55], v[148:151], v[164:167], v[52:55]
	v_mfma_f32_16x16x32_bf16 v[48:51], v[152:155], v[160:163], v[48:51]
	v_mfma_f32_16x16x32_bf16 v[48:51], v[156:159], v[164:167], v[48:51]
	v_mfma_f32_16x16x32_bf16 v[36:39], v[144:147], v[168:171], v[36:39]
	v_mfma_f32_16x16x32_bf16 v[36:39], v[148:151], v[172:175], v[36:39]
	v_mfma_f32_16x16x32_bf16 v[32:35], v[152:155], v[168:171], v[32:35]
	v_mfma_f32_16x16x32_bf16 v[32:35], v[156:159], v[172:175], v[32:35]
	v_mfma_f32_16x16x32_bf16 v[20:23], v[144:147], v[176:179], v[20:23]
	v_mfma_f32_16x16x32_bf16 v[20:23], v[148:151], v[180:183], v[20:23]
	v_mfma_f32_16x16x32_bf16 v[16:19], v[152:155], v[176:179], v[16:19]
	v_mfma_f32_16x16x32_bf16 v[16:19], v[156:159], v[180:183], v[16:19]
	v_mfma_f32_16x16x32_bf16 v[4:7], v[144:147], v[212:215], v[4:7]
	v_mfma_f32_16x16x32_bf16 v[4:7], v[148:151], v[216:219], v[4:7]
	v_mfma_f32_16x16x32_bf16 v[0:3], v[152:155], v[212:215], v[0:3]
	v_mfma_f32_16x16x32_bf16 v[0:3], v[156:159], v[216:219], v[0:3]
	s_setprio 0
	s_barrier
	s_add_i32 s51, s51, 2
	s_add_u32 s13, s13, 0x80000
	s_addc_u32 s50, s50, 0
	s_add_u32 s82, s82, 0x400000
	s_addc_u32 s83, s83, 0
	s_cmpk_gt_u32 s51, 0x55
	s_cbranch_scc0 .LBB0_218
	s_branch .Lp2_kloop_done
.Lp2_kloop_y:
	ds_read_b128 v[64:67], v193
	ds_read_b128 v[68:71], v193 offset:1024
	ds_read_b128 v[80:83], v193 offset:2048
	ds_read_b128 v[84:87], v193 offset:3072
	ds_read_b128 v[144:147], v232
	ds_read_b128 v[148:151], v232 offset:1024
	ds_read_b128 v[152:155], v232 offset:2048
	ds_read_b128 v[156:159], v232 offset:3072
	s_add_u32 s54, s82, 0x1fc000
	s_addc_u32 s55, s83, 0
	s_cmpk_eq_i32 s51, 0x54
	s_cselect_b32 vcc_lo, s6, s54
	s_cselect_b32 vcc_hi, s7, s55
	s_cselect_b32 s96, s78, s13
	s_cselect_b32 s97, s79, s50
	s_add_u32 s94, vcc_lo, 0x200000
	s_addc_u32 s95, vcc_hi, 0
	v_lshl_add_u64 v[220:221], s[82:83], 0, v[204:205]
	s_add_i32 m0, s19, 0xc000
	ds_read_b128 v[160:163], v233
	ds_read_b128 v[164:167], v233 offset:1024
	ds_read_b128 v[168:171], v233 offset:2048
	ds_read_b128 v[172:175], v233 offset:3072
	ds_read_b128 v[176:179], v233 offset:4096
	ds_read_b128 v[180:183], v233 offset:5120
	ds_read_b128 v[212:215], v233 offset:6144
	ds_read_b128 v[216:219], v233 offset:7168
	global_load_lds_dwordx4 v[220:221], off
	v_lshl_add_u64 v[220:221], s[82:83], 0, v[206:207]
	s_add_i32 m0, s19, 0xe000
	s_nop 0
	global_load_lds_dwordx4 v[220:221], off
	s_waitcnt vmcnt(8)
	s_waitcnt lgkmcnt(0)
	s_barrier
; #define PG8_STAGE(bufoff, gbase, voff) do { _Pragma("unroll") for (int _i = 0; _i < 2; ++_i) \
;         __builtin_amdgcn_global_load_lds((const unsigned*)((const char*)(gbase) + (voff)[_i]), (LAS unsigned*)(lds + (bufoff) + ldsw + _i * 8192), 16, 0, 0); } while (0)
; #define PG8_LDA(dst, b, h) do { _Pragma("unroll") for (int m = 0; m < 4; ++m) _Pragma("unroll") for (int k = 0; k < 2; ++k) dst[m][k] = *(const LAS bf16x8*)(lds + PG8_SA(b, h) + aoff + m * 2048 + k * 1024); } while (0)
; #define PG8_LDB(dst, b, h) do { _Pragma("unroll") for (int n = 0; n < 2; ++n) _Pragma("unroll") for (int k = 0; k < 2; ++k) dst[n][k] = *(const LAS bf16x8*)(lds + PG8_SB(b, h) + boff + n * 2048 + k * 1024); } while (0)
; #define PG8_MMA(ai, bj, At, Bt) do { __builtin_amdgcn_s_setprio(1); _Pragma("unroll") for (int m = 0; m < 4; ++m) _Pragma("unroll") for (int n = 0; n < 2; ++n) _Pragma("unroll") for (int k = 0; k < 2; ++k) \
;         acc[ai][bj][m][n] = __builtin_amdgcn_mfma_f32_16x16x32_bf16(Bt[n][k], At[m][k], acc[ai][bj][m][n], 0, 0, 0); __builtin_amdgcn_s_setprio(0); } while (0)
; #define PG8_WAIT_V(n) asm volatile("s_waitcnt vmcnt(" #n ")" ::: "memory")
; #define PG8_WAIT_L(n) asm volatile("s_waitcnt lgkmcnt(" #n ")" ::: "memory")
; #define PG8_BAR __builtin_amdgcn_s_barrier()
; #define PG8_SCHED __builtin_amdgcn_sched_barrier(0)
; template <bool ALIGN_EPI, class Epi, class Sched>
; __device__ __forceinline__ void gemm_phase(LAS unsigned char* lds, const int lda, const int ldb, const int K, const Sched& S, const Epi& E, const size_t kstepA = (size_t)(BK * 2), const size_t kstepB = (size_t)(BK * 2)) {
;     ...
;             PG8_WAIT_V(8); PG8_WAIT_L(0); PG8_BAR; PG8_MMA(0, 0, At, B0); PG8_MMA(0, 1, At, B1); PG8_BAR; PG8_SCHED;
;             PG8_LDA(At, 0, 1); PG8_STAGE(PG8_SB(0, 0), b2, voffB); PG8_STAGE(PG8_SB(0, 1), b2 + hstepB, voffB); PG8_STAGE(PG8_SA(0, 0), a2, voffA);
;             PG8_WAIT_V(8); PG8_WAIT_L(0); PG8_BAR; PG8_MMA(1, 0, At, B0); PG8_MMA(1, 1, At, B1); PG8_BAR; PG8_SCHED;
;             PG8_LDB(B0, 1, 0); PG8_LDB(B1, 1, 1); PG8_SCHED; PG8_LDA(At, 1, 0); PG8_STAGE(PG8_SA(0, 1), a2 + hstepA, voffA);
;             PG8_WAIT_V(8); PG8_WAIT_L(0); PG8_BAR; PG8_MMA(0, 0, At, B0); PG8_MMA(0, 1, At, B1); PG8_BAR; PG8_SCHED;
	s_setprio 2
	s_waitcnt lgkmcnt(0)
	v_mfma_f32_16x16x32_bf16 v[140:143], v[64:67], v[160:163], v[140:143]
	v_mfma_f32_16x16x32_bf16 v[140:143], v[68:71], v[164:167], v[140:143]
	v_mfma_f32_16x16x32_bf16 v[136:139], v[80:83], v[160:163], v[136:139]
	v_mfma_f32_16x16x32_bf16 v[136:139], v[84:87], v[164:167], v[136:139]
	v_mfma_f32_16x16x32_bf16 v[124:127], v[64:67], v[168:171], v[124:127]
	v_mfma_f32_16x16x32_bf16 v[124:127], v[68:71], v[172:175], v[124:127]
	v_mfma_f32_16x16x32_bf16 v[120:123], v[80:83], v[168:171], v[120:123]
	v_mfma_f32_16x16x32_bf16 v[120:123], v[84:87], v[172:175], v[120:123]
	v_mfma_f32_16x16x32_bf16 v[108:111], v[64:67], v[176:179], v[108:111]
	v_mfma_f32_16x16x32_bf16 v[108:111], v[68:71], v[180:183], v[108:111]
	v_mfma_f32_16x16x32_bf16 v[104:107], v[80:83], v[176:179], v[104:107]
	v_mfma_f32_16x16x32_bf16 v[104:107], v[84:87], v[180:183], v[104:107]
	v_mfma_f32_16x16x32_bf16 v[92:95], v[64:67], v[212:215], v[92:95]
	v_mfma_f32_16x16x32_bf16 v[92:95], v[68:71], v[216:219], v[92:95]
	v_mfma_f32_16x16x32_bf16 v[88:91], v[80:83], v[212:215], v[88:91]
	v_mfma_f32_16x16x32_bf16 v[88:91], v[84:87], v[216:219], v[88:91]
	s_setprio 0
	s_setprio 2
	v_mfma_f32_16x16x32_bf16 v[132:135], v[144:147], v[160:163], v[132:135]
	v_mfma_f32_16x16x32_bf16 v[132:135], v[148:151], v[164:167], v[132:135]
	v_mfma_f32_16x16x32_bf16 v[128:131], v[152:155], v[160:163], v[128:131]
	v_mfma_f32_16x16x32_bf16 v[128:131], v[156:159], v[164:167], v[128:131]
	v_mfma_f32_16x16x32_bf16 v[116:119], v[144:147], v[168:171], v[116:119]
	v_mfma_f32_16x16x32_bf16 v[116:119], v[148:151], v[172:175], v[116:119]
	v_mfma_f32_16x16x32_bf16 v[112:115], v[152:155], v[168:171], v[112:115]
	v_mfma_f32_16x16x32_bf16 v[112:115], v[156:159], v[172:175], v[112:115]
	v_mfma_f32_16x16x32_bf16 v[100:103], v[144:147], v[176:179], v[100:103]
	v_mfma_f32_16x16x32_bf16 v[100:103], v[148:151], v[180:183], v[100:103]
	v_mfma_f32_16x16x32_bf16 v[96:99], v[152:155], v[176:179], v[96:99]
	v_mfma_f32_16x16x32_bf16 v[96:99], v[156:159], v[180:183], v[96:99]
	v_mfma_f32_16x16x32_bf16 v[76:79], v[144:147], v[212:215], v[76:79]
	v_mfma_f32_16x16x32_bf16 v[76:79], v[148:151], v[216:219], v[76:79]
	v_mfma_f32_16x16x32_bf16 v[72:75], v[152:155], v[212:215], v[72:75]
	v_mfma_f32_16x16x32_bf16 v[72:75], v[156:159], v[216:219], v[72:75]
	s_setprio 0
	s_add_i32 s54, s33, s18
	v_lshl_add_u64 v[220:221], s[96:97], 0, v[196:197]
	s_mov_b32 m0, s54
	ds_read_b128 v[160:163], v233 offset:16384
	ds_read_b128 v[164:167], v233 offset:17408
	ds_read_b128 v[168:171], v233 offset:18432
	ds_read_b128 v[172:175], v233 offset:19456
	ds_read_b128 v[176:179], v233 offset:20480
	ds_read_b128 v[180:183], v233 offset:21504
	ds_read_b128 v[212:215], v233 offset:22528
	ds_read_b128 v[216:219], v233 offset:23552
	global_load_lds_dwordx4 v[220:221], off
	s_add_i32 m0, s54, 0x2000
	s_add_u32 s54, s96, 0x4000
	v_lshl_add_u64 v[220:221], s[96:97], 0, v[200:201]
	s_addc_u32 s55, s97, 0
	s_add_i32 s56, s42, s18
	global_load_lds_dwordx4 v[220:221], off
	v_lshl_add_u64 v[220:221], s[54:55], 0, v[196:197]
	s_mov_b32 m0, s56
	s_nop 0
	global_load_lds_dwordx4 v[220:221], off
	v_lshl_add_u64 v[220:221], s[54:55], 0, v[200:201]
	s_add_i32 m0, s56, 0x2000
	s_nop 0
	global_load_lds_dwordx4 v[220:221], off
	v_lshl_add_u64 v[220:221], vcc, 0, v[194:195]
	s_mov_b32 m0, s19
	s_nop 0
	global_load_lds_dwordx4 v[220:221], off
	v_lshl_add_u64 v[220:221], vcc, 0, v[198:199]
	s_mov_b32 m0, s20
	s_nop 0
	global_load_lds_dwordx4 v[220:221], off
	s_waitcnt vmcnt(8)
	s_waitcnt lgkmcnt(0)
	s_barrier
	s_setprio 2
	s_waitcnt lgkmcnt(0)
	v_mfma_f32_16x16x32_bf16 v[60:63], v[64:67], v[160:163], v[60:63]
	v_mfma_f32_16x16x32_bf16 v[60:63], v[68:71], v[164:167], v[60:63]
	v_mfma_f32_16x16x32_bf16 v[56:59], v[80:83], v[160:163], v[56:59]
	v_mfma_f32_16x16x32_bf16 v[56:59], v[84:87], v[164:167], v[56:59]
	v_mfma_f32_16x16x32_bf16 v[44:47], v[64:67], v[168:171], v[44:47]
	v_mfma_f32_16x16x32_bf16 v[44:47], v[68:71], v[172:175], v[44:47]
	v_mfma_f32_16x16x32_bf16 v[40:43], v[80:83], v[168:171], v[40:43]
	v_mfma_f32_16x16x32_bf16 v[40:43], v[84:87], v[172:175], v[40:43]
	v_mfma_f32_16x16x32_bf16 v[28:31], v[64:67], v[176:179], v[28:31]
	v_mfma_f32_16x16x32_bf16 v[28:31], v[68:71], v[180:183], v[28:31]
	v_mfma_f32_16x16x32_bf16 v[24:27], v[80:83], v[176:179], v[24:27]
	v_mfma_f32_16x16x32_bf16 v[24:27], v[84:87], v[180:183], v[24:27]
	v_mfma_f32_16x16x32_bf16 v[12:15], v[64:67], v[212:215], v[12:15]
	v_mfma_f32_16x16x32_bf16 v[12:15], v[68:71], v[216:219], v[12:15]
	v_mfma_f32_16x16x32_bf16 v[8:11], v[80:83], v[212:215], v[8:11]
	v_mfma_f32_16x16x32_bf16 v[8:11], v[84:87], v[216:219], v[8:11]
	s_setprio 0
	s_setprio 2
	v_mfma_f32_16x16x32_bf16 v[52:55], v[144:147], v[160:163], v[52:55]
	v_mfma_f32_16x16x32_bf16 v[52:55], v[148:151], v[164:167], v[52:55]
	v_mfma_f32_16x16x32_bf16 v[48:51], v[152:155], v[160:163], v[48:51]
	v_mfma_f32_16x16x32_bf16 v[48:51], v[156:159], v[164:167], v[48:51]
	v_mfma_f32_16x16x32_bf16 v[36:39], v[144:147], v[168:171], v[36:39]
	v_mfma_f32_16x16x32_bf16 v[36:39], v[148:151], v[172:175], v[36:39]
	v_mfma_f32_16x16x32_bf16 v[32:35], v[152:155], v[168:171], v[32:35]
	v_mfma_f32_16x16x32_bf16 v[32:35], v[156:159], v[172:175], v[32:35]
	v_mfma_f32_16x16x32_bf16 v[20:23], v[144:147], v[176:179], v[20:23]
	v_mfma_f32_16x16x32_bf16 v[20:23], v[148:151], v[180:183], v[20:23]
	v_mfma_f32_16x16x32_bf16 v[16:19], v[152:155], v[176:179], v[16:19]
	v_mfma_f32_16x16x32_bf16 v[16:19], v[156:159], v[180:183], v[16:19]
	v_mfma_f32_16x16x32_bf16 v[4:7], v[144:147], v[212:215], v[4:7]
	v_mfma_f32_16x16x32_bf16 v[4:7], v[148:151], v[216:219], v[4:7]
	v_mfma_f32_16x16x32_bf16 v[0:3], v[152:155], v[212:215], v[0:3]
	v_mfma_f32_16x16x32_bf16 v[0:3], v[156:159], v[216:219], v[0:3]
	s_setprio 0
	s_add_i32 s56, 0, 0x18000
	s_add_i32 s57, 0, 0x1c000
	v_add_u32_e32 v84, s56, v191
	v_add_u32_e32 v156, s57, v191
	ds_read_b128 v[64:67], v84
	ds_read_b128 v[68:71], v84 offset:1024
	ds_read_b128 v[80:83], v84 offset:2048
	ds_read_b128 v[84:87], v84 offset:3072
	ds_read_b128 v[144:147], v156
	ds_read_b128 v[148:151], v156 offset:1024
	ds_read_b128 v[152:155], v156 offset:2048
	ds_read_b128 v[156:159], v156 offset:3072
	s_add_u32 s54, vcc_lo, 0x4000
	s_addc_u32 s55, vcc_hi, 0
	s_mov_b32 m0, s21
	v_lshl_add_u64 v[220:221], s[54:55], 0, v[194:195]
	ds_read_b128 v[160:163], v233 offset:32768
	ds_read_b128 v[164:167], v233 offset:33792
	ds_read_b128 v[168:171], v233 offset:34816
	ds_read_b128 v[172:175], v233 offset:35840
	ds_read_b128 v[176:179], v233 offset:36864
	ds_read_b128 v[180:183], v233 offset:37888
	ds_read_b128 v[212:215], v233 offset:38912
	ds_read_b128 v[216:219], v233 offset:39936
	global_load_lds_dwordx4 v[220:221], off
	v_lshl_add_u64 v[220:221], s[54:55], 0, v[198:199]
	s_mov_b32 m0, s22
	s_nop 0
	global_load_lds_dwordx4 v[220:221], off
	s_waitcnt vmcnt(8)
	s_waitcnt lgkmcnt(0)
	s_barrier
; #define PG8_STAGE(bufoff, gbase, voff) do { _Pragma("unroll") for (int _i = 0; _i < 2; ++_i) \
;         __builtin_amdgcn_global_load_lds((const unsigned*)((const char*)(gbase) + (voff)[_i]), (LAS unsigned*)(lds + (bufoff) + ldsw + _i * 8192), 16, 0, 0); } while (0)
; #define PG8_LDA(dst, b, h) do { _Pragma("unroll") for (int m = 0; m < 4; ++m) _Pragma("unroll") for (int k = 0; k < 2; ++k) dst[m][k] = *(const LAS bf16x8*)(lds + PG8_SA(b, h) + aoff + m * 2048 + k * 1024); } while (0)
; #define PG8_MMA(ai, bj, At, Bt) do { __builtin_amdgcn_s_setprio(1); _Pragma("unroll") for (int m = 0; m < 4; ++m) _Pragma("unroll") for (int n = 0; n < 2; ++n) _Pragma("unroll") for (int k = 0; k < 2; ++k) \
;         acc[ai][bj][m][n] = __builtin_amdgcn_mfma_f32_16x16x32_bf16(Bt[n][k], At[m][k], acc[ai][bj][m][n], 0, 0, 0); __builtin_amdgcn_s_setprio(0); } while (0)
; #define PG8_WAIT_V(n) asm volatile("s_waitcnt vmcnt(" #n ")" ::: "memory")
; #define PG8_WAIT_L(n) asm volatile("s_waitcnt lgkmcnt(" #n ")" ::: "memory")
; #define PG8_BAR __builtin_amdgcn_s_barrier()
; #define PG8_SCHED __builtin_amdgcn_sched_barrier(0)
; template <bool ALIGN_EPI, class Epi, class Sched>
; __device__ __forceinline__ void gemm_phase(LAS unsigned char* lds, const int lda, const int ldb, const int K, const Sched& S, const Epi& E, const size_t kstepA = (size_t)(BK * 2), const size_t kstepB = (size_t)(BK * 2)) {
;     ...
;             PG8_WAIT_V(8); PG8_WAIT_L(0); PG8_BAR; PG8_MMA(0, 0, At, B0); PG8_MMA(0, 1, At, B1); PG8_BAR; PG8_SCHED;
;             PG8_LDA(At, 1, 1); PG8_STAGE(PG8_SB(1, 0), b3, voffB); PG8_STAGE(PG8_SB(1, 1), b3 + hstepB, voffB); PG8_STAGE(PG8_SA(1, 0), a3, voffA);
;             PG8_WAIT_V(8); PG8_WAIT_L(0); PG8_BAR; PG8_MMA(1, 0, At, B0); PG8_MMA(1, 1, At, B1); PG8_BAR; PG8_SCHED;
;         }
;         if constexpr (ALIGN_EPI) { if (wr == 0) PG8_BAR; }
	s_setprio 2
	s_waitcnt lgkmcnt(0)
	v_mfma_f32_16x16x32_bf16 v[140:143], v[64:67], v[160:163], v[140:143]
	v_mfma_f32_16x16x32_bf16 v[140:143], v[68:71], v[164:167], v[140:143]
	v_mfma_f32_16x16x32_bf16 v[136:139], v[80:83], v[160:163], v[136:139]
	v_mfma_f32_16x16x32_bf16 v[136:139], v[84:87], v[164:167], v[136:139]
	v_mfma_f32_16x16x32_bf16 v[124:127], v[64:67], v[168:171], v[124:127]
	v_mfma_f32_16x16x32_bf16 v[124:127], v[68:71], v[172:175], v[124:127]
	v_mfma_f32_16x16x32_bf16 v[120:123], v[80:83], v[168:171], v[120:123]
	v_mfma_f32_16x16x32_bf16 v[120:123], v[84:87], v[172:175], v[120:123]
	v_mfma_f32_16x16x32_bf16 v[108:111], v[64:67], v[176:179], v[108:111]
	v_mfma_f32_16x16x32_bf16 v[108:111], v[68:71], v[180:183], v[108:111]
	v_mfma_f32_16x16x32_bf16 v[104:107], v[80:83], v[176:179], v[104:107]
	v_mfma_f32_16x16x32_bf16 v[104:107], v[84:87], v[180:183], v[104:107]
	v_mfma_f32_16x16x32_bf16 v[92:95], v[64:67], v[212:215], v[92:95]
	v_mfma_f32_16x16x32_bf16 v[92:95], v[68:71], v[216:219], v[92:95]
	v_mfma_f32_16x16x32_bf16 v[88:91], v[80:83], v[212:215], v[88:91]
	v_mfma_f32_16x16x32_bf16 v[88:91], v[84:87], v[216:219], v[88:91]
	s_setprio 0
	s_setprio 2
	v_mfma_f32_16x16x32_bf16 v[132:135], v[144:147], v[160:163], v[132:135]
	v_mfma_f32_16x16x32_bf16 v[132:135], v[148:151], v[164:167], v[132:135]
	v_mfma_f32_16x16x32_bf16 v[128:131], v[152:155], v[160:163], v[128:131]
	v_mfma_f32_16x16x32_bf16 v[128:131], v[156:159], v[164:167], v[128:131]
	v_mfma_f32_16x16x32_bf16 v[116:119], v[144:147], v[168:171], v[116:119]
	v_mfma_f32_16x16x32_bf16 v[116:119], v[148:151], v[172:175], v[116:119]
	v_mfma_f32_16x16x32_bf16 v[112:115], v[152:155], v[168:171], v[112:115]
	v_mfma_f32_16x16x32_bf16 v[112:115], v[156:159], v[172:175], v[112:115]
	v_mfma_f32_16x16x32_bf16 v[100:103], v[144:147], v[176:179], v[100:103]
	v_mfma_f32_16x16x32_bf16 v[100:103], v[148:151], v[180:183], v[100:103]
	v_mfma_f32_16x16x32_bf16 v[96:99], v[152:155], v[176:179], v[96:99]
	v_mfma_f32_16x16x32_bf16 v[96:99], v[156:159], v[180:183], v[96:99]
	v_mfma_f32_16x16x32_bf16 v[76:79], v[144:147], v[212:215], v[76:79]
	v_mfma_f32_16x16x32_bf16 v[76:79], v[148:151], v[216:219], v[76:79]
	v_mfma_f32_16x16x32_bf16 v[72:75], v[152:155], v[212:215], v[72:75]
	v_mfma_f32_16x16x32_bf16 v[72:75], v[156:159], v[216:219], v[72:75]
	s_setprio 0
	s_add_u32 s54, s96, 0x40000
	s_addc_u32 s55, s97, 0
	s_add_i32 s56, s56, s18
	v_lshl_add_u64 v[220:221], s[54:55], 0, v[196:197]
	s_mov_b32 m0, s56
	ds_read_b128 v[160:163], v233 offset:49152
	ds_read_b128 v[164:167], v233 offset:50176
	ds_read_b128 v[168:171], v233 offset:51200
	ds_read_b128 v[172:175], v233 offset:52224
	ds_read_b128 v[176:179], v233 offset:53248
	ds_read_b128 v[180:183], v233 offset:54272
	ds_read_b128 v[212:215], v233 offset:55296
	ds_read_b128 v[216:219], v233 offset:56320
	global_load_lds_dwordx4 v[220:221], off
	s_add_i32 m0, s56, 0x2000
	v_lshl_add_u64 v[220:221], s[54:55], 0, v[200:201]
	s_add_u32 s54, s96, 0x44000
	s_addc_u32 s55, s97, 0
	s_add_i32 s56, s57, s18
	global_load_lds_dwordx4 v[220:221], off
	v_lshl_add_u64 v[220:221], s[54:55], 0, v[196:197]
	s_mov_b32 m0, s56
	s_nop 0
	global_load_lds_dwordx4 v[220:221], off
	v_lshl_add_u64 v[220:221], s[54:55], 0, v[200:201]
	s_add_i32 m0, s56, 0x2000
	s_nop 0
	global_load_lds_dwordx4 v[220:221], off
	v_lshl_add_u64 v[220:221], s[94:95], 0, v[194:195]
	s_mov_b32 m0, s30
	s_nop 0
	global_load_lds_dwordx4 v[220:221], off
	v_lshl_add_u64 v[220:221], s[94:95], 0, v[198:199]
	s_mov_b32 m0, s31
	s_nop 0
	global_load_lds_dwordx4 v[220:221], off
	s_waitcnt vmcnt(8)
	s_waitcnt lgkmcnt(0)
	s_barrier
	s_setprio 2
	s_waitcnt lgkmcnt(0)
	v_mfma_f32_16x16x32_bf16 v[60:63], v[64:67], v[160:163], v[60:63]
	v_mfma_f32_16x16x32_bf16 v[60:63], v[68:71], v[164:167], v[60:63]
	v_mfma_f32_16x16x32_bf16 v[56:59], v[80:83], v[160:163], v[56:59]
	v_mfma_f32_16x16x32_bf16 v[56:59], v[84:87], v[164:167], v[56:59]
	v_mfma_f32_16x16x32_bf16 v[44:47], v[64:67], v[168:171], v[44:47]
	v_mfma_f32_16x16x32_bf16 v[44:47], v[68:71], v[172:175], v[44:47]
	v_mfma_f32_16x16x32_bf16 v[40:43], v[80:83], v[168:171], v[40:43]
	v_mfma_f32_16x16x32_bf16 v[40:43], v[84:87], v[172:175], v[40:43]
	v_mfma_f32_16x16x32_bf16 v[28:31], v[64:67], v[176:179], v[28:31]
	v_mfma_f32_16x16x32_bf16 v[28:31], v[68:71], v[180:183], v[28:31]
	v_mfma_f32_16x16x32_bf16 v[24:27], v[80:83], v[176:179], v[24:27]
	v_mfma_f32_16x16x32_bf16 v[24:27], v[84:87], v[180:183], v[24:27]
	v_mfma_f32_16x16x32_bf16 v[12:15], v[64:67], v[212:215], v[12:15]
	v_mfma_f32_16x16x32_bf16 v[12:15], v[68:71], v[216:219], v[12:15]
	v_mfma_f32_16x16x32_bf16 v[8:11], v[80:83], v[212:215], v[8:11]
	v_mfma_f32_16x16x32_bf16 v[8:11], v[84:87], v[216:219], v[8:11]
	s_setprio 0
	s_setprio 2
	v_mfma_f32_16x16x32_bf16 v[52:55], v[144:147], v[160:163], v[52:55]
	v_mfma_f32_16x16x32_bf16 v[52:55], v[148:151], v[164:167], v[52:55]
	v_mfma_f32_16x16x32_bf16 v[48:51], v[152:155], v[160:163], v[48:51]
	v_mfma_f32_16x16x32_bf16 v[48:51], v[156:159], v[164:167], v[48:51]
	v_mfma_f32_16x16x32_bf16 v[36:39], v[144:147], v[168:171], v[36:39]
	v_mfma_f32_16x16x32_bf16 v[36:39], v[148:151], v[172:175], v[36:39]
	v_mfma_f32_16x16x32_bf16 v[32:35], v[152:155], v[168:171], v[32:35]
	v_mfma_f32_16x16x32_bf16 v[32:35], v[156:159], v[172:175], v[32:35]
	v_mfma_f32_16x16x32_bf16 v[20:23], v[144:147], v[176:179], v[20:23]
	v_mfma_f32_16x16x32_bf16 v[20:23], v[148:151], v[180:183], v[20:23]
	v_mfma_f32_16x16x32_bf16 v[16:19], v[152:155], v[176:179], v[16:19]
	v_mfma_f32_16x16x32_bf16 v[16:19], v[156:159], v[180:183], v[16:19]
	v_mfma_f32_16x16x32_bf16 v[4:7], v[144:147], v[212:215], v[4:7]
	v_mfma_f32_16x16x32_bf16 v[4:7], v[148:151], v[216:219], v[4:7]
	v_mfma_f32_16x16x32_bf16 v[0:3], v[152:155], v[212:215], v[0:3]
	v_mfma_f32_16x16x32_bf16 v[0:3], v[156:159], v[216:219], v[0:3]
	s_setprio 0
	s_add_i32 s51, s51, 2
	s_add_u32 s13, s13, 0x80000
	s_addc_u32 s50, s50, 0
	s_add_u32 s82, s82, 0x400000
	s_addc_u32 s83, s83, 0
	s_cmpk_gt_u32 s51, 0x55
	s_cbranch_scc0 .Lp2_kloop_y
.Lp2_kloop_done:
	s_and_b64 vcc, exec, s[84:85]
	s_cbranch_vccz .LBB0_221

; #define PG8_BAR __builtin_amdgcn_s_barrier()
; template <bool ALIGN_EPI, class Epi, class Sched>
; __device__ __forceinline__ void gemm_phase(LAS unsigned char* lds, const int lda, const int ldb, const int K, const Sched& S, const Epi& E, const size_t kstepA = (size_t)(BK * 2), const size_t kstepB = (size_t)(BK * 2)) {
;     ...
;         if (!has_next) break;
; #pragma unroll
;         for (int a = 0; a < 2; ++a)
; #pragma unroll
;             for (int b = 0; b < 2; ++b)
; #pragma unroll
;                 for (int m = 0; m < 4; ++m)
; #pragma unroll
;                     for (int n = 0; n < 2; ++n) acc[a][b][m][n] = (f32x4){0.f, 0.f, 0.f, 0.f};
;         cur = nxt; cA = nA; cB = nB; ++ui;
;         if constexpr (ALIGN_EPI) { if (wr == 1) PG8_BAR; }
;     }
.LBB0_253:
	s_or_b64 exec, exec, s[6:7]
	s_andn2_b64 vcc, exec, s[10:11]
	s_mov_b64 s[6:7], -1
	s_cbranch_vccnz .LBB0_210
	s_andn2_b64 vcc, exec, s[48:49]
	s_cbranch_vccnz .LBB0_209
	s_branch .LBB0_209

; #define PG8_STAGE(bufoff, gbase, voff) do { _Pragma("unroll") for (int _i = 0; _i < 2; ++_i) \
;         __builtin_amdgcn_global_load_lds((const unsigned*)((const char*)(gbase) + (voff)[_i]), (LAS unsigned*)(lds + (bufoff) + ldsw + _i * 8192), 16, 0, 0); } while (0)
; #define PG8_WAIT_V(n) asm volatile("s_waitcnt vmcnt(" #n ")" ::: "memory")
; #define PG8_BAR __builtin_amdgcn_s_barrier()
;     __device__ bool next(int i, Unit& u) const { if (i > 0 || c >= 32 || c < 0) return false; u.pm = c & 1; u.pn = c >> 1; u.z = 0; u.o = 0; u.a = A + (size_t)u.pm * 256 * D * 2; u.b = B + (size_t)u.pn * 256 * D * 2; return true; }
; template <bool ALIGN_EPI, class Epi, class Sched>
; __device__ __forceinline__ void gemm_phase(LAS unsigned char* lds, const int lda, const int ldb, const int K, const Sched& S, const Epi& E, const size_t kstepA = (size_t)(BK * 2), const size_t kstepB = (size_t)(BK * 2)) {
;     ...
;     for (int i = 0; i < 2; ++i) { int R, C; stage_rc(tid * 16 + i * 8192, R, C); const int Rb = (R & ~31) + perm32(R & 31);
;         voffA[i] = (unsigned)(R * lda + C) * 2u; voffB[i] = (unsigned)(Rb * ldb + C) * 2u; }
;     const size_t kstep = kstepB;
;     const size_t hstepA = (size_t)HALF * lda * 2, hstepB = (size_t)HALF * ldb * 2;
;     const unsigned ldsw = (unsigned)wid * 1024u;
;     const int aoff = lds_byte(wr * 64 + fr, fq * 8), boff = lds_byte(wc * 32 + fr, fq * 8);
;     ...
;     Unit cur, nxt; int ui = 0;
;     if (!S.next(0, cur)) return;
;     f32x4 acc[2][2][4][2];
; #pragma unroll
;     for (int a = 0; a < 2; ++a)
; #pragma unroll
;         for (int b = 0; b < 2; ++b)
; #pragma unroll
;             for (int m = 0; m < 4; ++m)
; #pragma unroll
;                 for (int n = 0; n < 2; ++n) acc[a][b][m][n] = (f32x4){0.f, 0.f, 0.f, 0.f};
;     bf16x8 At[4][2], B0[2][2], B1[2][2];
;     const char* cA = cur.a; const char* cB = cur.b;
;     PG8_STAGE(PG8_SB(0, 0), cB, voffB); PG8_STAGE(PG8_SB(0, 1), cB + hstepB, voffB); PG8_STAGE(PG8_SA(0, 0), cA, voffA); PG8_STAGE(PG8_SA(0, 1), cA + hstepA, voffA);
;     if (wr == 1) PG8_BAR;
;     PG8_WAIT_V(2); PG8_BAR;
;     PG8_STAGE(PG8_SB(1, 0), cB + kstep, voffB); PG8_STAGE(PG8_SA(1, 0), cA + kstepA, voffA); PG8_STAGE(PG8_SB(1, 1), cB + hstepB + kstep, voffB);
;     PG8_WAIT_V(6); PG8_BAR;
.LBB0_334:
	s_add_u32 s44, s26, 0x18c14000
	s_addc_u32 s45, s27, 0
	s_add_u32 s79, s26, 0x19c14000
	s_addc_u32 s91, s27, 0
	s_and_b64 vcc, exec, s[8:9]
	s_cbranch_vccnz .LBB0_422
	v_bfe_i32 v2, v0, 27, 1
	v_lshlrev_b32_e32 v4, 4, v0
	v_lshrrev_b32_e32 v2, 22, v2
	v_ashrrev_i32_e32 v1, 31, v0
	v_add_u32_e32 v2, v4, v2
	v_lshrrev_b32_e32 v1, 26, v1
	v_and_b32_e32 v2, 0xfffffc00, v2
	v_add_u32_e32 v1, v0, v1
	v_sub_u32_e32 v2, v4, v2
	v_ashrrev_i32_e32 v1, 6, v1
	v_lshrrev_b32_e32 v3, 4, v2
	v_bitop3_b32 v3, v3, v2, 32 bitop3:0x6c
	v_lshlrev_b32_e32 v2, 3, v1
	v_and_b32_e32 v5, -16, v2
	v_ashrrev_i32_e32 v2, 31, v3
	v_lshrrev_b32_e32 v2, 26, v2
	v_add_u32_e32 v6, v3, v2
	v_ashrrev_i32_e32 v2, 6, v6
	v_and_b32_e32 v6, 0xc0, v6
	v_sub_u32_e32 v3, v3, v6
	v_mov_b32_e32 v6, 1
	v_lshlrev_b32_e32 v7, 5, v1
	v_ashrrev_i16_sdwa v3, v6, sext(v3) dst_sel:DWORD dst_unused:UNUSED_PAD src0_sel:DWORD src1_sel:BYTE_0
	v_and_b32_e32 v7, 32, v7
	v_bfe_i32 v3, v3, 0, 16
	v_add_u32_e32 v5, v2, v5
	v_and_b32_e32 v10, 3, v2
	s_mov_b32 s7, 0x1ffffe0
	v_add_lshl_u32 v7, v7, v3, 1
	v_lshlrev_b32_e32 v8, 1, v5
	v_lshrrev_b32_e32 v9, 2, v5
	v_and_or_b32 v10, v5, s7, v10
	v_lshl_add_u32 v128, v5, 7, v7
	v_add_u32_e32 v5, 0x2000, v4
	v_ashrrev_i32_e32 v4, 31, v5
	v_lshrrev_b32_e32 v4, 22, v4
	v_and_b32_e32 v8, 24, v8
	v_and_b32_e32 v9, 4, v9
	v_add_u32_e32 v4, v5, v4
	v_or3_b32 v8, v10, v9, v8
	v_ashrrev_i32_e32 v4, 10, v4
	v_lshl_add_u32 v130, v8, 7, v7
	v_mul_i32_i24_e32 v7, 0x400, v4
	v_sub_u32_e32 v5, v5, v7
	v_lshrrev_b32_e32 v7, 4, v5
	v_bitop3_b32 v7, v7, v5, 32 bitop3:0x6c
	v_lshlrev_b32_e32 v5, 3, v4
	v_and_b32_e32 v8, -16, v5
	v_ashrrev_i32_e32 v5, 31, v7
	v_lshrrev_b32_e32 v5, 26, v5
	v_add_u32_e32 v9, v7, v5
	v_ashrrev_i32_e32 v5, 6, v9
	v_add_u32_e32 v8, v5, v8
	v_and_b32_e32 v11, 3, v5
	v_and_b32_e32 v9, 0xc0, v9
	v_and_or_b32 v11, v8, s7, v11
	s_ashr_i32 s7, s10, 6
	v_sub_u32_e32 v7, v7, v9
	s_lshl_b32 s19, s7, 10
	v_lshlrev_b32_e32 v10, 5, v4
	v_ashrrev_i16_sdwa v6, v6, sext(v7) dst_sel:DWORD dst_unused:UNUSED_PAD src0_sel:DWORD src1_sel:BYTE_0
	v_lshlrev_b32_e32 v7, 1, v8
	v_lshrrev_b32_e32 v9, 2, v8
	s_add_i32 s20, s19, 0
	v_and_b32_e32 v10, 32, v10
	v_bfe_i32 v6, v6, 0, 16
	v_and_b32_e32 v7, 24, v7
	v_and_b32_e32 v9, 4, v9
	s_add_i32 m0, s20, 0x10000
	s_ashr_i32 s6, s10, 8
	v_or3_b32 v7, v11, v9, v7
	v_add_lshl_u32 v9, v10, v6, 1
	global_load_lds_dwordx4 v130, s[82:83]
	s_add_i32 m0, s20, 0x12000
	v_lshl_add_u32 v134, v7, 7, v9
	s_add_u32 s8, s82, 0x4000
	global_load_lds_dwordx4 v134, s[82:83]
	s_addc_u32 s9, s83, 0
	s_add_i32 m0, s20, 0x14000
	s_add_i32 s21, s20, 0x2000
	global_load_lds_dwordx4 v130, s[8:9]
	s_add_i32 m0, s20, 0x16000
	v_lshl_add_u32 v132, v8, 7, v9
	global_load_lds_dwordx4 v134, s[8:9]
	s_mov_b32 m0, s20
	s_add_u32 s8, s16, 0x4000
	global_load_lds_dwordx4 v128, s[16:17]
	s_mov_b32 m0, s21
	s_addc_u32 s9, s17, 0
	s_add_i32 s22, s20, 0x4000
	global_load_lds_dwordx4 v132, s[16:17]
	s_mov_b32 m0, s22
	s_add_i32 s23, s20, 0x6000
	global_load_lds_dwordx4 v128, s[8:9]
	s_mov_b32 m0, s23
	v_mov_b32_e32 v137, 0
	global_load_lds_dwordx4 v132, s[8:9]
	s_cmp_eq_u32 s6, 1
	s_mov_b32 s29, 0
	v_mov_b32_e32 v131, v137
	v_mov_b32_e32 v135, v137
	v_mov_b32_e32 v129, v137
	s_cselect_b64 s[66:67], -1, 0
	s_cmp_lg_u32 s6, 1
	v_mov_b32_e32 v133, v137
	s_cbranch_scc1 .LBB0_337
.LBB0_337:
	s_lshl_b32 s7, s7, 5
	s_and_b32 s7, s7, 0x60
	s_lshl_b32 s11, s6, 13
	s_lshl_b32 s12, s7, 7
	s_add_u32 s8, s82, 0x80000
	s_addc_u32 s9, s83, 0
	s_add_i32 m0, s20, 0x18000
	v_lshl_add_u64 v[8:9], s[8:9], 0, v[130:131]
	s_waitcnt vmcnt(2)
	s_barrier
	global_load_lds_dwordx4 v[8:9], off
	s_add_i32 m0, s20, 0x1a000
	v_lshl_add_u64 v[8:9], s[8:9], 0, v[134:135]
	s_add_u32 s8, s16, 0x200000
	s_addc_u32 s9, s17, 0
	s_add_i32 s30, s20, 0x8000
	global_load_lds_dwordx4 v[8:9], off
	v_lshl_add_u64 v[8:9], s[8:9], 0, v[128:129]
	s_mov_b32 m0, s30
	s_add_i32 s31, s20, 0xa000
	global_load_lds_dwordx4 v[8:9], off
	v_lshl_add_u64 v[8:9], s[8:9], 0, v[132:133]
	s_add_u32 s8, s82, 0x84000
	s_mov_b32 m0, s31
	s_addc_u32 s9, s83, 0
	global_load_lds_dwordx4 v[8:9], off
	s_add_i32 m0, s20, 0x1c000
	v_lshl_add_u64 v[8:9], s[8:9], 0, v[130:131]
	global_load_lds_dwordx4 v[8:9], off
	v_lshl_add_u64 v[8:9], s[8:9], 0, v[134:135]
	s_add_i32 m0, s20, 0x1e000
	v_and_b32_e32 v7, 15, v0
	global_load_lds_dwordx4 v[8:9], off
	v_lshrrev_b32_e32 v8, 1, v0
	v_and_b32_e32 v8, 24, v8
	v_lshl_or_b32 v139, s6, 6, v7
	v_lshlrev_b32_e32 v9, 1, v8
	v_lshl_or_b32 v7, v7, 6, v9
	v_lshlrev_b32_e32 v9, 2, v139
	v_lshlrev_b32_e32 v11, 2, v0
	v_and_b32_e32 v10, 32, v9
	v_and_b32_e32 v11, 32, v11
	v_bitop3_b32 v10, v7, s11, v10 bitop3:0xde
	v_bitop3_b32 v141, v7, s12, v11 bitop3:0xde
	v_and_b32_e32 v7, 1, v0
	v_cmp_eq_u32_e64 s[8:9], 0, v7
	v_and_b32_e32 v7, 2, v0
	s_cmpk_lt_u32 s10, 0x100
	v_cmp_eq_u32_e64 s[10:11], 0, v7
	v_bfrev_b32_e32 v7, v0
	v_lshrrev_b32_e32 v7, 30, v7
	v_or3_b32 v7, v8, v7, s7
	s_cselect_b64 s[68:69], -1, 0
	v_and_b32_e32 v138, 12, v0
	s_lshl_b32 s33, s6, 2
	v_lshlrev_b32_e32 v140, 6, v7
	s_movk_i32 s6, 0x1fc0
	v_mov_b32_e32 v0, 0x2100
	v_bitop3_b32 v0, v140, s6, v0 bitop3:0xc8
	v_lshlrev_b32_e32 v136, 7, v7
	v_lshl_add_u64 v[146:147], s[44:45], 0, v[136:137]
	v_lshlrev_b32_e32 v136, 1, v0
	v_lshlrev_b32_e32 v0, 10, v1
	v_and_b32_e32 v0, 0xfffff800, v0
	v_lshl_add_u32 v0, v2, 7, v0
	v_and_b32_e32 v1, 1, v1
	v_lshl_or_b32 v0, v1, 6, v0
	v_lshl_add_u32 v150, v3, 1, v0
	v_lshlrev_b32_e32 v0, 10, v4
	v_and_b32_e32 v0, 0xfffff800, v0
	s_waitcnt vmcnt(6)
	v_lshl_add_u32 v0, v5, 7, v0
	v_and_b32_e32 v1, 1, v4
	v_or_b32_e32 v143, 16, v139
	v_or_b32_e32 v145, 32, v139
	v_or_b32_e32 v173, 48, v139
	v_add_u32_e32 v174, 0x80, v139
	v_add_u32_e32 v175, 0x90, v139
	v_add_u32_e32 v176, 0xa0, v139
	v_add_u32_e32 v177, 0xb0, v139
	s_add_i32 s6, 0, 0x21000
	v_lshl_or_b32 v0, v1, 6, v0
	s_add_i32 s42, 0, 0x10000
	s_add_i32 s43, 0, 0x14000
	v_or_b32_e32 v142, 0x2000, v140
	v_or_b32_e32 v144, 0x2100, v140
	v_lshl_add_u64 v[148:149], s[44:45], 0, v[136:137]
	v_add_u32_e32 v178, s6, v9
	v_lshl_add_u32 v179, v143, 2, s6
	v_lshl_add_u32 v180, v145, 2, s6
	v_lshl_add_u32 v181, v173, 2, s6
	v_lshl_add_u32 v182, v174, 2, s6
	v_lshl_add_u32 v183, v175, 2, s6
	v_lshl_add_u32 v187, v176, 2, s6
	v_lshl_add_u32 v189, v177, 2, s6
	v_or_b32_e32 v191, s7, v8
	v_mov_b32_e32 v151, v137
	v_lshl_add_u32 v152, v6, 1, v0
	v_mov_b32_e32 v153, v137
	v_add_u32_e32 v193, 0, v10
	v_mov_b32_e32 v194, 0x358637bd
	s_mov_b32 s50, 0x800000
	s_mov_b32 s51, 0xffff
	s_mov_b32 s54, 0xffff0000
	v_mov_b64_e32 v[154:155], 0x400
	v_mov_b64_e32 v[156:157], 0x3ff
	v_add_u32_e32 v195, s42, v141
	v_add_u32_e32 v196, s43, v141
	s_barrier
	s_branch .LBB0_340

; #define PG8_STAGE(bufoff, gbase, voff) do { _Pragma("unroll") for (int _i = 0; _i < 2; ++_i) \
;         __builtin_amdgcn_global_load_lds((const unsigned*)((const char*)(gbase) + (voff)[_i]), (LAS unsigned*)(lds + (bufoff) + ldsw + _i * 8192), 16, 0, 0); } while (0)
; #define PG8_LDA(dst, b, h) do { _Pragma("unroll") for (int m = 0; m < 4; ++m) _Pragma("unroll") for (int k = 0; k < 2; ++k) dst[m][k] = *(const LAS bf16x8*)(lds + PG8_SA(b, h) + aoff + m * 2048 + k * 1024); } while (0)
; #define PG8_LDB(dst, b, h) do { _Pragma("unroll") for (int n = 0; n < 2; ++n) _Pragma("unroll") for (int k = 0; k < 2; ++k) dst[n][k] = *(const LAS bf16x8*)(lds + PG8_SB(b, h) + boff + n * 2048 + k * 1024); } while (0)
; #define PG8_MMA(ai, bj, At, Bt) do { __builtin_amdgcn_s_setprio(1); _Pragma("unroll") for (int m = 0; m < 4; ++m) _Pragma("unroll") for (int n = 0; n < 2; ++n) _Pragma("unroll") for (int k = 0; k < 2; ++k) \
;         acc[ai][bj][m][n] = __builtin_amdgcn_mfma_f32_16x16x32_bf16(Bt[n][k], At[m][k], acc[ai][bj][m][n], 0, 0, 0); __builtin_amdgcn_s_setprio(0); } while (0)
; #define PG8_WAIT_V(n) asm volatile("s_waitcnt vmcnt(" #n ")" ::: "memory")
; #define PG8_WAIT_L(n) asm volatile("s_waitcnt lgkmcnt(" #n ")" ::: "memory")
; #define PG8_BAR __builtin_amdgcn_s_barrier()
; #define PG8_SCHED __builtin_amdgcn_sched_barrier(0)
; template <bool ALIGN_EPI, class Epi, class Sched>
; __device__ __forceinline__ void gemm_phase(LAS unsigned char* lds, const int lda, const int ldb, const int K, const Sched& S, const Epi& E, const size_t kstepA = (size_t)(BK * 2), const size_t kstepB = (size_t)(BK * 2)) {
;     ...
;             PG8_LDB(B0, 0, 0); PG8_LDB(B1, 0, 1); PG8_SCHED; PG8_LDA(At, 0, 0); PG8_STAGE(PG8_SA(1, 1), a1 + hstepA, voffA);
;             PG8_WAIT_V(8); PG8_WAIT_L(0); PG8_BAR; PG8_MMA(0, 0, At, B0); PG8_MMA(0, 1, At, B1); PG8_BAR; PG8_SCHED;
;     ...
; #pragma unroll
;         for (int a = 0; a < 2; ++a)
; #pragma unroll
;             for (int b = 0; b < 2; ++b)
; #pragma unroll
;                 for (int m = 0; m < 4; ++m)
; #pragma unroll
;                     for (int n = 0; n < 2; ++n) acc[a][b][m][n] = (f32x4){0.f, 0.f, 0.f, 0.f};
;         cur = nxt; cA = nA; cB = nB; ++ui;
.LBB0_346:
	s_add_u32 s55, s82, 0x100000
	s_addc_u32 s57, s83, 0
	s_add_u32 s16, s16, 0x204000
	v_mov_b32_e32 v0, 0
	s_addc_u32 s17, s17, 0
	s_mov_b32 s58, -2
	v_mov_b32_e32 v1, v0
	v_mov_b32_e32 v2, v0
	v_mov_b32_e32 v3, v0
	v_mov_b32_e32 v4, v0
	v_mov_b32_e32 v5, v0
	v_mov_b32_e32 v6, v0
	v_mov_b32_e32 v7, v0
	v_mov_b32_e32 v16, v0
	v_mov_b32_e32 v17, v0
	v_mov_b32_e32 v18, v0
	v_mov_b32_e32 v19, v0
	v_mov_b32_e32 v20, v0
	v_mov_b32_e32 v21, v0
	v_mov_b32_e32 v22, v0
	v_mov_b32_e32 v23, v0
	v_mov_b32_e32 v32, v0
	v_mov_b32_e32 v33, v0
	v_mov_b32_e32 v34, v0
	v_mov_b32_e32 v35, v0
	v_mov_b32_e32 v36, v0
	v_mov_b32_e32 v37, v0
	v_mov_b32_e32 v38, v0
	v_mov_b32_e32 v39, v0
	v_mov_b32_e32 v48, v0
	v_mov_b32_e32 v49, v0
	v_mov_b32_e32 v50, v0
	v_mov_b32_e32 v51, v0
	v_mov_b32_e32 v52, v0
	v_mov_b32_e32 v53, v0
	v_mov_b32_e32 v54, v0
	v_mov_b32_e32 v55, v0
	v_mov_b32_e32 v8, v0
	v_mov_b32_e32 v9, v0
	v_mov_b32_e32 v10, v0
	v_mov_b32_e32 v11, v0
	v_mov_b32_e32 v12, v0
	v_mov_b32_e32 v13, v0
	v_mov_b32_e32 v14, v0
	v_mov_b32_e32 v15, v0
	v_mov_b32_e32 v24, v0
	v_mov_b32_e32 v25, v0
	v_mov_b32_e32 v26, v0
	v_mov_b32_e32 v27, v0
	v_mov_b32_e32 v28, v0
	v_mov_b32_e32 v29, v0
	v_mov_b32_e32 v30, v0
	v_mov_b32_e32 v31, v0
	v_mov_b32_e32 v40, v0
	v_mov_b32_e32 v41, v0
	v_mov_b32_e32 v42, v0
	v_mov_b32_e32 v43, v0
	v_mov_b32_e32 v44, v0
	v_mov_b32_e32 v45, v0
	v_mov_b32_e32 v46, v0
	v_mov_b32_e32 v47, v0
	v_mov_b32_e32 v56, v0
	v_mov_b32_e32 v57, v0
	v_mov_b32_e32 v58, v0
	v_mov_b32_e32 v59, v0
	v_mov_b32_e32 v60, v0
	v_mov_b32_e32 v61, v0
	v_mov_b32_e32 v62, v0
	v_mov_b32_e32 v63, v0
	v_mov_b32_e32 v64, v0
	v_mov_b32_e32 v65, v0
	v_mov_b32_e32 v66, v0
	v_mov_b32_e32 v67, v0
	v_mov_b32_e32 v68, v0
	v_mov_b32_e32 v69, v0
	v_mov_b32_e32 v70, v0
	v_mov_b32_e32 v71, v0
	v_mov_b32_e32 v80, v0
	v_mov_b32_e32 v81, v0
	v_mov_b32_e32 v82, v0
	v_mov_b32_e32 v83, v0
	v_mov_b32_e32 v84, v0
	v_mov_b32_e32 v85, v0
	v_mov_b32_e32 v86, v0
	v_mov_b32_e32 v87, v0
	v_mov_b32_e32 v96, v0
	v_mov_b32_e32 v97, v0
	v_mov_b32_e32 v98, v0
	v_mov_b32_e32 v99, v0
	v_mov_b32_e32 v100, v0
	v_mov_b32_e32 v101, v0
	v_mov_b32_e32 v102, v0
	v_mov_b32_e32 v103, v0
	v_mov_b32_e32 v112, v0
	v_mov_b32_e32 v113, v0
	v_mov_b32_e32 v114, v0
	v_mov_b32_e32 v115, v0
	v_mov_b32_e32 v116, v0
	v_mov_b32_e32 v117, v0
	v_mov_b32_e32 v118, v0
	v_mov_b32_e32 v119, v0
	v_mov_b32_e32 v72, v0
	v_mov_b32_e32 v73, v0
	v_mov_b32_e32 v74, v0
	v_mov_b32_e32 v75, v0
	v_mov_b32_e32 v76, v0
	v_mov_b32_e32 v77, v0
	v_mov_b32_e32 v78, v0
	v_mov_b32_e32 v79, v0
	v_mov_b32_e32 v88, v0
	v_mov_b32_e32 v89, v0
	v_mov_b32_e32 v90, v0
	v_mov_b32_e32 v91, v0
	v_mov_b32_e32 v92, v0
	v_mov_b32_e32 v93, v0
	v_mov_b32_e32 v94, v0
	v_mov_b32_e32 v95, v0
	v_mov_b32_e32 v104, v0
	v_mov_b32_e32 v105, v0
	v_mov_b32_e32 v106, v0
	v_mov_b32_e32 v107, v0
	v_mov_b32_e32 v108, v0
	v_mov_b32_e32 v109, v0
	v_mov_b32_e32 v110, v0
	v_mov_b32_e32 v111, v0
	v_mov_b32_e32 v120, v0
	v_mov_b32_e32 v121, v0
	v_mov_b32_e32 v122, v0
	v_mov_b32_e32 v123, v0
	v_mov_b32_e32 v124, v0
	v_mov_b32_e32 v125, v0
	v_mov_b32_e32 v126, v0
	v_mov_b32_e32 v127, v0
	s_cmp_lg_u64 s[68:69], 0
	s_cbranch_scc0 .Lp3_kloop_y
.LBB0_347:
	ds_read_b128 v[158:161], v195
	ds_read_b128 v[162:165], v195 offset:1024
	ds_read_b128 v[166:169], v195 offset:2048
	ds_read_b128 v[198:201], v195 offset:3072
	ds_read_b128 v[202:205], v196
	ds_read_b128 v[206:209], v196 offset:1024
	ds_read_b128 v[210:213], v196 offset:2048
	ds_read_b128 v[214:217], v196 offset:3072
	s_add_u32 s59, s16, 0x1fc000
	s_addc_u32 s60, s17, 0
	s_cmp_eq_u32 s58, 28
	s_cselect_b32 s94, s6, s59
	s_cselect_b32 s95, s7, s60
	s_cselect_b32 s92, s14, s55
	s_cselect_b32 s93, s15, s57
	s_add_u32 s82, s94, 0x200000
	s_addc_u32 s83, s95, 0
	v_lshl_add_u64 v[170:171], s[16:17], 0, v[150:151]
	s_add_i32 m0, s20, 0xc000
	ds_read_b128 v[218:221], v193
	ds_read_b128 v[222:225], v193 offset:1024
	ds_read_b128 v[226:229], v193 offset:2048
	ds_read_b128 v[230:233], v193 offset:3072
	ds_read_b128 v[234:237], v193 offset:4096
	ds_read_b128 v[238:241], v193 offset:5120
	ds_read_b128 v[242:245], v193 offset:6144
	ds_read_b128 v[246:249], v193 offset:7168
	global_load_lds_dwordx4 v[170:171], off
	v_lshl_add_u64 v[170:171], s[16:17], 0, v[152:153]
	s_add_i32 m0, s20, 0xe000
	s_nop 0
	global_load_lds_dwordx4 v[170:171], off
	s_waitcnt vmcnt(8)
	s_waitcnt lgkmcnt(0)
	s_setprio 1
	s_waitcnt lgkmcnt(0)
	v_mfma_f32_16x16x32_bf16 v[124:127], v[158:161], v[218:221], v[124:127]
	v_mfma_f32_16x16x32_bf16 v[124:127], v[162:165], v[222:225], v[124:127]
	v_mfma_f32_16x16x32_bf16 v[120:123], v[166:169], v[218:221], v[120:123]
	v_mfma_f32_16x16x32_bf16 v[120:123], v[198:201], v[222:225], v[120:123]
	v_mfma_f32_16x16x32_bf16 v[108:111], v[158:161], v[226:229], v[108:111]
	v_mfma_f32_16x16x32_bf16 v[108:111], v[162:165], v[230:233], v[108:111]
	v_mfma_f32_16x16x32_bf16 v[104:107], v[166:169], v[226:229], v[104:107]
	v_mfma_f32_16x16x32_bf16 v[104:107], v[198:201], v[230:233], v[104:107]
	v_mfma_f32_16x16x32_bf16 v[92:95], v[158:161], v[234:237], v[92:95]
	v_mfma_f32_16x16x32_bf16 v[92:95], v[162:165], v[238:241], v[92:95]
	v_mfma_f32_16x16x32_bf16 v[88:91], v[166:169], v[234:237], v[88:91]
	v_mfma_f32_16x16x32_bf16 v[88:91], v[198:201], v[238:241], v[88:91]
	v_mfma_f32_16x16x32_bf16 v[76:79], v[158:161], v[242:245], v[76:79]
	v_mfma_f32_16x16x32_bf16 v[76:79], v[162:165], v[246:249], v[76:79]
	v_mfma_f32_16x16x32_bf16 v[72:75], v[166:169], v[242:245], v[72:75]
	v_mfma_f32_16x16x32_bf16 v[72:75], v[198:201], v[246:249], v[72:75]
	s_setprio 0
	s_setprio 1
	v_mfma_f32_16x16x32_bf16 v[116:119], v[202:205], v[218:221], v[116:119]
	v_mfma_f32_16x16x32_bf16 v[116:119], v[206:209], v[222:225], v[116:119]
	v_mfma_f32_16x16x32_bf16 v[112:115], v[210:213], v[218:221], v[112:115]
	v_mfma_f32_16x16x32_bf16 v[112:115], v[214:217], v[222:225], v[112:115]
	v_mfma_f32_16x16x32_bf16 v[100:103], v[202:205], v[226:229], v[100:103]
	v_mfma_f32_16x16x32_bf16 v[100:103], v[206:209], v[230:233], v[100:103]
	v_mfma_f32_16x16x32_bf16 v[96:99], v[210:213], v[226:229], v[96:99]
	v_mfma_f32_16x16x32_bf16 v[96:99], v[214:217], v[230:233], v[96:99]
	v_mfma_f32_16x16x32_bf16 v[84:87], v[202:205], v[234:237], v[84:87]
	v_mfma_f32_16x16x32_bf16 v[84:87], v[206:209], v[238:241], v[84:87]
	v_mfma_f32_16x16x32_bf16 v[80:83], v[210:213], v[234:237], v[80:83]
	v_mfma_f32_16x16x32_bf16 v[80:83], v[214:217], v[238:241], v[80:83]
	v_mfma_f32_16x16x32_bf16 v[68:71], v[202:205], v[242:245], v[68:71]
	v_mfma_f32_16x16x32_bf16 v[68:71], v[206:209], v[246:249], v[68:71]
	v_mfma_f32_16x16x32_bf16 v[64:67], v[210:213], v[242:245], v[64:67]
	v_mfma_f32_16x16x32_bf16 v[64:67], v[214:217], v[246:249], v[64:67]
	s_setprio 0
	s_barrier
; #define PG8_STAGE(bufoff, gbase, voff) do { _Pragma("unroll") for (int _i = 0; _i < 2; ++_i) \
;         __builtin_amdgcn_global_load_lds((const unsigned*)((const char*)(gbase) + (voff)[_i]), (LAS unsigned*)(lds + (bufoff) + ldsw + _i * 8192), 16, 0, 0); } while (0)
; #define PG8_LDA(dst, b, h) do { _Pragma("unroll") for (int m = 0; m < 4; ++m) _Pragma("unroll") for (int k = 0; k < 2; ++k) dst[m][k] = *(const LAS bf16x8*)(lds + PG8_SA(b, h) + aoff + m * 2048 + k * 1024); } while (0)
; #define PG8_LDB(dst, b, h) do { _Pragma("unroll") for (int n = 0; n < 2; ++n) _Pragma("unroll") for (int k = 0; k < 2; ++k) dst[n][k] = *(const LAS bf16x8*)(lds + PG8_SB(b, h) + boff + n * 2048 + k * 1024); } while (0)
; #define PG8_MMA(ai, bj, At, Bt) do { __builtin_amdgcn_s_setprio(1); _Pragma("unroll") for (int m = 0; m < 4; ++m) _Pragma("unroll") for (int n = 0; n < 2; ++n) _Pragma("unroll") for (int k = 0; k < 2; ++k) \
;         acc[ai][bj][m][n] = __builtin_amdgcn_mfma_f32_16x16x32_bf16(Bt[n][k], At[m][k], acc[ai][bj][m][n], 0, 0, 0); __builtin_amdgcn_s_setprio(0); } while (0)
; #define PG8_WAIT_V(n) asm volatile("s_waitcnt vmcnt(" #n ")" ::: "memory")
; #define PG8_WAIT_L(n) asm volatile("s_waitcnt lgkmcnt(" #n ")" ::: "memory")
; #define PG8_BAR __builtin_amdgcn_s_barrier()
; #define PG8_SCHED __builtin_amdgcn_sched_barrier(0)
; template <bool ALIGN_EPI, class Epi, class Sched>
; __device__ __forceinline__ void gemm_phase(LAS unsigned char* lds, const int lda, const int ldb, const int K, const Sched& S, const Epi& E, const size_t kstepA = (size_t)(BK * 2), const size_t kstepB = (size_t)(BK * 2)) {
;     ...
;             PG8_WAIT_V(8); PG8_WAIT_L(0); PG8_BAR; PG8_MMA(0, 0, At, B0); PG8_MMA(0, 1, At, B1); PG8_BAR; PG8_SCHED;
;             PG8_LDA(At, 0, 1); PG8_STAGE(PG8_SB(0, 0), b2, voffB); PG8_STAGE(PG8_SB(0, 1), b2 + hstepB, voffB); PG8_STAGE(PG8_SA(0, 0), a2, voffA);
;             PG8_WAIT_V(8); PG8_WAIT_L(0); PG8_BAR; PG8_MMA(1, 0, At, B0); PG8_MMA(1, 1, At, B1); PG8_BAR; PG8_SCHED;
;             PG8_LDB(B0, 1, 0); PG8_LDB(B1, 1, 1); PG8_SCHED; PG8_LDA(At, 1, 0); PG8_STAGE(PG8_SA(0, 1), a2 + hstepA, voffA);
;             PG8_WAIT_V(8); PG8_WAIT_L(0); PG8_BAR; PG8_MMA(0, 0, At, B0); PG8_MMA(0, 1, At, B1); PG8_BAR; PG8_SCHED;
	s_add_i32 s59, s42, s19
	v_lshl_add_u64 v[170:171], s[92:93], 0, v[130:131]
	s_mov_b32 m0, s59
	ds_read_b128 v[218:221], v193 offset:16384
	ds_read_b128 v[222:225], v193 offset:17408
	ds_read_b128 v[226:229], v193 offset:18432
	ds_read_b128 v[230:233], v193 offset:19456
	ds_read_b128 v[234:237], v193 offset:20480
	ds_read_b128 v[238:241], v193 offset:21504
	ds_read_b128 v[242:245], v193 offset:22528
	ds_read_b128 v[246:249], v193 offset:23552
	global_load_lds_dwordx4 v[170:171], off
	s_add_i32 m0, s59, 0x2000
	s_add_u32 s60, s92, 0x4000
	v_lshl_add_u64 v[170:171], s[92:93], 0, v[134:135]
	s_addc_u32 s61, s93, 0
	s_add_i32 s59, s43, s19
	global_load_lds_dwordx4 v[170:171], off
	v_lshl_add_u64 v[170:171], s[60:61], 0, v[130:131]
	s_mov_b32 m0, s59
	s_nop 0
	global_load_lds_dwordx4 v[170:171], off
	v_lshl_add_u64 v[170:171], s[60:61], 0, v[134:135]
	s_add_i32 m0, s59, 0x2000
	s_nop 0
	global_load_lds_dwordx4 v[170:171], off
	v_lshl_add_u64 v[170:171], s[94:95], 0, v[128:129]
	s_mov_b32 m0, s20
	s_nop 0
	global_load_lds_dwordx4 v[170:171], off
	v_lshl_add_u64 v[170:171], s[94:95], 0, v[132:133]
	s_mov_b32 m0, s21
	s_nop 0
	global_load_lds_dwordx4 v[170:171], off
	s_waitcnt vmcnt(8)
	s_waitcnt lgkmcnt(0)
	s_setprio 1
	s_waitcnt lgkmcnt(0)
	v_mfma_f32_16x16x32_bf16 v[60:63], v[158:161], v[218:221], v[60:63]
	v_mfma_f32_16x16x32_bf16 v[60:63], v[162:165], v[222:225], v[60:63]
	v_mfma_f32_16x16x32_bf16 v[56:59], v[166:169], v[218:221], v[56:59]
	v_mfma_f32_16x16x32_bf16 v[56:59], v[198:201], v[222:225], v[56:59]
	v_mfma_f32_16x16x32_bf16 v[44:47], v[158:161], v[226:229], v[44:47]
	v_mfma_f32_16x16x32_bf16 v[44:47], v[162:165], v[230:233], v[44:47]
	v_mfma_f32_16x16x32_bf16 v[40:43], v[166:169], v[226:229], v[40:43]
	v_mfma_f32_16x16x32_bf16 v[40:43], v[198:201], v[230:233], v[40:43]
	v_mfma_f32_16x16x32_bf16 v[28:31], v[158:161], v[234:237], v[28:31]
	v_mfma_f32_16x16x32_bf16 v[28:31], v[162:165], v[238:241], v[28:31]
	v_mfma_f32_16x16x32_bf16 v[24:27], v[166:169], v[234:237], v[24:27]
	v_mfma_f32_16x16x32_bf16 v[24:27], v[198:201], v[238:241], v[24:27]
	v_mfma_f32_16x16x32_bf16 v[12:15], v[158:161], v[242:245], v[12:15]
	v_mfma_f32_16x16x32_bf16 v[12:15], v[162:165], v[246:249], v[12:15]
	v_mfma_f32_16x16x32_bf16 v[8:11], v[166:169], v[242:245], v[8:11]
	v_mfma_f32_16x16x32_bf16 v[8:11], v[198:201], v[246:249], v[8:11]
	s_setprio 0
	s_setprio 1
	v_mfma_f32_16x16x32_bf16 v[52:55], v[202:205], v[218:221], v[52:55]
	v_mfma_f32_16x16x32_bf16 v[52:55], v[206:209], v[222:225], v[52:55]
	v_mfma_f32_16x16x32_bf16 v[48:51], v[210:213], v[218:221], v[48:51]
	v_mfma_f32_16x16x32_bf16 v[48:51], v[214:217], v[222:225], v[48:51]
	v_mfma_f32_16x16x32_bf16 v[36:39], v[202:205], v[226:229], v[36:39]
	v_mfma_f32_16x16x32_bf16 v[36:39], v[206:209], v[230:233], v[36:39]
	v_mfma_f32_16x16x32_bf16 v[32:35], v[210:213], v[226:229], v[32:35]
	v_mfma_f32_16x16x32_bf16 v[32:35], v[214:217], v[230:233], v[32:35]
	v_mfma_f32_16x16x32_bf16 v[20:23], v[202:205], v[234:237], v[20:23]
	v_mfma_f32_16x16x32_bf16 v[20:23], v[206:209], v[238:241], v[20:23]
	v_mfma_f32_16x16x32_bf16 v[16:19], v[210:213], v[234:237], v[16:19]
	v_mfma_f32_16x16x32_bf16 v[16:19], v[214:217], v[238:241], v[16:19]
	v_mfma_f32_16x16x32_bf16 v[4:7], v[202:205], v[242:245], v[4:7]
	v_mfma_f32_16x16x32_bf16 v[4:7], v[206:209], v[246:249], v[4:7]
	v_mfma_f32_16x16x32_bf16 v[0:3], v[210:213], v[242:245], v[0:3]
	v_mfma_f32_16x16x32_bf16 v[0:3], v[214:217], v[246:249], v[0:3]
	s_setprio 0
	s_barrier
	s_add_i32 s59, 0, 0x18000
	v_add_u32_e32 v136, s59, v141
	s_add_i32 s64, 0, 0x1c000
	ds_read_b128 v[158:161], v136
	ds_read_b128 v[162:165], v136 offset:1024
	ds_read_b128 v[166:169], v136 offset:2048
	ds_read_b128 v[198:201], v136 offset:3072
	v_add_u32_e32 v136, s64, v141
	ds_read_b128 v[202:205], v136
	ds_read_b128 v[206:209], v136 offset:1024
	ds_read_b128 v[210:213], v136 offset:2048
	ds_read_b128 v[214:217], v136 offset:3072
	s_add_u32 s60, s94, 0x4000
	s_addc_u32 s61, s95, 0
	s_mov_b32 m0, s22
	v_lshl_add_u64 v[170:171], s[60:61], 0, v[128:129]
	ds_read_b128 v[218:221], v193 offset:32768
	ds_read_b128 v[222:225], v193 offset:33792
	ds_read_b128 v[226:229], v193 offset:34816
	ds_read_b128 v[230:233], v193 offset:35840
	ds_read_b128 v[234:237], v193 offset:36864
	ds_read_b128 v[238:241], v193 offset:37888
	ds_read_b128 v[242:245], v193 offset:38912
	ds_read_b128 v[246:249], v193 offset:39936
	global_load_lds_dwordx4 v[170:171], off
	v_lshl_add_u64 v[170:171], s[60:61], 0, v[132:133]
	s_mov_b32 m0, s23
	s_nop 0
	global_load_lds_dwordx4 v[170:171], off
	s_waitcnt vmcnt(8)
	s_waitcnt lgkmcnt(0)
	s_setprio 1
	s_waitcnt lgkmcnt(0)
	v_mfma_f32_16x16x32_bf16 v[124:127], v[158:161], v[218:221], v[124:127]
	v_mfma_f32_16x16x32_bf16 v[124:127], v[162:165], v[222:225], v[124:127]
	v_mfma_f32_16x16x32_bf16 v[120:123], v[166:169], v[218:221], v[120:123]
	v_mfma_f32_16x16x32_bf16 v[120:123], v[198:201], v[222:225], v[120:123]
	v_mfma_f32_16x16x32_bf16 v[108:111], v[158:161], v[226:229], v[108:111]
	v_mfma_f32_16x16x32_bf16 v[108:111], v[162:165], v[230:233], v[108:111]
	v_mfma_f32_16x16x32_bf16 v[104:107], v[166:169], v[226:229], v[104:107]
	v_mfma_f32_16x16x32_bf16 v[104:107], v[198:201], v[230:233], v[104:107]
	v_mfma_f32_16x16x32_bf16 v[92:95], v[158:161], v[234:237], v[92:95]
	v_mfma_f32_16x16x32_bf16 v[92:95], v[162:165], v[238:241], v[92:95]
	v_mfma_f32_16x16x32_bf16 v[88:91], v[166:169], v[234:237], v[88:91]
	v_mfma_f32_16x16x32_bf16 v[88:91], v[198:201], v[238:241], v[88:91]
	v_mfma_f32_16x16x32_bf16 v[76:79], v[158:161], v[242:245], v[76:79]
	v_mfma_f32_16x16x32_bf16 v[76:79], v[162:165], v[246:249], v[76:79]
	v_mfma_f32_16x16x32_bf16 v[72:75], v[166:169], v[242:245], v[72:75]
	v_mfma_f32_16x16x32_bf16 v[72:75], v[198:201], v[246:249], v[72:75]
	s_setprio 0
	s_setprio 1
	v_mfma_f32_16x16x32_bf16 v[116:119], v[202:205], v[218:221], v[116:119]
	v_mfma_f32_16x16x32_bf16 v[116:119], v[206:209], v[222:225], v[116:119]
	v_mfma_f32_16x16x32_bf16 v[112:115], v[210:213], v[218:221], v[112:115]
	v_mfma_f32_16x16x32_bf16 v[112:115], v[214:217], v[222:225], v[112:115]
	v_mfma_f32_16x16x32_bf16 v[100:103], v[202:205], v[226:229], v[100:103]
	v_mfma_f32_16x16x32_bf16 v[100:103], v[206:209], v[230:233], v[100:103]
	v_mfma_f32_16x16x32_bf16 v[96:99], v[210:213], v[226:229], v[96:99]
	v_mfma_f32_16x16x32_bf16 v[96:99], v[214:217], v[230:233], v[96:99]
	v_mfma_f32_16x16x32_bf16 v[84:87], v[202:205], v[234:237], v[84:87]
	v_mfma_f32_16x16x32_bf16 v[84:87], v[206:209], v[238:241], v[84:87]
	v_mfma_f32_16x16x32_bf16 v[80:83], v[210:213], v[234:237], v[80:83]
	v_mfma_f32_16x16x32_bf16 v[80:83], v[214:217], v[238:241], v[80:83]
	v_mfma_f32_16x16x32_bf16 v[68:71], v[202:205], v[242:245], v[68:71]
	v_mfma_f32_16x16x32_bf16 v[68:71], v[206:209], v[246:249], v[68:71]
	v_mfma_f32_16x16x32_bf16 v[64:67], v[210:213], v[242:245], v[64:67]
	v_mfma_f32_16x16x32_bf16 v[64:67], v[214:217], v[246:249], v[64:67]
	s_setprio 0
	s_barrier
; #define PG8_STAGE(bufoff, gbase, voff) do { _Pragma("unroll") for (int _i = 0; _i < 2; ++_i) \
;         __builtin_amdgcn_global_load_lds((const unsigned*)((const char*)(gbase) + (voff)[_i]), (LAS unsigned*)(lds + (bufoff) + ldsw + _i * 8192), 16, 0, 0); } while (0)
; #define PG8_LDA(dst, b, h) do { _Pragma("unroll") for (int m = 0; m < 4; ++m) _Pragma("unroll") for (int k = 0; k < 2; ++k) dst[m][k] = *(const LAS bf16x8*)(lds + PG8_SA(b, h) + aoff + m * 2048 + k * 1024); } while (0)
; #define PG8_LDB(dst, b, h) do { _Pragma("unroll") for (int n = 0; n < 2; ++n) _Pragma("unroll") for (int k = 0; k < 2; ++k) dst[n][k] = *(const LAS bf16x8*)(lds + PG8_SB(b, h) + boff + n * 2048 + k * 1024); } while (0)
; #define PG8_MMA(ai, bj, At, Bt) do { __builtin_amdgcn_s_setprio(1); _Pragma("unroll") for (int m = 0; m < 4; ++m) _Pragma("unroll") for (int n = 0; n < 2; ++n) _Pragma("unroll") for (int k = 0; k < 2; ++k) \
;         acc[ai][bj][m][n] = __builtin_amdgcn_mfma_f32_16x16x32_bf16(Bt[n][k], At[m][k], acc[ai][bj][m][n], 0, 0, 0); __builtin_amdgcn_s_setprio(0); } while (0)
; #define PG8_WAIT_V(n) asm volatile("s_waitcnt vmcnt(" #n ")" ::: "memory")
; #define PG8_WAIT_L(n) asm volatile("s_waitcnt lgkmcnt(" #n ")" ::: "memory")
; #define PG8_BAR __builtin_amdgcn_s_barrier()
; #define PG8_SCHED __builtin_amdgcn_sched_barrier(0)
; template <bool ALIGN_EPI, class Epi, class Sched>
; __device__ __forceinline__ void gemm_phase(LAS unsigned char* lds, const int lda, const int ldb, const int K, const Sched& S, const Epi& E, const size_t kstepA = (size_t)(BK * 2), const size_t kstepB = (size_t)(BK * 2)) {
;     ...
;             PG8_LDB(B0, 0, 0); PG8_LDB(B1, 0, 1); PG8_SCHED; PG8_LDA(At, 0, 0); PG8_STAGE(PG8_SA(1, 1), a1 + hstepA, voffA);
;             PG8_WAIT_V(8); PG8_WAIT_L(0); PG8_BAR; PG8_MMA(0, 0, At, B0); PG8_MMA(0, 1, At, B1); PG8_BAR; PG8_SCHED;
;     ...
;             PG8_LDA(At, 1, 1); PG8_STAGE(PG8_SB(1, 0), b3, voffB); PG8_STAGE(PG8_SB(1, 1), b3 + hstepB, voffB); PG8_STAGE(PG8_SA(1, 0), a3, voffA);
;             PG8_WAIT_V(8); PG8_WAIT_L(0); PG8_BAR; PG8_MMA(1, 0, At, B0); PG8_MMA(1, 1, At, B1); PG8_BAR; PG8_SCHED;
;         }
	s_add_u32 s60, s92, 0x80000
	s_addc_u32 s61, s93, 0
	s_add_i32 s59, s59, s19
	v_lshl_add_u64 v[170:171], s[60:61], 0, v[130:131]
	s_mov_b32 m0, s59
	ds_read_b128 v[218:221], v193 offset:49152
	ds_read_b128 v[222:225], v193 offset:50176
	ds_read_b128 v[226:229], v193 offset:51200
	ds_read_b128 v[230:233], v193 offset:52224
	ds_read_b128 v[234:237], v193 offset:53248
	ds_read_b128 v[238:241], v193 offset:54272
	ds_read_b128 v[242:245], v193 offset:55296
	ds_read_b128 v[246:249], v193 offset:56320
	global_load_lds_dwordx4 v[170:171], off
	s_add_i32 m0, s59, 0x2000
	v_lshl_add_u64 v[170:171], s[60:61], 0, v[134:135]
	s_add_u32 s60, s92, 0x84000
	s_addc_u32 s61, s93, 0
	s_add_i32 s59, s64, s19
	global_load_lds_dwordx4 v[170:171], off
	v_lshl_add_u64 v[170:171], s[60:61], 0, v[130:131]
	s_mov_b32 m0, s59
	s_nop 0
	global_load_lds_dwordx4 v[170:171], off
	v_lshl_add_u64 v[170:171], s[60:61], 0, v[134:135]
	s_add_i32 m0, s59, 0x2000
	s_nop 0
	global_load_lds_dwordx4 v[170:171], off
	v_lshl_add_u64 v[170:171], s[82:83], 0, v[128:129]
	s_mov_b32 m0, s30
	s_nop 0
	global_load_lds_dwordx4 v[170:171], off
	v_lshl_add_u64 v[170:171], s[82:83], 0, v[132:133]
	s_mov_b32 m0, s31
	s_nop 0
	global_load_lds_dwordx4 v[170:171], off
	s_waitcnt vmcnt(8)
	s_waitcnt lgkmcnt(0)
	s_setprio 1
	s_waitcnt lgkmcnt(0)
	v_mfma_f32_16x16x32_bf16 v[60:63], v[158:161], v[218:221], v[60:63]
	v_mfma_f32_16x16x32_bf16 v[60:63], v[162:165], v[222:225], v[60:63]
	v_mfma_f32_16x16x32_bf16 v[56:59], v[166:169], v[218:221], v[56:59]
	v_mfma_f32_16x16x32_bf16 v[56:59], v[198:201], v[222:225], v[56:59]
	v_mfma_f32_16x16x32_bf16 v[44:47], v[158:161], v[226:229], v[44:47]
	v_mfma_f32_16x16x32_bf16 v[44:47], v[162:165], v[230:233], v[44:47]
	v_mfma_f32_16x16x32_bf16 v[40:43], v[166:169], v[226:229], v[40:43]
	v_mfma_f32_16x16x32_bf16 v[40:43], v[198:201], v[230:233], v[40:43]
	v_mfma_f32_16x16x32_bf16 v[28:31], v[158:161], v[234:237], v[28:31]
	v_mfma_f32_16x16x32_bf16 v[28:31], v[162:165], v[238:241], v[28:31]
	v_mfma_f32_16x16x32_bf16 v[24:27], v[166:169], v[234:237], v[24:27]
	v_mfma_f32_16x16x32_bf16 v[24:27], v[198:201], v[238:241], v[24:27]
	v_mfma_f32_16x16x32_bf16 v[12:15], v[158:161], v[242:245], v[12:15]
	v_mfma_f32_16x16x32_bf16 v[12:15], v[162:165], v[246:249], v[12:15]
	v_mfma_f32_16x16x32_bf16 v[8:11], v[166:169], v[242:245], v[8:11]
	v_mfma_f32_16x16x32_bf16 v[8:11], v[198:201], v[246:249], v[8:11]
	s_setprio 0
	s_setprio 1
	v_mfma_f32_16x16x32_bf16 v[52:55], v[202:205], v[218:221], v[52:55]
	v_mfma_f32_16x16x32_bf16 v[52:55], v[206:209], v[222:225], v[52:55]
	v_mfma_f32_16x16x32_bf16 v[48:51], v[210:213], v[218:221], v[48:51]
	v_mfma_f32_16x16x32_bf16 v[48:51], v[214:217], v[222:225], v[48:51]
	v_mfma_f32_16x16x32_bf16 v[36:39], v[202:205], v[226:229], v[36:39]
	v_mfma_f32_16x16x32_bf16 v[36:39], v[206:209], v[230:233], v[36:39]
	v_mfma_f32_16x16x32_bf16 v[32:35], v[210:213], v[226:229], v[32:35]
	v_mfma_f32_16x16x32_bf16 v[32:35], v[214:217], v[230:233], v[32:35]
	v_mfma_f32_16x16x32_bf16 v[20:23], v[202:205], v[234:237], v[20:23]
	v_mfma_f32_16x16x32_bf16 v[20:23], v[206:209], v[238:241], v[20:23]
	v_mfma_f32_16x16x32_bf16 v[16:19], v[210:213], v[234:237], v[16:19]
	v_mfma_f32_16x16x32_bf16 v[16:19], v[214:217], v[238:241], v[16:19]
	v_mfma_f32_16x16x32_bf16 v[4:7], v[202:205], v[242:245], v[4:7]
	v_mfma_f32_16x16x32_bf16 v[4:7], v[206:209], v[246:249], v[4:7]
	v_mfma_f32_16x16x32_bf16 v[0:3], v[210:213], v[242:245], v[0:3]
	v_mfma_f32_16x16x32_bf16 v[0:3], v[214:217], v[246:249], v[0:3]
	s_setprio 0
	s_barrier
	s_add_i32 s58, s58, 2
	s_add_u32 s55, s55, 0x100000
	s_addc_u32 s57, s57, 0
	s_add_u32 s16, s16, 0x400000
	s_addc_u32 s17, s17, 0
	s_cmp_gt_u32 s58, 29
	s_cbranch_scc0 .LBB0_347
	s_branch .Lp3_kloop_done
.Lp3_kloop_y:
	ds_read_b128 v[158:161], v195
	ds_read_b128 v[162:165], v195 offset:1024
	ds_read_b128 v[166:169], v195 offset:2048
	ds_read_b128 v[198:201], v195 offset:3072
	ds_read_b128 v[202:205], v196
	ds_read_b128 v[206:209], v196 offset:1024
	ds_read_b128 v[210:213], v196 offset:2048
	ds_read_b128 v[214:217], v196 offset:3072
	s_add_u32 s59, s16, 0x1fc000
	s_addc_u32 s60, s17, 0
	s_cmp_eq_u32 s58, 28
	s_cselect_b32 s94, s6, s59
	s_cselect_b32 s95, s7, s60
	s_cselect_b32 s92, s14, s55
	s_cselect_b32 s93, s15, s57
	s_add_u32 s82, s94, 0x200000
	s_addc_u32 s83, s95, 0
	v_lshl_add_u64 v[170:171], s[16:17], 0, v[150:151]
	s_add_i32 m0, s20, 0xc000
	ds_read_b128 v[218:221], v193
	ds_read_b128 v[222:225], v193 offset:1024
	ds_read_b128 v[226:229], v193 offset:2048
	ds_read_b128 v[230:233], v193 offset:3072
	ds_read_b128 v[234:237], v193 offset:4096
	ds_read_b128 v[238:241], v193 offset:5120
	ds_read_b128 v[242:245], v193 offset:6144
	ds_read_b128 v[246:249], v193 offset:7168
	global_load_lds_dwordx4 v[170:171], off
	v_lshl_add_u64 v[170:171], s[16:17], 0, v[152:153]
	s_add_i32 m0, s20, 0xe000
	s_nop 0
	global_load_lds_dwordx4 v[170:171], off
	s_waitcnt vmcnt(8)
	s_waitcnt lgkmcnt(0)
	s_barrier
; #define PG8_STAGE(bufoff, gbase, voff) do { _Pragma("unroll") for (int _i = 0; _i < 2; ++_i) \
;         __builtin_amdgcn_global_load_lds((const unsigned*)((const char*)(gbase) + (voff)[_i]), (LAS unsigned*)(lds + (bufoff) + ldsw + _i * 8192), 16, 0, 0); } while (0)
; #define PG8_LDA(dst, b, h) do { _Pragma("unroll") for (int m = 0; m < 4; ++m) _Pragma("unroll") for (int k = 0; k < 2; ++k) dst[m][k] = *(const LAS bf16x8*)(lds + PG8_SA(b, h) + aoff + m * 2048 + k * 1024); } while (0)
; #define PG8_LDB(dst, b, h) do { _Pragma("unroll") for (int n = 0; n < 2; ++n) _Pragma("unroll") for (int k = 0; k < 2; ++k) dst[n][k] = *(const LAS bf16x8*)(lds + PG8_SB(b, h) + boff + n * 2048 + k * 1024); } while (0)
; #define PG8_MMA(ai, bj, At, Bt) do { __builtin_amdgcn_s_setprio(1); _Pragma("unroll") for (int m = 0; m < 4; ++m) _Pragma("unroll") for (int n = 0; n < 2; ++n) _Pragma("unroll") for (int k = 0; k < 2; ++k) \
;         acc[ai][bj][m][n] = __builtin_amdgcn_mfma_f32_16x16x32_bf16(Bt[n][k], At[m][k], acc[ai][bj][m][n], 0, 0, 0); __builtin_amdgcn_s_setprio(0); } while (0)
; #define PG8_WAIT_V(n) asm volatile("s_waitcnt vmcnt(" #n ")" ::: "memory")
; #define PG8_WAIT_L(n) asm volatile("s_waitcnt lgkmcnt(" #n ")" ::: "memory")
; #define PG8_BAR __builtin_amdgcn_s_barrier()
; #define PG8_SCHED __builtin_amdgcn_sched_barrier(0)
; template <bool ALIGN_EPI, class Epi, class Sched>
; __device__ __forceinline__ void gemm_phase(LAS unsigned char* lds, const int lda, const int ldb, const int K, const Sched& S, const Epi& E, const size_t kstepA = (size_t)(BK * 2), const size_t kstepB = (size_t)(BK * 2)) {
;     ...
;             PG8_LDB(B0, 0, 0); PG8_LDB(B1, 0, 1); PG8_SCHED; PG8_LDA(At, 0, 0); PG8_STAGE(PG8_SA(1, 1), a1 + hstepA, voffA);
;             PG8_WAIT_V(8); PG8_WAIT_L(0); PG8_BAR; PG8_MMA(0, 0, At, B0); PG8_MMA(0, 1, At, B1); PG8_BAR; PG8_SCHED;
;             PG8_LDA(At, 0, 1); PG8_STAGE(PG8_SB(0, 0), b2, voffB); PG8_STAGE(PG8_SB(0, 1), b2 + hstepB, voffB); PG8_STAGE(PG8_SA(0, 0), a2, voffA);
;             PG8_WAIT_V(8); PG8_WAIT_L(0); PG8_BAR; PG8_MMA(1, 0, At, B0); PG8_MMA(1, 1, At, B1); PG8_BAR; PG8_SCHED;
;             PG8_LDB(B0, 1, 0); PG8_LDB(B1, 1, 1); PG8_SCHED; PG8_LDA(At, 1, 0); PG8_STAGE(PG8_SA(0, 1), a2 + hstepA, voffA);
;             PG8_WAIT_V(8); PG8_WAIT_L(0); PG8_BAR; PG8_MMA(0, 0, At, B0); PG8_MMA(0, 1, At, B1); PG8_BAR; PG8_SCHED;
	s_setprio 2
	s_waitcnt lgkmcnt(0)
	v_mfma_f32_16x16x32_bf16 v[124:127], v[158:161], v[218:221], v[124:127]
	v_mfma_f32_16x16x32_bf16 v[124:127], v[162:165], v[222:225], v[124:127]
	v_mfma_f32_16x16x32_bf16 v[120:123], v[166:169], v[218:221], v[120:123]
	v_mfma_f32_16x16x32_bf16 v[120:123], v[198:201], v[222:225], v[120:123]
	v_mfma_f32_16x16x32_bf16 v[108:111], v[158:161], v[226:229], v[108:111]
	v_mfma_f32_16x16x32_bf16 v[108:111], v[162:165], v[230:233], v[108:111]
	v_mfma_f32_16x16x32_bf16 v[104:107], v[166:169], v[226:229], v[104:107]
	v_mfma_f32_16x16x32_bf16 v[104:107], v[198:201], v[230:233], v[104:107]
	v_mfma_f32_16x16x32_bf16 v[92:95], v[158:161], v[234:237], v[92:95]
	v_mfma_f32_16x16x32_bf16 v[92:95], v[162:165], v[238:241], v[92:95]
	v_mfma_f32_16x16x32_bf16 v[88:91], v[166:169], v[234:237], v[88:91]
	v_mfma_f32_16x16x32_bf16 v[88:91], v[198:201], v[238:241], v[88:91]
	v_mfma_f32_16x16x32_bf16 v[76:79], v[158:161], v[242:245], v[76:79]
	v_mfma_f32_16x16x32_bf16 v[76:79], v[162:165], v[246:249], v[76:79]
	v_mfma_f32_16x16x32_bf16 v[72:75], v[166:169], v[242:245], v[72:75]
	v_mfma_f32_16x16x32_bf16 v[72:75], v[198:201], v[246:249], v[72:75]
	s_setprio 0
	s_setprio 2
	v_mfma_f32_16x16x32_bf16 v[116:119], v[202:205], v[218:221], v[116:119]
	v_mfma_f32_16x16x32_bf16 v[116:119], v[206:209], v[222:225], v[116:119]
	v_mfma_f32_16x16x32_bf16 v[112:115], v[210:213], v[218:221], v[112:115]
	v_mfma_f32_16x16x32_bf16 v[112:115], v[214:217], v[222:225], v[112:115]
	v_mfma_f32_16x16x32_bf16 v[100:103], v[202:205], v[226:229], v[100:103]
	v_mfma_f32_16x16x32_bf16 v[100:103], v[206:209], v[230:233], v[100:103]
	v_mfma_f32_16x16x32_bf16 v[96:99], v[210:213], v[226:229], v[96:99]
	v_mfma_f32_16x16x32_bf16 v[96:99], v[214:217], v[230:233], v[96:99]
	v_mfma_f32_16x16x32_bf16 v[84:87], v[202:205], v[234:237], v[84:87]
	v_mfma_f32_16x16x32_bf16 v[84:87], v[206:209], v[238:241], v[84:87]
	v_mfma_f32_16x16x32_bf16 v[80:83], v[210:213], v[234:237], v[80:83]
	v_mfma_f32_16x16x32_bf16 v[80:83], v[214:217], v[238:241], v[80:83]
	v_mfma_f32_16x16x32_bf16 v[68:71], v[202:205], v[242:245], v[68:71]
	v_mfma_f32_16x16x32_bf16 v[68:71], v[206:209], v[246:249], v[68:71]
	v_mfma_f32_16x16x32_bf16 v[64:67], v[210:213], v[242:245], v[64:67]
	v_mfma_f32_16x16x32_bf16 v[64:67], v[214:217], v[246:249], v[64:67]
	s_setprio 0
	s_add_i32 s59, s42, s19
	v_lshl_add_u64 v[170:171], s[92:93], 0, v[130:131]
	s_mov_b32 m0, s59
	ds_read_b128 v[218:221], v193 offset:16384
	ds_read_b128 v[222:225], v193 offset:17408
	ds_read_b128 v[226:229], v193 offset:18432
	ds_read_b128 v[230:233], v193 offset:19456
	ds_read_b128 v[234:237], v193 offset:20480
	ds_read_b128 v[238:241], v193 offset:21504
	ds_read_b128 v[242:245], v193 offset:22528
	ds_read_b128 v[246:249], v193 offset:23552
	global_load_lds_dwordx4 v[170:171], off
	s_add_i32 m0, s59, 0x2000
	s_add_u32 s60, s92, 0x4000
	v_lshl_add_u64 v[170:171], s[92:93], 0, v[134:135]
	s_addc_u32 s61, s93, 0
	s_add_i32 s59, s43, s19
	global_load_lds_dwordx4 v[170:171], off
	v_lshl_add_u64 v[170:171], s[60:61], 0, v[130:131]
	s_mov_b32 m0, s59
	s_nop 0
	global_load_lds_dwordx4 v[170:171], off
	v_lshl_add_u64 v[170:171], s[60:61], 0, v[134:135]
	s_add_i32 m0, s59, 0x2000
	s_nop 0
	global_load_lds_dwordx4 v[170:171], off
	v_lshl_add_u64 v[170:171], s[94:95], 0, v[128:129]
	s_mov_b32 m0, s20
	s_nop 0
	global_load_lds_dwordx4 v[170:171], off
	v_lshl_add_u64 v[170:171], s[94:95], 0, v[132:133]
	s_mov_b32 m0, s21
	s_nop 0
	global_load_lds_dwordx4 v[170:171], off
	s_waitcnt vmcnt(8)
	s_waitcnt lgkmcnt(0)
	s_barrier
	s_setprio 2
	s_waitcnt lgkmcnt(0)
	v_mfma_f32_16x16x32_bf16 v[60:63], v[158:161], v[218:221], v[60:63]
	v_mfma_f32_16x16x32_bf16 v[60:63], v[162:165], v[222:225], v[60:63]
	v_mfma_f32_16x16x32_bf16 v[56:59], v[166:169], v[218:221], v[56:59]
	v_mfma_f32_16x16x32_bf16 v[56:59], v[198:201], v[222:225], v[56:59]
	v_mfma_f32_16x16x32_bf16 v[44:47], v[158:161], v[226:229], v[44:47]
	v_mfma_f32_16x16x32_bf16 v[44:47], v[162:165], v[230:233], v[44:47]
	v_mfma_f32_16x16x32_bf16 v[40:43], v[166:169], v[226:229], v[40:43]
	v_mfma_f32_16x16x32_bf16 v[40:43], v[198:201], v[230:233], v[40:43]
	v_mfma_f32_16x16x32_bf16 v[28:31], v[158:161], v[234:237], v[28:31]
	v_mfma_f32_16x16x32_bf16 v[28:31], v[162:165], v[238:241], v[28:31]
	v_mfma_f32_16x16x32_bf16 v[24:27], v[166:169], v[234:237], v[24:27]
	v_mfma_f32_16x16x32_bf16 v[24:27], v[198:201], v[238:241], v[24:27]
	v_mfma_f32_16x16x32_bf16 v[12:15], v[158:161], v[242:245], v[12:15]
	v_mfma_f32_16x16x32_bf16 v[12:15], v[162:165], v[246:249], v[12:15]
	v_mfma_f32_16x16x32_bf16 v[8:11], v[166:169], v[242:245], v[8:11]
	v_mfma_f32_16x16x32_bf16 v[8:11], v[198:201], v[246:249], v[8:11]
	s_setprio 0
	s_setprio 2
	v_mfma_f32_16x16x32_bf16 v[52:55], v[202:205], v[218:221], v[52:55]
	v_mfma_f32_16x16x32_bf16 v[52:55], v[206:209], v[222:225], v[52:55]
	v_mfma_f32_16x16x32_bf16 v[48:51], v[210:213], v[218:221], v[48:51]
	v_mfma_f32_16x16x32_bf16 v[48:51], v[214:217], v[222:225], v[48:51]
	v_mfma_f32_16x16x32_bf16 v[36:39], v[202:205], v[226:229], v[36:39]
	v_mfma_f32_16x16x32_bf16 v[36:39], v[206:209], v[230:233], v[36:39]
	v_mfma_f32_16x16x32_bf16 v[32:35], v[210:213], v[226:229], v[32:35]
	v_mfma_f32_16x16x32_bf16 v[32:35], v[214:217], v[230:233], v[32:35]
	v_mfma_f32_16x16x32_bf16 v[20:23], v[202:205], v[234:237], v[20:23]
	v_mfma_f32_16x16x32_bf16 v[20:23], v[206:209], v[238:241], v[20:23]
	v_mfma_f32_16x16x32_bf16 v[16:19], v[210:213], v[234:237], v[16:19]
	v_mfma_f32_16x16x32_bf16 v[16:19], v[214:217], v[238:241], v[16:19]
	v_mfma_f32_16x16x32_bf16 v[4:7], v[202:205], v[242:245], v[4:7]
	v_mfma_f32_16x16x32_bf16 v[4:7], v[206:209], v[246:249], v[4:7]
	v_mfma_f32_16x16x32_bf16 v[0:3], v[210:213], v[242:245], v[0:3]
	v_mfma_f32_16x16x32_bf16 v[0:3], v[214:217], v[246:249], v[0:3]
	s_setprio 0
	s_add_i32 s59, 0, 0x18000
	v_add_u32_e32 v136, s59, v141
	s_add_i32 s64, 0, 0x1c000
	ds_read_b128 v[158:161], v136
	ds_read_b128 v[162:165], v136 offset:1024
	ds_read_b128 v[166:169], v136 offset:2048
	ds_read_b128 v[198:201], v136 offset:3072
	v_add_u32_e32 v136, s64, v141
	ds_read_b128 v[202:205], v136
	ds_read_b128 v[206:209], v136 offset:1024
	ds_read_b128 v[210:213], v136 offset:2048
	ds_read_b128 v[214:217], v136 offset:3072
	s_add_u32 s60, s94, 0x4000
	s_addc_u32 s61, s95, 0
	s_mov_b32 m0, s22
	v_lshl_add_u64 v[170:171], s[60:61], 0, v[128:129]
	ds_read_b128 v[218:221], v193 offset:32768
	ds_read_b128 v[222:225], v193 offset:33792
	ds_read_b128 v[226:229], v193 offset:34816
	ds_read_b128 v[230:233], v193 offset:35840
	ds_read_b128 v[234:237], v193 offset:36864
	ds_read_b128 v[238:241], v193 offset:37888
	ds_read_b128 v[242:245], v193 offset:38912
	ds_read_b128 v[246:249], v193 offset:39936
	global_load_lds_dwordx4 v[170:171], off
	v_lshl_add_u64 v[170:171], s[60:61], 0, v[132:133]
	s_mov_b32 m0, s23
	s_nop 0
	global_load_lds_dwordx4 v[170:171], off
	s_waitcnt vmcnt(8)
	s_waitcnt lgkmcnt(0)
	s_barrier
; #define PG8_STAGE(bufoff, gbase, voff) do { _Pragma("unroll") for (int _i = 0; _i < 2; ++_i) \
;         __builtin_amdgcn_global_load_lds((const unsigned*)((const char*)(gbase) + (voff)[_i]), (LAS unsigned*)(lds + (bufoff) + ldsw + _i * 8192), 16, 0, 0); } while (0)
; #define PG8_LDA(dst, b, h) do { _Pragma("unroll") for (int m = 0; m < 4; ++m) _Pragma("unroll") for (int k = 0; k < 2; ++k) dst[m][k] = *(const LAS bf16x8*)(lds + PG8_SA(b, h) + aoff + m * 2048 + k * 1024); } while (0)
; #define PG8_MMA(ai, bj, At, Bt) do { __builtin_amdgcn_s_setprio(1); _Pragma("unroll") for (int m = 0; m < 4; ++m) _Pragma("unroll") for (int n = 0; n < 2; ++n) _Pragma("unroll") for (int k = 0; k < 2; ++k) \
;         acc[ai][bj][m][n] = __builtin_amdgcn_mfma_f32_16x16x32_bf16(Bt[n][k], At[m][k], acc[ai][bj][m][n], 0, 0, 0); __builtin_amdgcn_s_setprio(0); } while (0)
; #define PG8_WAIT_V(n) asm volatile("s_waitcnt vmcnt(" #n ")" ::: "memory")
; #define PG8_WAIT_L(n) asm volatile("s_waitcnt lgkmcnt(" #n ")" ::: "memory")
; #define PG8_BAR __builtin_amdgcn_s_barrier()
; #define PG8_SCHED __builtin_amdgcn_sched_barrier(0)
; template <bool ALIGN_EPI, class Epi, class Sched>
; __device__ __forceinline__ void gemm_phase(LAS unsigned char* lds, const int lda, const int ldb, const int K, const Sched& S, const Epi& E, const size_t kstepA = (size_t)(BK * 2), const size_t kstepB = (size_t)(BK * 2)) {
;     ...
;             PG8_LDA(At, 1, 1); PG8_STAGE(PG8_SB(1, 0), b3, voffB); PG8_STAGE(PG8_SB(1, 1), b3 + hstepB, voffB); PG8_STAGE(PG8_SA(1, 0), a3, voffA);
;             PG8_WAIT_V(8); PG8_WAIT_L(0); PG8_BAR; PG8_MMA(1, 0, At, B0); PG8_MMA(1, 1, At, B1); PG8_BAR; PG8_SCHED;
;         }
;         if constexpr (ALIGN_EPI) { if (wr == 0) PG8_BAR; }
	s_setprio 2
	s_waitcnt lgkmcnt(0)
	v_mfma_f32_16x16x32_bf16 v[124:127], v[158:161], v[218:221], v[124:127]
	v_mfma_f32_16x16x32_bf16 v[124:127], v[162:165], v[222:225], v[124:127]
	v_mfma_f32_16x16x32_bf16 v[120:123], v[166:169], v[218:221], v[120:123]
	v_mfma_f32_16x16x32_bf16 v[120:123], v[198:201], v[222:225], v[120:123]
	v_mfma_f32_16x16x32_bf16 v[108:111], v[158:161], v[226:229], v[108:111]
	v_mfma_f32_16x16x32_bf16 v[108:111], v[162:165], v[230:233], v[108:111]
	v_mfma_f32_16x16x32_bf16 v[104:107], v[166:169], v[226:229], v[104:107]
	v_mfma_f32_16x16x32_bf16 v[104:107], v[198:201], v[230:233], v[104:107]
	v_mfma_f32_16x16x32_bf16 v[92:95], v[158:161], v[234:237], v[92:95]
	v_mfma_f32_16x16x32_bf16 v[92:95], v[162:165], v[238:241], v[92:95]
	v_mfma_f32_16x16x32_bf16 v[88:91], v[166:169], v[234:237], v[88:91]
	v_mfma_f32_16x16x32_bf16 v[88:91], v[198:201], v[238:241], v[88:91]
	v_mfma_f32_16x16x32_bf16 v[76:79], v[158:161], v[242:245], v[76:79]
	v_mfma_f32_16x16x32_bf16 v[76:79], v[162:165], v[246:249], v[76:79]
	v_mfma_f32_16x16x32_bf16 v[72:75], v[166:169], v[242:245], v[72:75]
	v_mfma_f32_16x16x32_bf16 v[72:75], v[198:201], v[246:249], v[72:75]
	s_setprio 0
	s_setprio 2
	v_mfma_f32_16x16x32_bf16 v[116:119], v[202:205], v[218:221], v[116:119]
	v_mfma_f32_16x16x32_bf16 v[116:119], v[206:209], v[222:225], v[116:119]
	v_mfma_f32_16x16x32_bf16 v[112:115], v[210:213], v[218:221], v[112:115]
	v_mfma_f32_16x16x32_bf16 v[112:115], v[214:217], v[222:225], v[112:115]
	v_mfma_f32_16x16x32_bf16 v[100:103], v[202:205], v[226:229], v[100:103]
	v_mfma_f32_16x16x32_bf16 v[100:103], v[206:209], v[230:233], v[100:103]
	v_mfma_f32_16x16x32_bf16 v[96:99], v[210:213], v[226:229], v[96:99]
	v_mfma_f32_16x16x32_bf16 v[96:99], v[214:217], v[230:233], v[96:99]
	v_mfma_f32_16x16x32_bf16 v[84:87], v[202:205], v[234:237], v[84:87]
	v_mfma_f32_16x16x32_bf16 v[84:87], v[206:209], v[238:241], v[84:87]
	v_mfma_f32_16x16x32_bf16 v[80:83], v[210:213], v[234:237], v[80:83]
	v_mfma_f32_16x16x32_bf16 v[80:83], v[214:217], v[238:241], v[80:83]
	v_mfma_f32_16x16x32_bf16 v[68:71], v[202:205], v[242:245], v[68:71]
	v_mfma_f32_16x16x32_bf16 v[68:71], v[206:209], v[246:249], v[68:71]
	v_mfma_f32_16x16x32_bf16 v[64:67], v[210:213], v[242:245], v[64:67]
	v_mfma_f32_16x16x32_bf16 v[64:67], v[214:217], v[246:249], v[64:67]
	s_setprio 0
	s_add_u32 s60, s92, 0x80000
	s_addc_u32 s61, s93, 0
	s_add_i32 s59, s59, s19
	v_lshl_add_u64 v[170:171], s[60:61], 0, v[130:131]
	s_mov_b32 m0, s59
	ds_read_b128 v[218:221], v193 offset:49152
	ds_read_b128 v[222:225], v193 offset:50176
	ds_read_b128 v[226:229], v193 offset:51200
	ds_read_b128 v[230:233], v193 offset:52224
	ds_read_b128 v[234:237], v193 offset:53248
	ds_read_b128 v[238:241], v193 offset:54272
	ds_read_b128 v[242:245], v193 offset:55296
	ds_read_b128 v[246:249], v193 offset:56320
	global_load_lds_dwordx4 v[170:171], off
	s_add_i32 m0, s59, 0x2000
	v_lshl_add_u64 v[170:171], s[60:61], 0, v[134:135]
	s_add_u32 s60, s92, 0x84000
	s_addc_u32 s61, s93, 0
	s_add_i32 s59, s64, s19
	global_load_lds_dwordx4 v[170:171], off
	v_lshl_add_u64 v[170:171], s[60:61], 0, v[130:131]
	s_mov_b32 m0, s59
	s_nop 0
	global_load_lds_dwordx4 v[170:171], off
	v_lshl_add_u64 v[170:171], s[60:61], 0, v[134:135]
	s_add_i32 m0, s59, 0x2000
	s_nop 0
	global_load_lds_dwordx4 v[170:171], off
	v_lshl_add_u64 v[170:171], s[82:83], 0, v[128:129]
	s_mov_b32 m0, s30
	s_nop 0
	global_load_lds_dwordx4 v[170:171], off
	v_lshl_add_u64 v[170:171], s[82:83], 0, v[132:133]
	s_mov_b32 m0, s31
	s_nop 0
	global_load_lds_dwordx4 v[170:171], off
	s_waitcnt vmcnt(8)
	s_waitcnt lgkmcnt(0)
	s_barrier
	s_setprio 2
	s_waitcnt lgkmcnt(0)
	v_mfma_f32_16x16x32_bf16 v[60:63], v[158:161], v[218:221], v[60:63]
	v_mfma_f32_16x16x32_bf16 v[60:63], v[162:165], v[222:225], v[60:63]
	v_mfma_f32_16x16x32_bf16 v[56:59], v[166:169], v[218:221], v[56:59]
	v_mfma_f32_16x16x32_bf16 v[56:59], v[198:201], v[222:225], v[56:59]
	v_mfma_f32_16x16x32_bf16 v[44:47], v[158:161], v[226:229], v[44:47]
	v_mfma_f32_16x16x32_bf16 v[44:47], v[162:165], v[230:233], v[44:47]
	v_mfma_f32_16x16x32_bf16 v[40:43], v[166:169], v[226:229], v[40:43]
	v_mfma_f32_16x16x32_bf16 v[40:43], v[198:201], v[230:233], v[40:43]
	v_mfma_f32_16x16x32_bf16 v[28:31], v[158:161], v[234:237], v[28:31]
	v_mfma_f32_16x16x32_bf16 v[28:31], v[162:165], v[238:241], v[28:31]
	v_mfma_f32_16x16x32_bf16 v[24:27], v[166:169], v[234:237], v[24:27]
	v_mfma_f32_16x16x32_bf16 v[24:27], v[198:201], v[238:241], v[24:27]
	v_mfma_f32_16x16x32_bf16 v[12:15], v[158:161], v[242:245], v[12:15]
	v_mfma_f32_16x16x32_bf16 v[12:15], v[162:165], v[246:249], v[12:15]
	v_mfma_f32_16x16x32_bf16 v[8:11], v[166:169], v[242:245], v[8:11]
	v_mfma_f32_16x16x32_bf16 v[8:11], v[198:201], v[246:249], v[8:11]
	s_setprio 0
	s_setprio 2
	v_mfma_f32_16x16x32_bf16 v[52:55], v[202:205], v[218:221], v[52:55]
	v_mfma_f32_16x16x32_bf16 v[52:55], v[206:209], v[222:225], v[52:55]
	v_mfma_f32_16x16x32_bf16 v[48:51], v[210:213], v[218:221], v[48:51]
	v_mfma_f32_16x16x32_bf16 v[48:51], v[214:217], v[222:225], v[48:51]
	v_mfma_f32_16x16x32_bf16 v[36:39], v[202:205], v[226:229], v[36:39]
	v_mfma_f32_16x16x32_bf16 v[36:39], v[206:209], v[230:233], v[36:39]
	v_mfma_f32_16x16x32_bf16 v[32:35], v[210:213], v[226:229], v[32:35]
	v_mfma_f32_16x16x32_bf16 v[32:35], v[214:217], v[230:233], v[32:35]
	v_mfma_f32_16x16x32_bf16 v[20:23], v[202:205], v[234:237], v[20:23]
	v_mfma_f32_16x16x32_bf16 v[20:23], v[206:209], v[238:241], v[20:23]
	v_mfma_f32_16x16x32_bf16 v[16:19], v[210:213], v[234:237], v[16:19]
	v_mfma_f32_16x16x32_bf16 v[16:19], v[214:217], v[238:241], v[16:19]
	v_mfma_f32_16x16x32_bf16 v[4:7], v[202:205], v[242:245], v[4:7]
	v_mfma_f32_16x16x32_bf16 v[4:7], v[206:209], v[246:249], v[4:7]
	v_mfma_f32_16x16x32_bf16 v[0:3], v[210:213], v[242:245], v[0:3]
	v_mfma_f32_16x16x32_bf16 v[0:3], v[214:217], v[246:249], v[0:3]
	s_setprio 0
	s_add_i32 s58, s58, 2
	s_add_u32 s55, s55, 0x100000
	s_addc_u32 s57, s57, 0
	s_add_u32 s16, s16, 0x400000
	s_addc_u32 s17, s17, 0
	s_cmp_gt_u32 s58, 29
	s_cbranch_scc0 .Lp3_kloop_y
.Lp3_kloop_done:
	s_and_b64 vcc, exec, s[68:69]
	s_cbranch_vccz .LBB0_350

; #define PG8_BAR __builtin_amdgcn_s_barrier()
; template <bool ALIGN_EPI, class Epi, class Sched>
; __device__ __forceinline__ void gemm_phase(LAS unsigned char* lds, const int lda, const int ldb, const int K, const Sched& S, const Epi& E, const size_t kstepA = (size_t)(BK * 2), const size_t kstepB = (size_t)(BK * 2)) {
;     ...
;         cur = nxt; cA = nA; cB = nB; ++ui;
;         if constexpr (ALIGN_EPI) { if (wr == 1) PG8_BAR; }
;     }
.LBB0_419:
	s_andn2_b64 vcc, exec, s[66:67]
	s_cbranch_vccnz .LBB0_338
	s_branch .LBB0_338

; #define PG8_STAGE(bufoff, gbase, voff) do { _Pragma("unroll") for (int _i = 0; _i < 2; ++_i) \
;         __builtin_amdgcn_global_load_lds((const unsigned*)((const char*)(gbase) + (voff)[_i]), (LAS unsigned*)(lds + (bufoff) + ldsw + _i * 8192), 16, 0, 0); } while (0)
; #define PG8_WAIT_V(n) asm volatile("s_waitcnt vmcnt(" #n ")" ::: "memory")
; #define PG8_BAR __builtin_amdgcn_s_barrier()
;     __device__ bool next(int i, Unit& u) const { if (i > 0 || c >= 32 || c < 0) return false; u.pm = c & 1; u.pn = c >> 1; u.z = 0; u.o = 0; u.a = A + (size_t)u.pm * 256 * D * 2; u.b = B + (size_t)u.pn * 256 * D * 2; return true; }
; template <bool ALIGN_EPI, class Epi, class Sched>
; __device__ __forceinline__ void gemm_phase(LAS unsigned char* lds, const int lda, const int ldb, const int K, const Sched& S, const Epi& E, const size_t kstepA = (size_t)(BK * 2), const size_t kstepB = (size_t)(BK * 2)) {
;     ...
;     for (int i = 0; i < 2; ++i) { int R, C; stage_rc(tid * 16 + i * 8192, R, C); const int Rb = (R & ~31) + perm32(R & 31);
;         voffA[i] = (unsigned)(R * lda + C) * 2u; voffB[i] = (unsigned)(Rb * ldb + C) * 2u; }
;     const size_t kstep = kstepB;
;     const size_t hstepA = (size_t)HALF * lda * 2, hstepB = (size_t)HALF * ldb * 2;
;     const unsigned ldsw = (unsigned)wid * 1024u;
;     const int aoff = lds_byte(wr * 64 + fr, fq * 8), boff = lds_byte(wc * 32 + fr, fq * 8);
;     ...
;     Unit cur, nxt; int ui = 0;
;     if (!S.next(0, cur)) return;
;     f32x4 acc[2][2][4][2];
; #pragma unroll
;     for (int a = 0; a < 2; ++a)
; #pragma unroll
;         for (int b = 0; b < 2; ++b)
; #pragma unroll
;             for (int m = 0; m < 4; ++m)
; #pragma unroll
;                 for (int n = 0; n < 2; ++n) acc[a][b][m][n] = (f32x4){0.f, 0.f, 0.f, 0.f};
;     bf16x8 At[4][2], B0[2][2], B1[2][2];
;     const char* cA = cur.a; const char* cB = cur.b;
;     PG8_STAGE(PG8_SB(0, 0), cB, voffB); PG8_STAGE(PG8_SB(0, 1), cB + hstepB, voffB); PG8_STAGE(PG8_SA(0, 0), cA, voffA); PG8_STAGE(PG8_SA(0, 1), cA + hstepA, voffA);
;     if (wr == 1) PG8_BAR;
;     PG8_WAIT_V(2); PG8_BAR;
;     PG8_STAGE(PG8_SB(1, 0), cB + kstep, voffB); PG8_STAGE(PG8_SA(1, 0), cA + kstepA, voffA); PG8_STAGE(PG8_SB(1, 1), cB + hstepB + kstep, voffB);
;     PG8_WAIT_V(6); PG8_BAR;
.LBB0_714:
	v_bfe_i32 v2, v0, 27, 1
	v_lshlrev_b32_e32 v4, 4, v0
	v_lshrrev_b32_e32 v2, 22, v2
	v_ashrrev_i32_e32 v1, 31, v0
	v_add_u32_e32 v2, v4, v2
	v_lshrrev_b32_e32 v1, 26, v1
	v_and_b32_e32 v2, 0xfffffc00, v2
	v_add_u32_e32 v1, v0, v1
	v_sub_u32_e32 v2, v4, v2
	v_ashrrev_i32_e32 v1, 6, v1
	v_lshrrev_b32_e32 v3, 4, v2
	v_bitop3_b32 v3, v3, v2, 32 bitop3:0x6c
	v_lshlrev_b32_e32 v2, 3, v1
	v_and_b32_e32 v5, -16, v2
	v_ashrrev_i32_e32 v2, 31, v3
	v_lshrrev_b32_e32 v2, 26, v2
	v_add_u32_e32 v6, v3, v2
	v_ashrrev_i32_e32 v2, 6, v6
	v_and_b32_e32 v6, 0xc0, v6
	v_sub_u32_e32 v3, v3, v6
	v_mov_b32_e32 v6, 1
	v_lshlrev_b32_e32 v7, 5, v1
	v_ashrrev_i16_sdwa v3, v6, sext(v3) dst_sel:DWORD dst_unused:UNUSED_PAD src0_sel:DWORD src1_sel:BYTE_0
	v_and_b32_e32 v7, 32, v7
	v_bfe_i32 v3, v3, 0, 16
	v_add_u32_e32 v5, v2, v5
	v_and_b32_e32 v10, 3, v2
	s_mov_b32 s1, 0x1ffffe0
	v_add_lshl_u32 v7, v7, v3, 1
	v_lshlrev_b32_e32 v8, 1, v5
	v_lshrrev_b32_e32 v9, 2, v5
	v_and_or_b32 v10, v5, s1, v10
	v_lshl_add_u32 v168, v5, 7, v7
	v_add_u32_e32 v5, 0x2000, v4
	v_ashrrev_i32_e32 v4, 31, v5
	v_lshrrev_b32_e32 v4, 22, v4
	v_and_b32_e32 v8, 24, v8
	v_and_b32_e32 v9, 4, v9
	v_add_u32_e32 v4, v5, v4
	v_or3_b32 v8, v10, v9, v8
	v_ashrrev_i32_e32 v4, 10, v4
	v_lshl_add_u32 v170, v8, 7, v7
	v_mul_i32_i24_e32 v7, 0x400, v4
	v_sub_u32_e32 v5, v5, v7
	v_lshrrev_b32_e32 v7, 4, v5
	v_bitop3_b32 v7, v7, v5, 32 bitop3:0x6c
	v_lshlrev_b32_e32 v5, 3, v4
	v_and_b32_e32 v8, -16, v5
	v_ashrrev_i32_e32 v5, 31, v7
	v_lshrrev_b32_e32 v5, 26, v5
	v_add_u32_e32 v9, v7, v5
	s_ashr_i32 s0, s6, 6
	v_ashrrev_i32_e32 v5, 6, v9
	v_and_b32_e32 v9, 0xc0, v9
	v_add_u32_e32 v8, v5, v8
	v_sub_u32_e32 v7, v7, v9
	s_lshl_b32 s18, s0, 10
	v_lshlrev_b32_e32 v10, 5, v4
	v_ashrrev_i16_sdwa v6, v6, sext(v7) dst_sel:DWORD dst_unused:UNUSED_PAD src0_sel:DWORD src1_sel:BYTE_0
	v_lshlrev_b32_e32 v7, 1, v8
	v_lshrrev_b32_e32 v9, 2, v8
	v_and_b32_e32 v11, 3, v5
	s_add_i32 s19, s18, 0
	v_and_b32_e32 v10, 32, v10
	v_bfe_i32 v6, v6, 0, 16
	v_and_b32_e32 v7, 24, v7
	v_and_b32_e32 v9, 4, v9
	v_and_or_b32 v11, v8, s1, v11
	s_add_i32 m0, s19, 0x10000
	v_or3_b32 v7, v11, v9, v7
	v_add_lshl_u32 v9, v10, v6, 1
	s_ashr_i32 s1, s6, 8
	global_load_lds_dwordx4 v170, s[14:15]
	s_add_i32 m0, s19, 0x12000
	v_lshl_add_u32 v174, v7, 7, v9
	s_add_u32 s8, s14, 0x4000
	global_load_lds_dwordx4 v174, s[14:15]
	s_addc_u32 s9, s15, 0
	s_add_i32 m0, s19, 0x14000
	s_add_i32 s30, s19, 0x2000
	global_load_lds_dwordx4 v170, s[8:9]
	s_add_i32 m0, s19, 0x16000
	v_lshl_add_u32 v172, v8, 7, v9
	global_load_lds_dwordx4 v174, s[8:9]
	s_mov_b32 m0, s19
	s_add_u32 s8, s12, 0x4000
	global_load_lds_dwordx4 v168, s[12:13]
	s_mov_b32 m0, s30
	s_addc_u32 s9, s13, 0
	s_add_i32 s33, s19, 0x4000
	global_load_lds_dwordx4 v172, s[12:13]
	s_mov_b32 m0, s33
	s_add_i32 s42, s19, 0x6000
	global_load_lds_dwordx4 v168, s[8:9]
	s_mov_b32 m0, s42
	v_mov_b32_e32 v177, 0
	global_load_lds_dwordx4 v172, s[8:9]
	s_cmp_eq_u32 s1, 1
	s_mov_b32 s49, 0
	v_mov_b32_e32 v171, v177
	v_mov_b32_e32 v175, v177
	s_mov_b64 s[52:53], 0x4000
	v_mov_b32_e32 v169, v177
	s_cselect_b64 s[54:55], -1, 0
	s_cmp_lg_u32 s1, 1
	v_mov_b32_e32 v173, v177
	s_cbranch_scc1 .LBB0_716
.LBB0_716:
	s_and_b32 s43, s0, 3
	s_lshl_b32 s0, s1, 13
	s_lshl_b32 s50, s43, 5
	s_lshl_b32 s7, s43, 12
	s_add_u32 s8, s14, 0x40000
	s_addc_u32 s9, s15, 0
	s_add_i32 m0, s19, 0x18000
	v_lshl_add_u64 v[8:9], s[8:9], 0, v[170:171]
	s_waitcnt vmcnt(2)
	s_barrier
	global_load_lds_dwordx4 v[8:9], off
	s_add_i32 m0, s19, 0x1a000
	v_lshl_add_u64 v[8:9], s[8:9], 0, v[174:175]
	s_add_u32 s8, s12, 0x200000
	s_addc_u32 s9, s13, 0
	s_add_i32 s51, s19, 0x8000
	global_load_lds_dwordx4 v[8:9], off
	v_lshl_add_u64 v[8:9], s[8:9], 0, v[168:169]
	s_mov_b32 m0, s51
	s_add_i32 s64, s19, 0xa000
	global_load_lds_dwordx4 v[8:9], off
	v_lshl_add_u64 v[8:9], s[8:9], 0, v[172:173]
	s_add_u32 s8, s14, 0x44000
	s_mov_b32 m0, s64
	s_addc_u32 s9, s15, 0
	global_load_lds_dwordx4 v[8:9], off
	s_add_i32 m0, s19, 0x1c000
	v_lshl_add_u64 v[8:9], s[8:9], 0, v[170:171]
	global_load_lds_dwordx4 v[8:9], off
	v_lshl_add_u64 v[8:9], s[8:9], 0, v[174:175]
	s_add_i32 m0, s19, 0x1e000
	v_bfe_u32 v7, v0, 4, 2
	global_load_lds_dwordx4 v[8:9], off
	v_and_b32_e32 v8, 15, v0
	v_lshlrev_b32_e32 v9, 4, v7
	v_lshlrev_b32_e32 v0, 2, v0
	v_lshl_or_b32 v216, s1, 6, v8
	v_lshl_or_b32 v8, v8, 6, v9
	v_and_b32_e32 v0, 32, v0
	v_bitop3_b32 v9, v8, s0, v0 bitop3:0xde
	v_bitop3_b32 v218, v8, s7, v0 bitop3:0xde
	v_lshlrev_b32_e32 v0, 10, v1
	v_and_b32_e32 v0, 0xfffff800, v0
	v_lshl_add_u32 v0, v2, 7, v0
	v_and_b32_e32 v1, 1, v1
	v_lshl_or_b32 v0, v1, 6, v0
	v_lshl_add_u32 v178, v3, 1, v0
	v_lshlrev_b32_e32 v0, 10, v4
	v_and_b32_e32 v0, 0xfffff800, v0
	s_waitcnt vmcnt(6)
	s_cmpk_lt_u32 s6, 0x100
	v_lshl_add_u32 v0, v5, 7, v0
	v_and_b32_e32 v1, 1, v4
	s_cselect_b64 s[56:57], -1, 0
	v_lshl_or_b32 v0, v1, 6, v0
	s_add_i32 s65, 0, 0x10000
	s_add_i32 s74, 0, 0x14000
	v_lshlrev_b32_e32 v217, 3, v7
	v_cmp_eq_u32_e64 s[8:9], 0, v7
	v_mov_b32_e32 v179, v177
	v_lshl_add_u32 v180, v6, 1, v0
	v_mov_b32_e32 v181, v177
	v_mov_b64_e32 v[182:183], 0x200
	v_mov_b64_e32 v[186:187], 0x1ff
	v_add_u32_e32 v219, s65, v218
	v_add_u32_e32 v220, s74, v218
	v_add_u32_e32 v221, 0, v9
	v_mbcnt_hi_u32_b32 v222, -1, v185
	s_mov_b64 s[58:59], 0x4800
	s_mov_b64 s[60:61], 0x5000
	s_mov_b64 s[62:63], 0x5800
	s_mov_b32 s75, 0
	s_barrier
	s_branch .LBB0_719

; #define PG8_STAGE(bufoff, gbase, voff) do { _Pragma("unroll") for (int _i = 0; _i < 2; ++_i) \
;         __builtin_amdgcn_global_load_lds((const unsigned*)((const char*)(gbase) + (voff)[_i]), (LAS unsigned*)(lds + (bufoff) + ldsw + _i * 8192), 16, 0, 0); } while (0)
; #define PG8_LDA(dst, b, h) do { _Pragma("unroll") for (int m = 0; m < 4; ++m) _Pragma("unroll") for (int k = 0; k < 2; ++k) dst[m][k] = *(const LAS bf16x8*)(lds + PG8_SA(b, h) + aoff + m * 2048 + k * 1024); } while (0)
; #define PG8_LDB(dst, b, h) do { _Pragma("unroll") for (int n = 0; n < 2; ++n) _Pragma("unroll") for (int k = 0; k < 2; ++k) dst[n][k] = *(const LAS bf16x8*)(lds + PG8_SB(b, h) + boff + n * 2048 + k * 1024); } while (0)
; #define PG8_MMA(ai, bj, At, Bt) do { __builtin_amdgcn_s_setprio(1); _Pragma("unroll") for (int m = 0; m < 4; ++m) _Pragma("unroll") for (int n = 0; n < 2; ++n) _Pragma("unroll") for (int k = 0; k < 2; ++k) \
;         acc[ai][bj][m][n] = __builtin_amdgcn_mfma_f32_16x16x32_bf16(Bt[n][k], At[m][k], acc[ai][bj][m][n], 0, 0, 0); __builtin_amdgcn_s_setprio(0); } while (0)
; #define PG8_WAIT_V(n) asm volatile("s_waitcnt vmcnt(" #n ")" ::: "memory")
; #define PG8_WAIT_L(n) asm volatile("s_waitcnt lgkmcnt(" #n ")" ::: "memory")
; #define PG8_BAR __builtin_amdgcn_s_barrier()
; #define PG8_SCHED __builtin_amdgcn_sched_barrier(0)
; template <bool ALIGN_EPI, class Epi, class Sched>
; __device__ __forceinline__ void gemm_phase(LAS unsigned char* lds, const int lda, const int ldb, const int K, const Sched& S, const Epi& E, const size_t kstepA = (size_t)(BK * 2), const size_t kstepB = (size_t)(BK * 2)) {
;     ...
;             PG8_LDB(B0, 0, 0); PG8_LDB(B1, 0, 1); PG8_SCHED; PG8_LDA(At, 0, 0); PG8_STAGE(PG8_SA(1, 1), a1 + hstepA, voffA);
;             PG8_WAIT_V(8); PG8_WAIT_L(0); PG8_BAR; PG8_MMA(0, 0, At, B0); PG8_MMA(0, 1, At, B1); PG8_BAR; PG8_SCHED;
;     ...
; #pragma unroll
;         for (int a = 0; a < 2; ++a)
; #pragma unroll
;             for (int b = 0; b < 2; ++b)
; #pragma unroll
;                 for (int m = 0; m < 4; ++m)
; #pragma unroll
;                     for (int n = 0; n < 2; ++n) acc[a][b][m][n] = (f32x4){0.f, 0.f, 0.f, 0.f};
;         cur = nxt; cA = nA; cB = nB; ++ui;
.LBB0_725:
	s_add_u32 s22, s14, 0x80000
	s_addc_u32 s23, s15, 0
	s_add_u32 s12, s12, 0x204000
	v_mov_b32_e32 v0, 0
	s_addc_u32 s13, s13, 0
	s_mov_b32 s67, -2
	s_waitcnt lgkmcnt(0)
	v_mov_b32_e32 v1, v0
	v_mov_b32_e32 v2, v0
	v_mov_b32_e32 v3, v0
	v_mov_b32_e32 v4, v0
	v_mov_b32_e32 v5, v0
	v_mov_b32_e32 v6, v0
	v_mov_b32_e32 v7, v0
	v_mov_b32_e32 v16, v0
	v_mov_b32_e32 v17, v0
	v_mov_b32_e32 v18, v0
	v_mov_b32_e32 v19, v0
	v_mov_b32_e32 v20, v0
	v_mov_b32_e32 v21, v0
	v_mov_b32_e32 v22, v0
	v_mov_b32_e32 v23, v0
	v_mov_b32_e32 v32, v0
	v_mov_b32_e32 v33, v0
	v_mov_b32_e32 v34, v0
	v_mov_b32_e32 v35, v0
	v_mov_b32_e32 v36, v0
	v_mov_b32_e32 v37, v0
	v_mov_b32_e32 v38, v0
	v_mov_b32_e32 v39, v0
	v_mov_b32_e32 v48, v0
	v_mov_b32_e32 v49, v0
	v_mov_b32_e32 v50, v0
	v_mov_b32_e32 v51, v0
	v_mov_b32_e32 v52, v0
	v_mov_b32_e32 v53, v0
	v_mov_b32_e32 v54, v0
	v_mov_b32_e32 v55, v0
	v_mov_b32_e32 v8, v0
	v_mov_b32_e32 v9, v0
	v_mov_b32_e32 v10, v0
	v_mov_b32_e32 v11, v0
	v_mov_b32_e32 v12, v0
	v_mov_b32_e32 v13, v0
	v_mov_b32_e32 v14, v0
	v_mov_b32_e32 v15, v0
	v_mov_b32_e32 v24, v0
	v_mov_b32_e32 v25, v0
	v_mov_b32_e32 v26, v0
	v_mov_b32_e32 v27, v0
	v_mov_b32_e32 v28, v0
	v_mov_b32_e32 v29, v0
	v_mov_b32_e32 v30, v0
	v_mov_b32_e32 v31, v0
	v_mov_b32_e32 v40, v0
	v_mov_b32_e32 v41, v0
	v_mov_b32_e32 v42, v0
	v_mov_b32_e32 v43, v0
	v_mov_b32_e32 v44, v0
	v_mov_b32_e32 v45, v0
	v_mov_b32_e32 v46, v0
	v_mov_b32_e32 v47, v0
	v_mov_b32_e32 v56, v0
	v_mov_b32_e32 v57, v0
	v_mov_b32_e32 v58, v0
	v_mov_b32_e32 v59, v0
	v_mov_b32_e32 v60, v0
	v_mov_b32_e32 v61, v0
	v_mov_b32_e32 v62, v0
	v_mov_b32_e32 v63, v0
	v_mov_b32_e32 v64, v0
	v_mov_b32_e32 v65, v0
	v_mov_b32_e32 v66, v0
	v_mov_b32_e32 v67, v0
	v_mov_b32_e32 v68, v0
	v_mov_b32_e32 v69, v0
	v_mov_b32_e32 v70, v0
	v_mov_b32_e32 v71, v0
	v_mov_b32_e32 v80, v0
	v_mov_b32_e32 v81, v0
	v_mov_b32_e32 v82, v0
	v_mov_b32_e32 v83, v0
	v_mov_b32_e32 v84, v0
	v_mov_b32_e32 v85, v0
	v_mov_b32_e32 v86, v0
	v_mov_b32_e32 v87, v0
	v_mov_b32_e32 v104, v0
	v_mov_b32_e32 v105, v0
	v_mov_b32_e32 v106, v0
	v_mov_b32_e32 v107, v0
	v_mov_b32_e32 v108, v0
	v_mov_b32_e32 v109, v0
	v_mov_b32_e32 v110, v0
	v_mov_b32_e32 v111, v0
	v_mov_b32_e32 v128, v0
	v_mov_b32_e32 v129, v0
	v_mov_b32_e32 v130, v0
	v_mov_b32_e32 v131, v0
	v_mov_b32_e32 v132, v0
	v_mov_b32_e32 v133, v0
	v_mov_b32_e32 v134, v0
	v_mov_b32_e32 v135, v0
	v_mov_b32_e32 v72, v0
	v_mov_b32_e32 v73, v0
	v_mov_b32_e32 v74, v0
	v_mov_b32_e32 v75, v0
	v_mov_b32_e32 v76, v0
	v_mov_b32_e32 v77, v0
	v_mov_b32_e32 v78, v0
	v_mov_b32_e32 v79, v0
	v_mov_b32_e32 v96, v0
	v_mov_b32_e32 v97, v0
	v_mov_b32_e32 v98, v0
	v_mov_b32_e32 v99, v0
	v_mov_b32_e32 v100, v0
	v_mov_b32_e32 v101, v0
	v_mov_b32_e32 v102, v0
	v_mov_b32_e32 v103, v0
	v_mov_b32_e32 v120, v0
	v_mov_b32_e32 v121, v0
	v_mov_b32_e32 v122, v0
	v_mov_b32_e32 v123, v0
	v_mov_b32_e32 v124, v0
	v_mov_b32_e32 v125, v0
	v_mov_b32_e32 v126, v0
	v_mov_b32_e32 v127, v0
	v_mov_b32_e32 v136, v0
	v_mov_b32_e32 v137, v0
	v_mov_b32_e32 v138, v0
	v_mov_b32_e32 v139, v0
	v_mov_b32_e32 v140, v0
	v_mov_b32_e32 v141, v0
	v_mov_b32_e32 v142, v0
	v_mov_b32_e32 v143, v0
	s_cmp_lg_u64 s[56:57], 0
	s_cbranch_scc0 .Lp7_kloop_y
.LBB0_726:
	ds_read_b128 v[88:91], v219
	ds_read_b128 v[92:95], v219 offset:1024
	ds_read_b128 v[112:115], v219 offset:2048
	ds_read_b128 v[116:119], v219 offset:3072
	ds_read_b128 v[144:147], v220
	ds_read_b128 v[148:151], v220 offset:1024
	ds_read_b128 v[152:155], v220 offset:2048
	ds_read_b128 v[156:159], v220 offset:3072
	s_add_u32 s14, s12, 0x1fc000
	s_addc_u32 s15, s13, 0
	s_cmp_eq_u32 s67, 28
	s_cselect_b32 s20, s0, s14
	s_cselect_b32 s21, s1, s15
	s_cselect_b32 s16, s6, s22
	s_cselect_b32 s17, s7, s23
	s_add_u32 s14, s20, 0x200000
	s_addc_u32 s15, s21, 0
	v_lshl_add_u64 v[212:213], s[12:13], 0, v[178:179]
	s_add_i32 m0, s19, 0xc000
	ds_read_b128 v[160:163], v221
	ds_read_b128 v[164:167], v221 offset:1024
	ds_read_b128 v[188:191], v221 offset:2048
	ds_read_b128 v[192:195], v221 offset:3072
	ds_read_b128 v[196:199], v221 offset:4096
	ds_read_b128 v[200:203], v221 offset:5120
	ds_read_b128 v[204:207], v221 offset:6144
	ds_read_b128 v[208:211], v221 offset:7168
	global_load_lds_dwordx4 v[212:213], off
	v_lshl_add_u64 v[212:213], s[12:13], 0, v[180:181]
	s_add_i32 m0, s19, 0xe000
	s_nop 0
	global_load_lds_dwordx4 v[212:213], off
	s_waitcnt vmcnt(8)
	s_waitcnt lgkmcnt(0)
	s_setprio 1
	s_waitcnt lgkmcnt(0)
	v_mfma_f32_16x16x32_bf16 v[140:143], v[88:91], v[160:163], v[140:143]
	v_mfma_f32_16x16x32_bf16 v[140:143], v[92:95], v[164:167], v[140:143]
	v_mfma_f32_16x16x32_bf16 v[136:139], v[112:115], v[160:163], v[136:139]
	v_mfma_f32_16x16x32_bf16 v[136:139], v[116:119], v[164:167], v[136:139]
	v_mfma_f32_16x16x32_bf16 v[124:127], v[88:91], v[188:191], v[124:127]
	v_mfma_f32_16x16x32_bf16 v[124:127], v[92:95], v[192:195], v[124:127]
	v_mfma_f32_16x16x32_bf16 v[120:123], v[112:115], v[188:191], v[120:123]
	v_mfma_f32_16x16x32_bf16 v[120:123], v[116:119], v[192:195], v[120:123]
	v_mfma_f32_16x16x32_bf16 v[100:103], v[88:91], v[196:199], v[100:103]
	v_mfma_f32_16x16x32_bf16 v[100:103], v[92:95], v[200:203], v[100:103]
	v_mfma_f32_16x16x32_bf16 v[96:99], v[112:115], v[196:199], v[96:99]
	v_mfma_f32_16x16x32_bf16 v[96:99], v[116:119], v[200:203], v[96:99]
	v_mfma_f32_16x16x32_bf16 v[76:79], v[88:91], v[204:207], v[76:79]
	v_mfma_f32_16x16x32_bf16 v[76:79], v[92:95], v[208:211], v[76:79]
	v_mfma_f32_16x16x32_bf16 v[72:75], v[112:115], v[204:207], v[72:75]
	v_mfma_f32_16x16x32_bf16 v[72:75], v[116:119], v[208:211], v[72:75]
	s_setprio 0
	s_setprio 1
	v_mfma_f32_16x16x32_bf16 v[132:135], v[144:147], v[160:163], v[132:135]
	v_mfma_f32_16x16x32_bf16 v[132:135], v[148:151], v[164:167], v[132:135]
	v_mfma_f32_16x16x32_bf16 v[128:131], v[152:155], v[160:163], v[128:131]
	v_mfma_f32_16x16x32_bf16 v[128:131], v[156:159], v[164:167], v[128:131]
	v_mfma_f32_16x16x32_bf16 v[108:111], v[144:147], v[188:191], v[108:111]
	v_mfma_f32_16x16x32_bf16 v[108:111], v[148:151], v[192:195], v[108:111]
	v_mfma_f32_16x16x32_bf16 v[104:107], v[152:155], v[188:191], v[104:107]
	v_mfma_f32_16x16x32_bf16 v[104:107], v[156:159], v[192:195], v[104:107]
	v_mfma_f32_16x16x32_bf16 v[84:87], v[144:147], v[196:199], v[84:87]
	v_mfma_f32_16x16x32_bf16 v[84:87], v[148:151], v[200:203], v[84:87]
	v_mfma_f32_16x16x32_bf16 v[80:83], v[152:155], v[196:199], v[80:83]
	v_mfma_f32_16x16x32_bf16 v[80:83], v[156:159], v[200:203], v[80:83]
	v_mfma_f32_16x16x32_bf16 v[68:71], v[144:147], v[204:207], v[68:71]
	v_mfma_f32_16x16x32_bf16 v[68:71], v[148:151], v[208:211], v[68:71]
	v_mfma_f32_16x16x32_bf16 v[64:67], v[152:155], v[204:207], v[64:67]
	v_mfma_f32_16x16x32_bf16 v[64:67], v[156:159], v[208:211], v[64:67]
	s_setprio 0
	s_barrier
; #define PG8_STAGE(bufoff, gbase, voff) do { _Pragma("unroll") for (int _i = 0; _i < 2; ++_i) \
;         __builtin_amdgcn_global_load_lds((const unsigned*)((const char*)(gbase) + (voff)[_i]), (LAS unsigned*)(lds + (bufoff) + ldsw + _i * 8192), 16, 0, 0); } while (0)
; #define PG8_LDA(dst, b, h) do { _Pragma("unroll") for (int m = 0; m < 4; ++m) _Pragma("unroll") for (int k = 0; k < 2; ++k) dst[m][k] = *(const LAS bf16x8*)(lds + PG8_SA(b, h) + aoff + m * 2048 + k * 1024); } while (0)
; #define PG8_LDB(dst, b, h) do { _Pragma("unroll") for (int n = 0; n < 2; ++n) _Pragma("unroll") for (int k = 0; k < 2; ++k) dst[n][k] = *(const LAS bf16x8*)(lds + PG8_SB(b, h) + boff + n * 2048 + k * 1024); } while (0)
; #define PG8_MMA(ai, bj, At, Bt) do { __builtin_amdgcn_s_setprio(1); _Pragma("unroll") for (int m = 0; m < 4; ++m) _Pragma("unroll") for (int n = 0; n < 2; ++n) _Pragma("unroll") for (int k = 0; k < 2; ++k) \
;         acc[ai][bj][m][n] = __builtin_amdgcn_mfma_f32_16x16x32_bf16(Bt[n][k], At[m][k], acc[ai][bj][m][n], 0, 0, 0); __builtin_amdgcn_s_setprio(0); } while (0)
; #define PG8_WAIT_V(n) asm volatile("s_waitcnt vmcnt(" #n ")" ::: "memory")
; #define PG8_WAIT_L(n) asm volatile("s_waitcnt lgkmcnt(" #n ")" ::: "memory")
; #define PG8_BAR __builtin_amdgcn_s_barrier()
; #define PG8_SCHED __builtin_amdgcn_sched_barrier(0)
; template <bool ALIGN_EPI, class Epi, class Sched>
; __device__ __forceinline__ void gemm_phase(LAS unsigned char* lds, const int lda, const int ldb, const int K, const Sched& S, const Epi& E, const size_t kstepA = (size_t)(BK * 2), const size_t kstepB = (size_t)(BK * 2)) {
;     ...
;             PG8_WAIT_V(8); PG8_WAIT_L(0); PG8_BAR; PG8_MMA(0, 0, At, B0); PG8_MMA(0, 1, At, B1); PG8_BAR; PG8_SCHED;
;             PG8_LDA(At, 0, 1); PG8_STAGE(PG8_SB(0, 0), b2, voffB); PG8_STAGE(PG8_SB(0, 1), b2 + hstepB, voffB); PG8_STAGE(PG8_SA(0, 0), a2, voffA);
;             PG8_WAIT_V(8); PG8_WAIT_L(0); PG8_BAR; PG8_MMA(1, 0, At, B0); PG8_MMA(1, 1, At, B1); PG8_BAR; PG8_SCHED;
;             PG8_LDB(B0, 1, 0); PG8_LDB(B1, 1, 1); PG8_SCHED; PG8_LDA(At, 1, 0); PG8_STAGE(PG8_SA(0, 1), a2 + hstepA, voffA);
;             PG8_WAIT_V(8); PG8_WAIT_L(0); PG8_BAR; PG8_MMA(0, 0, At, B0); PG8_MMA(0, 1, At, B1); PG8_BAR; PG8_SCHED;
	s_add_i32 s69, s65, s18
	v_lshl_add_u64 v[212:213], s[16:17], 0, v[170:171]
	s_mov_b32 m0, s69
	ds_read_b128 v[160:163], v221 offset:16384
	ds_read_b128 v[164:167], v221 offset:17408
	ds_read_b128 v[188:191], v221 offset:18432
	ds_read_b128 v[192:195], v221 offset:19456
	ds_read_b128 v[196:199], v221 offset:20480
	ds_read_b128 v[200:203], v221 offset:21504
	ds_read_b128 v[204:207], v221 offset:22528
	ds_read_b128 v[208:211], v221 offset:23552
	global_load_lds_dwordx4 v[212:213], off
	s_add_i32 m0, s69, 0x2000
	s_add_u32 s78, s16, 0x4000
	v_lshl_add_u64 v[212:213], s[16:17], 0, v[174:175]
	s_addc_u32 s79, s17, 0
	s_add_i32 s69, s74, s18
	global_load_lds_dwordx4 v[212:213], off
	v_lshl_add_u64 v[212:213], s[78:79], 0, v[170:171]
	s_mov_b32 m0, s69
	s_nop 0
	global_load_lds_dwordx4 v[212:213], off
	v_lshl_add_u64 v[212:213], s[78:79], 0, v[174:175]
	s_add_i32 m0, s69, 0x2000
	s_nop 0
	global_load_lds_dwordx4 v[212:213], off
	v_lshl_add_u64 v[212:213], s[20:21], 0, v[168:169]
	s_mov_b32 m0, s19
	s_nop 0
	global_load_lds_dwordx4 v[212:213], off
	v_lshl_add_u64 v[212:213], s[20:21], 0, v[172:173]
	s_mov_b32 m0, s30
	s_nop 0
	global_load_lds_dwordx4 v[212:213], off
	s_waitcnt vmcnt(8)
	s_waitcnt lgkmcnt(0)
	s_setprio 1
	s_waitcnt lgkmcnt(0)
	v_mfma_f32_16x16x32_bf16 v[60:63], v[88:91], v[160:163], v[60:63]
	v_mfma_f32_16x16x32_bf16 v[60:63], v[92:95], v[164:167], v[60:63]
	v_mfma_f32_16x16x32_bf16 v[56:59], v[112:115], v[160:163], v[56:59]
	v_mfma_f32_16x16x32_bf16 v[56:59], v[116:119], v[164:167], v[56:59]
	v_mfma_f32_16x16x32_bf16 v[44:47], v[88:91], v[188:191], v[44:47]
	v_mfma_f32_16x16x32_bf16 v[44:47], v[92:95], v[192:195], v[44:47]
	v_mfma_f32_16x16x32_bf16 v[40:43], v[112:115], v[188:191], v[40:43]
	v_mfma_f32_16x16x32_bf16 v[40:43], v[116:119], v[192:195], v[40:43]
	v_mfma_f32_16x16x32_bf16 v[28:31], v[88:91], v[196:199], v[28:31]
	v_mfma_f32_16x16x32_bf16 v[28:31], v[92:95], v[200:203], v[28:31]
	v_mfma_f32_16x16x32_bf16 v[24:27], v[112:115], v[196:199], v[24:27]
	v_mfma_f32_16x16x32_bf16 v[24:27], v[116:119], v[200:203], v[24:27]
	v_mfma_f32_16x16x32_bf16 v[12:15], v[88:91], v[204:207], v[12:15]
	v_mfma_f32_16x16x32_bf16 v[12:15], v[92:95], v[208:211], v[12:15]
	v_mfma_f32_16x16x32_bf16 v[8:11], v[112:115], v[204:207], v[8:11]
	v_mfma_f32_16x16x32_bf16 v[8:11], v[116:119], v[208:211], v[8:11]
	s_setprio 0
	s_setprio 1
	v_mfma_f32_16x16x32_bf16 v[52:55], v[144:147], v[160:163], v[52:55]
	v_mfma_f32_16x16x32_bf16 v[52:55], v[148:151], v[164:167], v[52:55]
	v_mfma_f32_16x16x32_bf16 v[48:51], v[152:155], v[160:163], v[48:51]
	v_mfma_f32_16x16x32_bf16 v[48:51], v[156:159], v[164:167], v[48:51]
	v_mfma_f32_16x16x32_bf16 v[36:39], v[144:147], v[188:191], v[36:39]
	v_mfma_f32_16x16x32_bf16 v[36:39], v[148:151], v[192:195], v[36:39]
	v_mfma_f32_16x16x32_bf16 v[32:35], v[152:155], v[188:191], v[32:35]
	v_mfma_f32_16x16x32_bf16 v[32:35], v[156:159], v[192:195], v[32:35]
	v_mfma_f32_16x16x32_bf16 v[20:23], v[144:147], v[196:199], v[20:23]
	v_mfma_f32_16x16x32_bf16 v[20:23], v[148:151], v[200:203], v[20:23]
	v_mfma_f32_16x16x32_bf16 v[16:19], v[152:155], v[196:199], v[16:19]
	v_mfma_f32_16x16x32_bf16 v[16:19], v[156:159], v[200:203], v[16:19]
	v_mfma_f32_16x16x32_bf16 v[4:7], v[144:147], v[204:207], v[4:7]
	v_mfma_f32_16x16x32_bf16 v[4:7], v[148:151], v[208:211], v[4:7]
	v_mfma_f32_16x16x32_bf16 v[0:3], v[152:155], v[204:207], v[0:3]
	v_mfma_f32_16x16x32_bf16 v[0:3], v[156:159], v[208:211], v[0:3]
	s_setprio 0
	s_barrier
	s_add_i32 s69, 0, 0x18000
	s_add_i32 s77, 0, 0x1c000
	v_add_u32_e32 v116, s69, v218
	v_add_u32_e32 v156, s77, v218
	ds_read_b128 v[88:91], v116
	ds_read_b128 v[92:95], v116 offset:1024
	ds_read_b128 v[112:115], v116 offset:2048
	ds_read_b128 v[116:119], v116 offset:3072
	ds_read_b128 v[144:147], v156
	ds_read_b128 v[148:151], v156 offset:1024
	ds_read_b128 v[152:155], v156 offset:2048
	ds_read_b128 v[156:159], v156 offset:3072
	s_add_u32 s20, s20, 0x4000
	s_addc_u32 s21, s21, 0
	s_mov_b32 m0, s33
	v_lshl_add_u64 v[212:213], s[20:21], 0, v[168:169]
	ds_read_b128 v[160:163], v221 offset:32768
	ds_read_b128 v[164:167], v221 offset:33792
	ds_read_b128 v[188:191], v221 offset:34816
	ds_read_b128 v[192:195], v221 offset:35840
	ds_read_b128 v[196:199], v221 offset:36864
	ds_read_b128 v[200:203], v221 offset:37888
	ds_read_b128 v[204:207], v221 offset:38912
	ds_read_b128 v[208:211], v221 offset:39936
	global_load_lds_dwordx4 v[212:213], off
	v_lshl_add_u64 v[212:213], s[20:21], 0, v[172:173]
	s_mov_b32 m0, s42
	s_nop 0
	global_load_lds_dwordx4 v[212:213], off
	s_waitcnt vmcnt(8)
	s_waitcnt lgkmcnt(0)
	s_setprio 1
	s_waitcnt lgkmcnt(0)
	v_mfma_f32_16x16x32_bf16 v[140:143], v[88:91], v[160:163], v[140:143]
	v_mfma_f32_16x16x32_bf16 v[140:143], v[92:95], v[164:167], v[140:143]
	v_mfma_f32_16x16x32_bf16 v[136:139], v[112:115], v[160:163], v[136:139]
	v_mfma_f32_16x16x32_bf16 v[136:139], v[116:119], v[164:167], v[136:139]
	v_mfma_f32_16x16x32_bf16 v[124:127], v[88:91], v[188:191], v[124:127]
	v_mfma_f32_16x16x32_bf16 v[124:127], v[92:95], v[192:195], v[124:127]
	v_mfma_f32_16x16x32_bf16 v[120:123], v[112:115], v[188:191], v[120:123]
	v_mfma_f32_16x16x32_bf16 v[120:123], v[116:119], v[192:195], v[120:123]
	v_mfma_f32_16x16x32_bf16 v[100:103], v[88:91], v[196:199], v[100:103]
	v_mfma_f32_16x16x32_bf16 v[100:103], v[92:95], v[200:203], v[100:103]
	v_mfma_f32_16x16x32_bf16 v[96:99], v[112:115], v[196:199], v[96:99]
	v_mfma_f32_16x16x32_bf16 v[96:99], v[116:119], v[200:203], v[96:99]
	v_mfma_f32_16x16x32_bf16 v[76:79], v[88:91], v[204:207], v[76:79]
	v_mfma_f32_16x16x32_bf16 v[76:79], v[92:95], v[208:211], v[76:79]
	v_mfma_f32_16x16x32_bf16 v[72:75], v[112:115], v[204:207], v[72:75]
	v_mfma_f32_16x16x32_bf16 v[72:75], v[116:119], v[208:211], v[72:75]
	s_setprio 0
	s_setprio 1
	v_mfma_f32_16x16x32_bf16 v[132:135], v[144:147], v[160:163], v[132:135]
	v_mfma_f32_16x16x32_bf16 v[132:135], v[148:151], v[164:167], v[132:135]
	v_mfma_f32_16x16x32_bf16 v[128:131], v[152:155], v[160:163], v[128:131]
	v_mfma_f32_16x16x32_bf16 v[128:131], v[156:159], v[164:167], v[128:131]
	v_mfma_f32_16x16x32_bf16 v[108:111], v[144:147], v[188:191], v[108:111]
	v_mfma_f32_16x16x32_bf16 v[108:111], v[148:151], v[192:195], v[108:111]
	v_mfma_f32_16x16x32_bf16 v[104:107], v[152:155], v[188:191], v[104:107]
	v_mfma_f32_16x16x32_bf16 v[104:107], v[156:159], v[192:195], v[104:107]
	v_mfma_f32_16x16x32_bf16 v[84:87], v[144:147], v[196:199], v[84:87]
	v_mfma_f32_16x16x32_bf16 v[84:87], v[148:151], v[200:203], v[84:87]
	v_mfma_f32_16x16x32_bf16 v[80:83], v[152:155], v[196:199], v[80:83]
	v_mfma_f32_16x16x32_bf16 v[80:83], v[156:159], v[200:203], v[80:83]
	v_mfma_f32_16x16x32_bf16 v[68:71], v[144:147], v[204:207], v[68:71]
	v_mfma_f32_16x16x32_bf16 v[68:71], v[148:151], v[208:211], v[68:71]
	v_mfma_f32_16x16x32_bf16 v[64:67], v[152:155], v[204:207], v[64:67]
	v_mfma_f32_16x16x32_bf16 v[64:67], v[156:159], v[208:211], v[64:67]
	s_setprio 0
	s_barrier
; #define PG8_STAGE(bufoff, gbase, voff) do { _Pragma("unroll") for (int _i = 0; _i < 2; ++_i) \
;         __builtin_amdgcn_global_load_lds((const unsigned*)((const char*)(gbase) + (voff)[_i]), (LAS unsigned*)(lds + (bufoff) + ldsw + _i * 8192), 16, 0, 0); } while (0)
; #define PG8_LDA(dst, b, h) do { _Pragma("unroll") for (int m = 0; m < 4; ++m) _Pragma("unroll") for (int k = 0; k < 2; ++k) dst[m][k] = *(const LAS bf16x8*)(lds + PG8_SA(b, h) + aoff + m * 2048 + k * 1024); } while (0)
; #define PG8_LDB(dst, b, h) do { _Pragma("unroll") for (int n = 0; n < 2; ++n) _Pragma("unroll") for (int k = 0; k < 2; ++k) dst[n][k] = *(const LAS bf16x8*)(lds + PG8_SB(b, h) + boff + n * 2048 + k * 1024); } while (0)
; #define PG8_MMA(ai, bj, At, Bt) do { __builtin_amdgcn_s_setprio(1); _Pragma("unroll") for (int m = 0; m < 4; ++m) _Pragma("unroll") for (int n = 0; n < 2; ++n) _Pragma("unroll") for (int k = 0; k < 2; ++k) \
;         acc[ai][bj][m][n] = __builtin_amdgcn_mfma_f32_16x16x32_bf16(Bt[n][k], At[m][k], acc[ai][bj][m][n], 0, 0, 0); __builtin_amdgcn_s_setprio(0); } while (0)
; #define PG8_WAIT_V(n) asm volatile("s_waitcnt vmcnt(" #n ")" ::: "memory")
; #define PG8_WAIT_L(n) asm volatile("s_waitcnt lgkmcnt(" #n ")" ::: "memory")
; #define PG8_BAR __builtin_amdgcn_s_barrier()
; #define PG8_SCHED __builtin_amdgcn_sched_barrier(0)
; template <bool ALIGN_EPI, class Epi, class Sched>
; __device__ __forceinline__ void gemm_phase(LAS unsigned char* lds, const int lda, const int ldb, const int K, const Sched& S, const Epi& E, const size_t kstepA = (size_t)(BK * 2), const size_t kstepB = (size_t)(BK * 2)) {
;     ...
;             PG8_LDB(B0, 0, 0); PG8_LDB(B1, 0, 1); PG8_SCHED; PG8_LDA(At, 0, 0); PG8_STAGE(PG8_SA(1, 1), a1 + hstepA, voffA);
;             PG8_WAIT_V(8); PG8_WAIT_L(0); PG8_BAR; PG8_MMA(0, 0, At, B0); PG8_MMA(0, 1, At, B1); PG8_BAR; PG8_SCHED;
;     ...
;             PG8_LDA(At, 1, 1); PG8_STAGE(PG8_SB(1, 0), b3, voffB); PG8_STAGE(PG8_SB(1, 1), b3 + hstepB, voffB); PG8_STAGE(PG8_SA(1, 0), a3, voffA);
;             PG8_WAIT_V(8); PG8_WAIT_L(0); PG8_BAR; PG8_MMA(1, 0, At, B0); PG8_MMA(1, 1, At, B1); PG8_BAR; PG8_SCHED;
;         }
	s_add_u32 s20, s16, 0x40000
	s_addc_u32 s21, s17, 0
	s_add_i32 s69, s69, s18
	v_lshl_add_u64 v[212:213], s[20:21], 0, v[170:171]
	s_mov_b32 m0, s69
	ds_read_b128 v[160:163], v221 offset:49152
	ds_read_b128 v[164:167], v221 offset:50176
	ds_read_b128 v[188:191], v221 offset:51200
	ds_read_b128 v[192:195], v221 offset:52224
	ds_read_b128 v[196:199], v221 offset:53248
	ds_read_b128 v[200:203], v221 offset:54272
	ds_read_b128 v[204:207], v221 offset:55296
	ds_read_b128 v[208:211], v221 offset:56320
	global_load_lds_dwordx4 v[212:213], off
	s_add_i32 m0, s69, 0x2000
	s_add_u32 s16, s16, 0x44000
	v_lshl_add_u64 v[212:213], s[20:21], 0, v[174:175]
	s_addc_u32 s17, s17, 0
	s_add_i32 s20, s77, s18
	global_load_lds_dwordx4 v[212:213], off
	v_lshl_add_u64 v[212:213], s[16:17], 0, v[170:171]
	s_mov_b32 m0, s20
	s_nop 0
	global_load_lds_dwordx4 v[212:213], off
	v_lshl_add_u64 v[212:213], s[16:17], 0, v[174:175]
	s_add_i32 m0, s20, 0x2000
	s_nop 0
	global_load_lds_dwordx4 v[212:213], off
	v_lshl_add_u64 v[212:213], s[14:15], 0, v[168:169]
	s_mov_b32 m0, s51
	s_nop 0
	global_load_lds_dwordx4 v[212:213], off
	v_lshl_add_u64 v[212:213], s[14:15], 0, v[172:173]
	s_mov_b32 m0, s64
	s_nop 0
	global_load_lds_dwordx4 v[212:213], off
	s_waitcnt vmcnt(8)
	s_waitcnt lgkmcnt(0)
	s_setprio 1
	s_waitcnt lgkmcnt(0)
	v_mfma_f32_16x16x32_bf16 v[60:63], v[88:91], v[160:163], v[60:63]
	v_mfma_f32_16x16x32_bf16 v[60:63], v[92:95], v[164:167], v[60:63]
	v_mfma_f32_16x16x32_bf16 v[56:59], v[112:115], v[160:163], v[56:59]
	v_mfma_f32_16x16x32_bf16 v[56:59], v[116:119], v[164:167], v[56:59]
	v_mfma_f32_16x16x32_bf16 v[44:47], v[88:91], v[188:191], v[44:47]
	v_mfma_f32_16x16x32_bf16 v[44:47], v[92:95], v[192:195], v[44:47]
	v_mfma_f32_16x16x32_bf16 v[40:43], v[112:115], v[188:191], v[40:43]
	v_mfma_f32_16x16x32_bf16 v[40:43], v[116:119], v[192:195], v[40:43]
	v_mfma_f32_16x16x32_bf16 v[28:31], v[88:91], v[196:199], v[28:31]
	v_mfma_f32_16x16x32_bf16 v[28:31], v[92:95], v[200:203], v[28:31]
	v_mfma_f32_16x16x32_bf16 v[24:27], v[112:115], v[196:199], v[24:27]
	v_mfma_f32_16x16x32_bf16 v[24:27], v[116:119], v[200:203], v[24:27]
	v_mfma_f32_16x16x32_bf16 v[12:15], v[88:91], v[204:207], v[12:15]
	v_mfma_f32_16x16x32_bf16 v[12:15], v[92:95], v[208:211], v[12:15]
	v_mfma_f32_16x16x32_bf16 v[8:11], v[112:115], v[204:207], v[8:11]
	v_mfma_f32_16x16x32_bf16 v[8:11], v[116:119], v[208:211], v[8:11]
	s_setprio 0
	s_setprio 1
	v_mfma_f32_16x16x32_bf16 v[52:55], v[144:147], v[160:163], v[52:55]
	v_mfma_f32_16x16x32_bf16 v[52:55], v[148:151], v[164:167], v[52:55]
	v_mfma_f32_16x16x32_bf16 v[48:51], v[152:155], v[160:163], v[48:51]
	v_mfma_f32_16x16x32_bf16 v[48:51], v[156:159], v[164:167], v[48:51]
	v_mfma_f32_16x16x32_bf16 v[36:39], v[144:147], v[188:191], v[36:39]
	v_mfma_f32_16x16x32_bf16 v[36:39], v[148:151], v[192:195], v[36:39]
	v_mfma_f32_16x16x32_bf16 v[32:35], v[152:155], v[188:191], v[32:35]
	v_mfma_f32_16x16x32_bf16 v[32:35], v[156:159], v[192:195], v[32:35]
	v_mfma_f32_16x16x32_bf16 v[20:23], v[144:147], v[196:199], v[20:23]
	v_mfma_f32_16x16x32_bf16 v[20:23], v[148:151], v[200:203], v[20:23]
	v_mfma_f32_16x16x32_bf16 v[16:19], v[152:155], v[196:199], v[16:19]
	v_mfma_f32_16x16x32_bf16 v[16:19], v[156:159], v[200:203], v[16:19]
	v_mfma_f32_16x16x32_bf16 v[4:7], v[144:147], v[204:207], v[4:7]
	v_mfma_f32_16x16x32_bf16 v[4:7], v[148:151], v[208:211], v[4:7]
	v_mfma_f32_16x16x32_bf16 v[0:3], v[152:155], v[204:207], v[0:3]
	v_mfma_f32_16x16x32_bf16 v[0:3], v[156:159], v[208:211], v[0:3]
	s_setprio 0
	s_barrier
	s_add_i32 s67, s67, 2
	s_add_u32 s22, s22, 0x80000
	s_addc_u32 s23, s23, 0
	s_add_u32 s12, s12, 0x400000
	s_addc_u32 s13, s13, 0
	s_cmp_gt_u32 s67, 29
	s_cbranch_scc0 .LBB0_726
	s_branch .Lp7_kloop_done
.Lp7_kloop_y:
	ds_read_b128 v[88:91], v219
	ds_read_b128 v[92:95], v219 offset:1024
	ds_read_b128 v[112:115], v219 offset:2048
	ds_read_b128 v[116:119], v219 offset:3072
	ds_read_b128 v[144:147], v220
	ds_read_b128 v[148:151], v220 offset:1024
	ds_read_b128 v[152:155], v220 offset:2048
	ds_read_b128 v[156:159], v220 offset:3072
	s_add_u32 s14, s12, 0x1fc000
	s_addc_u32 s15, s13, 0
	s_cmp_eq_u32 s67, 28
	s_cselect_b32 s20, s0, s14
	s_cselect_b32 s21, s1, s15
	s_cselect_b32 s16, s6, s22
	s_cselect_b32 s17, s7, s23
	s_add_u32 s14, s20, 0x200000
	s_addc_u32 s15, s21, 0
	v_lshl_add_u64 v[212:213], s[12:13], 0, v[178:179]
	s_add_i32 m0, s19, 0xc000
	ds_read_b128 v[160:163], v221
	ds_read_b128 v[164:167], v221 offset:1024
	ds_read_b128 v[188:191], v221 offset:2048
	ds_read_b128 v[192:195], v221 offset:3072
	ds_read_b128 v[196:199], v221 offset:4096
	ds_read_b128 v[200:203], v221 offset:5120
	ds_read_b128 v[204:207], v221 offset:6144
	ds_read_b128 v[208:211], v221 offset:7168
	global_load_lds_dwordx4 v[212:213], off
	v_lshl_add_u64 v[212:213], s[12:13], 0, v[180:181]
	s_add_i32 m0, s19, 0xe000
	s_nop 0
	global_load_lds_dwordx4 v[212:213], off
	s_waitcnt vmcnt(8)
	s_waitcnt lgkmcnt(0)
	s_barrier
; #define PG8_STAGE(bufoff, gbase, voff) do { _Pragma("unroll") for (int _i = 0; _i < 2; ++_i) \
;         __builtin_amdgcn_global_load_lds((const unsigned*)((const char*)(gbase) + (voff)[_i]), (LAS unsigned*)(lds + (bufoff) + ldsw + _i * 8192), 16, 0, 0); } while (0)
; #define PG8_LDA(dst, b, h) do { _Pragma("unroll") for (int m = 0; m < 4; ++m) _Pragma("unroll") for (int k = 0; k < 2; ++k) dst[m][k] = *(const LAS bf16x8*)(lds + PG8_SA(b, h) + aoff + m * 2048 + k * 1024); } while (0)
; #define PG8_LDB(dst, b, h) do { _Pragma("unroll") for (int n = 0; n < 2; ++n) _Pragma("unroll") for (int k = 0; k < 2; ++k) dst[n][k] = *(const LAS bf16x8*)(lds + PG8_SB(b, h) + boff + n * 2048 + k * 1024); } while (0)
; #define PG8_MMA(ai, bj, At, Bt) do { __builtin_amdgcn_s_setprio(1); _Pragma("unroll") for (int m = 0; m < 4; ++m) _Pragma("unroll") for (int n = 0; n < 2; ++n) _Pragma("unroll") for (int k = 0; k < 2; ++k) \
;         acc[ai][bj][m][n] = __builtin_amdgcn_mfma_f32_16x16x32_bf16(Bt[n][k], At[m][k], acc[ai][bj][m][n], 0, 0, 0); __builtin_amdgcn_s_setprio(0); } while (0)
; #define PG8_WAIT_V(n) asm volatile("s_waitcnt vmcnt(" #n ")" ::: "memory")
; #define PG8_WAIT_L(n) asm volatile("s_waitcnt lgkmcnt(" #n ")" ::: "memory")
; #define PG8_BAR __builtin_amdgcn_s_barrier()
; #define PG8_SCHED __builtin_amdgcn_sched_barrier(0)
; template <bool ALIGN_EPI, class Epi, class Sched>
; __device__ __forceinline__ void gemm_phase(LAS unsigned char* lds, const int lda, const int ldb, const int K, const Sched& S, const Epi& E, const size_t kstepA = (size_t)(BK * 2), const size_t kstepB = (size_t)(BK * 2)) {
;     ...
;             PG8_LDB(B0, 0, 0); PG8_LDB(B1, 0, 1); PG8_SCHED; PG8_LDA(At, 0, 0); PG8_STAGE(PG8_SA(1, 1), a1 + hstepA, voffA);
;             PG8_WAIT_V(8); PG8_WAIT_L(0); PG8_BAR; PG8_MMA(0, 0, At, B0); PG8_MMA(0, 1, At, B1); PG8_BAR; PG8_SCHED;
;             PG8_LDA(At, 0, 1); PG8_STAGE(PG8_SB(0, 0), b2, voffB); PG8_STAGE(PG8_SB(0, 1), b2 + hstepB, voffB); PG8_STAGE(PG8_SA(0, 0), a2, voffA);
;             PG8_WAIT_V(8); PG8_WAIT_L(0); PG8_BAR; PG8_MMA(1, 0, At, B0); PG8_MMA(1, 1, At, B1); PG8_BAR; PG8_SCHED;
;             PG8_LDB(B0, 1, 0); PG8_LDB(B1, 1, 1); PG8_SCHED; PG8_LDA(At, 1, 0); PG8_STAGE(PG8_SA(0, 1), a2 + hstepA, voffA);
;             PG8_WAIT_V(8); PG8_WAIT_L(0); PG8_BAR; PG8_MMA(0, 0, At, B0); PG8_MMA(0, 1, At, B1); PG8_BAR; PG8_SCHED;
	s_setprio 2
	s_waitcnt lgkmcnt(0)
	v_mfma_f32_16x16x32_bf16 v[140:143], v[88:91], v[160:163], v[140:143]
	v_mfma_f32_16x16x32_bf16 v[140:143], v[92:95], v[164:167], v[140:143]
	v_mfma_f32_16x16x32_bf16 v[136:139], v[112:115], v[160:163], v[136:139]
	v_mfma_f32_16x16x32_bf16 v[136:139], v[116:119], v[164:167], v[136:139]
	v_mfma_f32_16x16x32_bf16 v[124:127], v[88:91], v[188:191], v[124:127]
	v_mfma_f32_16x16x32_bf16 v[124:127], v[92:95], v[192:195], v[124:127]
	v_mfma_f32_16x16x32_bf16 v[120:123], v[112:115], v[188:191], v[120:123]
	v_mfma_f32_16x16x32_bf16 v[120:123], v[116:119], v[192:195], v[120:123]
	v_mfma_f32_16x16x32_bf16 v[100:103], v[88:91], v[196:199], v[100:103]
	v_mfma_f32_16x16x32_bf16 v[100:103], v[92:95], v[200:203], v[100:103]
	v_mfma_f32_16x16x32_bf16 v[96:99], v[112:115], v[196:199], v[96:99]
	v_mfma_f32_16x16x32_bf16 v[96:99], v[116:119], v[200:203], v[96:99]
	v_mfma_f32_16x16x32_bf16 v[76:79], v[88:91], v[204:207], v[76:79]
	v_mfma_f32_16x16x32_bf16 v[76:79], v[92:95], v[208:211], v[76:79]
	v_mfma_f32_16x16x32_bf16 v[72:75], v[112:115], v[204:207], v[72:75]
	v_mfma_f32_16x16x32_bf16 v[72:75], v[116:119], v[208:211], v[72:75]
	s_setprio 0
	s_setprio 2
	v_mfma_f32_16x16x32_bf16 v[132:135], v[144:147], v[160:163], v[132:135]
	v_mfma_f32_16x16x32_bf16 v[132:135], v[148:151], v[164:167], v[132:135]
	v_mfma_f32_16x16x32_bf16 v[128:131], v[152:155], v[160:163], v[128:131]
	v_mfma_f32_16x16x32_bf16 v[128:131], v[156:159], v[164:167], v[128:131]
	v_mfma_f32_16x16x32_bf16 v[108:111], v[144:147], v[188:191], v[108:111]
	v_mfma_f32_16x16x32_bf16 v[108:111], v[148:151], v[192:195], v[108:111]
	v_mfma_f32_16x16x32_bf16 v[104:107], v[152:155], v[188:191], v[104:107]
	v_mfma_f32_16x16x32_bf16 v[104:107], v[156:159], v[192:195], v[104:107]
	v_mfma_f32_16x16x32_bf16 v[84:87], v[144:147], v[196:199], v[84:87]
	v_mfma_f32_16x16x32_bf16 v[84:87], v[148:151], v[200:203], v[84:87]
	v_mfma_f32_16x16x32_bf16 v[80:83], v[152:155], v[196:199], v[80:83]
	v_mfma_f32_16x16x32_bf16 v[80:83], v[156:159], v[200:203], v[80:83]
	v_mfma_f32_16x16x32_bf16 v[68:71], v[144:147], v[204:207], v[68:71]
	v_mfma_f32_16x16x32_bf16 v[68:71], v[148:151], v[208:211], v[68:71]
	v_mfma_f32_16x16x32_bf16 v[64:67], v[152:155], v[204:207], v[64:67]
	v_mfma_f32_16x16x32_bf16 v[64:67], v[156:159], v[208:211], v[64:67]
	s_setprio 0
	s_add_i32 s69, s65, s18
	v_lshl_add_u64 v[212:213], s[16:17], 0, v[170:171]
	s_mov_b32 m0, s69
	ds_read_b128 v[160:163], v221 offset:16384
	ds_read_b128 v[164:167], v221 offset:17408
	ds_read_b128 v[188:191], v221 offset:18432
	ds_read_b128 v[192:195], v221 offset:19456
	ds_read_b128 v[196:199], v221 offset:20480
	ds_read_b128 v[200:203], v221 offset:21504
	ds_read_b128 v[204:207], v221 offset:22528
	ds_read_b128 v[208:211], v221 offset:23552
	global_load_lds_dwordx4 v[212:213], off
	s_add_i32 m0, s69, 0x2000
	s_add_u32 s78, s16, 0x4000
	v_lshl_add_u64 v[212:213], s[16:17], 0, v[174:175]
	s_addc_u32 s79, s17, 0
	s_add_i32 s69, s74, s18
	global_load_lds_dwordx4 v[212:213], off
	v_lshl_add_u64 v[212:213], s[78:79], 0, v[170:171]
	s_mov_b32 m0, s69
	s_nop 0
	global_load_lds_dwordx4 v[212:213], off
	v_lshl_add_u64 v[212:213], s[78:79], 0, v[174:175]
	s_add_i32 m0, s69, 0x2000
	s_nop 0
	global_load_lds_dwordx4 v[212:213], off
	v_lshl_add_u64 v[212:213], s[20:21], 0, v[168:169]
	s_mov_b32 m0, s19
	s_nop 0
	global_load_lds_dwordx4 v[212:213], off
	v_lshl_add_u64 v[212:213], s[20:21], 0, v[172:173]
	s_mov_b32 m0, s30
	s_nop 0
	global_load_lds_dwordx4 v[212:213], off
	s_waitcnt vmcnt(8)
	s_waitcnt lgkmcnt(0)
	s_barrier
	s_setprio 2
	s_waitcnt lgkmcnt(0)
	v_mfma_f32_16x16x32_bf16 v[60:63], v[88:91], v[160:163], v[60:63]
	v_mfma_f32_16x16x32_bf16 v[60:63], v[92:95], v[164:167], v[60:63]
	v_mfma_f32_16x16x32_bf16 v[56:59], v[112:115], v[160:163], v[56:59]
	v_mfma_f32_16x16x32_bf16 v[56:59], v[116:119], v[164:167], v[56:59]
	v_mfma_f32_16x16x32_bf16 v[44:47], v[88:91], v[188:191], v[44:47]
	v_mfma_f32_16x16x32_bf16 v[44:47], v[92:95], v[192:195], v[44:47]
	v_mfma_f32_16x16x32_bf16 v[40:43], v[112:115], v[188:191], v[40:43]
	v_mfma_f32_16x16x32_bf16 v[40:43], v[116:119], v[192:195], v[40:43]
	v_mfma_f32_16x16x32_bf16 v[28:31], v[88:91], v[196:199], v[28:31]
	v_mfma_f32_16x16x32_bf16 v[28:31], v[92:95], v[200:203], v[28:31]
	v_mfma_f32_16x16x32_bf16 v[24:27], v[112:115], v[196:199], v[24:27]
	v_mfma_f32_16x16x32_bf16 v[24:27], v[116:119], v[200:203], v[24:27]
	v_mfma_f32_16x16x32_bf16 v[12:15], v[88:91], v[204:207], v[12:15]
	v_mfma_f32_16x16x32_bf16 v[12:15], v[92:95], v[208:211], v[12:15]
	v_mfma_f32_16x16x32_bf16 v[8:11], v[112:115], v[204:207], v[8:11]
	v_mfma_f32_16x16x32_bf16 v[8:11], v[116:119], v[208:211], v[8:11]
	s_setprio 0
	s_setprio 2
	v_mfma_f32_16x16x32_bf16 v[52:55], v[144:147], v[160:163], v[52:55]
	v_mfma_f32_16x16x32_bf16 v[52:55], v[148:151], v[164:167], v[52:55]
	v_mfma_f32_16x16x32_bf16 v[48:51], v[152:155], v[160:163], v[48:51]
	v_mfma_f32_16x16x32_bf16 v[48:51], v[156:159], v[164:167], v[48:51]
	v_mfma_f32_16x16x32_bf16 v[36:39], v[144:147], v[188:191], v[36:39]
	v_mfma_f32_16x16x32_bf16 v[36:39], v[148:151], v[192:195], v[36:39]
	v_mfma_f32_16x16x32_bf16 v[32:35], v[152:155], v[188:191], v[32:35]
	v_mfma_f32_16x16x32_bf16 v[32:35], v[156:159], v[192:195], v[32:35]
	v_mfma_f32_16x16x32_bf16 v[20:23], v[144:147], v[196:199], v[20:23]
	v_mfma_f32_16x16x32_bf16 v[20:23], v[148:151], v[200:203], v[20:23]
	v_mfma_f32_16x16x32_bf16 v[16:19], v[152:155], v[196:199], v[16:19]
	v_mfma_f32_16x16x32_bf16 v[16:19], v[156:159], v[200:203], v[16:19]
	v_mfma_f32_16x16x32_bf16 v[4:7], v[144:147], v[204:207], v[4:7]
	v_mfma_f32_16x16x32_bf16 v[4:7], v[148:151], v[208:211], v[4:7]
	v_mfma_f32_16x16x32_bf16 v[0:3], v[152:155], v[204:207], v[0:3]
	v_mfma_f32_16x16x32_bf16 v[0:3], v[156:159], v[208:211], v[0:3]
	s_setprio 0
	s_add_i32 s69, 0, 0x18000
	s_add_i32 s77, 0, 0x1c000
	v_add_u32_e32 v116, s69, v218
	v_add_u32_e32 v156, s77, v218
	ds_read_b128 v[88:91], v116
	ds_read_b128 v[92:95], v116 offset:1024
	ds_read_b128 v[112:115], v116 offset:2048
	ds_read_b128 v[116:119], v116 offset:3072
	ds_read_b128 v[144:147], v156
	ds_read_b128 v[148:151], v156 offset:1024
	ds_read_b128 v[152:155], v156 offset:2048
	ds_read_b128 v[156:159], v156 offset:3072
	s_add_u32 s20, s20, 0x4000
	s_addc_u32 s21, s21, 0
	s_mov_b32 m0, s33
	v_lshl_add_u64 v[212:213], s[20:21], 0, v[168:169]
	ds_read_b128 v[160:163], v221 offset:32768
	ds_read_b128 v[164:167], v221 offset:33792
	ds_read_b128 v[188:191], v221 offset:34816
	ds_read_b128 v[192:195], v221 offset:35840
	ds_read_b128 v[196:199], v221 offset:36864
	ds_read_b128 v[200:203], v221 offset:37888
	ds_read_b128 v[204:207], v221 offset:38912
	ds_read_b128 v[208:211], v221 offset:39936
	global_load_lds_dwordx4 v[212:213], off
	v_lshl_add_u64 v[212:213], s[20:21], 0, v[172:173]
	s_mov_b32 m0, s42
	s_nop 0
	global_load_lds_dwordx4 v[212:213], off
	s_waitcnt vmcnt(8)
	s_waitcnt lgkmcnt(0)
	s_barrier
; #define PG8_STAGE(bufoff, gbase, voff) do { _Pragma("unroll") for (int _i = 0; _i < 2; ++_i) \
;         __builtin_amdgcn_global_load_lds((const unsigned*)((const char*)(gbase) + (voff)[_i]), (LAS unsigned*)(lds + (bufoff) + ldsw + _i * 8192), 16, 0, 0); } while (0)
; #define PG8_LDA(dst, b, h) do { _Pragma("unroll") for (int m = 0; m < 4; ++m) _Pragma("unroll") for (int k = 0; k < 2; ++k) dst[m][k] = *(const LAS bf16x8*)(lds + PG8_SA(b, h) + aoff + m * 2048 + k * 1024); } while (0)
; #define PG8_MMA(ai, bj, At, Bt) do { __builtin_amdgcn_s_setprio(1); _Pragma("unroll") for (int m = 0; m < 4; ++m) _Pragma("unroll") for (int n = 0; n < 2; ++n) _Pragma("unroll") for (int k = 0; k < 2; ++k) \
;         acc[ai][bj][m][n] = __builtin_amdgcn_mfma_f32_16x16x32_bf16(Bt[n][k], At[m][k], acc[ai][bj][m][n], 0, 0, 0); __builtin_amdgcn_s_setprio(0); } while (0)
; #define PG8_WAIT_V(n) asm volatile("s_waitcnt vmcnt(" #n ")" ::: "memory")
; #define PG8_WAIT_L(n) asm volatile("s_waitcnt lgkmcnt(" #n ")" ::: "memory")
; #define PG8_BAR __builtin_amdgcn_s_barrier()
; #define PG8_SCHED __builtin_amdgcn_sched_barrier(0)
; template <bool ALIGN_EPI, class Epi, class Sched>
; __device__ __forceinline__ void gemm_phase(LAS unsigned char* lds, const int lda, const int ldb, const int K, const Sched& S, const Epi& E, const size_t kstepA = (size_t)(BK * 2), const size_t kstepB = (size_t)(BK * 2)) {
;     ...
;             PG8_LDA(At, 1, 1); PG8_STAGE(PG8_SB(1, 0), b3, voffB); PG8_STAGE(PG8_SB(1, 1), b3 + hstepB, voffB); PG8_STAGE(PG8_SA(1, 0), a3, voffA);
;             PG8_WAIT_V(8); PG8_WAIT_L(0); PG8_BAR; PG8_MMA(1, 0, At, B0); PG8_MMA(1, 1, At, B1); PG8_BAR; PG8_SCHED;
;         }
;         if constexpr (ALIGN_EPI) { if (wr == 0) PG8_BAR; }
	s_setprio 2
	s_waitcnt lgkmcnt(0)
	v_mfma_f32_16x16x32_bf16 v[140:143], v[88:91], v[160:163], v[140:143]
	v_mfma_f32_16x16x32_bf16 v[140:143], v[92:95], v[164:167], v[140:143]
	v_mfma_f32_16x16x32_bf16 v[136:139], v[112:115], v[160:163], v[136:139]
	v_mfma_f32_16x16x32_bf16 v[136:139], v[116:119], v[164:167], v[136:139]
	v_mfma_f32_16x16x32_bf16 v[124:127], v[88:91], v[188:191], v[124:127]
	v_mfma_f32_16x16x32_bf16 v[124:127], v[92:95], v[192:195], v[124:127]
	v_mfma_f32_16x16x32_bf16 v[120:123], v[112:115], v[188:191], v[120:123]
	v_mfma_f32_16x16x32_bf16 v[120:123], v[116:119], v[192:195], v[120:123]
	v_mfma_f32_16x16x32_bf16 v[100:103], v[88:91], v[196:199], v[100:103]
	v_mfma_f32_16x16x32_bf16 v[100:103], v[92:95], v[200:203], v[100:103]
	v_mfma_f32_16x16x32_bf16 v[96:99], v[112:115], v[196:199], v[96:99]
	v_mfma_f32_16x16x32_bf16 v[96:99], v[116:119], v[200:203], v[96:99]
	v_mfma_f32_16x16x32_bf16 v[76:79], v[88:91], v[204:207], v[76:79]
	v_mfma_f32_16x16x32_bf16 v[76:79], v[92:95], v[208:211], v[76:79]
	v_mfma_f32_16x16x32_bf16 v[72:75], v[112:115], v[204:207], v[72:75]
	v_mfma_f32_16x16x32_bf16 v[72:75], v[116:119], v[208:211], v[72:75]
	s_setprio 0
	s_setprio 2
	v_mfma_f32_16x16x32_bf16 v[132:135], v[144:147], v[160:163], v[132:135]
	v_mfma_f32_16x16x32_bf16 v[132:135], v[148:151], v[164:167], v[132:135]
	v_mfma_f32_16x16x32_bf16 v[128:131], v[152:155], v[160:163], v[128:131]
	v_mfma_f32_16x16x32_bf16 v[128:131], v[156:159], v[164:167], v[128:131]
	v_mfma_f32_16x16x32_bf16 v[108:111], v[144:147], v[188:191], v[108:111]
	v_mfma_f32_16x16x32_bf16 v[108:111], v[148:151], v[192:195], v[108:111]
	v_mfma_f32_16x16x32_bf16 v[104:107], v[152:155], v[188:191], v[104:107]
	v_mfma_f32_16x16x32_bf16 v[104:107], v[156:159], v[192:195], v[104:107]
	v_mfma_f32_16x16x32_bf16 v[84:87], v[144:147], v[196:199], v[84:87]
	v_mfma_f32_16x16x32_bf16 v[84:87], v[148:151], v[200:203], v[84:87]
	v_mfma_f32_16x16x32_bf16 v[80:83], v[152:155], v[196:199], v[80:83]
	v_mfma_f32_16x16x32_bf16 v[80:83], v[156:159], v[200:203], v[80:83]
	v_mfma_f32_16x16x32_bf16 v[68:71], v[144:147], v[204:207], v[68:71]
	v_mfma_f32_16x16x32_bf16 v[68:71], v[148:151], v[208:211], v[68:71]
	v_mfma_f32_16x16x32_bf16 v[64:67], v[152:155], v[204:207], v[64:67]
	v_mfma_f32_16x16x32_bf16 v[64:67], v[156:159], v[208:211], v[64:67]
	s_setprio 0
	s_add_u32 s20, s16, 0x40000
	s_addc_u32 s21, s17, 0
	s_add_i32 s69, s69, s18
	v_lshl_add_u64 v[212:213], s[20:21], 0, v[170:171]
	s_mov_b32 m0, s69
	ds_read_b128 v[160:163], v221 offset:49152
	ds_read_b128 v[164:167], v221 offset:50176
	ds_read_b128 v[188:191], v221 offset:51200
	ds_read_b128 v[192:195], v221 offset:52224
	ds_read_b128 v[196:199], v221 offset:53248
	ds_read_b128 v[200:203], v221 offset:54272
	ds_read_b128 v[204:207], v221 offset:55296
	ds_read_b128 v[208:211], v221 offset:56320
	global_load_lds_dwordx4 v[212:213], off
	s_add_i32 m0, s69, 0x2000
	s_add_u32 s16, s16, 0x44000
	v_lshl_add_u64 v[212:213], s[20:21], 0, v[174:175]
	s_addc_u32 s17, s17, 0
	s_add_i32 s20, s77, s18
	global_load_lds_dwordx4 v[212:213], off
	v_lshl_add_u64 v[212:213], s[16:17], 0, v[170:171]
	s_mov_b32 m0, s20
	s_nop 0
	global_load_lds_dwordx4 v[212:213], off
	v_lshl_add_u64 v[212:213], s[16:17], 0, v[174:175]
	s_add_i32 m0, s20, 0x2000
	s_nop 0
	global_load_lds_dwordx4 v[212:213], off
	v_lshl_add_u64 v[212:213], s[14:15], 0, v[168:169]
	s_mov_b32 m0, s51
	s_nop 0
	global_load_lds_dwordx4 v[212:213], off
	v_lshl_add_u64 v[212:213], s[14:15], 0, v[172:173]
	s_mov_b32 m0, s64
	s_nop 0
	global_load_lds_dwordx4 v[212:213], off
	s_waitcnt vmcnt(8)
	s_waitcnt lgkmcnt(0)
	s_barrier
	s_setprio 2
	s_waitcnt lgkmcnt(0)
	v_mfma_f32_16x16x32_bf16 v[60:63], v[88:91], v[160:163], v[60:63]
	v_mfma_f32_16x16x32_bf16 v[60:63], v[92:95], v[164:167], v[60:63]
	v_mfma_f32_16x16x32_bf16 v[56:59], v[112:115], v[160:163], v[56:59]
	v_mfma_f32_16x16x32_bf16 v[56:59], v[116:119], v[164:167], v[56:59]
	v_mfma_f32_16x16x32_bf16 v[44:47], v[88:91], v[188:191], v[44:47]
	v_mfma_f32_16x16x32_bf16 v[44:47], v[92:95], v[192:195], v[44:47]
	v_mfma_f32_16x16x32_bf16 v[40:43], v[112:115], v[188:191], v[40:43]
	v_mfma_f32_16x16x32_bf16 v[40:43], v[116:119], v[192:195], v[40:43]
	v_mfma_f32_16x16x32_bf16 v[28:31], v[88:91], v[196:199], v[28:31]
	v_mfma_f32_16x16x32_bf16 v[28:31], v[92:95], v[200:203], v[28:31]
	v_mfma_f32_16x16x32_bf16 v[24:27], v[112:115], v[196:199], v[24:27]
	v_mfma_f32_16x16x32_bf16 v[24:27], v[116:119], v[200:203], v[24:27]
	v_mfma_f32_16x16x32_bf16 v[12:15], v[88:91], v[204:207], v[12:15]
	v_mfma_f32_16x16x32_bf16 v[12:15], v[92:95], v[208:211], v[12:15]
	v_mfma_f32_16x16x32_bf16 v[8:11], v[112:115], v[204:207], v[8:11]
	v_mfma_f32_16x16x32_bf16 v[8:11], v[116:119], v[208:211], v[8:11]
	s_setprio 0
	s_setprio 2
	v_mfma_f32_16x16x32_bf16 v[52:55], v[144:147], v[160:163], v[52:55]
	v_mfma_f32_16x16x32_bf16 v[52:55], v[148:151], v[164:167], v[52:55]
	v_mfma_f32_16x16x32_bf16 v[48:51], v[152:155], v[160:163], v[48:51]
	v_mfma_f32_16x16x32_bf16 v[48:51], v[156:159], v[164:167], v[48:51]
	v_mfma_f32_16x16x32_bf16 v[36:39], v[144:147], v[188:191], v[36:39]
	v_mfma_f32_16x16x32_bf16 v[36:39], v[148:151], v[192:195], v[36:39]
	v_mfma_f32_16x16x32_bf16 v[32:35], v[152:155], v[188:191], v[32:35]
	v_mfma_f32_16x16x32_bf16 v[32:35], v[156:159], v[192:195], v[32:35]
	v_mfma_f32_16x16x32_bf16 v[20:23], v[144:147], v[196:199], v[20:23]
	v_mfma_f32_16x16x32_bf16 v[20:23], v[148:151], v[200:203], v[20:23]
	v_mfma_f32_16x16x32_bf16 v[16:19], v[152:155], v[196:199], v[16:19]
	v_mfma_f32_16x16x32_bf16 v[16:19], v[156:159], v[200:203], v[16:19]
	v_mfma_f32_16x16x32_bf16 v[4:7], v[144:147], v[204:207], v[4:7]
	v_mfma_f32_16x16x32_bf16 v[4:7], v[148:151], v[208:211], v[4:7]
	v_mfma_f32_16x16x32_bf16 v[0:3], v[152:155], v[204:207], v[0:3]
	v_mfma_f32_16x16x32_bf16 v[0:3], v[156:159], v[208:211], v[0:3]
	s_setprio 0
	s_add_i32 s67, s67, 2
	s_add_u32 s22, s22, 0x80000
	s_addc_u32 s23, s23, 0
	s_add_u32 s12, s12, 0x400000
	s_addc_u32 s13, s13, 0
	s_cmp_gt_u32 s67, 29
	s_cbranch_scc0 .Lp7_kloop_y
.Lp7_kloop_done:
	s_and_b64 vcc, exec, s[56:57]
	s_cbranch_vccz .LBB0_729

; #define PG8_BAR __builtin_amdgcn_s_barrier()
; template <bool ALIGN_EPI, class Epi, class Sched>
; __device__ __forceinline__ void gemm_phase(LAS unsigned char* lds, const int lda, const int ldb, const int K, const Sched& S, const Epi& E, const size_t kstepA = (size_t)(BK * 2), const size_t kstepB = (size_t)(BK * 2)) {
;     ...
;         cur = nxt; cA = nA; cB = nB; ++ui;
;         if constexpr (ALIGN_EPI) { if (wr == 1) PG8_BAR; }
;     }
.LBB0_745:
	s_or_b64 exec, exec, s[6:7]
	s_andn2_b64 vcc, exec, s[10:11]
	s_mov_b64 s[0:1], -1
	s_cbranch_vccnz .LBB0_718
	s_andn2_b64 vcc, exec, s[54:55]
	s_cbranch_vccnz .LBB0_717
	s_branch .LBB0_717

; #define PG8_STAGE(bufoff, gbase, voff) do { _Pragma("unroll") for (int _i = 0; _i < 2; ++_i) \
;         __builtin_amdgcn_global_load_lds((const unsigned*)((const char*)(gbase) + (voff)[_i]), (LAS unsigned*)(lds + (bufoff) + ldsw + _i * 8192), 16, 0, 0); } while (0)
; #define PG8_WAIT_V(n) asm volatile("s_waitcnt vmcnt(" #n ")" ::: "memory")
; #define PG8_BAR __builtin_amdgcn_s_barrier()
;     __device__ bool next(int i, Unit& u) const { if (i > 0 || c >= 32 || c < 0) return false; u.pm = c & 1; u.pn = c >> 1; u.z = 0; u.o = 0; u.a = A + (size_t)u.pm * 256 * D * 2; u.b = B + (size_t)u.pn * 256 * D * 2; return true; }
; template <bool ALIGN_EPI, class Epi, class Sched>
; __device__ __forceinline__ void gemm_phase(LAS unsigned char* lds, const int lda, const int ldb, const int K, const Sched& S, const Epi& E, const size_t kstepA = (size_t)(BK * 2), const size_t kstepB = (size_t)(BK * 2)) {
;     ...
;     for (int i = 0; i < 2; ++i) { int R, C; stage_rc(tid * 16 + i * 8192, R, C); const int Rb = (R & ~31) + perm32(R & 31);
;         voffA[i] = (unsigned)(R * lda + C) * 2u; voffB[i] = (unsigned)(Rb * ldb + C) * 2u; }
;     const size_t kstep = kstepB;
;     const size_t hstepA = (size_t)HALF * lda * 2, hstepB = (size_t)HALF * ldb * 2;
;     const unsigned ldsw = (unsigned)wid * 1024u;
;     const int aoff = lds_byte(wr * 64 + fr, fq * 8), boff = lds_byte(wc * 32 + fr, fq * 8);
;     ...
;     Unit cur, nxt; int ui = 0;
;     if (!S.next(0, cur)) return;
;     f32x4 acc[2][2][4][2];
; #pragma unroll
;     for (int a = 0; a < 2; ++a)
; #pragma unroll
;         for (int b = 0; b < 2; ++b)
; #pragma unroll
;             for (int m = 0; m < 4; ++m)
; #pragma unroll
;                 for (int n = 0; n < 2; ++n) acc[a][b][m][n] = (f32x4){0.f, 0.f, 0.f, 0.f};
;     bf16x8 At[4][2], B0[2][2], B1[2][2];
;     const char* cA = cur.a; const char* cB = cur.b;
;     PG8_STAGE(PG8_SB(0, 0), cB, voffB); PG8_STAGE(PG8_SB(0, 1), cB + hstepB, voffB); PG8_STAGE(PG8_SA(0, 0), cA, voffA); PG8_STAGE(PG8_SA(0, 1), cA + hstepA, voffA);
;     if (wr == 1) PG8_BAR;
;     PG8_WAIT_V(2); PG8_BAR;
;     PG8_STAGE(PG8_SB(1, 0), cB + kstep, voffB); PG8_STAGE(PG8_SA(1, 0), cA + kstepA, voffA); PG8_STAGE(PG8_SB(1, 1), cB + hstepB + kstep, voffB);
;     PG8_WAIT_V(6); PG8_BAR;
.LBB0_940:
	v_bfe_i32 v2, v0, 27, 1
	v_lshlrev_b32_e32 v4, 4, v0
	v_lshrrev_b32_e32 v2, 22, v2
	v_ashrrev_i32_e32 v1, 31, v0
	v_add_u32_e32 v2, v4, v2
	v_lshrrev_b32_e32 v1, 26, v1
	v_and_b32_e32 v2, 0xfffffc00, v2
	v_add_u32_e32 v1, v0, v1
	v_sub_u32_e32 v2, v4, v2
	v_ashrrev_i32_e32 v1, 6, v1
	v_lshrrev_b32_e32 v3, 4, v2
	v_bitop3_b32 v3, v3, v2, 32 bitop3:0x6c
	v_lshlrev_b32_e32 v2, 3, v1
	v_and_b32_e32 v5, -16, v2
	v_ashrrev_i32_e32 v2, 31, v3
	v_lshrrev_b32_e32 v2, 26, v2
	v_add_u32_e32 v6, v3, v2
	v_ashrrev_i32_e32 v2, 6, v6
	v_and_b32_e32 v6, 0xc0, v6
	v_sub_u32_e32 v3, v3, v6
	v_mov_b32_e32 v6, 1
	v_lshlrev_b32_e32 v7, 5, v1
	v_ashrrev_i16_sdwa v3, v6, sext(v3) dst_sel:DWORD dst_unused:UNUSED_PAD src0_sel:DWORD src1_sel:BYTE_0
	v_and_b32_e32 v7, 32, v7
	v_bfe_i32 v3, v3, 0, 16
	v_add_u32_e32 v5, v2, v5
	v_and_b32_e32 v10, 3, v2
	s_mov_b32 s1, 0x1ffffe0
	v_add_lshl_u32 v7, v7, v3, 1
	v_lshlrev_b32_e32 v8, 1, v5
	v_lshrrev_b32_e32 v9, 2, v5
	v_and_or_b32 v10, v5, s1, v10
	v_lshl_add_u32 v168, v5, 7, v7
	v_add_u32_e32 v5, 0x2000, v4
	v_ashrrev_i32_e32 v4, 31, v5
	v_lshrrev_b32_e32 v4, 22, v4
	v_and_b32_e32 v8, 24, v8
	v_and_b32_e32 v9, 4, v9
	v_add_u32_e32 v4, v5, v4
	v_or3_b32 v8, v10, v9, v8
	v_ashrrev_i32_e32 v4, 10, v4
	v_lshl_add_u32 v170, v8, 7, v7
	v_mul_i32_i24_e32 v7, 0x400, v4
	v_sub_u32_e32 v5, v5, v7
	v_lshrrev_b32_e32 v7, 4, v5
	v_bitop3_b32 v7, v7, v5, 32 bitop3:0x6c
	v_lshlrev_b32_e32 v5, 3, v4
	v_and_b32_e32 v8, -16, v5
	v_ashrrev_i32_e32 v5, 31, v7
	v_lshrrev_b32_e32 v5, 26, v5
	v_add_u32_e32 v9, v7, v5
	s_ashr_i32 s0, s6, 6
	v_ashrrev_i32_e32 v5, 6, v9
	v_and_b32_e32 v9, 0xc0, v9
	v_add_u32_e32 v8, v5, v8
	v_sub_u32_e32 v7, v7, v9
	s_lshl_b32 s18, s0, 10
	v_lshlrev_b32_e32 v10, 5, v4
	v_ashrrev_i16_sdwa v6, v6, sext(v7) dst_sel:DWORD dst_unused:UNUSED_PAD src0_sel:DWORD src1_sel:BYTE_0
	v_lshlrev_b32_e32 v7, 1, v8
	v_lshrrev_b32_e32 v9, 2, v8
	v_and_b32_e32 v11, 3, v5
	s_add_i32 s19, s18, 0
	v_and_b32_e32 v10, 32, v10
	v_bfe_i32 v6, v6, 0, 16
	v_and_b32_e32 v7, 24, v7
	v_and_b32_e32 v9, 4, v9
	v_and_or_b32 v11, v8, s1, v11
	s_add_i32 m0, s19, 0x10000
	v_or3_b32 v7, v11, v9, v7
	v_add_lshl_u32 v9, v10, v6, 1
	s_ashr_i32 s1, s6, 8
	global_load_lds_dwordx4 v170, s[14:15]
	s_add_i32 m0, s19, 0x12000
	v_lshl_add_u32 v174, v7, 7, v9
	s_add_u32 s8, s14, 0x4000
	global_load_lds_dwordx4 v174, s[14:15]
	s_addc_u32 s9, s15, 0
	s_add_i32 m0, s19, 0x14000
	s_add_i32 s33, s19, 0x2000
	global_load_lds_dwordx4 v170, s[8:9]
	s_add_i32 m0, s19, 0x16000
	v_lshl_add_u32 v172, v8, 7, v9
	global_load_lds_dwordx4 v174, s[8:9]
	s_mov_b32 m0, s19
	s_add_u32 s8, s12, 0x4000
	global_load_lds_dwordx4 v168, s[12:13]
	s_mov_b32 m0, s33
	s_addc_u32 s9, s13, 0
	s_add_i32 s42, s19, 0x4000
	global_load_lds_dwordx4 v172, s[12:13]
	s_mov_b32 m0, s42
	s_add_i32 s43, s19, 0x6000
	global_load_lds_dwordx4 v168, s[8:9]
	s_mov_b32 m0, s43
	v_mov_b32_e32 v177, 0
	global_load_lds_dwordx4 v172, s[8:9]
	s_cmp_eq_u32 s1, 1
	s_mov_b32 s45, 0
	v_mov_b32_e32 v171, v177
	v_mov_b32_e32 v175, v177
	s_mov_b64 s[46:47], 0x4000
	v_mov_b32_e32 v169, v177
	s_cselect_b64 s[48:49], -1, 0
	s_cmp_lg_u32 s1, 1
	v_mov_b32_e32 v173, v177
	s_cbranch_scc1 .LBB0_942
.LBB0_942:
	s_and_b32 s50, s0, 3
	s_lshl_b32 s0, s1, 13
	s_lshl_b32 s51, s50, 5
	s_lshl_b32 s7, s50, 12
	s_add_u32 s8, s14, 0x40000
	s_addc_u32 s9, s15, 0
	s_add_i32 m0, s19, 0x18000
	v_lshl_add_u64 v[8:9], s[8:9], 0, v[170:171]
	s_waitcnt vmcnt(2)
	s_barrier
	global_load_lds_dwordx4 v[8:9], off
	s_add_i32 m0, s19, 0x1a000
	v_lshl_add_u64 v[8:9], s[8:9], 0, v[174:175]
	s_add_u32 s8, s12, 0x200000
	s_addc_u32 s9, s13, 0
	s_add_i32 s64, s19, 0x8000
	global_load_lds_dwordx4 v[8:9], off
	v_lshl_add_u64 v[8:9], s[8:9], 0, v[168:169]
	s_mov_b32 m0, s64
	s_add_i32 s65, s19, 0xa000
	global_load_lds_dwordx4 v[8:9], off
	v_lshl_add_u64 v[8:9], s[8:9], 0, v[172:173]
	s_add_u32 s8, s14, 0x44000
	s_mov_b32 m0, s65
	s_addc_u32 s9, s15, 0
	global_load_lds_dwordx4 v[8:9], off
	s_add_i32 m0, s19, 0x1c000
	v_lshl_add_u64 v[8:9], s[8:9], 0, v[170:171]
	global_load_lds_dwordx4 v[8:9], off
	v_lshl_add_u64 v[8:9], s[8:9], 0, v[174:175]
	s_add_i32 m0, s19, 0x1e000
	v_bfe_u32 v7, v0, 4, 2
	global_load_lds_dwordx4 v[8:9], off
	v_and_b32_e32 v8, 15, v0
	v_lshlrev_b32_e32 v9, 4, v7
	v_lshlrev_b32_e32 v0, 2, v0
	v_lshl_or_b32 v216, s1, 6, v8
	v_lshl_or_b32 v8, v8, 6, v9
	v_and_b32_e32 v0, 32, v0
	v_bitop3_b32 v9, v8, s0, v0 bitop3:0xde
	v_bitop3_b32 v218, v8, s7, v0 bitop3:0xde
	v_lshlrev_b32_e32 v0, 10, v1
	v_and_b32_e32 v0, 0xfffff800, v0
	v_lshl_add_u32 v0, v2, 7, v0
	v_and_b32_e32 v1, 1, v1
	v_lshl_or_b32 v0, v1, 6, v0
	v_lshl_add_u32 v178, v3, 1, v0
	v_lshlrev_b32_e32 v0, 10, v4
	v_and_b32_e32 v0, 0xfffff800, v0
	s_waitcnt vmcnt(6)
	s_cmpk_lt_u32 s6, 0x100
	v_lshl_add_u32 v0, v5, 7, v0
	v_and_b32_e32 v1, 1, v4
	s_cselect_b64 s[52:53], -1, 0
	v_lshl_or_b32 v0, v1, 6, v0
	s_add_i32 s71, 0, 0x10000
	s_add_i32 s72, 0, 0x14000
	v_lshlrev_b32_e32 v217, 3, v7
	v_cmp_eq_u32_e64 s[8:9], 0, v7
	v_mov_b32_e32 v179, v177
	v_lshl_add_u32 v180, v6, 1, v0
	v_mov_b32_e32 v181, v177
	v_mov_b64_e32 v[182:183], 0x200
	v_mov_b64_e32 v[186:187], 0x1ff
	v_add_u32_e32 v219, s71, v218
	v_add_u32_e32 v220, s72, v218
	v_add_u32_e32 v221, 0, v9
	v_mbcnt_hi_u32_b32 v222, -1, v185
	s_mov_b64 s[54:55], 0x4800
	s_mov_b64 s[56:57], 0x5000
	s_mov_b64 s[58:59], 0x5800
	s_mov_b32 s73, 0
	s_barrier
	s_branch .LBB0_945

; #define PG8_STAGE(bufoff, gbase, voff) do { _Pragma("unroll") for (int _i = 0; _i < 2; ++_i) \
;         __builtin_amdgcn_global_load_lds((const unsigned*)((const char*)(gbase) + (voff)[_i]), (LAS unsigned*)(lds + (bufoff) + ldsw + _i * 8192), 16, 0, 0); } while (0)
; #define PG8_LDA(dst, b, h) do { _Pragma("unroll") for (int m = 0; m < 4; ++m) _Pragma("unroll") for (int k = 0; k < 2; ++k) dst[m][k] = *(const LAS bf16x8*)(lds + PG8_SA(b, h) + aoff + m * 2048 + k * 1024); } while (0)
; #define PG8_LDB(dst, b, h) do { _Pragma("unroll") for (int n = 0; n < 2; ++n) _Pragma("unroll") for (int k = 0; k < 2; ++k) dst[n][k] = *(const LAS bf16x8*)(lds + PG8_SB(b, h) + boff + n * 2048 + k * 1024); } while (0)
; #define PG8_MMA(ai, bj, At, Bt) do { __builtin_amdgcn_s_setprio(1); _Pragma("unroll") for (int m = 0; m < 4; ++m) _Pragma("unroll") for (int n = 0; n < 2; ++n) _Pragma("unroll") for (int k = 0; k < 2; ++k) \
;         acc[ai][bj][m][n] = __builtin_amdgcn_mfma_f32_16x16x32_bf16(Bt[n][k], At[m][k], acc[ai][bj][m][n], 0, 0, 0); __builtin_amdgcn_s_setprio(0); } while (0)
; #define PG8_WAIT_V(n) asm volatile("s_waitcnt vmcnt(" #n ")" ::: "memory")
; #define PG8_WAIT_L(n) asm volatile("s_waitcnt lgkmcnt(" #n ")" ::: "memory")
; #define PG8_BAR __builtin_amdgcn_s_barrier()
; #define PG8_SCHED __builtin_amdgcn_sched_barrier(0)
; template <bool ALIGN_EPI, class Epi, class Sched>
; __device__ __forceinline__ void gemm_phase(LAS unsigned char* lds, const int lda, const int ldb, const int K, const Sched& S, const Epi& E, const size_t kstepA = (size_t)(BK * 2), const size_t kstepB = (size_t)(BK * 2)) {
;     ...
;             PG8_LDB(B0, 0, 0); PG8_LDB(B1, 0, 1); PG8_SCHED; PG8_LDA(At, 0, 0); PG8_STAGE(PG8_SA(1, 1), a1 + hstepA, voffA);
;             PG8_WAIT_V(8); PG8_WAIT_L(0); PG8_BAR; PG8_MMA(0, 0, At, B0); PG8_MMA(0, 1, At, B1); PG8_BAR; PG8_SCHED;
;     ...
; #pragma unroll
;         for (int a = 0; a < 2; ++a)
; #pragma unroll
;             for (int b = 0; b < 2; ++b)
; #pragma unroll
;                 for (int m = 0; m < 4; ++m)
; #pragma unroll
;                     for (int n = 0; n < 2; ++n) acc[a][b][m][n] = (f32x4){0.f, 0.f, 0.f, 0.f};
;         cur = nxt; cA = nA; cB = nB; ++ui;
.LBB0_951:
	s_add_u32 s22, s14, 0x80000
	s_addc_u32 s23, s15, 0
	s_add_u32 s12, s12, 0x204000
	v_mov_b32_e32 v0, 0
	s_addc_u32 s13, s13, 0
	s_mov_b32 s61, -2
	s_waitcnt lgkmcnt(0)
	v_mov_b32_e32 v1, v0
	v_mov_b32_e32 v2, v0
	v_mov_b32_e32 v3, v0
	v_mov_b32_e32 v4, v0
	v_mov_b32_e32 v5, v0
	v_mov_b32_e32 v6, v0
	v_mov_b32_e32 v7, v0
	v_mov_b32_e32 v16, v0
	v_mov_b32_e32 v17, v0
	v_mov_b32_e32 v18, v0
	v_mov_b32_e32 v19, v0
	v_mov_b32_e32 v20, v0
	v_mov_b32_e32 v21, v0
	v_mov_b32_e32 v22, v0
	v_mov_b32_e32 v23, v0
	v_mov_b32_e32 v32, v0
	v_mov_b32_e32 v33, v0
	v_mov_b32_e32 v34, v0
	v_mov_b32_e32 v35, v0
	v_mov_b32_e32 v36, v0
	v_mov_b32_e32 v37, v0
	v_mov_b32_e32 v38, v0
	v_mov_b32_e32 v39, v0
	v_mov_b32_e32 v48, v0
	v_mov_b32_e32 v49, v0
	v_mov_b32_e32 v50, v0
	v_mov_b32_e32 v51, v0
	v_mov_b32_e32 v52, v0
	v_mov_b32_e32 v53, v0
	v_mov_b32_e32 v54, v0
	v_mov_b32_e32 v55, v0
	v_mov_b32_e32 v8, v0
	v_mov_b32_e32 v9, v0
	v_mov_b32_e32 v10, v0
	v_mov_b32_e32 v11, v0
	v_mov_b32_e32 v12, v0
	v_mov_b32_e32 v13, v0
	v_mov_b32_e32 v14, v0
	v_mov_b32_e32 v15, v0
	v_mov_b32_e32 v24, v0
	v_mov_b32_e32 v25, v0
	v_mov_b32_e32 v26, v0
	v_mov_b32_e32 v27, v0
	v_mov_b32_e32 v28, v0
	v_mov_b32_e32 v29, v0
	v_mov_b32_e32 v30, v0
	v_mov_b32_e32 v31, v0
	v_mov_b32_e32 v40, v0
	v_mov_b32_e32 v41, v0
	v_mov_b32_e32 v42, v0
	v_mov_b32_e32 v43, v0
	v_mov_b32_e32 v44, v0
	v_mov_b32_e32 v45, v0
	v_mov_b32_e32 v46, v0
	v_mov_b32_e32 v47, v0
	v_mov_b32_e32 v56, v0
	v_mov_b32_e32 v57, v0
	v_mov_b32_e32 v58, v0
	v_mov_b32_e32 v59, v0
	v_mov_b32_e32 v60, v0
	v_mov_b32_e32 v61, v0
	v_mov_b32_e32 v62, v0
	v_mov_b32_e32 v63, v0
	v_mov_b32_e32 v64, v0
	v_mov_b32_e32 v65, v0
	v_mov_b32_e32 v66, v0
	v_mov_b32_e32 v67, v0
	v_mov_b32_e32 v68, v0
	v_mov_b32_e32 v69, v0
	v_mov_b32_e32 v70, v0
	v_mov_b32_e32 v71, v0
	v_mov_b32_e32 v80, v0
	v_mov_b32_e32 v81, v0
	v_mov_b32_e32 v82, v0
	v_mov_b32_e32 v83, v0
	v_mov_b32_e32 v84, v0
	v_mov_b32_e32 v85, v0
	v_mov_b32_e32 v86, v0
	v_mov_b32_e32 v87, v0
	v_mov_b32_e32 v104, v0
	v_mov_b32_e32 v105, v0
	v_mov_b32_e32 v106, v0
	v_mov_b32_e32 v107, v0
	v_mov_b32_e32 v108, v0
	v_mov_b32_e32 v109, v0
	v_mov_b32_e32 v110, v0
	v_mov_b32_e32 v111, v0
	v_mov_b32_e32 v128, v0
	v_mov_b32_e32 v129, v0
	v_mov_b32_e32 v130, v0
	v_mov_b32_e32 v131, v0
	v_mov_b32_e32 v132, v0
	v_mov_b32_e32 v133, v0
	v_mov_b32_e32 v134, v0
	v_mov_b32_e32 v135, v0
	v_mov_b32_e32 v72, v0
	v_mov_b32_e32 v73, v0
	v_mov_b32_e32 v74, v0
	v_mov_b32_e32 v75, v0
	v_mov_b32_e32 v76, v0
	v_mov_b32_e32 v77, v0
	v_mov_b32_e32 v78, v0
	v_mov_b32_e32 v79, v0
	v_mov_b32_e32 v96, v0
	v_mov_b32_e32 v97, v0
	v_mov_b32_e32 v98, v0
	v_mov_b32_e32 v99, v0
	v_mov_b32_e32 v100, v0
	v_mov_b32_e32 v101, v0
	v_mov_b32_e32 v102, v0
	v_mov_b32_e32 v103, v0
	v_mov_b32_e32 v120, v0
	v_mov_b32_e32 v121, v0
	v_mov_b32_e32 v122, v0
	v_mov_b32_e32 v123, v0
	v_mov_b32_e32 v124, v0
	v_mov_b32_e32 v125, v0
	v_mov_b32_e32 v126, v0
	v_mov_b32_e32 v127, v0
	v_mov_b32_e32 v136, v0
	v_mov_b32_e32 v137, v0
	v_mov_b32_e32 v138, v0
	v_mov_b32_e32 v139, v0
	v_mov_b32_e32 v140, v0
	v_mov_b32_e32 v141, v0
	v_mov_b32_e32 v142, v0
	v_mov_b32_e32 v143, v0
	s_cmp_lg_u64 s[52:53], 0
	s_cbranch_scc0 .Lp11_kloop_y
.LBB0_952:
	ds_read_b128 v[88:91], v219
	ds_read_b128 v[92:95], v219 offset:1024
	ds_read_b128 v[112:115], v219 offset:2048
	ds_read_b128 v[116:119], v219 offset:3072
	ds_read_b128 v[144:147], v220
	ds_read_b128 v[148:151], v220 offset:1024
	ds_read_b128 v[152:155], v220 offset:2048
	ds_read_b128 v[156:159], v220 offset:3072
	s_add_u32 s14, s12, 0x1fc000
	s_addc_u32 s15, s13, 0
	s_cmp_eq_u32 s61, 12
	s_cselect_b32 s20, s0, s14
	s_cselect_b32 s21, s1, s15
	s_cselect_b32 s16, s6, s22
	s_cselect_b32 s17, s7, s23
	s_add_u32 s14, s20, 0x200000
	s_addc_u32 s15, s21, 0
	v_lshl_add_u64 v[212:213], s[12:13], 0, v[178:179]
	s_add_i32 m0, s19, 0xc000
	ds_read_b128 v[160:163], v221
	ds_read_b128 v[164:167], v221 offset:1024
	ds_read_b128 v[188:191], v221 offset:2048
	ds_read_b128 v[192:195], v221 offset:3072
	ds_read_b128 v[196:199], v221 offset:4096
	ds_read_b128 v[200:203], v221 offset:5120
	ds_read_b128 v[204:207], v221 offset:6144
	ds_read_b128 v[208:211], v221 offset:7168
	global_load_lds_dwordx4 v[212:213], off
	v_lshl_add_u64 v[212:213], s[12:13], 0, v[180:181]
	s_add_i32 m0, s19, 0xe000
	s_nop 0
	global_load_lds_dwordx4 v[212:213], off
	s_waitcnt vmcnt(8)
	s_waitcnt lgkmcnt(0)
	s_setprio 1
	s_waitcnt lgkmcnt(0)
	v_mfma_f32_16x16x32_bf16 v[140:143], v[88:91], v[160:163], v[140:143]
	v_mfma_f32_16x16x32_bf16 v[140:143], v[92:95], v[164:167], v[140:143]
	v_mfma_f32_16x16x32_bf16 v[136:139], v[112:115], v[160:163], v[136:139]
	v_mfma_f32_16x16x32_bf16 v[136:139], v[116:119], v[164:167], v[136:139]
	v_mfma_f32_16x16x32_bf16 v[124:127], v[88:91], v[188:191], v[124:127]
	v_mfma_f32_16x16x32_bf16 v[124:127], v[92:95], v[192:195], v[124:127]
	v_mfma_f32_16x16x32_bf16 v[120:123], v[112:115], v[188:191], v[120:123]
	v_mfma_f32_16x16x32_bf16 v[120:123], v[116:119], v[192:195], v[120:123]
	v_mfma_f32_16x16x32_bf16 v[100:103], v[88:91], v[196:199], v[100:103]
	v_mfma_f32_16x16x32_bf16 v[100:103], v[92:95], v[200:203], v[100:103]
	v_mfma_f32_16x16x32_bf16 v[96:99], v[112:115], v[196:199], v[96:99]
	v_mfma_f32_16x16x32_bf16 v[96:99], v[116:119], v[200:203], v[96:99]
	v_mfma_f32_16x16x32_bf16 v[76:79], v[88:91], v[204:207], v[76:79]
	v_mfma_f32_16x16x32_bf16 v[76:79], v[92:95], v[208:211], v[76:79]
	v_mfma_f32_16x16x32_bf16 v[72:75], v[112:115], v[204:207], v[72:75]
	v_mfma_f32_16x16x32_bf16 v[72:75], v[116:119], v[208:211], v[72:75]
	s_setprio 0
	s_setprio 1
	v_mfma_f32_16x16x32_bf16 v[132:135], v[144:147], v[160:163], v[132:135]
	v_mfma_f32_16x16x32_bf16 v[132:135], v[148:151], v[164:167], v[132:135]
	v_mfma_f32_16x16x32_bf16 v[128:131], v[152:155], v[160:163], v[128:131]
	v_mfma_f32_16x16x32_bf16 v[128:131], v[156:159], v[164:167], v[128:131]
	v_mfma_f32_16x16x32_bf16 v[108:111], v[144:147], v[188:191], v[108:111]
	v_mfma_f32_16x16x32_bf16 v[108:111], v[148:151], v[192:195], v[108:111]
	v_mfma_f32_16x16x32_bf16 v[104:107], v[152:155], v[188:191], v[104:107]
	v_mfma_f32_16x16x32_bf16 v[104:107], v[156:159], v[192:195], v[104:107]
	v_mfma_f32_16x16x32_bf16 v[84:87], v[144:147], v[196:199], v[84:87]
	v_mfma_f32_16x16x32_bf16 v[84:87], v[148:151], v[200:203], v[84:87]
	v_mfma_f32_16x16x32_bf16 v[80:83], v[152:155], v[196:199], v[80:83]
	v_mfma_f32_16x16x32_bf16 v[80:83], v[156:159], v[200:203], v[80:83]
	v_mfma_f32_16x16x32_bf16 v[68:71], v[144:147], v[204:207], v[68:71]
	v_mfma_f32_16x16x32_bf16 v[68:71], v[148:151], v[208:211], v[68:71]
	v_mfma_f32_16x16x32_bf16 v[64:67], v[152:155], v[204:207], v[64:67]
	v_mfma_f32_16x16x32_bf16 v[64:67], v[156:159], v[208:211], v[64:67]
	s_setprio 0
	s_barrier
; #define PG8_STAGE(bufoff, gbase, voff) do { _Pragma("unroll") for (int _i = 0; _i < 2; ++_i) \
;         __builtin_amdgcn_global_load_lds((const unsigned*)((const char*)(gbase) + (voff)[_i]), (LAS unsigned*)(lds + (bufoff) + ldsw + _i * 8192), 16, 0, 0); } while (0)
; #define PG8_LDA(dst, b, h) do { _Pragma("unroll") for (int m = 0; m < 4; ++m) _Pragma("unroll") for (int k = 0; k < 2; ++k) dst[m][k] = *(const LAS bf16x8*)(lds + PG8_SA(b, h) + aoff + m * 2048 + k * 1024); } while (0)
; #define PG8_LDB(dst, b, h) do { _Pragma("unroll") for (int n = 0; n < 2; ++n) _Pragma("unroll") for (int k = 0; k < 2; ++k) dst[n][k] = *(const LAS bf16x8*)(lds + PG8_SB(b, h) + boff + n * 2048 + k * 1024); } while (0)
; #define PG8_MMA(ai, bj, At, Bt) do { __builtin_amdgcn_s_setprio(1); _Pragma("unroll") for (int m = 0; m < 4; ++m) _Pragma("unroll") for (int n = 0; n < 2; ++n) _Pragma("unroll") for (int k = 0; k < 2; ++k) \
;         acc[ai][bj][m][n] = __builtin_amdgcn_mfma_f32_16x16x32_bf16(Bt[n][k], At[m][k], acc[ai][bj][m][n], 0, 0, 0); __builtin_amdgcn_s_setprio(0); } while (0)
; #define PG8_WAIT_V(n) asm volatile("s_waitcnt vmcnt(" #n ")" ::: "memory")
; #define PG8_WAIT_L(n) asm volatile("s_waitcnt lgkmcnt(" #n ")" ::: "memory")
; #define PG8_BAR __builtin_amdgcn_s_barrier()
; #define PG8_SCHED __builtin_amdgcn_sched_barrier(0)
; template <bool ALIGN_EPI, class Epi, class Sched>
; __device__ __forceinline__ void gemm_phase(LAS unsigned char* lds, const int lda, const int ldb, const int K, const Sched& S, const Epi& E, const size_t kstepA = (size_t)(BK * 2), const size_t kstepB = (size_t)(BK * 2)) {
;     ...
;             PG8_WAIT_V(8); PG8_WAIT_L(0); PG8_BAR; PG8_MMA(0, 0, At, B0); PG8_MMA(0, 1, At, B1); PG8_BAR; PG8_SCHED;
;             PG8_LDA(At, 0, 1); PG8_STAGE(PG8_SB(0, 0), b2, voffB); PG8_STAGE(PG8_SB(0, 1), b2 + hstepB, voffB); PG8_STAGE(PG8_SA(0, 0), a2, voffA);
;             PG8_WAIT_V(8); PG8_WAIT_L(0); PG8_BAR; PG8_MMA(1, 0, At, B0); PG8_MMA(1, 1, At, B1); PG8_BAR; PG8_SCHED;
;             PG8_LDB(B0, 1, 0); PG8_LDB(B1, 1, 1); PG8_SCHED; PG8_LDA(At, 1, 0); PG8_STAGE(PG8_SA(0, 1), a2 + hstepA, voffA);
;             PG8_WAIT_V(8); PG8_WAIT_L(0); PG8_BAR; PG8_MMA(0, 0, At, B0); PG8_MMA(0, 1, At, B1); PG8_BAR; PG8_SCHED;
	s_add_i32 s63, s71, s18
	v_lshl_add_u64 v[212:213], s[16:17], 0, v[170:171]
	s_mov_b32 m0, s63
	ds_read_b128 v[160:163], v221 offset:16384
	ds_read_b128 v[164:167], v221 offset:17408
	ds_read_b128 v[188:191], v221 offset:18432
	ds_read_b128 v[192:195], v221 offset:19456
	ds_read_b128 v[196:199], v221 offset:20480
	ds_read_b128 v[200:203], v221 offset:21504
	ds_read_b128 v[204:207], v221 offset:22528
	ds_read_b128 v[208:211], v221 offset:23552
	global_load_lds_dwordx4 v[212:213], off
	s_add_i32 m0, s63, 0x2000
	s_add_u32 s76, s16, 0x4000
	v_lshl_add_u64 v[212:213], s[16:17], 0, v[174:175]
	s_addc_u32 s77, s17, 0
	s_add_i32 s63, s72, s18
	global_load_lds_dwordx4 v[212:213], off
	v_lshl_add_u64 v[212:213], s[76:77], 0, v[170:171]
	s_mov_b32 m0, s63
	s_nop 0
	global_load_lds_dwordx4 v[212:213], off
	v_lshl_add_u64 v[212:213], s[76:77], 0, v[174:175]
	s_add_i32 m0, s63, 0x2000
	s_nop 0
	global_load_lds_dwordx4 v[212:213], off
	v_lshl_add_u64 v[212:213], s[20:21], 0, v[168:169]
	s_mov_b32 m0, s19
	s_nop 0
	global_load_lds_dwordx4 v[212:213], off
	v_lshl_add_u64 v[212:213], s[20:21], 0, v[172:173]
	s_mov_b32 m0, s33
	s_nop 0
	global_load_lds_dwordx4 v[212:213], off
	s_waitcnt vmcnt(8)
	s_waitcnt lgkmcnt(0)
	s_setprio 1
	s_waitcnt lgkmcnt(0)
	v_mfma_f32_16x16x32_bf16 v[60:63], v[88:91], v[160:163], v[60:63]
	v_mfma_f32_16x16x32_bf16 v[60:63], v[92:95], v[164:167], v[60:63]
	v_mfma_f32_16x16x32_bf16 v[56:59], v[112:115], v[160:163], v[56:59]
	v_mfma_f32_16x16x32_bf16 v[56:59], v[116:119], v[164:167], v[56:59]
	v_mfma_f32_16x16x32_bf16 v[44:47], v[88:91], v[188:191], v[44:47]
	v_mfma_f32_16x16x32_bf16 v[44:47], v[92:95], v[192:195], v[44:47]
	v_mfma_f32_16x16x32_bf16 v[40:43], v[112:115], v[188:191], v[40:43]
	v_mfma_f32_16x16x32_bf16 v[40:43], v[116:119], v[192:195], v[40:43]
	v_mfma_f32_16x16x32_bf16 v[28:31], v[88:91], v[196:199], v[28:31]
	v_mfma_f32_16x16x32_bf16 v[28:31], v[92:95], v[200:203], v[28:31]
	v_mfma_f32_16x16x32_bf16 v[24:27], v[112:115], v[196:199], v[24:27]
	v_mfma_f32_16x16x32_bf16 v[24:27], v[116:119], v[200:203], v[24:27]
	v_mfma_f32_16x16x32_bf16 v[12:15], v[88:91], v[204:207], v[12:15]
	v_mfma_f32_16x16x32_bf16 v[12:15], v[92:95], v[208:211], v[12:15]
	v_mfma_f32_16x16x32_bf16 v[8:11], v[112:115], v[204:207], v[8:11]
	v_mfma_f32_16x16x32_bf16 v[8:11], v[116:119], v[208:211], v[8:11]
	s_setprio 0
	s_setprio 1
	v_mfma_f32_16x16x32_bf16 v[52:55], v[144:147], v[160:163], v[52:55]
	v_mfma_f32_16x16x32_bf16 v[52:55], v[148:151], v[164:167], v[52:55]
	v_mfma_f32_16x16x32_bf16 v[48:51], v[152:155], v[160:163], v[48:51]
	v_mfma_f32_16x16x32_bf16 v[48:51], v[156:159], v[164:167], v[48:51]
	v_mfma_f32_16x16x32_bf16 v[36:39], v[144:147], v[188:191], v[36:39]
	v_mfma_f32_16x16x32_bf16 v[36:39], v[148:151], v[192:195], v[36:39]
	v_mfma_f32_16x16x32_bf16 v[32:35], v[152:155], v[188:191], v[32:35]
	v_mfma_f32_16x16x32_bf16 v[32:35], v[156:159], v[192:195], v[32:35]
	v_mfma_f32_16x16x32_bf16 v[20:23], v[144:147], v[196:199], v[20:23]
	v_mfma_f32_16x16x32_bf16 v[20:23], v[148:151], v[200:203], v[20:23]
	v_mfma_f32_16x16x32_bf16 v[16:19], v[152:155], v[196:199], v[16:19]
	v_mfma_f32_16x16x32_bf16 v[16:19], v[156:159], v[200:203], v[16:19]
	v_mfma_f32_16x16x32_bf16 v[4:7], v[144:147], v[204:207], v[4:7]
	v_mfma_f32_16x16x32_bf16 v[4:7], v[148:151], v[208:211], v[4:7]
	v_mfma_f32_16x16x32_bf16 v[0:3], v[152:155], v[204:207], v[0:3]
	v_mfma_f32_16x16x32_bf16 v[0:3], v[156:159], v[208:211], v[0:3]
	s_setprio 0
	s_barrier
	s_add_i32 s63, 0, 0x18000
	s_add_i32 s75, 0, 0x1c000
	v_add_u32_e32 v116, s63, v218
	v_add_u32_e32 v156, s75, v218
	ds_read_b128 v[88:91], v116
	ds_read_b128 v[92:95], v116 offset:1024
	ds_read_b128 v[112:115], v116 offset:2048
	ds_read_b128 v[116:119], v116 offset:3072
	ds_read_b128 v[144:147], v156
	ds_read_b128 v[148:151], v156 offset:1024
	ds_read_b128 v[152:155], v156 offset:2048
	ds_read_b128 v[156:159], v156 offset:3072
	s_add_u32 s20, s20, 0x4000
	s_addc_u32 s21, s21, 0
	s_mov_b32 m0, s42
	v_lshl_add_u64 v[212:213], s[20:21], 0, v[168:169]
	ds_read_b128 v[160:163], v221 offset:32768
	ds_read_b128 v[164:167], v221 offset:33792
	ds_read_b128 v[188:191], v221 offset:34816
	ds_read_b128 v[192:195], v221 offset:35840
	ds_read_b128 v[196:199], v221 offset:36864
	ds_read_b128 v[200:203], v221 offset:37888
	ds_read_b128 v[204:207], v221 offset:38912
	ds_read_b128 v[208:211], v221 offset:39936
	global_load_lds_dwordx4 v[212:213], off
	v_lshl_add_u64 v[212:213], s[20:21], 0, v[172:173]
	s_mov_b32 m0, s43
	s_nop 0
	global_load_lds_dwordx4 v[212:213], off
	s_waitcnt vmcnt(8)
	s_waitcnt lgkmcnt(0)
	s_setprio 1
	s_waitcnt lgkmcnt(0)
	v_mfma_f32_16x16x32_bf16 v[140:143], v[88:91], v[160:163], v[140:143]
	v_mfma_f32_16x16x32_bf16 v[140:143], v[92:95], v[164:167], v[140:143]
	v_mfma_f32_16x16x32_bf16 v[136:139], v[112:115], v[160:163], v[136:139]
	v_mfma_f32_16x16x32_bf16 v[136:139], v[116:119], v[164:167], v[136:139]
	v_mfma_f32_16x16x32_bf16 v[124:127], v[88:91], v[188:191], v[124:127]
	v_mfma_f32_16x16x32_bf16 v[124:127], v[92:95], v[192:195], v[124:127]
	v_mfma_f32_16x16x32_bf16 v[120:123], v[112:115], v[188:191], v[120:123]
	v_mfma_f32_16x16x32_bf16 v[120:123], v[116:119], v[192:195], v[120:123]
	v_mfma_f32_16x16x32_bf16 v[100:103], v[88:91], v[196:199], v[100:103]
	v_mfma_f32_16x16x32_bf16 v[100:103], v[92:95], v[200:203], v[100:103]
	v_mfma_f32_16x16x32_bf16 v[96:99], v[112:115], v[196:199], v[96:99]
	v_mfma_f32_16x16x32_bf16 v[96:99], v[116:119], v[200:203], v[96:99]
	v_mfma_f32_16x16x32_bf16 v[76:79], v[88:91], v[204:207], v[76:79]
	v_mfma_f32_16x16x32_bf16 v[76:79], v[92:95], v[208:211], v[76:79]
	v_mfma_f32_16x16x32_bf16 v[72:75], v[112:115], v[204:207], v[72:75]
	v_mfma_f32_16x16x32_bf16 v[72:75], v[116:119], v[208:211], v[72:75]
	s_setprio 0
	s_setprio 1
	v_mfma_f32_16x16x32_bf16 v[132:135], v[144:147], v[160:163], v[132:135]
	v_mfma_f32_16x16x32_bf16 v[132:135], v[148:151], v[164:167], v[132:135]
	v_mfma_f32_16x16x32_bf16 v[128:131], v[152:155], v[160:163], v[128:131]
	v_mfma_f32_16x16x32_bf16 v[128:131], v[156:159], v[164:167], v[128:131]
	v_mfma_f32_16x16x32_bf16 v[108:111], v[144:147], v[188:191], v[108:111]
	v_mfma_f32_16x16x32_bf16 v[108:111], v[148:151], v[192:195], v[108:111]
	v_mfma_f32_16x16x32_bf16 v[104:107], v[152:155], v[188:191], v[104:107]
	v_mfma_f32_16x16x32_bf16 v[104:107], v[156:159], v[192:195], v[104:107]
	v_mfma_f32_16x16x32_bf16 v[84:87], v[144:147], v[196:199], v[84:87]
	v_mfma_f32_16x16x32_bf16 v[84:87], v[148:151], v[200:203], v[84:87]
	v_mfma_f32_16x16x32_bf16 v[80:83], v[152:155], v[196:199], v[80:83]
	v_mfma_f32_16x16x32_bf16 v[80:83], v[156:159], v[200:203], v[80:83]
	v_mfma_f32_16x16x32_bf16 v[68:71], v[144:147], v[204:207], v[68:71]
	v_mfma_f32_16x16x32_bf16 v[68:71], v[148:151], v[208:211], v[68:71]
	v_mfma_f32_16x16x32_bf16 v[64:67], v[152:155], v[204:207], v[64:67]
	v_mfma_f32_16x16x32_bf16 v[64:67], v[156:159], v[208:211], v[64:67]
	s_setprio 0
	s_barrier
; #define PG8_STAGE(bufoff, gbase, voff) do { _Pragma("unroll") for (int _i = 0; _i < 2; ++_i) \
;         __builtin_amdgcn_global_load_lds((const unsigned*)((const char*)(gbase) + (voff)[_i]), (LAS unsigned*)(lds + (bufoff) + ldsw + _i * 8192), 16, 0, 0); } while (0)
; #define PG8_LDA(dst, b, h) do { _Pragma("unroll") for (int m = 0; m < 4; ++m) _Pragma("unroll") for (int k = 0; k < 2; ++k) dst[m][k] = *(const LAS bf16x8*)(lds + PG8_SA(b, h) + aoff + m * 2048 + k * 1024); } while (0)
; #define PG8_LDB(dst, b, h) do { _Pragma("unroll") for (int n = 0; n < 2; ++n) _Pragma("unroll") for (int k = 0; k < 2; ++k) dst[n][k] = *(const LAS bf16x8*)(lds + PG8_SB(b, h) + boff + n * 2048 + k * 1024); } while (0)
; #define PG8_MMA(ai, bj, At, Bt) do { __builtin_amdgcn_s_setprio(1); _Pragma("unroll") for (int m = 0; m < 4; ++m) _Pragma("unroll") for (int n = 0; n < 2; ++n) _Pragma("unroll") for (int k = 0; k < 2; ++k) \
;         acc[ai][bj][m][n] = __builtin_amdgcn_mfma_f32_16x16x32_bf16(Bt[n][k], At[m][k], acc[ai][bj][m][n], 0, 0, 0); __builtin_amdgcn_s_setprio(0); } while (0)
; #define PG8_WAIT_V(n) asm volatile("s_waitcnt vmcnt(" #n ")" ::: "memory")
; #define PG8_WAIT_L(n) asm volatile("s_waitcnt lgkmcnt(" #n ")" ::: "memory")
; #define PG8_BAR __builtin_amdgcn_s_barrier()
; #define PG8_SCHED __builtin_amdgcn_sched_barrier(0)
; template <bool ALIGN_EPI, class Epi, class Sched>
; __device__ __forceinline__ void gemm_phase(LAS unsigned char* lds, const int lda, const int ldb, const int K, const Sched& S, const Epi& E, const size_t kstepA = (size_t)(BK * 2), const size_t kstepB = (size_t)(BK * 2)) {
;     ...
;             PG8_LDB(B0, 0, 0); PG8_LDB(B1, 0, 1); PG8_SCHED; PG8_LDA(At, 0, 0); PG8_STAGE(PG8_SA(1, 1), a1 + hstepA, voffA);
;             PG8_WAIT_V(8); PG8_WAIT_L(0); PG8_BAR; PG8_MMA(0, 0, At, B0); PG8_MMA(0, 1, At, B1); PG8_BAR; PG8_SCHED;
;     ...
;             PG8_LDA(At, 1, 1); PG8_STAGE(PG8_SB(1, 0), b3, voffB); PG8_STAGE(PG8_SB(1, 1), b3 + hstepB, voffB); PG8_STAGE(PG8_SA(1, 0), a3, voffA);
;             PG8_WAIT_V(8); PG8_WAIT_L(0); PG8_BAR; PG8_MMA(1, 0, At, B0); PG8_MMA(1, 1, At, B1); PG8_BAR; PG8_SCHED;
;         }
	s_add_u32 s20, s16, 0x40000
	s_addc_u32 s21, s17, 0
	s_add_i32 s63, s63, s18
	v_lshl_add_u64 v[212:213], s[20:21], 0, v[170:171]
	s_mov_b32 m0, s63
	ds_read_b128 v[160:163], v221 offset:49152
	ds_read_b128 v[164:167], v221 offset:50176
	ds_read_b128 v[188:191], v221 offset:51200
	ds_read_b128 v[192:195], v221 offset:52224
	ds_read_b128 v[196:199], v221 offset:53248
	ds_read_b128 v[200:203], v221 offset:54272
	ds_read_b128 v[204:207], v221 offset:55296
	ds_read_b128 v[208:211], v221 offset:56320
	global_load_lds_dwordx4 v[212:213], off
	s_add_i32 m0, s63, 0x2000
	s_add_u32 s16, s16, 0x44000
	v_lshl_add_u64 v[212:213], s[20:21], 0, v[174:175]
	s_addc_u32 s17, s17, 0
	s_add_i32 s20, s75, s18
	global_load_lds_dwordx4 v[212:213], off
	v_lshl_add_u64 v[212:213], s[16:17], 0, v[170:171]
	s_mov_b32 m0, s20
	s_nop 0
	global_load_lds_dwordx4 v[212:213], off
	v_lshl_add_u64 v[212:213], s[16:17], 0, v[174:175]
	s_add_i32 m0, s20, 0x2000
	s_nop 0
	global_load_lds_dwordx4 v[212:213], off
	v_lshl_add_u64 v[212:213], s[14:15], 0, v[168:169]
	s_mov_b32 m0, s64
	s_nop 0
	global_load_lds_dwordx4 v[212:213], off
	v_lshl_add_u64 v[212:213], s[14:15], 0, v[172:173]
	s_mov_b32 m0, s65
	s_nop 0
	global_load_lds_dwordx4 v[212:213], off
	s_waitcnt vmcnt(8)
	s_waitcnt lgkmcnt(0)
	s_setprio 1
	s_waitcnt lgkmcnt(0)
	v_mfma_f32_16x16x32_bf16 v[60:63], v[88:91], v[160:163], v[60:63]
	v_mfma_f32_16x16x32_bf16 v[60:63], v[92:95], v[164:167], v[60:63]
	v_mfma_f32_16x16x32_bf16 v[56:59], v[112:115], v[160:163], v[56:59]
	v_mfma_f32_16x16x32_bf16 v[56:59], v[116:119], v[164:167], v[56:59]
	v_mfma_f32_16x16x32_bf16 v[44:47], v[88:91], v[188:191], v[44:47]
	v_mfma_f32_16x16x32_bf16 v[44:47], v[92:95], v[192:195], v[44:47]
	v_mfma_f32_16x16x32_bf16 v[40:43], v[112:115], v[188:191], v[40:43]
	v_mfma_f32_16x16x32_bf16 v[40:43], v[116:119], v[192:195], v[40:43]
	v_mfma_f32_16x16x32_bf16 v[28:31], v[88:91], v[196:199], v[28:31]
	v_mfma_f32_16x16x32_bf16 v[28:31], v[92:95], v[200:203], v[28:31]
	v_mfma_f32_16x16x32_bf16 v[24:27], v[112:115], v[196:199], v[24:27]
	v_mfma_f32_16x16x32_bf16 v[24:27], v[116:119], v[200:203], v[24:27]
	v_mfma_f32_16x16x32_bf16 v[12:15], v[88:91], v[204:207], v[12:15]
	v_mfma_f32_16x16x32_bf16 v[12:15], v[92:95], v[208:211], v[12:15]
	v_mfma_f32_16x16x32_bf16 v[8:11], v[112:115], v[204:207], v[8:11]
	v_mfma_f32_16x16x32_bf16 v[8:11], v[116:119], v[208:211], v[8:11]
	s_setprio 0
	s_setprio 1
	v_mfma_f32_16x16x32_bf16 v[52:55], v[144:147], v[160:163], v[52:55]
	v_mfma_f32_16x16x32_bf16 v[52:55], v[148:151], v[164:167], v[52:55]
	v_mfma_f32_16x16x32_bf16 v[48:51], v[152:155], v[160:163], v[48:51]
	v_mfma_f32_16x16x32_bf16 v[48:51], v[156:159], v[164:167], v[48:51]
	v_mfma_f32_16x16x32_bf16 v[36:39], v[144:147], v[188:191], v[36:39]
	v_mfma_f32_16x16x32_bf16 v[36:39], v[148:151], v[192:195], v[36:39]
	v_mfma_f32_16x16x32_bf16 v[32:35], v[152:155], v[188:191], v[32:35]
	v_mfma_f32_16x16x32_bf16 v[32:35], v[156:159], v[192:195], v[32:35]
	v_mfma_f32_16x16x32_bf16 v[20:23], v[144:147], v[196:199], v[20:23]
	v_mfma_f32_16x16x32_bf16 v[20:23], v[148:151], v[200:203], v[20:23]
	v_mfma_f32_16x16x32_bf16 v[16:19], v[152:155], v[196:199], v[16:19]
	v_mfma_f32_16x16x32_bf16 v[16:19], v[156:159], v[200:203], v[16:19]
	v_mfma_f32_16x16x32_bf16 v[4:7], v[144:147], v[204:207], v[4:7]
	v_mfma_f32_16x16x32_bf16 v[4:7], v[148:151], v[208:211], v[4:7]
	v_mfma_f32_16x16x32_bf16 v[0:3], v[152:155], v[204:207], v[0:3]
	v_mfma_f32_16x16x32_bf16 v[0:3], v[156:159], v[208:211], v[0:3]
	s_setprio 0
	s_barrier
	s_add_i32 s61, s61, 2
	s_add_u32 s22, s22, 0x80000
	s_addc_u32 s23, s23, 0
	s_add_u32 s12, s12, 0x400000
	s_addc_u32 s13, s13, 0
	s_cmp_gt_u32 s61, 13
	s_cbranch_scc0 .LBB0_952
	s_branch .Lp11_kloop_done
.Lp11_kloop_y:
	ds_read_b128 v[88:91], v219
	ds_read_b128 v[92:95], v219 offset:1024
	ds_read_b128 v[112:115], v219 offset:2048
	ds_read_b128 v[116:119], v219 offset:3072
	ds_read_b128 v[144:147], v220
	ds_read_b128 v[148:151], v220 offset:1024
	ds_read_b128 v[152:155], v220 offset:2048
	ds_read_b128 v[156:159], v220 offset:3072
	s_add_u32 s14, s12, 0x1fc000
	s_addc_u32 s15, s13, 0
	s_cmp_eq_u32 s61, 12
	s_cselect_b32 s20, s0, s14
	s_cselect_b32 s21, s1, s15
	s_cselect_b32 s16, s6, s22
	s_cselect_b32 s17, s7, s23
	s_add_u32 s14, s20, 0x200000
	s_addc_u32 s15, s21, 0
	v_lshl_add_u64 v[212:213], s[12:13], 0, v[178:179]
	s_add_i32 m0, s19, 0xc000
	ds_read_b128 v[160:163], v221
	ds_read_b128 v[164:167], v221 offset:1024
	ds_read_b128 v[188:191], v221 offset:2048
	ds_read_b128 v[192:195], v221 offset:3072
	ds_read_b128 v[196:199], v221 offset:4096
	ds_read_b128 v[200:203], v221 offset:5120
	ds_read_b128 v[204:207], v221 offset:6144
	ds_read_b128 v[208:211], v221 offset:7168
	global_load_lds_dwordx4 v[212:213], off
	v_lshl_add_u64 v[212:213], s[12:13], 0, v[180:181]
	s_add_i32 m0, s19, 0xe000
	s_nop 0
	global_load_lds_dwordx4 v[212:213], off
	s_waitcnt vmcnt(8)
	s_waitcnt lgkmcnt(0)
	s_barrier
; #define PG8_STAGE(bufoff, gbase, voff) do { _Pragma("unroll") for (int _i = 0; _i < 2; ++_i) \
;         __builtin_amdgcn_global_load_lds((const unsigned*)((const char*)(gbase) + (voff)[_i]), (LAS unsigned*)(lds + (bufoff) + ldsw + _i * 8192), 16, 0, 0); } while (0)
; #define PG8_LDA(dst, b, h) do { _Pragma("unroll") for (int m = 0; m < 4; ++m) _Pragma("unroll") for (int k = 0; k < 2; ++k) dst[m][k] = *(const LAS bf16x8*)(lds + PG8_SA(b, h) + aoff + m * 2048 + k * 1024); } while (0)
; #define PG8_LDB(dst, b, h) do { _Pragma("unroll") for (int n = 0; n < 2; ++n) _Pragma("unroll") for (int k = 0; k < 2; ++k) dst[n][k] = *(const LAS bf16x8*)(lds + PG8_SB(b, h) + boff + n * 2048 + k * 1024); } while (0)
; #define PG8_MMA(ai, bj, At, Bt) do { __builtin_amdgcn_s_setprio(1); _Pragma("unroll") for (int m = 0; m < 4; ++m) _Pragma("unroll") for (int n = 0; n < 2; ++n) _Pragma("unroll") for (int k = 0; k < 2; ++k) \
;         acc[ai][bj][m][n] = __builtin_amdgcn_mfma_f32_16x16x32_bf16(Bt[n][k], At[m][k], acc[ai][bj][m][n], 0, 0, 0); __builtin_amdgcn_s_setprio(0); } while (0)
; #define PG8_WAIT_V(n) asm volatile("s_waitcnt vmcnt(" #n ")" ::: "memory")
; #define PG8_WAIT_L(n) asm volatile("s_waitcnt lgkmcnt(" #n ")" ::: "memory")
; #define PG8_BAR __builtin_amdgcn_s_barrier()
; #define PG8_SCHED __builtin_amdgcn_sched_barrier(0)
; template <bool ALIGN_EPI, class Epi, class Sched>
; __device__ __forceinline__ void gemm_phase(LAS unsigned char* lds, const int lda, const int ldb, const int K, const Sched& S, const Epi& E, const size_t kstepA = (size_t)(BK * 2), const size_t kstepB = (size_t)(BK * 2)) {
;     ...
;             PG8_LDB(B0, 0, 0); PG8_LDB(B1, 0, 1); PG8_SCHED; PG8_LDA(At, 0, 0); PG8_STAGE(PG8_SA(1, 1), a1 + hstepA, voffA);
;             PG8_WAIT_V(8); PG8_WAIT_L(0); PG8_BAR; PG8_MMA(0, 0, At, B0); PG8_MMA(0, 1, At, B1); PG8_BAR; PG8_SCHED;
;             PG8_LDA(At, 0, 1); PG8_STAGE(PG8_SB(0, 0), b2, voffB); PG8_STAGE(PG8_SB(0, 1), b2 + hstepB, voffB); PG8_STAGE(PG8_SA(0, 0), a2, voffA);
;             PG8_WAIT_V(8); PG8_WAIT_L(0); PG8_BAR; PG8_MMA(1, 0, At, B0); PG8_MMA(1, 1, At, B1); PG8_BAR; PG8_SCHED;
;             PG8_LDB(B0, 1, 0); PG8_LDB(B1, 1, 1); PG8_SCHED; PG8_LDA(At, 1, 0); PG8_STAGE(PG8_SA(0, 1), a2 + hstepA, voffA);
;             PG8_WAIT_V(8); PG8_WAIT_L(0); PG8_BAR; PG8_MMA(0, 0, At, B0); PG8_MMA(0, 1, At, B1); PG8_BAR; PG8_SCHED;
	s_setprio 2
	s_waitcnt lgkmcnt(0)
	v_mfma_f32_16x16x32_bf16 v[140:143], v[88:91], v[160:163], v[140:143]
	v_mfma_f32_16x16x32_bf16 v[140:143], v[92:95], v[164:167], v[140:143]
	v_mfma_f32_16x16x32_bf16 v[136:139], v[112:115], v[160:163], v[136:139]
	v_mfma_f32_16x16x32_bf16 v[136:139], v[116:119], v[164:167], v[136:139]
	v_mfma_f32_16x16x32_bf16 v[124:127], v[88:91], v[188:191], v[124:127]
	v_mfma_f32_16x16x32_bf16 v[124:127], v[92:95], v[192:195], v[124:127]
	v_mfma_f32_16x16x32_bf16 v[120:123], v[112:115], v[188:191], v[120:123]
	v_mfma_f32_16x16x32_bf16 v[120:123], v[116:119], v[192:195], v[120:123]
	v_mfma_f32_16x16x32_bf16 v[100:103], v[88:91], v[196:199], v[100:103]
	v_mfma_f32_16x16x32_bf16 v[100:103], v[92:95], v[200:203], v[100:103]
	v_mfma_f32_16x16x32_bf16 v[96:99], v[112:115], v[196:199], v[96:99]
	v_mfma_f32_16x16x32_bf16 v[96:99], v[116:119], v[200:203], v[96:99]
	v_mfma_f32_16x16x32_bf16 v[76:79], v[88:91], v[204:207], v[76:79]
	v_mfma_f32_16x16x32_bf16 v[76:79], v[92:95], v[208:211], v[76:79]
	v_mfma_f32_16x16x32_bf16 v[72:75], v[112:115], v[204:207], v[72:75]
	v_mfma_f32_16x16x32_bf16 v[72:75], v[116:119], v[208:211], v[72:75]
	s_setprio 0
	s_setprio 2
	v_mfma_f32_16x16x32_bf16 v[132:135], v[144:147], v[160:163], v[132:135]
	v_mfma_f32_16x16x32_bf16 v[132:135], v[148:151], v[164:167], v[132:135]
	v_mfma_f32_16x16x32_bf16 v[128:131], v[152:155], v[160:163], v[128:131]
	v_mfma_f32_16x16x32_bf16 v[128:131], v[156:159], v[164:167], v[128:131]
	v_mfma_f32_16x16x32_bf16 v[108:111], v[144:147], v[188:191], v[108:111]
	v_mfma_f32_16x16x32_bf16 v[108:111], v[148:151], v[192:195], v[108:111]
	v_mfma_f32_16x16x32_bf16 v[104:107], v[152:155], v[188:191], v[104:107]
	v_mfma_f32_16x16x32_bf16 v[104:107], v[156:159], v[192:195], v[104:107]
	v_mfma_f32_16x16x32_bf16 v[84:87], v[144:147], v[196:199], v[84:87]
	v_mfma_f32_16x16x32_bf16 v[84:87], v[148:151], v[200:203], v[84:87]
	v_mfma_f32_16x16x32_bf16 v[80:83], v[152:155], v[196:199], v[80:83]
	v_mfma_f32_16x16x32_bf16 v[80:83], v[156:159], v[200:203], v[80:83]
	v_mfma_f32_16x16x32_bf16 v[68:71], v[144:147], v[204:207], v[68:71]
	v_mfma_f32_16x16x32_bf16 v[68:71], v[148:151], v[208:211], v[68:71]
	v_mfma_f32_16x16x32_bf16 v[64:67], v[152:155], v[204:207], v[64:67]
	v_mfma_f32_16x16x32_bf16 v[64:67], v[156:159], v[208:211], v[64:67]
	s_setprio 0
	s_add_i32 s63, s71, s18
	v_lshl_add_u64 v[212:213], s[16:17], 0, v[170:171]
	s_mov_b32 m0, s63
	ds_read_b128 v[160:163], v221 offset:16384
	ds_read_b128 v[164:167], v221 offset:17408
	ds_read_b128 v[188:191], v221 offset:18432
	ds_read_b128 v[192:195], v221 offset:19456
	ds_read_b128 v[196:199], v221 offset:20480
	ds_read_b128 v[200:203], v221 offset:21504
	ds_read_b128 v[204:207], v221 offset:22528
	ds_read_b128 v[208:211], v221 offset:23552
	global_load_lds_dwordx4 v[212:213], off
	s_add_i32 m0, s63, 0x2000
	s_add_u32 s76, s16, 0x4000
	v_lshl_add_u64 v[212:213], s[16:17], 0, v[174:175]
	s_addc_u32 s77, s17, 0
	s_add_i32 s63, s72, s18
	global_load_lds_dwordx4 v[212:213], off
	v_lshl_add_u64 v[212:213], s[76:77], 0, v[170:171]
	s_mov_b32 m0, s63
	s_nop 0
	global_load_lds_dwordx4 v[212:213], off
	v_lshl_add_u64 v[212:213], s[76:77], 0, v[174:175]
	s_add_i32 m0, s63, 0x2000
	s_nop 0
	global_load_lds_dwordx4 v[212:213], off
	v_lshl_add_u64 v[212:213], s[20:21], 0, v[168:169]
	s_mov_b32 m0, s19
	s_nop 0
	global_load_lds_dwordx4 v[212:213], off
	v_lshl_add_u64 v[212:213], s[20:21], 0, v[172:173]
	s_mov_b32 m0, s33
	s_nop 0
	global_load_lds_dwordx4 v[212:213], off
	s_waitcnt vmcnt(8)
	s_waitcnt lgkmcnt(0)
	s_barrier
	s_setprio 2
	s_waitcnt lgkmcnt(0)
	v_mfma_f32_16x16x32_bf16 v[60:63], v[88:91], v[160:163], v[60:63]
	v_mfma_f32_16x16x32_bf16 v[60:63], v[92:95], v[164:167], v[60:63]
	v_mfma_f32_16x16x32_bf16 v[56:59], v[112:115], v[160:163], v[56:59]
	v_mfma_f32_16x16x32_bf16 v[56:59], v[116:119], v[164:167], v[56:59]
	v_mfma_f32_16x16x32_bf16 v[44:47], v[88:91], v[188:191], v[44:47]
	v_mfma_f32_16x16x32_bf16 v[44:47], v[92:95], v[192:195], v[44:47]
	v_mfma_f32_16x16x32_bf16 v[40:43], v[112:115], v[188:191], v[40:43]
	v_mfma_f32_16x16x32_bf16 v[40:43], v[116:119], v[192:195], v[40:43]
	v_mfma_f32_16x16x32_bf16 v[28:31], v[88:91], v[196:199], v[28:31]
	v_mfma_f32_16x16x32_bf16 v[28:31], v[92:95], v[200:203], v[28:31]
	v_mfma_f32_16x16x32_bf16 v[24:27], v[112:115], v[196:199], v[24:27]
	v_mfma_f32_16x16x32_bf16 v[24:27], v[116:119], v[200:203], v[24:27]
	v_mfma_f32_16x16x32_bf16 v[12:15], v[88:91], v[204:207], v[12:15]
	v_mfma_f32_16x16x32_bf16 v[12:15], v[92:95], v[208:211], v[12:15]
	v_mfma_f32_16x16x32_bf16 v[8:11], v[112:115], v[204:207], v[8:11]
	v_mfma_f32_16x16x32_bf16 v[8:11], v[116:119], v[208:211], v[8:11]
	s_setprio 0
	s_setprio 2
	v_mfma_f32_16x16x32_bf16 v[52:55], v[144:147], v[160:163], v[52:55]
	v_mfma_f32_16x16x32_bf16 v[52:55], v[148:151], v[164:167], v[52:55]
	v_mfma_f32_16x16x32_bf16 v[48:51], v[152:155], v[160:163], v[48:51]
	v_mfma_f32_16x16x32_bf16 v[48:51], v[156:159], v[164:167], v[48:51]
	v_mfma_f32_16x16x32_bf16 v[36:39], v[144:147], v[188:191], v[36:39]
	v_mfma_f32_16x16x32_bf16 v[36:39], v[148:151], v[192:195], v[36:39]
	v_mfma_f32_16x16x32_bf16 v[32:35], v[152:155], v[188:191], v[32:35]
	v_mfma_f32_16x16x32_bf16 v[32:35], v[156:159], v[192:195], v[32:35]
	v_mfma_f32_16x16x32_bf16 v[20:23], v[144:147], v[196:199], v[20:23]
	v_mfma_f32_16x16x32_bf16 v[20:23], v[148:151], v[200:203], v[20:23]
	v_mfma_f32_16x16x32_bf16 v[16:19], v[152:155], v[196:199], v[16:19]
	v_mfma_f32_16x16x32_bf16 v[16:19], v[156:159], v[200:203], v[16:19]
	v_mfma_f32_16x16x32_bf16 v[4:7], v[144:147], v[204:207], v[4:7]
	v_mfma_f32_16x16x32_bf16 v[4:7], v[148:151], v[208:211], v[4:7]
	v_mfma_f32_16x16x32_bf16 v[0:3], v[152:155], v[204:207], v[0:3]
	v_mfma_f32_16x16x32_bf16 v[0:3], v[156:159], v[208:211], v[0:3]
	s_setprio 0
	s_add_i32 s63, 0, 0x18000
	s_add_i32 s75, 0, 0x1c000
	v_add_u32_e32 v116, s63, v218
	v_add_u32_e32 v156, s75, v218
	ds_read_b128 v[88:91], v116
	ds_read_b128 v[92:95], v116 offset:1024
	ds_read_b128 v[112:115], v116 offset:2048
	ds_read_b128 v[116:119], v116 offset:3072
	ds_read_b128 v[144:147], v156
	ds_read_b128 v[148:151], v156 offset:1024
	ds_read_b128 v[152:155], v156 offset:2048
	ds_read_b128 v[156:159], v156 offset:3072
	s_add_u32 s20, s20, 0x4000
	s_addc_u32 s21, s21, 0
	s_mov_b32 m0, s42
	v_lshl_add_u64 v[212:213], s[20:21], 0, v[168:169]
	ds_read_b128 v[160:163], v221 offset:32768
	ds_read_b128 v[164:167], v221 offset:33792
	ds_read_b128 v[188:191], v221 offset:34816
	ds_read_b128 v[192:195], v221 offset:35840
	ds_read_b128 v[196:199], v221 offset:36864
	ds_read_b128 v[200:203], v221 offset:37888
	ds_read_b128 v[204:207], v221 offset:38912
	ds_read_b128 v[208:211], v221 offset:39936
	global_load_lds_dwordx4 v[212:213], off
	v_lshl_add_u64 v[212:213], s[20:21], 0, v[172:173]
	s_mov_b32 m0, s43
	s_nop 0
	global_load_lds_dwordx4 v[212:213], off
	s_waitcnt vmcnt(8)
	s_waitcnt lgkmcnt(0)
	s_barrier
; #define PG8_STAGE(bufoff, gbase, voff) do { _Pragma("unroll") for (int _i = 0; _i < 2; ++_i) \
;         __builtin_amdgcn_global_load_lds((const unsigned*)((const char*)(gbase) + (voff)[_i]), (LAS unsigned*)(lds + (bufoff) + ldsw + _i * 8192), 16, 0, 0); } while (0)
; #define PG8_LDA(dst, b, h) do { _Pragma("unroll") for (int m = 0; m < 4; ++m) _Pragma("unroll") for (int k = 0; k < 2; ++k) dst[m][k] = *(const LAS bf16x8*)(lds + PG8_SA(b, h) + aoff + m * 2048 + k * 1024); } while (0)
; #define PG8_MMA(ai, bj, At, Bt) do { __builtin_amdgcn_s_setprio(1); _Pragma("unroll") for (int m = 0; m < 4; ++m) _Pragma("unroll") for (int n = 0; n < 2; ++n) _Pragma("unroll") for (int k = 0; k < 2; ++k) \
;         acc[ai][bj][m][n] = __builtin_amdgcn_mfma_f32_16x16x32_bf16(Bt[n][k], At[m][k], acc[ai][bj][m][n], 0, 0, 0); __builtin_amdgcn_s_setprio(0); } while (0)
; #define PG8_WAIT_V(n) asm volatile("s_waitcnt vmcnt(" #n ")" ::: "memory")
; #define PG8_WAIT_L(n) asm volatile("s_waitcnt lgkmcnt(" #n ")" ::: "memory")
; #define PG8_BAR __builtin_amdgcn_s_barrier()
; #define PG8_SCHED __builtin_amdgcn_sched_barrier(0)
; template <bool ALIGN_EPI, class Epi, class Sched>
; __device__ __forceinline__ void gemm_phase(LAS unsigned char* lds, const int lda, const int ldb, const int K, const Sched& S, const Epi& E, const size_t kstepA = (size_t)(BK * 2), const size_t kstepB = (size_t)(BK * 2)) {
;     ...
;             PG8_LDA(At, 1, 1); PG8_STAGE(PG8_SB(1, 0), b3, voffB); PG8_STAGE(PG8_SB(1, 1), b3 + hstepB, voffB); PG8_STAGE(PG8_SA(1, 0), a3, voffA);
;             PG8_WAIT_V(8); PG8_WAIT_L(0); PG8_BAR; PG8_MMA(1, 0, At, B0); PG8_MMA(1, 1, At, B1); PG8_BAR; PG8_SCHED;
;         }
;         if constexpr (ALIGN_EPI) { if (wr == 0) PG8_BAR; }
	s_setprio 2
	s_waitcnt lgkmcnt(0)
	v_mfma_f32_16x16x32_bf16 v[140:143], v[88:91], v[160:163], v[140:143]
	v_mfma_f32_16x16x32_bf16 v[140:143], v[92:95], v[164:167], v[140:143]
	v_mfma_f32_16x16x32_bf16 v[136:139], v[112:115], v[160:163], v[136:139]
	v_mfma_f32_16x16x32_bf16 v[136:139], v[116:119], v[164:167], v[136:139]
	v_mfma_f32_16x16x32_bf16 v[124:127], v[88:91], v[188:191], v[124:127]
	v_mfma_f32_16x16x32_bf16 v[124:127], v[92:95], v[192:195], v[124:127]
	v_mfma_f32_16x16x32_bf16 v[120:123], v[112:115], v[188:191], v[120:123]
	v_mfma_f32_16x16x32_bf16 v[120:123], v[116:119], v[192:195], v[120:123]
	v_mfma_f32_16x16x32_bf16 v[100:103], v[88:91], v[196:199], v[100:103]
	v_mfma_f32_16x16x32_bf16 v[100:103], v[92:95], v[200:203], v[100:103]
	v_mfma_f32_16x16x32_bf16 v[96:99], v[112:115], v[196:199], v[96:99]
	v_mfma_f32_16x16x32_bf16 v[96:99], v[116:119], v[200:203], v[96:99]
	v_mfma_f32_16x16x32_bf16 v[76:79], v[88:91], v[204:207], v[76:79]
	v_mfma_f32_16x16x32_bf16 v[76:79], v[92:95], v[208:211], v[76:79]
	v_mfma_f32_16x16x32_bf16 v[72:75], v[112:115], v[204:207], v[72:75]
	v_mfma_f32_16x16x32_bf16 v[72:75], v[116:119], v[208:211], v[72:75]
	s_setprio 0
	s_setprio 2
	v_mfma_f32_16x16x32_bf16 v[132:135], v[144:147], v[160:163], v[132:135]
	v_mfma_f32_16x16x32_bf16 v[132:135], v[148:151], v[164:167], v[132:135]
	v_mfma_f32_16x16x32_bf16 v[128:131], v[152:155], v[160:163], v[128:131]
	v_mfma_f32_16x16x32_bf16 v[128:131], v[156:159], v[164:167], v[128:131]
	v_mfma_f32_16x16x32_bf16 v[108:111], v[144:147], v[188:191], v[108:111]
	v_mfma_f32_16x16x32_bf16 v[108:111], v[148:151], v[192:195], v[108:111]
	v_mfma_f32_16x16x32_bf16 v[104:107], v[152:155], v[188:191], v[104:107]
	v_mfma_f32_16x16x32_bf16 v[104:107], v[156:159], v[192:195], v[104:107]
	v_mfma_f32_16x16x32_bf16 v[84:87], v[144:147], v[196:199], v[84:87]
	v_mfma_f32_16x16x32_bf16 v[84:87], v[148:151], v[200:203], v[84:87]
	v_mfma_f32_16x16x32_bf16 v[80:83], v[152:155], v[196:199], v[80:83]
	v_mfma_f32_16x16x32_bf16 v[80:83], v[156:159], v[200:203], v[80:83]
	v_mfma_f32_16x16x32_bf16 v[68:71], v[144:147], v[204:207], v[68:71]
	v_mfma_f32_16x16x32_bf16 v[68:71], v[148:151], v[208:211], v[68:71]
	v_mfma_f32_16x16x32_bf16 v[64:67], v[152:155], v[204:207], v[64:67]
	v_mfma_f32_16x16x32_bf16 v[64:67], v[156:159], v[208:211], v[64:67]
	s_setprio 0
	s_add_u32 s20, s16, 0x40000
	s_addc_u32 s21, s17, 0
	s_add_i32 s63, s63, s18
	v_lshl_add_u64 v[212:213], s[20:21], 0, v[170:171]
	s_mov_b32 m0, s63
	ds_read_b128 v[160:163], v221 offset:49152
	ds_read_b128 v[164:167], v221 offset:50176
	ds_read_b128 v[188:191], v221 offset:51200
	ds_read_b128 v[192:195], v221 offset:52224
	ds_read_b128 v[196:199], v221 offset:53248
	ds_read_b128 v[200:203], v221 offset:54272
	ds_read_b128 v[204:207], v221 offset:55296
	ds_read_b128 v[208:211], v221 offset:56320
	global_load_lds_dwordx4 v[212:213], off
	s_add_i32 m0, s63, 0x2000
	s_add_u32 s16, s16, 0x44000
	v_lshl_add_u64 v[212:213], s[20:21], 0, v[174:175]
	s_addc_u32 s17, s17, 0
	s_add_i32 s20, s75, s18
	global_load_lds_dwordx4 v[212:213], off
	v_lshl_add_u64 v[212:213], s[16:17], 0, v[170:171]
	s_mov_b32 m0, s20
	s_nop 0
	global_load_lds_dwordx4 v[212:213], off
	v_lshl_add_u64 v[212:213], s[16:17], 0, v[174:175]
	s_add_i32 m0, s20, 0x2000
	s_nop 0
	global_load_lds_dwordx4 v[212:213], off
	v_lshl_add_u64 v[212:213], s[14:15], 0, v[168:169]
	s_mov_b32 m0, s64
	s_nop 0
	global_load_lds_dwordx4 v[212:213], off
	v_lshl_add_u64 v[212:213], s[14:15], 0, v[172:173]
	s_mov_b32 m0, s65
	s_nop 0
	global_load_lds_dwordx4 v[212:213], off
	s_waitcnt vmcnt(8)
	s_waitcnt lgkmcnt(0)
	s_barrier
	s_setprio 2
	s_waitcnt lgkmcnt(0)
	v_mfma_f32_16x16x32_bf16 v[60:63], v[88:91], v[160:163], v[60:63]
	v_mfma_f32_16x16x32_bf16 v[60:63], v[92:95], v[164:167], v[60:63]
	v_mfma_f32_16x16x32_bf16 v[56:59], v[112:115], v[160:163], v[56:59]
	v_mfma_f32_16x16x32_bf16 v[56:59], v[116:119], v[164:167], v[56:59]
	v_mfma_f32_16x16x32_bf16 v[44:47], v[88:91], v[188:191], v[44:47]
	v_mfma_f32_16x16x32_bf16 v[44:47], v[92:95], v[192:195], v[44:47]
	v_mfma_f32_16x16x32_bf16 v[40:43], v[112:115], v[188:191], v[40:43]
	v_mfma_f32_16x16x32_bf16 v[40:43], v[116:119], v[192:195], v[40:43]
	v_mfma_f32_16x16x32_bf16 v[28:31], v[88:91], v[196:199], v[28:31]
	v_mfma_f32_16x16x32_bf16 v[28:31], v[92:95], v[200:203], v[28:31]
	v_mfma_f32_16x16x32_bf16 v[24:27], v[112:115], v[196:199], v[24:27]
	v_mfma_f32_16x16x32_bf16 v[24:27], v[116:119], v[200:203], v[24:27]
	v_mfma_f32_16x16x32_bf16 v[12:15], v[88:91], v[204:207], v[12:15]
	v_mfma_f32_16x16x32_bf16 v[12:15], v[92:95], v[208:211], v[12:15]
	v_mfma_f32_16x16x32_bf16 v[8:11], v[112:115], v[204:207], v[8:11]
	v_mfma_f32_16x16x32_bf16 v[8:11], v[116:119], v[208:211], v[8:11]
	s_setprio 0
	s_setprio 2
	v_mfma_f32_16x16x32_bf16 v[52:55], v[144:147], v[160:163], v[52:55]
	v_mfma_f32_16x16x32_bf16 v[52:55], v[148:151], v[164:167], v[52:55]
	v_mfma_f32_16x16x32_bf16 v[48:51], v[152:155], v[160:163], v[48:51]
	v_mfma_f32_16x16x32_bf16 v[48:51], v[156:159], v[164:167], v[48:51]
	v_mfma_f32_16x16x32_bf16 v[36:39], v[144:147], v[188:191], v[36:39]
	v_mfma_f32_16x16x32_bf16 v[36:39], v[148:151], v[192:195], v[36:39]
	v_mfma_f32_16x16x32_bf16 v[32:35], v[152:155], v[188:191], v[32:35]
	v_mfma_f32_16x16x32_bf16 v[32:35], v[156:159], v[192:195], v[32:35]
	v_mfma_f32_16x16x32_bf16 v[20:23], v[144:147], v[196:199], v[20:23]
	v_mfma_f32_16x16x32_bf16 v[20:23], v[148:151], v[200:203], v[20:23]
	v_mfma_f32_16x16x32_bf16 v[16:19], v[152:155], v[196:199], v[16:19]
	v_mfma_f32_16x16x32_bf16 v[16:19], v[156:159], v[200:203], v[16:19]
	v_mfma_f32_16x16x32_bf16 v[4:7], v[144:147], v[204:207], v[4:7]
	v_mfma_f32_16x16x32_bf16 v[4:7], v[148:151], v[208:211], v[4:7]
	v_mfma_f32_16x16x32_bf16 v[0:3], v[152:155], v[204:207], v[0:3]
	v_mfma_f32_16x16x32_bf16 v[0:3], v[156:159], v[208:211], v[0:3]
	s_setprio 0
	s_add_i32 s61, s61, 2
	s_add_u32 s22, s22, 0x80000
	s_addc_u32 s23, s23, 0
	s_add_u32 s12, s12, 0x400000
	s_addc_u32 s13, s13, 0
	s_cmp_gt_u32 s61, 13
	s_cbranch_scc0 .Lp11_kloop_y
.Lp11_kloop_done:
	s_and_b64 vcc, exec, s[52:53]
	s_cbranch_vccz .LBB0_955

; #define PG8_BAR __builtin_amdgcn_s_barrier()
; template <bool ALIGN_EPI, class Epi, class Sched>
; __device__ __forceinline__ void gemm_phase(LAS unsigned char* lds, const int lda, const int ldb, const int K, const Sched& S, const Epi& E, const size_t kstepA = (size_t)(BK * 2), const size_t kstepB = (size_t)(BK * 2)) {
;     ...
;         cur = nxt; cA = nA; cB = nB; ++ui;
;         if constexpr (ALIGN_EPI) { if (wr == 1) PG8_BAR; }
;     }
.LBB0_971:
	s_or_b64 exec, exec, s[6:7]
	s_andn2_b64 vcc, exec, s[10:11]
	s_mov_b64 s[0:1], -1
	s_cbranch_vccnz .LBB0_944
	s_andn2_b64 vcc, exec, s[48:49]
	s_cbranch_vccnz .LBB0_943
	s_branch .LBB0_943

; #define PG8_STAGE(bufoff, gbase, voff) do { _Pragma("unroll") for (int _i = 0; _i < 2; ++_i) \
;         __builtin_amdgcn_global_load_lds((const unsigned*)((const char*)(gbase) + (voff)[_i]), (LAS unsigned*)(lds + (bufoff) + ldsw + _i * 8192), 16, 0, 0); } while (0)
; #define PG8_WAIT_V(n) asm volatile("s_waitcnt vmcnt(" #n ")" ::: "memory")
; #define PG8_BAR __builtin_amdgcn_s_barrier()
;     __device__ bool next(int i, Unit& u) const { if (i > 0 || c >= 32 || c < 0) return false; u.pm = c & 1; u.pn = c >> 1; u.z = 0; u.o = 0; u.a = A + (size_t)u.pm * 256 * D * 2; u.b = B + (size_t)u.pn * 256 * D * 2; return true; }
; template <bool ALIGN_EPI, class Epi, class Sched>
; __device__ __forceinline__ void gemm_phase(LAS unsigned char* lds, const int lda, const int ldb, const int K, const Sched& S, const Epi& E, const size_t kstepA = (size_t)(BK * 2), const size_t kstepB = (size_t)(BK * 2)) {
;     ...
;     for (int i = 0; i < 2; ++i) { int R, C; stage_rc(tid * 16 + i * 8192, R, C); const int Rb = (R & ~31) + perm32(R & 31);
;         voffA[i] = (unsigned)(R * lda + C) * 2u; voffB[i] = (unsigned)(Rb * ldb + C) * 2u; }
;     const size_t kstep = kstepB;
;     const size_t hstepA = (size_t)HALF * lda * 2, hstepB = (size_t)HALF * ldb * 2;
;     const unsigned ldsw = (unsigned)wid * 1024u;
;     const int aoff = lds_byte(wr * 64 + fr, fq * 8), boff = lds_byte(wc * 32 + fr, fq * 8);
;     ...
;     Unit cur, nxt; int ui = 0;
;     if (!S.next(0, cur)) return;
;     f32x4 acc[2][2][4][2];
; #pragma unroll
;     for (int a = 0; a < 2; ++a)
; #pragma unroll
;         for (int b = 0; b < 2; ++b)
; #pragma unroll
;             for (int m = 0; m < 4; ++m)
; #pragma unroll
;                 for (int n = 0; n < 2; ++n) acc[a][b][m][n] = (f32x4){0.f, 0.f, 0.f, 0.f};
;     bf16x8 At[4][2], B0[2][2], B1[2][2];
;     const char* cA = cur.a; const char* cB = cur.b;
;     PG8_STAGE(PG8_SB(0, 0), cB, voffB); PG8_STAGE(PG8_SB(0, 1), cB + hstepB, voffB); PG8_STAGE(PG8_SA(0, 0), cA, voffA); PG8_STAGE(PG8_SA(0, 1), cA + hstepA, voffA);
;     if (wr == 1) PG8_BAR;
;     PG8_WAIT_V(2); PG8_BAR;
;     PG8_STAGE(PG8_SB(1, 0), cB + kstep, voffB); PG8_STAGE(PG8_SA(1, 0), cA + kstepA, voffA); PG8_STAGE(PG8_SB(1, 1), cB + hstepB + kstep, voffB);
;     PG8_WAIT_V(6); PG8_BAR;
.LBB0_1036:
	v_bfe_i32 v2, v0, 27, 1
	v_lshlrev_b32_e32 v4, 4, v0
	v_lshrrev_b32_e32 v2, 22, v2
	v_ashrrev_i32_e32 v1, 31, v0
	v_add_u32_e32 v2, v4, v2
	v_lshrrev_b32_e32 v1, 26, v1
	v_and_b32_e32 v2, 0xfffffc00, v2
	v_add_u32_e32 v1, v0, v1
	v_sub_u32_e32 v2, v4, v2
	v_ashrrev_i32_e32 v1, 6, v1
	v_lshrrev_b32_e32 v3, 4, v2
	v_bitop3_b32 v3, v3, v2, 32 bitop3:0x6c
	v_lshlrev_b32_e32 v2, 3, v1
	v_and_b32_e32 v5, -16, v2
	v_ashrrev_i32_e32 v2, 31, v3
	v_lshrrev_b32_e32 v2, 26, v2
	v_add_u32_e32 v6, v3, v2
	v_ashrrev_i32_e32 v2, 6, v6
	v_and_b32_e32 v6, 0xc0, v6
	v_sub_u32_e32 v3, v3, v6
	v_mov_b32_e32 v6, 1
	v_lshlrev_b32_e32 v7, 5, v1
	v_ashrrev_i16_sdwa v3, v6, sext(v3) dst_sel:DWORD dst_unused:UNUSED_PAD src0_sel:DWORD src1_sel:BYTE_0
	v_and_b32_e32 v7, 32, v7
	v_bfe_i32 v3, v3, 0, 16
	v_add_u32_e32 v5, v2, v5
	v_and_b32_e32 v10, 3, v2
	s_mov_b32 s0, 0x1ffffe0
	v_add_lshl_u32 v7, v7, v3, 1
	v_lshlrev_b32_e32 v8, 1, v5
	v_lshrrev_b32_e32 v9, 2, v5
	v_and_or_b32 v10, v5, s0, v10
	v_lshl_add_u32 v128, v5, 7, v7
	v_add_u32_e32 v5, 0x2000, v4
	v_ashrrev_i32_e32 v4, 31, v5
	v_lshrrev_b32_e32 v4, 22, v4
	v_and_b32_e32 v8, 24, v8
	v_and_b32_e32 v9, 4, v9
	v_add_u32_e32 v4, v5, v4
	v_or3_b32 v8, v10, v9, v8
	v_ashrrev_i32_e32 v4, 10, v4
	v_lshl_add_u32 v130, v8, 7, v7
	v_mul_i32_i24_e32 v7, 0x400, v4
	v_sub_u32_e32 v5, v5, v7
	v_lshrrev_b32_e32 v7, 4, v5
	v_bitop3_b32 v7, v7, v5, 32 bitop3:0x6c
	v_lshlrev_b32_e32 v5, 3, v4
	v_and_b32_e32 v8, -16, v5
	v_ashrrev_i32_e32 v5, 31, v7
	v_lshrrev_b32_e32 v5, 26, v5
	v_add_u32_e32 v9, v7, v5
	v_ashrrev_i32_e32 v5, 6, v9
	v_and_b32_e32 v9, 0xc0, v9
	s_ashr_i32 s9, s6, 6
	v_add_u32_e32 v8, v5, v8
	v_sub_u32_e32 v7, v7, v9
	s_lshl_b32 s19, s9, 10
	v_lshlrev_b32_e32 v10, 5, v4
	v_ashrrev_i16_sdwa v6, v6, sext(v7) dst_sel:DWORD dst_unused:UNUSED_PAD src0_sel:DWORD src1_sel:BYTE_0
	v_lshlrev_b32_e32 v7, 1, v8
	v_lshrrev_b32_e32 v9, 2, v8
	v_and_b32_e32 v11, 3, v5
	s_add_i32 s29, s19, 0
	v_and_b32_e32 v10, 32, v10
	v_bfe_i32 v6, v6, 0, 16
	v_and_b32_e32 v7, 24, v7
	v_and_b32_e32 v9, 4, v9
	v_and_or_b32 v11, v8, s0, v11
	s_add_i32 m0, s29, 0x10000
	s_ashr_i32 s7, s6, 8
	v_or3_b32 v7, v11, v9, v7
	v_add_lshl_u32 v9, v10, v6, 1
	global_load_lds_dwordx4 v130, s[48:49]
	s_add_i32 m0, s29, 0x12000
	v_lshl_add_u32 v134, v7, 7, v9
	s_add_u32 s0, s48, 0x4000
	global_load_lds_dwordx4 v134, s[48:49]
	s_addc_u32 s1, s49, 0
	s_add_i32 m0, s29, 0x14000
	s_add_i32 s30, s29, 0x2000
	global_load_lds_dwordx4 v130, s[0:1]
	s_add_i32 m0, s29, 0x16000
	v_lshl_add_u32 v132, v8, 7, v9
	global_load_lds_dwordx4 v134, s[0:1]
	s_mov_b32 m0, s29
	s_add_u32 s0, s46, 0x4000
	global_load_lds_dwordx4 v128, s[46:47]
	s_mov_b32 m0, s30
	s_addc_u32 s1, s47, 0
	s_add_i32 s31, s29, 0x4000
	global_load_lds_dwordx4 v132, s[46:47]
	s_mov_b32 m0, s31
	s_add_i32 s33, s29, 0x6000
	global_load_lds_dwordx4 v128, s[0:1]
	s_mov_b32 m0, s33
	v_mov_b32_e32 v137, 0
	global_load_lds_dwordx4 v132, s[0:1]
	s_cmp_eq_u32 s7, 1
	s_mov_b32 s42, 0
	v_mov_b32_e32 v131, v137
	v_mov_b32_e32 v135, v137
	v_mov_b32_e32 v129, v137
	s_cselect_b64 s[0:1], -1, 0
	s_cmp_lg_u32 s7, 1
	v_mov_b32_e32 v133, v137
	s_cbranch_scc1 .LBB0_1038
.LBB0_1038:
	s_lshl_b32 s9, s9, 5
	s_and_b32 s43, s9, 0x60
	s_lshl_b32 s12, s7, 13
	s_lshl_b32 s13, s43, 7
	s_add_u32 s10, s48, 0x160000
	s_addc_u32 s11, s49, 0
	s_add_i32 m0, s29, 0x18000
	v_lshl_add_u64 v[8:9], s[10:11], 0, v[130:131]
	s_waitcnt vmcnt(2)
	s_barrier
	global_load_lds_dwordx4 v[8:9], off
	s_add_i32 m0, s29, 0x1a000
	v_lshl_add_u64 v[8:9], s[10:11], 0, v[134:135]
	s_add_u32 s10, s46, 0x200000
	s_addc_u32 s11, s47, 0
	s_add_i32 s50, s29, 0x8000
	global_load_lds_dwordx4 v[8:9], off
	v_lshl_add_u64 v[8:9], s[10:11], 0, v[128:129]
	s_mov_b32 m0, s50
	s_add_i32 s51, s29, 0xa000
	global_load_lds_dwordx4 v[8:9], off
	v_lshl_add_u64 v[8:9], s[10:11], 0, v[132:133]
	s_add_u32 s10, s48, 0x164000
	s_mov_b32 m0, s51
	s_addc_u32 s11, s49, 0
	global_load_lds_dwordx4 v[8:9], off
	s_add_i32 m0, s29, 0x1c000
	v_lshl_add_u64 v[8:9], s[10:11], 0, v[130:131]
	global_load_lds_dwordx4 v[8:9], off
	v_lshl_add_u64 v[8:9], s[10:11], 0, v[134:135]
	s_add_i32 m0, s29, 0x1e000
	v_and_b32_e32 v7, 15, v0
	global_load_lds_dwordx4 v[8:9], off
	v_lshrrev_b32_e32 v8, 1, v0
	v_and_b32_e32 v8, 24, v8
	v_lshlrev_b32_e32 v9, 1, v8
	v_lshlrev_b32_e32 v0, 2, v0
	v_lshl_or_b32 v139, s7, 6, v7
	v_lshl_or_b32 v7, v7, 6, v9
	v_and_b32_e32 v0, 32, v0
	v_bitop3_b32 v152, v7, s13, v0 bitop3:0xde
	v_lshlrev_b32_e32 v0, 10, v1
	v_and_b32_e32 v0, 0xfffff800, v0
	v_lshl_add_u32 v0, v2, 7, v0
	v_and_b32_e32 v1, 1, v1
	v_lshl_or_b32 v0, v1, 6, v0
	v_lshl_add_u32 v140, v3, 1, v0
	v_lshlrev_b32_e32 v0, 10, v4
	v_lshlrev_b32_e32 v9, 2, v139
	v_and_b32_e32 v0, 0xfffff800, v0
	v_and_b32_e32 v10, 32, v9
	s_waitcnt vmcnt(6)
	s_cmpk_lt_u32 s6, 0x100
	v_lshl_add_u32 v0, v5, 7, v0
	v_and_b32_e32 v1, 1, v4
	v_bitop3_b32 v10, v7, s12, v10 bitop3:0xde
	s_cselect_b64 s[10:11], -1, 0
	v_or_b32_e32 v153, 16, v139
	v_or_b32_e32 v154, 32, v139
	v_or_b32_e32 v155, 48, v139
	v_add_u32_e32 v156, 0x80, v139
	v_add_u32_e32 v157, 0x90, v139
	v_add_u32_e32 v158, 0xa0, v139
	v_add_u32_e32 v159, 0xb0, v139
	s_add_i32 s6, 0, 0x21000
	v_lshl_or_b32 v0, v1, 6, v0
	s_add_i32 s57, 0, 0x10000
	s_add_i32 s58, 0, 0x14000
	v_and_or_b32 v138, s9, 32, v8
	v_add_u32_e32 v160, s6, v9
	v_lshl_add_u32 v161, v153, 2, s6
	v_lshl_add_u32 v162, v154, 2, s6
	v_lshl_add_u32 v163, v155, 2, s6
	v_lshl_add_u32 v164, v156, 2, s6
	v_lshl_add_u32 v165, v157, 2, s6
	v_lshl_add_u32 v166, v158, 2, s6
	v_lshl_add_u32 v167, v159, 2, s6
	v_mov_b32_e32 v141, v137
	v_lshl_add_u32 v142, v6, 1, v0
	v_mov_b32_e32 v143, v137
	v_mov_b64_e32 v[144:145], 0xb00
	v_mov_b64_e32 v[146:147], 0xaff
	s_movk_i32 s56, 0x161
	v_add_u32_e32 v168, s57, v152
	v_add_u32_e32 v169, s58, v152
	v_add_u32_e32 v170, 0, v10
	v_mov_b32_e32 v171, 0x358637bd
	s_mov_b32 s59, 0x800000
	s_barrier
	s_branch .LBB0_1041

; #define PG8_STAGE(bufoff, gbase, voff) do { _Pragma("unroll") for (int _i = 0; _i < 2; ++_i) \
;         __builtin_amdgcn_global_load_lds((const unsigned*)((const char*)(gbase) + (voff)[_i]), (LAS unsigned*)(lds + (bufoff) + ldsw + _i * 8192), 16, 0, 0); } while (0)
; #define PG8_LDA(dst, b, h) do { _Pragma("unroll") for (int m = 0; m < 4; ++m) _Pragma("unroll") for (int k = 0; k < 2; ++k) dst[m][k] = *(const LAS bf16x8*)(lds + PG8_SA(b, h) + aoff + m * 2048 + k * 1024); } while (0)
; #define PG8_LDB(dst, b, h) do { _Pragma("unroll") for (int n = 0; n < 2; ++n) _Pragma("unroll") for (int k = 0; k < 2; ++k) dst[n][k] = *(const LAS bf16x8*)(lds + PG8_SB(b, h) + boff + n * 2048 + k * 1024); } while (0)
; #define PG8_MMA(ai, bj, At, Bt) do { __builtin_amdgcn_s_setprio(1); _Pragma("unroll") for (int m = 0; m < 4; ++m) _Pragma("unroll") for (int n = 0; n < 2; ++n) _Pragma("unroll") for (int k = 0; k < 2; ++k) \
;         acc[ai][bj][m][n] = __builtin_amdgcn_mfma_f32_16x16x32_bf16(Bt[n][k], At[m][k], acc[ai][bj][m][n], 0, 0, 0); __builtin_amdgcn_s_setprio(0); } while (0)
; #define PG8_WAIT_V(n) asm volatile("s_waitcnt vmcnt(" #n ")" ::: "memory")
; template <bool ALIGN_EPI, class Epi, class Sched>
; __device__ __forceinline__ void gemm_phase(LAS unsigned char* lds, const int lda, const int ldb, const int K, const Sched& S, const Epi& E, const size_t kstepA = (size_t)(BK * 2), const size_t kstepB = (size_t)(BK * 2)) {
;     ...
;         for (int t = 0; t < nt; t += 2) {
;             const bool last = (t == nt - 2);
;             const char* a1 = cA + (size_t)(t + 1) * kstepA;
;             const char* a2 = last ? nA : cA + (size_t)(t + 2) * kstepA; const char* b2 = last ? nB : cB + (size_t)(t + 2) * kstep;
;             const char* a3 = a2 + kstepA; const char* b3 = b2 + kstep;
;             PG8_LDB(B0, 0, 0); PG8_LDB(B1, 0, 1); PG8_SCHED; PG8_LDA(At, 0, 0); PG8_STAGE(PG8_SA(1, 1), a1 + hstepA, voffA);
;             PG8_WAIT_V(8); PG8_WAIT_L(0); PG8_BAR; PG8_MMA(0, 0, At, B0); PG8_MMA(0, 1, At, B1); PG8_BAR; PG8_SCHED;
;     ...
; #pragma unroll
;         for (int a = 0; a < 2; ++a)
; #pragma unroll
;             for (int b = 0; b < 2; ++b)
; #pragma unroll
;                 for (int m = 0; m < 4; ++m)
; #pragma unroll
;                     for (int n = 0; n < 2; ++n) acc[a][b][m][n] = (f32x4){0.f, 0.f, 0.f, 0.f};
;         cur = nxt; cA = nA; cB = nB; ++ui;
.LBB0_1043:
	s_add_u32 s9, s48, 0x2c0000
	s_addc_u32 s13, s49, 0
	s_add_u32 s46, s46, 0x204000
	v_mov_b32_e32 v0, 0
	s_addc_u32 s47, s47, 0
	s_mov_b32 s15, -2
	v_mov_b32_e32 v1, v0
	v_mov_b32_e32 v2, v0
	v_mov_b32_e32 v3, v0
	v_mov_b32_e32 v4, v0
	v_mov_b32_e32 v5, v0
	v_mov_b32_e32 v6, v0
	v_mov_b32_e32 v7, v0
	v_mov_b32_e32 v16, v0
	v_mov_b32_e32 v17, v0
	v_mov_b32_e32 v18, v0
	v_mov_b32_e32 v19, v0
	v_mov_b32_e32 v20, v0
	v_mov_b32_e32 v21, v0
	v_mov_b32_e32 v22, v0
	v_mov_b32_e32 v23, v0
	v_mov_b32_e32 v32, v0
	v_mov_b32_e32 v33, v0
	v_mov_b32_e32 v34, v0
	v_mov_b32_e32 v35, v0
	v_mov_b32_e32 v36, v0
	v_mov_b32_e32 v37, v0
	v_mov_b32_e32 v38, v0
	v_mov_b32_e32 v39, v0
	v_mov_b32_e32 v48, v0
	v_mov_b32_e32 v49, v0
	v_mov_b32_e32 v50, v0
	v_mov_b32_e32 v51, v0
	v_mov_b32_e32 v52, v0
	v_mov_b32_e32 v53, v0
	v_mov_b32_e32 v54, v0
	v_mov_b32_e32 v55, v0
	v_mov_b32_e32 v8, v0
	v_mov_b32_e32 v9, v0
	v_mov_b32_e32 v10, v0
	v_mov_b32_e32 v11, v0
	v_mov_b32_e32 v12, v0
	v_mov_b32_e32 v13, v0
	v_mov_b32_e32 v14, v0
	v_mov_b32_e32 v15, v0
	v_mov_b32_e32 v24, v0
	v_mov_b32_e32 v25, v0
	v_mov_b32_e32 v26, v0
	v_mov_b32_e32 v27, v0
	v_mov_b32_e32 v28, v0
	v_mov_b32_e32 v29, v0
	v_mov_b32_e32 v30, v0
	v_mov_b32_e32 v31, v0
	v_mov_b32_e32 v40, v0
	v_mov_b32_e32 v41, v0
	v_mov_b32_e32 v42, v0
	v_mov_b32_e32 v43, v0
	v_mov_b32_e32 v44, v0
	v_mov_b32_e32 v45, v0
	v_mov_b32_e32 v46, v0
	v_mov_b32_e32 v47, v0
	v_mov_b32_e32 v56, v0
	v_mov_b32_e32 v57, v0
	v_mov_b32_e32 v58, v0
	v_mov_b32_e32 v59, v0
	v_mov_b32_e32 v60, v0
	v_mov_b32_e32 v61, v0
	v_mov_b32_e32 v62, v0
	v_mov_b32_e32 v63, v0
	v_mov_b32_e32 v64, v0
	v_mov_b32_e32 v65, v0
	v_mov_b32_e32 v66, v0
	v_mov_b32_e32 v67, v0
	v_mov_b32_e32 v68, v0
	v_mov_b32_e32 v69, v0
	v_mov_b32_e32 v70, v0
	v_mov_b32_e32 v71, v0
	v_mov_b32_e32 v80, v0
	v_mov_b32_e32 v81, v0
	v_mov_b32_e32 v82, v0
	v_mov_b32_e32 v83, v0
	v_mov_b32_e32 v84, v0
	v_mov_b32_e32 v85, v0
	v_mov_b32_e32 v86, v0
	v_mov_b32_e32 v87, v0
	v_mov_b32_e32 v96, v0
	v_mov_b32_e32 v97, v0
	v_mov_b32_e32 v98, v0
	v_mov_b32_e32 v99, v0
	v_mov_b32_e32 v100, v0
	v_mov_b32_e32 v101, v0
	v_mov_b32_e32 v102, v0
	v_mov_b32_e32 v103, v0
	v_mov_b32_e32 v112, v0
	v_mov_b32_e32 v113, v0
	v_mov_b32_e32 v114, v0
	v_mov_b32_e32 v115, v0
	v_mov_b32_e32 v116, v0
	v_mov_b32_e32 v117, v0
	v_mov_b32_e32 v118, v0
	v_mov_b32_e32 v119, v0
	v_mov_b32_e32 v72, v0
	v_mov_b32_e32 v73, v0
	v_mov_b32_e32 v74, v0
	v_mov_b32_e32 v75, v0
	v_mov_b32_e32 v76, v0
	v_mov_b32_e32 v77, v0
	v_mov_b32_e32 v78, v0
	v_mov_b32_e32 v79, v0
	v_mov_b32_e32 v88, v0
	v_mov_b32_e32 v89, v0
	v_mov_b32_e32 v90, v0
	v_mov_b32_e32 v91, v0
	v_mov_b32_e32 v92, v0
	v_mov_b32_e32 v93, v0
	v_mov_b32_e32 v94, v0
	v_mov_b32_e32 v95, v0
	v_mov_b32_e32 v104, v0
	v_mov_b32_e32 v105, v0
	v_mov_b32_e32 v106, v0
	v_mov_b32_e32 v107, v0
	v_mov_b32_e32 v108, v0
	v_mov_b32_e32 v109, v0
	v_mov_b32_e32 v110, v0
	v_mov_b32_e32 v111, v0
	v_mov_b32_e32 v120, v0
	v_mov_b32_e32 v121, v0
	v_mov_b32_e32 v122, v0
	v_mov_b32_e32 v123, v0
	v_mov_b32_e32 v124, v0
	v_mov_b32_e32 v125, v0
	v_mov_b32_e32 v126, v0
	v_mov_b32_e32 v127, v0
	s_cmp_lg_u64 s[10:11], 0
	s_cbranch_scc0 .Lp12_kloop_y
.LBB0_1044:
	ds_read_b128 v[148:151], v168
	ds_read_b128 v[172:175], v168 offset:1024
	ds_read_b128 v[176:179], v168 offset:2048
	ds_read_b128 v[180:183], v168 offset:3072
	ds_read_b128 v[186:189], v169
	ds_read_b128 v[190:193], v169 offset:1024
	ds_read_b128 v[194:197], v169 offset:2048
	ds_read_b128 v[198:201], v169 offset:3072
	s_add_u32 s48, s46, 0x1fc000
	s_addc_u32 s49, s47, 0
	s_cmp_eq_u32 s15, 28
	s_cselect_b32 s54, s22, s48
	s_cselect_b32 s55, s23, s49
	s_cselect_b32 s52, s44, s9
	s_cselect_b32 s53, s45, s13
	s_add_u32 s48, s54, 0x200000
	s_addc_u32 s49, s55, 0
	v_lshl_add_u64 v[234:235], s[46:47], 0, v[140:141]
	s_add_i32 m0, s29, 0xc000
	ds_read_b128 v[202:205], v170
	ds_read_b128 v[206:209], v170 offset:1024
	ds_read_b128 v[210:213], v170 offset:2048
	ds_read_b128 v[214:217], v170 offset:3072
	ds_read_b128 v[218:221], v170 offset:4096
	ds_read_b128 v[222:225], v170 offset:5120
	ds_read_b128 v[226:229], v170 offset:6144
	ds_read_b128 v[230:233], v170 offset:7168
	global_load_lds_dwordx4 v[234:235], off
	v_lshl_add_u64 v[234:235], s[46:47], 0, v[142:143]
	s_add_i32 m0, s29, 0xe000
	s_nop 0
	global_load_lds_dwordx4 v[234:235], off
	s_waitcnt vmcnt(8)
	s_waitcnt lgkmcnt(0)
	s_setprio 1
	s_waitcnt lgkmcnt(0)
	v_mfma_f32_16x16x32_bf16 v[124:127], v[148:151], v[202:205], v[124:127]
	v_mfma_f32_16x16x32_bf16 v[124:127], v[172:175], v[206:209], v[124:127]
	v_mfma_f32_16x16x32_bf16 v[120:123], v[176:179], v[202:205], v[120:123]
	v_mfma_f32_16x16x32_bf16 v[120:123], v[180:183], v[206:209], v[120:123]
	v_mfma_f32_16x16x32_bf16 v[108:111], v[148:151], v[210:213], v[108:111]
	v_mfma_f32_16x16x32_bf16 v[108:111], v[172:175], v[214:217], v[108:111]
	v_mfma_f32_16x16x32_bf16 v[104:107], v[176:179], v[210:213], v[104:107]
	v_mfma_f32_16x16x32_bf16 v[104:107], v[180:183], v[214:217], v[104:107]
	v_mfma_f32_16x16x32_bf16 v[92:95], v[148:151], v[218:221], v[92:95]
	v_mfma_f32_16x16x32_bf16 v[92:95], v[172:175], v[222:225], v[92:95]
	v_mfma_f32_16x16x32_bf16 v[88:91], v[176:179], v[218:221], v[88:91]
	v_mfma_f32_16x16x32_bf16 v[88:91], v[180:183], v[222:225], v[88:91]
	v_mfma_f32_16x16x32_bf16 v[76:79], v[148:151], v[226:229], v[76:79]
	v_mfma_f32_16x16x32_bf16 v[76:79], v[172:175], v[230:233], v[76:79]
	v_mfma_f32_16x16x32_bf16 v[72:75], v[176:179], v[226:229], v[72:75]
	v_mfma_f32_16x16x32_bf16 v[72:75], v[180:183], v[230:233], v[72:75]
	s_setprio 0
	s_setprio 1
	v_mfma_f32_16x16x32_bf16 v[116:119], v[186:189], v[202:205], v[116:119]
	v_mfma_f32_16x16x32_bf16 v[116:119], v[190:193], v[206:209], v[116:119]
	v_mfma_f32_16x16x32_bf16 v[112:115], v[194:197], v[202:205], v[112:115]
	v_mfma_f32_16x16x32_bf16 v[112:115], v[198:201], v[206:209], v[112:115]
	v_mfma_f32_16x16x32_bf16 v[100:103], v[186:189], v[210:213], v[100:103]
	v_mfma_f32_16x16x32_bf16 v[100:103], v[190:193], v[214:217], v[100:103]
	v_mfma_f32_16x16x32_bf16 v[96:99], v[194:197], v[210:213], v[96:99]
	v_mfma_f32_16x16x32_bf16 v[96:99], v[198:201], v[214:217], v[96:99]
	v_mfma_f32_16x16x32_bf16 v[84:87], v[186:189], v[218:221], v[84:87]
	v_mfma_f32_16x16x32_bf16 v[84:87], v[190:193], v[222:225], v[84:87]
	v_mfma_f32_16x16x32_bf16 v[80:83], v[194:197], v[218:221], v[80:83]
	v_mfma_f32_16x16x32_bf16 v[80:83], v[198:201], v[222:225], v[80:83]
	v_mfma_f32_16x16x32_bf16 v[68:71], v[186:189], v[226:229], v[68:71]
	v_mfma_f32_16x16x32_bf16 v[68:71], v[190:193], v[230:233], v[68:71]
	v_mfma_f32_16x16x32_bf16 v[64:67], v[194:197], v[226:229], v[64:67]
	v_mfma_f32_16x16x32_bf16 v[64:67], v[198:201], v[230:233], v[64:67]
	s_setprio 0
	s_barrier
; #define PG8_STAGE(bufoff, gbase, voff) do { _Pragma("unroll") for (int _i = 0; _i < 2; ++_i) \
;         __builtin_amdgcn_global_load_lds((const unsigned*)((const char*)(gbase) + (voff)[_i]), (LAS unsigned*)(lds + (bufoff) + ldsw + _i * 8192), 16, 0, 0); } while (0)
; #define PG8_LDA(dst, b, h) do { _Pragma("unroll") for (int m = 0; m < 4; ++m) _Pragma("unroll") for (int k = 0; k < 2; ++k) dst[m][k] = *(const LAS bf16x8*)(lds + PG8_SA(b, h) + aoff + m * 2048 + k * 1024); } while (0)
; #define PG8_LDB(dst, b, h) do { _Pragma("unroll") for (int n = 0; n < 2; ++n) _Pragma("unroll") for (int k = 0; k < 2; ++k) dst[n][k] = *(const LAS bf16x8*)(lds + PG8_SB(b, h) + boff + n * 2048 + k * 1024); } while (0)
; #define PG8_MMA(ai, bj, At, Bt) do { __builtin_amdgcn_s_setprio(1); _Pragma("unroll") for (int m = 0; m < 4; ++m) _Pragma("unroll") for (int n = 0; n < 2; ++n) _Pragma("unroll") for (int k = 0; k < 2; ++k) \
;         acc[ai][bj][m][n] = __builtin_amdgcn_mfma_f32_16x16x32_bf16(Bt[n][k], At[m][k], acc[ai][bj][m][n], 0, 0, 0); __builtin_amdgcn_s_setprio(0); } while (0)
; #define PG8_WAIT_V(n) asm volatile("s_waitcnt vmcnt(" #n ")" ::: "memory")
; #define PG8_WAIT_L(n) asm volatile("s_waitcnt lgkmcnt(" #n ")" ::: "memory")
; #define PG8_BAR __builtin_amdgcn_s_barrier()
; #define PG8_SCHED __builtin_amdgcn_sched_barrier(0)
; template <bool ALIGN_EPI, class Epi, class Sched>
; __device__ __forceinline__ void gemm_phase(LAS unsigned char* lds, const int lda, const int ldb, const int K, const Sched& S, const Epi& E, const size_t kstepA = (size_t)(BK * 2), const size_t kstepB = (size_t)(BK * 2)) {
;     ...
;             PG8_LDA(At, 0, 1); PG8_STAGE(PG8_SB(0, 0), b2, voffB); PG8_STAGE(PG8_SB(0, 1), b2 + hstepB, voffB); PG8_STAGE(PG8_SA(0, 0), a2, voffA);
;             PG8_WAIT_V(8); PG8_WAIT_L(0); PG8_BAR; PG8_MMA(1, 0, At, B0); PG8_MMA(1, 1, At, B1); PG8_BAR; PG8_SCHED;
;             PG8_LDB(B0, 1, 0); PG8_LDB(B1, 1, 1); PG8_SCHED; PG8_LDA(At, 1, 0); PG8_STAGE(PG8_SA(0, 1), a2 + hstepA, voffA);
;             PG8_WAIT_V(8); PG8_WAIT_L(0); PG8_BAR; PG8_MMA(0, 0, At, B0); PG8_MMA(0, 1, At, B1); PG8_BAR; PG8_SCHED;
	s_add_i32 s61, s57, s19
	v_lshl_add_u64 v[234:235], s[52:53], 0, v[130:131]
	s_mov_b32 m0, s61
	ds_read_b128 v[202:205], v170 offset:16384
	ds_read_b128 v[206:209], v170 offset:17408
	ds_read_b128 v[210:213], v170 offset:18432
	ds_read_b128 v[214:217], v170 offset:19456
	ds_read_b128 v[218:221], v170 offset:20480
	ds_read_b128 v[222:225], v170 offset:21504
	ds_read_b128 v[226:229], v170 offset:22528
	ds_read_b128 v[230:233], v170 offset:23552
	global_load_lds_dwordx4 v[234:235], off
	s_add_i32 m0, s61, 0x2000
	s_add_u32 s62, s52, 0x4000
	v_lshl_add_u64 v[234:235], s[52:53], 0, v[134:135]
	s_addc_u32 s63, s53, 0
	s_add_i32 s61, s58, s19
	global_load_lds_dwordx4 v[234:235], off
	v_lshl_add_u64 v[234:235], s[62:63], 0, v[130:131]
	s_mov_b32 m0, s61
	s_nop 0
	global_load_lds_dwordx4 v[234:235], off
	v_lshl_add_u64 v[234:235], s[62:63], 0, v[134:135]
	s_add_i32 m0, s61, 0x2000
	s_nop 0
	global_load_lds_dwordx4 v[234:235], off
	v_lshl_add_u64 v[234:235], s[54:55], 0, v[128:129]
	s_mov_b32 m0, s29
	s_nop 0
	global_load_lds_dwordx4 v[234:235], off
	v_lshl_add_u64 v[234:235], s[54:55], 0, v[132:133]
	s_mov_b32 m0, s30
	s_nop 0
	global_load_lds_dwordx4 v[234:235], off
	s_waitcnt vmcnt(8)
	s_waitcnt lgkmcnt(0)
	s_setprio 1
	s_waitcnt lgkmcnt(0)
	v_mfma_f32_16x16x32_bf16 v[60:63], v[148:151], v[202:205], v[60:63]
	v_mfma_f32_16x16x32_bf16 v[60:63], v[172:175], v[206:209], v[60:63]
	v_mfma_f32_16x16x32_bf16 v[56:59], v[176:179], v[202:205], v[56:59]
	v_mfma_f32_16x16x32_bf16 v[56:59], v[180:183], v[206:209], v[56:59]
	v_mfma_f32_16x16x32_bf16 v[44:47], v[148:151], v[210:213], v[44:47]
	v_mfma_f32_16x16x32_bf16 v[44:47], v[172:175], v[214:217], v[44:47]
	v_mfma_f32_16x16x32_bf16 v[40:43], v[176:179], v[210:213], v[40:43]
	v_mfma_f32_16x16x32_bf16 v[40:43], v[180:183], v[214:217], v[40:43]
	v_mfma_f32_16x16x32_bf16 v[28:31], v[148:151], v[218:221], v[28:31]
	v_mfma_f32_16x16x32_bf16 v[28:31], v[172:175], v[222:225], v[28:31]
	v_mfma_f32_16x16x32_bf16 v[24:27], v[176:179], v[218:221], v[24:27]
	v_mfma_f32_16x16x32_bf16 v[24:27], v[180:183], v[222:225], v[24:27]
	v_mfma_f32_16x16x32_bf16 v[12:15], v[148:151], v[226:229], v[12:15]
	v_mfma_f32_16x16x32_bf16 v[12:15], v[172:175], v[230:233], v[12:15]
	v_mfma_f32_16x16x32_bf16 v[8:11], v[176:179], v[226:229], v[8:11]
	v_mfma_f32_16x16x32_bf16 v[8:11], v[180:183], v[230:233], v[8:11]
	s_setprio 0
	s_setprio 1
	v_mfma_f32_16x16x32_bf16 v[52:55], v[186:189], v[202:205], v[52:55]
	v_mfma_f32_16x16x32_bf16 v[52:55], v[190:193], v[206:209], v[52:55]
	v_mfma_f32_16x16x32_bf16 v[48:51], v[194:197], v[202:205], v[48:51]
	v_mfma_f32_16x16x32_bf16 v[48:51], v[198:201], v[206:209], v[48:51]
	v_mfma_f32_16x16x32_bf16 v[36:39], v[186:189], v[210:213], v[36:39]
	v_mfma_f32_16x16x32_bf16 v[36:39], v[190:193], v[214:217], v[36:39]
	v_mfma_f32_16x16x32_bf16 v[32:35], v[194:197], v[210:213], v[32:35]
	v_mfma_f32_16x16x32_bf16 v[32:35], v[198:201], v[214:217], v[32:35]
	v_mfma_f32_16x16x32_bf16 v[20:23], v[186:189], v[218:221], v[20:23]
	v_mfma_f32_16x16x32_bf16 v[20:23], v[190:193], v[222:225], v[20:23]
	v_mfma_f32_16x16x32_bf16 v[16:19], v[194:197], v[218:221], v[16:19]
	v_mfma_f32_16x16x32_bf16 v[16:19], v[198:201], v[222:225], v[16:19]
	v_mfma_f32_16x16x32_bf16 v[4:7], v[186:189], v[226:229], v[4:7]
	v_mfma_f32_16x16x32_bf16 v[4:7], v[190:193], v[230:233], v[4:7]
	v_mfma_f32_16x16x32_bf16 v[0:3], v[194:197], v[226:229], v[0:3]
	v_mfma_f32_16x16x32_bf16 v[0:3], v[198:201], v[230:233], v[0:3]
	s_setprio 0
	s_barrier
	s_add_i32 s61, 0, 0x18000
	v_add_u32_e32 v136, s61, v152
	s_add_i32 s62, 0, 0x1c000
	ds_read_b128 v[148:151], v136
	ds_read_b128 v[172:175], v136 offset:1024
	ds_read_b128 v[176:179], v136 offset:2048
	ds_read_b128 v[180:183], v136 offset:3072
	v_add_u32_e32 v136, s62, v152
	ds_read_b128 v[186:189], v136
	ds_read_b128 v[190:193], v136 offset:1024
	ds_read_b128 v[194:197], v136 offset:2048
	ds_read_b128 v[198:201], v136 offset:3072
	s_add_u32 s54, s54, 0x4000
	s_addc_u32 s55, s55, 0
	s_mov_b32 m0, s31
	v_lshl_add_u64 v[234:235], s[54:55], 0, v[128:129]
	ds_read_b128 v[202:205], v170 offset:32768
	ds_read_b128 v[206:209], v170 offset:33792
	ds_read_b128 v[210:213], v170 offset:34816
	ds_read_b128 v[214:217], v170 offset:35840
	ds_read_b128 v[218:221], v170 offset:36864
	ds_read_b128 v[222:225], v170 offset:37888
	ds_read_b128 v[226:229], v170 offset:38912
	ds_read_b128 v[230:233], v170 offset:39936
	global_load_lds_dwordx4 v[234:235], off
	v_lshl_add_u64 v[234:235], s[54:55], 0, v[132:133]
	s_mov_b32 m0, s33
	s_nop 0
	global_load_lds_dwordx4 v[234:235], off
	s_waitcnt vmcnt(8)
	s_waitcnt lgkmcnt(0)
	s_setprio 1
	s_waitcnt lgkmcnt(0)
	v_mfma_f32_16x16x32_bf16 v[124:127], v[148:151], v[202:205], v[124:127]
	v_mfma_f32_16x16x32_bf16 v[124:127], v[172:175], v[206:209], v[124:127]
	v_mfma_f32_16x16x32_bf16 v[120:123], v[176:179], v[202:205], v[120:123]
	v_mfma_f32_16x16x32_bf16 v[120:123], v[180:183], v[206:209], v[120:123]
	v_mfma_f32_16x16x32_bf16 v[108:111], v[148:151], v[210:213], v[108:111]
	v_mfma_f32_16x16x32_bf16 v[108:111], v[172:175], v[214:217], v[108:111]
	v_mfma_f32_16x16x32_bf16 v[104:107], v[176:179], v[210:213], v[104:107]
	v_mfma_f32_16x16x32_bf16 v[104:107], v[180:183], v[214:217], v[104:107]
	v_mfma_f32_16x16x32_bf16 v[92:95], v[148:151], v[218:221], v[92:95]
	v_mfma_f32_16x16x32_bf16 v[92:95], v[172:175], v[222:225], v[92:95]
	v_mfma_f32_16x16x32_bf16 v[88:91], v[176:179], v[218:221], v[88:91]
	v_mfma_f32_16x16x32_bf16 v[88:91], v[180:183], v[222:225], v[88:91]
	v_mfma_f32_16x16x32_bf16 v[76:79], v[148:151], v[226:229], v[76:79]
	v_mfma_f32_16x16x32_bf16 v[76:79], v[172:175], v[230:233], v[76:79]
	v_mfma_f32_16x16x32_bf16 v[72:75], v[176:179], v[226:229], v[72:75]
	v_mfma_f32_16x16x32_bf16 v[72:75], v[180:183], v[230:233], v[72:75]
	s_setprio 0
	s_setprio 1
	v_mfma_f32_16x16x32_bf16 v[116:119], v[186:189], v[202:205], v[116:119]
	v_mfma_f32_16x16x32_bf16 v[116:119], v[190:193], v[206:209], v[116:119]
	v_mfma_f32_16x16x32_bf16 v[112:115], v[194:197], v[202:205], v[112:115]
	v_mfma_f32_16x16x32_bf16 v[112:115], v[198:201], v[206:209], v[112:115]
	v_mfma_f32_16x16x32_bf16 v[100:103], v[186:189], v[210:213], v[100:103]
	v_mfma_f32_16x16x32_bf16 v[100:103], v[190:193], v[214:217], v[100:103]
	v_mfma_f32_16x16x32_bf16 v[96:99], v[194:197], v[210:213], v[96:99]
	v_mfma_f32_16x16x32_bf16 v[96:99], v[198:201], v[214:217], v[96:99]
	v_mfma_f32_16x16x32_bf16 v[84:87], v[186:189], v[218:221], v[84:87]
	v_mfma_f32_16x16x32_bf16 v[84:87], v[190:193], v[222:225], v[84:87]
	v_mfma_f32_16x16x32_bf16 v[80:83], v[194:197], v[218:221], v[80:83]
	v_mfma_f32_16x16x32_bf16 v[80:83], v[198:201], v[222:225], v[80:83]
	v_mfma_f32_16x16x32_bf16 v[68:71], v[186:189], v[226:229], v[68:71]
	v_mfma_f32_16x16x32_bf16 v[68:71], v[190:193], v[230:233], v[68:71]
	v_mfma_f32_16x16x32_bf16 v[64:67], v[194:197], v[226:229], v[64:67]
	v_mfma_f32_16x16x32_bf16 v[64:67], v[198:201], v[230:233], v[64:67]
	s_setprio 0
	s_barrier
; #define PG8_STAGE(bufoff, gbase, voff) do { _Pragma("unroll") for (int _i = 0; _i < 2; ++_i) \
;         __builtin_amdgcn_global_load_lds((const unsigned*)((const char*)(gbase) + (voff)[_i]), (LAS unsigned*)(lds + (bufoff) + ldsw + _i * 8192), 16, 0, 0); } while (0)
; #define PG8_LDA(dst, b, h) do { _Pragma("unroll") for (int m = 0; m < 4; ++m) _Pragma("unroll") for (int k = 0; k < 2; ++k) dst[m][k] = *(const LAS bf16x8*)(lds + PG8_SA(b, h) + aoff + m * 2048 + k * 1024); } while (0)
; #define PG8_LDB(dst, b, h) do { _Pragma("unroll") for (int n = 0; n < 2; ++n) _Pragma("unroll") for (int k = 0; k < 2; ++k) dst[n][k] = *(const LAS bf16x8*)(lds + PG8_SB(b, h) + boff + n * 2048 + k * 1024); } while (0)
; template <bool ALIGN_EPI, class Epi, class Sched>
; __device__ __forceinline__ void gemm_phase(LAS unsigned char* lds, const int lda, const int ldb, const int K, const Sched& S, const Epi& E, const size_t kstepA = (size_t)(BK * 2), const size_t kstepB = (size_t)(BK * 2)) {
;     ...
;         for (int t = 0; t < nt; t += 2) {
;             const bool last = (t == nt - 2);
;             const char* a1 = cA + (size_t)(t + 1) * kstepA;
;             const char* a2 = last ? nA : cA + (size_t)(t + 2) * kstepA; const char* b2 = last ? nB : cB + (size_t)(t + 2) * kstep;
;             const char* a3 = a2 + kstepA; const char* b3 = b2 + kstep;
;             PG8_LDB(B0, 0, 0); PG8_LDB(B1, 0, 1); PG8_SCHED; PG8_LDA(At, 0, 0); PG8_STAGE(PG8_SA(1, 1), a1 + hstepA, voffA);
;             PG8_WAIT_V(8); PG8_WAIT_L(0); PG8_BAR; PG8_MMA(0, 0, At, B0); PG8_MMA(0, 1, At, B1); PG8_BAR; PG8_SCHED;
;             PG8_LDA(At, 0, 1); PG8_STAGE(PG8_SB(0, 0), b2, voffB); PG8_STAGE(PG8_SB(0, 1), b2 + hstepB, voffB); PG8_STAGE(PG8_SA(0, 0), a2, voffA);
;             PG8_WAIT_V(8); PG8_WAIT_L(0); PG8_BAR; PG8_MMA(1, 0, At, B0); PG8_MMA(1, 1, At, B1); PG8_BAR; PG8_SCHED;
;             PG8_LDB(B0, 1, 0); PG8_LDB(B1, 1, 1); PG8_SCHED; PG8_LDA(At, 1, 0); PG8_STAGE(PG8_SA(0, 1), a2 + hstepA, voffA);
;             PG8_WAIT_V(8); PG8_WAIT_L(0); PG8_BAR; PG8_MMA(0, 0, At, B0); PG8_MMA(0, 1, At, B1); PG8_BAR; PG8_SCHED;
;             PG8_LDA(At, 1, 1); PG8_STAGE(PG8_SB(1, 0), b3, voffB); PG8_STAGE(PG8_SB(1, 1), b3 + hstepB, voffB); PG8_STAGE(PG8_SA(1, 0), a3, voffA);
;             PG8_WAIT_V(8); PG8_WAIT_L(0); PG8_BAR; PG8_MMA(1, 0, At, B0); PG8_MMA(1, 1, At, B1); PG8_BAR; PG8_SCHED;
	s_add_u32 s54, s52, 0x160000
	s_addc_u32 s55, s53, 0
	s_add_i32 s61, s61, s19
	v_lshl_add_u64 v[234:235], s[54:55], 0, v[130:131]
	s_mov_b32 m0, s61
	ds_read_b128 v[202:205], v170 offset:49152
	ds_read_b128 v[206:209], v170 offset:50176
	ds_read_b128 v[210:213], v170 offset:51200
	ds_read_b128 v[214:217], v170 offset:52224
	ds_read_b128 v[218:221], v170 offset:53248
	ds_read_b128 v[222:225], v170 offset:54272
	ds_read_b128 v[226:229], v170 offset:55296
	ds_read_b128 v[230:233], v170 offset:56320
	global_load_lds_dwordx4 v[234:235], off
	s_add_i32 m0, s61, 0x2000
	s_add_u32 s52, s52, 0x164000
	v_lshl_add_u64 v[234:235], s[54:55], 0, v[134:135]
	s_addc_u32 s53, s53, 0
	s_add_i32 s54, s62, s19
	global_load_lds_dwordx4 v[234:235], off
	v_lshl_add_u64 v[234:235], s[52:53], 0, v[130:131]
	s_mov_b32 m0, s54
	s_nop 0
	global_load_lds_dwordx4 v[234:235], off
	v_lshl_add_u64 v[234:235], s[52:53], 0, v[134:135]
	s_add_i32 m0, s54, 0x2000
	s_nop 0
	global_load_lds_dwordx4 v[234:235], off
	v_lshl_add_u64 v[234:235], s[48:49], 0, v[128:129]
	s_mov_b32 m0, s50
	s_nop 0
	global_load_lds_dwordx4 v[234:235], off
	v_lshl_add_u64 v[234:235], s[48:49], 0, v[132:133]
	s_mov_b32 m0, s51
	s_nop 0
	global_load_lds_dwordx4 v[234:235], off
	s_waitcnt vmcnt(8)
	s_waitcnt lgkmcnt(0)
	s_setprio 1
	s_waitcnt lgkmcnt(0)
	v_mfma_f32_16x16x32_bf16 v[60:63], v[148:151], v[202:205], v[60:63]
	v_mfma_f32_16x16x32_bf16 v[60:63], v[172:175], v[206:209], v[60:63]
	v_mfma_f32_16x16x32_bf16 v[56:59], v[176:179], v[202:205], v[56:59]
	v_mfma_f32_16x16x32_bf16 v[56:59], v[180:183], v[206:209], v[56:59]
	v_mfma_f32_16x16x32_bf16 v[44:47], v[148:151], v[210:213], v[44:47]
	v_mfma_f32_16x16x32_bf16 v[44:47], v[172:175], v[214:217], v[44:47]
	v_mfma_f32_16x16x32_bf16 v[40:43], v[176:179], v[210:213], v[40:43]
	v_mfma_f32_16x16x32_bf16 v[40:43], v[180:183], v[214:217], v[40:43]
	v_mfma_f32_16x16x32_bf16 v[28:31], v[148:151], v[218:221], v[28:31]
	v_mfma_f32_16x16x32_bf16 v[28:31], v[172:175], v[222:225], v[28:31]
	v_mfma_f32_16x16x32_bf16 v[24:27], v[176:179], v[218:221], v[24:27]
	v_mfma_f32_16x16x32_bf16 v[24:27], v[180:183], v[222:225], v[24:27]
	v_mfma_f32_16x16x32_bf16 v[12:15], v[148:151], v[226:229], v[12:15]
	v_mfma_f32_16x16x32_bf16 v[12:15], v[172:175], v[230:233], v[12:15]
	v_mfma_f32_16x16x32_bf16 v[8:11], v[176:179], v[226:229], v[8:11]
	v_mfma_f32_16x16x32_bf16 v[8:11], v[180:183], v[230:233], v[8:11]
	s_setprio 0
	s_setprio 1
	v_mfma_f32_16x16x32_bf16 v[52:55], v[186:189], v[202:205], v[52:55]
	v_mfma_f32_16x16x32_bf16 v[52:55], v[190:193], v[206:209], v[52:55]
	v_mfma_f32_16x16x32_bf16 v[48:51], v[194:197], v[202:205], v[48:51]
	v_mfma_f32_16x16x32_bf16 v[48:51], v[198:201], v[206:209], v[48:51]
	v_mfma_f32_16x16x32_bf16 v[36:39], v[186:189], v[210:213], v[36:39]
	v_mfma_f32_16x16x32_bf16 v[36:39], v[190:193], v[214:217], v[36:39]
	v_mfma_f32_16x16x32_bf16 v[32:35], v[194:197], v[210:213], v[32:35]
	v_mfma_f32_16x16x32_bf16 v[32:35], v[198:201], v[214:217], v[32:35]
	v_mfma_f32_16x16x32_bf16 v[20:23], v[186:189], v[218:221], v[20:23]
	v_mfma_f32_16x16x32_bf16 v[20:23], v[190:193], v[222:225], v[20:23]
	v_mfma_f32_16x16x32_bf16 v[16:19], v[194:197], v[218:221], v[16:19]
	v_mfma_f32_16x16x32_bf16 v[16:19], v[198:201], v[222:225], v[16:19]
	v_mfma_f32_16x16x32_bf16 v[4:7], v[186:189], v[226:229], v[4:7]
	v_mfma_f32_16x16x32_bf16 v[4:7], v[190:193], v[230:233], v[4:7]
	v_mfma_f32_16x16x32_bf16 v[0:3], v[194:197], v[226:229], v[0:3]
	v_mfma_f32_16x16x32_bf16 v[0:3], v[198:201], v[230:233], v[0:3]
	s_setprio 0
	s_barrier
	s_add_i32 s15, s15, 2
	s_add_u32 s9, s9, 0x2c0000
	s_addc_u32 s13, s13, 0
	s_add_u32 s46, s46, 0x400000
	s_addc_u32 s47, s47, 0
	s_cmp_gt_u32 s15, 29
	s_cbranch_scc0 .LBB0_1044
	s_branch .Lp12_kloop_done
.Lp12_kloop_y:
	ds_read_b128 v[148:151], v168
	ds_read_b128 v[172:175], v168 offset:1024
	ds_read_b128 v[176:179], v168 offset:2048
	ds_read_b128 v[180:183], v168 offset:3072
	ds_read_b128 v[186:189], v169
	ds_read_b128 v[190:193], v169 offset:1024
	ds_read_b128 v[194:197], v169 offset:2048
	ds_read_b128 v[198:201], v169 offset:3072
	s_add_u32 s48, s46, 0x1fc000
	s_addc_u32 s49, s47, 0
	s_cmp_eq_u32 s15, 28
	s_cselect_b32 s54, s22, s48
	s_cselect_b32 s55, s23, s49
	s_cselect_b32 s52, s44, s9
	s_cselect_b32 s53, s45, s13
	s_add_u32 s48, s54, 0x200000
	s_addc_u32 s49, s55, 0
	v_lshl_add_u64 v[234:235], s[46:47], 0, v[140:141]
	s_add_i32 m0, s29, 0xc000
	ds_read_b128 v[202:205], v170
	ds_read_b128 v[206:209], v170 offset:1024
	ds_read_b128 v[210:213], v170 offset:2048
	ds_read_b128 v[214:217], v170 offset:3072
	ds_read_b128 v[218:221], v170 offset:4096
	ds_read_b128 v[222:225], v170 offset:5120
	ds_read_b128 v[226:229], v170 offset:6144
	ds_read_b128 v[230:233], v170 offset:7168
	global_load_lds_dwordx4 v[234:235], off
	v_lshl_add_u64 v[234:235], s[46:47], 0, v[142:143]
	s_add_i32 m0, s29, 0xe000
	s_nop 0
	global_load_lds_dwordx4 v[234:235], off
	s_waitcnt vmcnt(8)
	s_waitcnt lgkmcnt(0)
	s_barrier
; #define PG8_STAGE(bufoff, gbase, voff) do { _Pragma("unroll") for (int _i = 0; _i < 2; ++_i) \
;         __builtin_amdgcn_global_load_lds((const unsigned*)((const char*)(gbase) + (voff)[_i]), (LAS unsigned*)(lds + (bufoff) + ldsw + _i * 8192), 16, 0, 0); } while (0)
; #define PG8_LDA(dst, b, h) do { _Pragma("unroll") for (int m = 0; m < 4; ++m) _Pragma("unroll") for (int k = 0; k < 2; ++k) dst[m][k] = *(const LAS bf16x8*)(lds + PG8_SA(b, h) + aoff + m * 2048 + k * 1024); } while (0)
; #define PG8_LDB(dst, b, h) do { _Pragma("unroll") for (int n = 0; n < 2; ++n) _Pragma("unroll") for (int k = 0; k < 2; ++k) dst[n][k] = *(const LAS bf16x8*)(lds + PG8_SB(b, h) + boff + n * 2048 + k * 1024); } while (0)
; #define PG8_MMA(ai, bj, At, Bt) do { __builtin_amdgcn_s_setprio(1); _Pragma("unroll") for (int m = 0; m < 4; ++m) _Pragma("unroll") for (int n = 0; n < 2; ++n) _Pragma("unroll") for (int k = 0; k < 2; ++k) \
;         acc[ai][bj][m][n] = __builtin_amdgcn_mfma_f32_16x16x32_bf16(Bt[n][k], At[m][k], acc[ai][bj][m][n], 0, 0, 0); __builtin_amdgcn_s_setprio(0); } while (0)
; template <bool ALIGN_EPI, class Epi, class Sched>
; __device__ __forceinline__ void gemm_phase(LAS unsigned char* lds, const int lda, const int ldb, const int K, const Sched& S, const Epi& E, const size_t kstepA = (size_t)(BK * 2), const size_t kstepB = (size_t)(BK * 2)) {
;     ...
;             PG8_LDB(B0, 0, 0); PG8_LDB(B1, 0, 1); PG8_SCHED; PG8_LDA(At, 0, 0); PG8_STAGE(PG8_SA(1, 1), a1 + hstepA, voffA);
;             PG8_WAIT_V(8); PG8_WAIT_L(0); PG8_BAR; PG8_MMA(0, 0, At, B0); PG8_MMA(0, 1, At, B1); PG8_BAR; PG8_SCHED;
;             PG8_LDA(At, 0, 1); PG8_STAGE(PG8_SB(0, 0), b2, voffB); PG8_STAGE(PG8_SB(0, 1), b2 + hstepB, voffB); PG8_STAGE(PG8_SA(0, 0), a2, voffA);
;             PG8_WAIT_V(8); PG8_WAIT_L(0); PG8_BAR; PG8_MMA(1, 0, At, B0); PG8_MMA(1, 1, At, B1); PG8_BAR; PG8_SCHED;
;             PG8_LDB(B0, 1, 0); PG8_LDB(B1, 1, 1); PG8_SCHED; PG8_LDA(At, 1, 0); PG8_STAGE(PG8_SA(0, 1), a2 + hstepA, voffA);
;             PG8_WAIT_V(8); PG8_WAIT_L(0); PG8_BAR; PG8_MMA(0, 0, At, B0); PG8_MMA(0, 1, At, B1); PG8_BAR; PG8_SCHED;
;             PG8_LDA(At, 1, 1); PG8_STAGE(PG8_SB(1, 0), b3, voffB); PG8_STAGE(PG8_SB(1, 1), b3 + hstepB, voffB); PG8_STAGE(PG8_SA(1, 0), a3, voffA);
;             PG8_WAIT_V(8); PG8_WAIT_L(0); PG8_BAR; PG8_MMA(1, 0, At, B0); PG8_MMA(1, 1, At, B1); PG8_BAR; PG8_SCHED;
	s_setprio 2
	s_waitcnt lgkmcnt(0)
	v_mfma_f32_16x16x32_bf16 v[124:127], v[148:151], v[202:205], v[124:127]
	v_mfma_f32_16x16x32_bf16 v[124:127], v[172:175], v[206:209], v[124:127]
	v_mfma_f32_16x16x32_bf16 v[120:123], v[176:179], v[202:205], v[120:123]
	v_mfma_f32_16x16x32_bf16 v[120:123], v[180:183], v[206:209], v[120:123]
	v_mfma_f32_16x16x32_bf16 v[108:111], v[148:151], v[210:213], v[108:111]
	v_mfma_f32_16x16x32_bf16 v[108:111], v[172:175], v[214:217], v[108:111]
	v_mfma_f32_16x16x32_bf16 v[104:107], v[176:179], v[210:213], v[104:107]
	v_mfma_f32_16x16x32_bf16 v[104:107], v[180:183], v[214:217], v[104:107]
	v_mfma_f32_16x16x32_bf16 v[92:95], v[148:151], v[218:221], v[92:95]
	v_mfma_f32_16x16x32_bf16 v[92:95], v[172:175], v[222:225], v[92:95]
	v_mfma_f32_16x16x32_bf16 v[88:91], v[176:179], v[218:221], v[88:91]
	v_mfma_f32_16x16x32_bf16 v[88:91], v[180:183], v[222:225], v[88:91]
	v_mfma_f32_16x16x32_bf16 v[76:79], v[148:151], v[226:229], v[76:79]
	v_mfma_f32_16x16x32_bf16 v[76:79], v[172:175], v[230:233], v[76:79]
	v_mfma_f32_16x16x32_bf16 v[72:75], v[176:179], v[226:229], v[72:75]
	v_mfma_f32_16x16x32_bf16 v[72:75], v[180:183], v[230:233], v[72:75]
	s_setprio 0
	s_setprio 2
	v_mfma_f32_16x16x32_bf16 v[116:119], v[186:189], v[202:205], v[116:119]
	v_mfma_f32_16x16x32_bf16 v[116:119], v[190:193], v[206:209], v[116:119]
	v_mfma_f32_16x16x32_bf16 v[112:115], v[194:197], v[202:205], v[112:115]
	v_mfma_f32_16x16x32_bf16 v[112:115], v[198:201], v[206:209], v[112:115]
	v_mfma_f32_16x16x32_bf16 v[100:103], v[186:189], v[210:213], v[100:103]
	v_mfma_f32_16x16x32_bf16 v[100:103], v[190:193], v[214:217], v[100:103]
	v_mfma_f32_16x16x32_bf16 v[96:99], v[194:197], v[210:213], v[96:99]
	v_mfma_f32_16x16x32_bf16 v[96:99], v[198:201], v[214:217], v[96:99]
	v_mfma_f32_16x16x32_bf16 v[84:87], v[186:189], v[218:221], v[84:87]
	v_mfma_f32_16x16x32_bf16 v[84:87], v[190:193], v[222:225], v[84:87]
	v_mfma_f32_16x16x32_bf16 v[80:83], v[194:197], v[218:221], v[80:83]
	v_mfma_f32_16x16x32_bf16 v[80:83], v[198:201], v[222:225], v[80:83]
	v_mfma_f32_16x16x32_bf16 v[68:71], v[186:189], v[226:229], v[68:71]
	v_mfma_f32_16x16x32_bf16 v[68:71], v[190:193], v[230:233], v[68:71]
	v_mfma_f32_16x16x32_bf16 v[64:67], v[194:197], v[226:229], v[64:67]
	v_mfma_f32_16x16x32_bf16 v[64:67], v[198:201], v[230:233], v[64:67]
	s_setprio 0
	s_add_i32 s61, s57, s19
	v_lshl_add_u64 v[234:235], s[52:53], 0, v[130:131]
	s_mov_b32 m0, s61
	ds_read_b128 v[202:205], v170 offset:16384
	ds_read_b128 v[206:209], v170 offset:17408
	ds_read_b128 v[210:213], v170 offset:18432
	ds_read_b128 v[214:217], v170 offset:19456
	ds_read_b128 v[218:221], v170 offset:20480
	ds_read_b128 v[222:225], v170 offset:21504
	ds_read_b128 v[226:229], v170 offset:22528
	ds_read_b128 v[230:233], v170 offset:23552
	global_load_lds_dwordx4 v[234:235], off
	s_add_i32 m0, s61, 0x2000
	s_add_u32 s62, s52, 0x4000
	v_lshl_add_u64 v[234:235], s[52:53], 0, v[134:135]
	s_addc_u32 s63, s53, 0
	s_add_i32 s61, s58, s19
	global_load_lds_dwordx4 v[234:235], off
	v_lshl_add_u64 v[234:235], s[62:63], 0, v[130:131]
	s_mov_b32 m0, s61
	s_nop 0
	global_load_lds_dwordx4 v[234:235], off
	v_lshl_add_u64 v[234:235], s[62:63], 0, v[134:135]
	s_add_i32 m0, s61, 0x2000
	s_nop 0
	global_load_lds_dwordx4 v[234:235], off
	v_lshl_add_u64 v[234:235], s[54:55], 0, v[128:129]
	s_mov_b32 m0, s29
	s_nop 0
	global_load_lds_dwordx4 v[234:235], off
	v_lshl_add_u64 v[234:235], s[54:55], 0, v[132:133]
	s_mov_b32 m0, s30
	s_nop 0
	global_load_lds_dwordx4 v[234:235], off
	s_waitcnt vmcnt(8)
	s_waitcnt lgkmcnt(0)
	s_barrier
	s_setprio 2
	s_waitcnt lgkmcnt(0)
	v_mfma_f32_16x16x32_bf16 v[60:63], v[148:151], v[202:205], v[60:63]
	v_mfma_f32_16x16x32_bf16 v[60:63], v[172:175], v[206:209], v[60:63]
	v_mfma_f32_16x16x32_bf16 v[56:59], v[176:179], v[202:205], v[56:59]
	v_mfma_f32_16x16x32_bf16 v[56:59], v[180:183], v[206:209], v[56:59]
	v_mfma_f32_16x16x32_bf16 v[44:47], v[148:151], v[210:213], v[44:47]
	v_mfma_f32_16x16x32_bf16 v[44:47], v[172:175], v[214:217], v[44:47]
	v_mfma_f32_16x16x32_bf16 v[40:43], v[176:179], v[210:213], v[40:43]
	v_mfma_f32_16x16x32_bf16 v[40:43], v[180:183], v[214:217], v[40:43]
	v_mfma_f32_16x16x32_bf16 v[28:31], v[148:151], v[218:221], v[28:31]
	v_mfma_f32_16x16x32_bf16 v[28:31], v[172:175], v[222:225], v[28:31]
	v_mfma_f32_16x16x32_bf16 v[24:27], v[176:179], v[218:221], v[24:27]
	v_mfma_f32_16x16x32_bf16 v[24:27], v[180:183], v[222:225], v[24:27]
	v_mfma_f32_16x16x32_bf16 v[12:15], v[148:151], v[226:229], v[12:15]
	v_mfma_f32_16x16x32_bf16 v[12:15], v[172:175], v[230:233], v[12:15]
	v_mfma_f32_16x16x32_bf16 v[8:11], v[176:179], v[226:229], v[8:11]
	v_mfma_f32_16x16x32_bf16 v[8:11], v[180:183], v[230:233], v[8:11]
	s_setprio 0
	s_setprio 2
	v_mfma_f32_16x16x32_bf16 v[52:55], v[186:189], v[202:205], v[52:55]
	v_mfma_f32_16x16x32_bf16 v[52:55], v[190:193], v[206:209], v[52:55]
	v_mfma_f32_16x16x32_bf16 v[48:51], v[194:197], v[202:205], v[48:51]
	v_mfma_f32_16x16x32_bf16 v[48:51], v[198:201], v[206:209], v[48:51]
	v_mfma_f32_16x16x32_bf16 v[36:39], v[186:189], v[210:213], v[36:39]
	v_mfma_f32_16x16x32_bf16 v[36:39], v[190:193], v[214:217], v[36:39]
	v_mfma_f32_16x16x32_bf16 v[32:35], v[194:197], v[210:213], v[32:35]
	v_mfma_f32_16x16x32_bf16 v[32:35], v[198:201], v[214:217], v[32:35]
	v_mfma_f32_16x16x32_bf16 v[20:23], v[186:189], v[218:221], v[20:23]
	v_mfma_f32_16x16x32_bf16 v[20:23], v[190:193], v[222:225], v[20:23]
	v_mfma_f32_16x16x32_bf16 v[16:19], v[194:197], v[218:221], v[16:19]
	v_mfma_f32_16x16x32_bf16 v[16:19], v[198:201], v[222:225], v[16:19]
	v_mfma_f32_16x16x32_bf16 v[4:7], v[186:189], v[226:229], v[4:7]
	v_mfma_f32_16x16x32_bf16 v[4:7], v[190:193], v[230:233], v[4:7]
	v_mfma_f32_16x16x32_bf16 v[0:3], v[194:197], v[226:229], v[0:3]
	v_mfma_f32_16x16x32_bf16 v[0:3], v[198:201], v[230:233], v[0:3]
	s_setprio 0
	s_add_i32 s61, 0, 0x18000
	v_add_u32_e32 v136, s61, v152
	s_add_i32 s62, 0, 0x1c000
	ds_read_b128 v[148:151], v136
	ds_read_b128 v[172:175], v136 offset:1024
	ds_read_b128 v[176:179], v136 offset:2048
	ds_read_b128 v[180:183], v136 offset:3072
	v_add_u32_e32 v136, s62, v152
	ds_read_b128 v[186:189], v136
	ds_read_b128 v[190:193], v136 offset:1024
	ds_read_b128 v[194:197], v136 offset:2048
	ds_read_b128 v[198:201], v136 offset:3072
	s_add_u32 s54, s54, 0x4000
	s_addc_u32 s55, s55, 0
	s_mov_b32 m0, s31
	v_lshl_add_u64 v[234:235], s[54:55], 0, v[128:129]
	ds_read_b128 v[202:205], v170 offset:32768
	ds_read_b128 v[206:209], v170 offset:33792
	ds_read_b128 v[210:213], v170 offset:34816
	ds_read_b128 v[214:217], v170 offset:35840
	ds_read_b128 v[218:221], v170 offset:36864
	ds_read_b128 v[222:225], v170 offset:37888
	ds_read_b128 v[226:229], v170 offset:38912
	ds_read_b128 v[230:233], v170 offset:39936
	global_load_lds_dwordx4 v[234:235], off
	v_lshl_add_u64 v[234:235], s[54:55], 0, v[132:133]
	s_mov_b32 m0, s33
	s_nop 0
	global_load_lds_dwordx4 v[234:235], off
	s_waitcnt vmcnt(8)
	s_waitcnt lgkmcnt(0)
	s_barrier
; #define PG8_STAGE(bufoff, gbase, voff) do { _Pragma("unroll") for (int _i = 0; _i < 2; ++_i) \
;         __builtin_amdgcn_global_load_lds((const unsigned*)((const char*)(gbase) + (voff)[_i]), (LAS unsigned*)(lds + (bufoff) + ldsw + _i * 8192), 16, 0, 0); } while (0)
; #define PG8_LDA(dst, b, h) do { _Pragma("unroll") for (int m = 0; m < 4; ++m) _Pragma("unroll") for (int k = 0; k < 2; ++k) dst[m][k] = *(const LAS bf16x8*)(lds + PG8_SA(b, h) + aoff + m * 2048 + k * 1024); } while (0)
; #define PG8_LDB(dst, b, h) do { _Pragma("unroll") for (int n = 0; n < 2; ++n) _Pragma("unroll") for (int k = 0; k < 2; ++k) dst[n][k] = *(const LAS bf16x8*)(lds + PG8_SB(b, h) + boff + n * 2048 + k * 1024); } while (0)
; #define PG8_WAIT_V(n) asm volatile("s_waitcnt vmcnt(" #n ")" ::: "memory")
; #define PG8_WAIT_L(n) asm volatile("s_waitcnt lgkmcnt(" #n ")" ::: "memory")
; #define PG8_BAR __builtin_amdgcn_s_barrier()
; #define PG8_SCHED __builtin_amdgcn_sched_barrier(0)
; template <bool ALIGN_EPI, class Epi, class Sched>
; __device__ __forceinline__ void gemm_phase(LAS unsigned char* lds, const int lda, const int ldb, const int K, const Sched& S, const Epi& E, const size_t kstepA = (size_t)(BK * 2), const size_t kstepB = (size_t)(BK * 2)) {
;     ...
;             PG8_LDB(B0, 0, 0); PG8_LDB(B1, 0, 1); PG8_SCHED; PG8_LDA(At, 0, 0); PG8_STAGE(PG8_SA(1, 1), a1 + hstepA, voffA);
;             PG8_WAIT_V(8); PG8_WAIT_L(0); PG8_BAR; PG8_MMA(0, 0, At, B0); PG8_MMA(0, 1, At, B1); PG8_BAR; PG8_SCHED;
;             PG8_LDA(At, 0, 1); PG8_STAGE(PG8_SB(0, 0), b2, voffB); PG8_STAGE(PG8_SB(0, 1), b2 + hstepB, voffB); PG8_STAGE(PG8_SA(0, 0), a2, voffA);
;             PG8_WAIT_V(8); PG8_WAIT_L(0); PG8_BAR; PG8_MMA(1, 0, At, B0); PG8_MMA(1, 1, At, B1); PG8_BAR; PG8_SCHED;
;             PG8_LDB(B0, 1, 0); PG8_LDB(B1, 1, 1); PG8_SCHED; PG8_LDA(At, 1, 0); PG8_STAGE(PG8_SA(0, 1), a2 + hstepA, voffA);
;             PG8_WAIT_V(8); PG8_WAIT_L(0); PG8_BAR; PG8_MMA(0, 0, At, B0); PG8_MMA(0, 1, At, B1); PG8_BAR; PG8_SCHED;
;             PG8_LDA(At, 1, 1); PG8_STAGE(PG8_SB(1, 0), b3, voffB); PG8_STAGE(PG8_SB(1, 1), b3 + hstepB, voffB); PG8_STAGE(PG8_SA(1, 0), a3, voffA);
;             PG8_WAIT_V(8); PG8_WAIT_L(0); PG8_BAR; PG8_MMA(1, 0, At, B0); PG8_MMA(1, 1, At, B1); PG8_BAR; PG8_SCHED;
;         }
;         if constexpr (ALIGN_EPI) { if (wr == 0) PG8_BAR; }
	s_setprio 2
	s_waitcnt lgkmcnt(0)
	v_mfma_f32_16x16x32_bf16 v[124:127], v[148:151], v[202:205], v[124:127]
	v_mfma_f32_16x16x32_bf16 v[124:127], v[172:175], v[206:209], v[124:127]
	v_mfma_f32_16x16x32_bf16 v[120:123], v[176:179], v[202:205], v[120:123]
	v_mfma_f32_16x16x32_bf16 v[120:123], v[180:183], v[206:209], v[120:123]
	v_mfma_f32_16x16x32_bf16 v[108:111], v[148:151], v[210:213], v[108:111]
	v_mfma_f32_16x16x32_bf16 v[108:111], v[172:175], v[214:217], v[108:111]
	v_mfma_f32_16x16x32_bf16 v[104:107], v[176:179], v[210:213], v[104:107]
	v_mfma_f32_16x16x32_bf16 v[104:107], v[180:183], v[214:217], v[104:107]
	v_mfma_f32_16x16x32_bf16 v[92:95], v[148:151], v[218:221], v[92:95]
	v_mfma_f32_16x16x32_bf16 v[92:95], v[172:175], v[222:225], v[92:95]
	v_mfma_f32_16x16x32_bf16 v[88:91], v[176:179], v[218:221], v[88:91]
	v_mfma_f32_16x16x32_bf16 v[88:91], v[180:183], v[222:225], v[88:91]
	v_mfma_f32_16x16x32_bf16 v[76:79], v[148:151], v[226:229], v[76:79]
	v_mfma_f32_16x16x32_bf16 v[76:79], v[172:175], v[230:233], v[76:79]
	v_mfma_f32_16x16x32_bf16 v[72:75], v[176:179], v[226:229], v[72:75]
	v_mfma_f32_16x16x32_bf16 v[72:75], v[180:183], v[230:233], v[72:75]
	s_setprio 0
	s_setprio 2
	v_mfma_f32_16x16x32_bf16 v[116:119], v[186:189], v[202:205], v[116:119]
	v_mfma_f32_16x16x32_bf16 v[116:119], v[190:193], v[206:209], v[116:119]
	v_mfma_f32_16x16x32_bf16 v[112:115], v[194:197], v[202:205], v[112:115]
	v_mfma_f32_16x16x32_bf16 v[112:115], v[198:201], v[206:209], v[112:115]
	v_mfma_f32_16x16x32_bf16 v[100:103], v[186:189], v[210:213], v[100:103]
	v_mfma_f32_16x16x32_bf16 v[100:103], v[190:193], v[214:217], v[100:103]
	v_mfma_f32_16x16x32_bf16 v[96:99], v[194:197], v[210:213], v[96:99]
	v_mfma_f32_16x16x32_bf16 v[96:99], v[198:201], v[214:217], v[96:99]
	v_mfma_f32_16x16x32_bf16 v[84:87], v[186:189], v[218:221], v[84:87]
	v_mfma_f32_16x16x32_bf16 v[84:87], v[190:193], v[222:225], v[84:87]
	v_mfma_f32_16x16x32_bf16 v[80:83], v[194:197], v[218:221], v[80:83]
	v_mfma_f32_16x16x32_bf16 v[80:83], v[198:201], v[222:225], v[80:83]
	v_mfma_f32_16x16x32_bf16 v[68:71], v[186:189], v[226:229], v[68:71]
	v_mfma_f32_16x16x32_bf16 v[68:71], v[190:193], v[230:233], v[68:71]
	v_mfma_f32_16x16x32_bf16 v[64:67], v[194:197], v[226:229], v[64:67]
	v_mfma_f32_16x16x32_bf16 v[64:67], v[198:201], v[230:233], v[64:67]
	s_setprio 0
	s_add_u32 s54, s52, 0x160000
	s_addc_u32 s55, s53, 0
	s_add_i32 s61, s61, s19
	v_lshl_add_u64 v[234:235], s[54:55], 0, v[130:131]
	s_mov_b32 m0, s61
	ds_read_b128 v[202:205], v170 offset:49152
	ds_read_b128 v[206:209], v170 offset:50176
	ds_read_b128 v[210:213], v170 offset:51200
	ds_read_b128 v[214:217], v170 offset:52224
	ds_read_b128 v[218:221], v170 offset:53248
	ds_read_b128 v[222:225], v170 offset:54272
	ds_read_b128 v[226:229], v170 offset:55296
	ds_read_b128 v[230:233], v170 offset:56320
	global_load_lds_dwordx4 v[234:235], off
	s_add_i32 m0, s61, 0x2000
	s_add_u32 s52, s52, 0x164000
	v_lshl_add_u64 v[234:235], s[54:55], 0, v[134:135]
	s_addc_u32 s53, s53, 0
	s_add_i32 s54, s62, s19
	global_load_lds_dwordx4 v[234:235], off
	v_lshl_add_u64 v[234:235], s[52:53], 0, v[130:131]
	s_mov_b32 m0, s54
	s_nop 0
	global_load_lds_dwordx4 v[234:235], off
	v_lshl_add_u64 v[234:235], s[52:53], 0, v[134:135]
	s_add_i32 m0, s54, 0x2000
	s_nop 0
	global_load_lds_dwordx4 v[234:235], off
	v_lshl_add_u64 v[234:235], s[48:49], 0, v[128:129]
	s_mov_b32 m0, s50
	s_nop 0
	global_load_lds_dwordx4 v[234:235], off
	v_lshl_add_u64 v[234:235], s[48:49], 0, v[132:133]
	s_mov_b32 m0, s51
	s_nop 0
	global_load_lds_dwordx4 v[234:235], off
	s_waitcnt vmcnt(8)
	s_waitcnt lgkmcnt(0)
	s_barrier
	s_setprio 2
	s_waitcnt lgkmcnt(0)
	v_mfma_f32_16x16x32_bf16 v[60:63], v[148:151], v[202:205], v[60:63]
	v_mfma_f32_16x16x32_bf16 v[60:63], v[172:175], v[206:209], v[60:63]
	v_mfma_f32_16x16x32_bf16 v[56:59], v[176:179], v[202:205], v[56:59]
	v_mfma_f32_16x16x32_bf16 v[56:59], v[180:183], v[206:209], v[56:59]
	v_mfma_f32_16x16x32_bf16 v[44:47], v[148:151], v[210:213], v[44:47]
	v_mfma_f32_16x16x32_bf16 v[44:47], v[172:175], v[214:217], v[44:47]
	v_mfma_f32_16x16x32_bf16 v[40:43], v[176:179], v[210:213], v[40:43]
	v_mfma_f32_16x16x32_bf16 v[40:43], v[180:183], v[214:217], v[40:43]
	v_mfma_f32_16x16x32_bf16 v[28:31], v[148:151], v[218:221], v[28:31]
	v_mfma_f32_16x16x32_bf16 v[28:31], v[172:175], v[222:225], v[28:31]
	v_mfma_f32_16x16x32_bf16 v[24:27], v[176:179], v[218:221], v[24:27]
	v_mfma_f32_16x16x32_bf16 v[24:27], v[180:183], v[222:225], v[24:27]
	v_mfma_f32_16x16x32_bf16 v[12:15], v[148:151], v[226:229], v[12:15]
	v_mfma_f32_16x16x32_bf16 v[12:15], v[172:175], v[230:233], v[12:15]
	v_mfma_f32_16x16x32_bf16 v[8:11], v[176:179], v[226:229], v[8:11]
	v_mfma_f32_16x16x32_bf16 v[8:11], v[180:183], v[230:233], v[8:11]
	s_setprio 0
	s_setprio 2
	v_mfma_f32_16x16x32_bf16 v[52:55], v[186:189], v[202:205], v[52:55]
	v_mfma_f32_16x16x32_bf16 v[52:55], v[190:193], v[206:209], v[52:55]
	v_mfma_f32_16x16x32_bf16 v[48:51], v[194:197], v[202:205], v[48:51]
	v_mfma_f32_16x16x32_bf16 v[48:51], v[198:201], v[206:209], v[48:51]
	v_mfma_f32_16x16x32_bf16 v[36:39], v[186:189], v[210:213], v[36:39]
	v_mfma_f32_16x16x32_bf16 v[36:39], v[190:193], v[214:217], v[36:39]
	v_mfma_f32_16x16x32_bf16 v[32:35], v[194:197], v[210:213], v[32:35]
	v_mfma_f32_16x16x32_bf16 v[32:35], v[198:201], v[214:217], v[32:35]
	v_mfma_f32_16x16x32_bf16 v[20:23], v[186:189], v[218:221], v[20:23]
	v_mfma_f32_16x16x32_bf16 v[20:23], v[190:193], v[222:225], v[20:23]
	v_mfma_f32_16x16x32_bf16 v[16:19], v[194:197], v[218:221], v[16:19]
	v_mfma_f32_16x16x32_bf16 v[16:19], v[198:201], v[222:225], v[16:19]
	v_mfma_f32_16x16x32_bf16 v[4:7], v[186:189], v[226:229], v[4:7]
	v_mfma_f32_16x16x32_bf16 v[4:7], v[190:193], v[230:233], v[4:7]
	v_mfma_f32_16x16x32_bf16 v[0:3], v[194:197], v[226:229], v[0:3]
	v_mfma_f32_16x16x32_bf16 v[0:3], v[198:201], v[230:233], v[0:3]
	s_setprio 0
	s_add_i32 s15, s15, 2
	s_add_u32 s9, s9, 0x2c0000
	s_addc_u32 s13, s13, 0
	s_add_u32 s46, s46, 0x400000
	s_addc_u32 s47, s47, 0
	s_cmp_gt_u32 s15, 29
	s_cbranch_scc0 .Lp12_kloop_y
.Lp12_kloop_done:
	s_and_b64 vcc, exec, s[10:11]
	s_cbranch_vccz .LBB0_1047

; __device__ __forceinline__ unsigned cvt_pk_bf16(float lo, float hi) { const f32x2 v = {lo, hi}; const bf16x2_t r = __builtin_convertvector(v, bf16x2_t); return __builtin_bit_cast(unsigned, r); }
; __device__ __forceinline__ float silu_f(float g) { return g * __builtin_amdgcn_rcpf(1.0f + __builtin_amdgcn_exp2f(-1.44269504f * g)); }
; __device__ __forceinline__ float row_rs(const RowScale& R, int pm, int lr) { return (R.rsl && pm == R.pm0) ? R.rsl[lr] : rstd_of(R.ss, pm * 256 + lr); }
; #define PG8_BAR __builtin_amdgcn_s_barrier()
; template <bool ALIGN_EPI, class Epi, class Sched>
; __device__ __forceinline__ void gemm_phase(LAS unsigned char* lds, const int lda, const int ldb, const int K, const Sched& S, const Epi& E, const size_t kstepA = (size_t)(BK * 2), const size_t kstepB = (size_t)(BK * 2)) {
;     ...
;         if (!has_next) break;
; #pragma unroll
;         for (int a = 0; a < 2; ++a)
; #pragma unroll
;             for (int b = 0; b < 2; ++b)
; #pragma unroll
;                 for (int m = 0; m < 4; ++m)
; #pragma unroll
;                     for (int n = 0; n < 2; ++n) acc[a][b][m][n] = (f32x4){0.f, 0.f, 0.f, 0.f};
;         cur = nxt; cA = nA; cB = nB; ++ui;
;         if constexpr (ALIGN_EPI) { if (wr == 1) PG8_BAR; }
;     }
;     __device__ __forceinline__ void operator()(const Acc& acc, const Unit& u, int wr, int wc, int fr, int fq) const {
;     ...
;             for (int m = 0; m < 4; ++m) { const int row = row0 + ai * HALF + m * 16; const float rs = scaled ? row_rs(R, u.pm, ai * HALF + wr * 64 + m * 16 + fr) : 1.0f;
;                 const f32x4 g0 = acc[ai][0][m][0] * rs, g1 = acc[ai][0][m][1] * rs, u0 = acc[ai][1][m][0] * rs, u1 = acc[ai][1][m][1] * rs;
;                 u32x4 w; w.x = cvt_pk_bf16(silu_f(g0[0]) * u0[0], silu_f(g0[1]) * u0[1]); w.y = cvt_pk_bf16(silu_f(g0[2]) * u0[2], silu_f(g0[3]) * u0[3]);
;                 w.z = cvt_pk_bf16(silu_f(g1[0]) * u1[0], silu_f(g1[1]) * u1[1]); w.w = cvt_pk_bf16(silu_f(g1[2]) * u1[2], silu_f(g1[3]) * u1[3]);
;                 *(u32x4*)(O + ((size_t)(col0 >> 6) * T + row) * 64 + (col0 & 63)) = w; }
.LBB0_1079:
	s_waitcnt lgkmcnt(0)
	v_pk_mul_f32 v[12:13], v[12:13], v[16:17] op_sel_hi:[1,0]
	v_pk_mul_f32 v[18:19], v[2:3], v[16:17] op_sel_hi:[1,0]
	v_mul_f32_e32 v2, 0xbfb8aa3b, v12
	v_pk_mul_f32 v[14:15], v[14:15], v[16:17] op_sel_hi:[1,0]
	v_pk_mul_f32 v[10:11], v[10:11], v[16:17] op_sel_hi:[1,0]
	v_pk_mul_f32 v[8:9], v[8:9], v[16:17] op_sel_hi:[1,0]
	v_pk_mul_f32 v[6:7], v[6:7], v[16:17] op_sel_hi:[1,0]
	v_pk_mul_f32 v[4:5], v[4:5], v[16:17] op_sel_hi:[1,0]
	v_exp_f32_e32 v17, v2
	v_mul_f32_e32 v2, 0xbfb8aa3b, v13
	v_exp_f32_e32 v20, v2
	v_pk_mul_f32 v[2:3], v[0:1], v[16:17] op_sel_hi:[1,0]
	v_add_f32_e32 v0, 1.0, v17
	v_mul_f32_e32 v16, 0xbfb8aa3b, v14
	v_mul_f32_e32 v17, 0xbfb8aa3b, v15
	v_exp_f32_e32 v16, v16
	v_exp_f32_e32 v17, v17
	v_add_f32_e32 v1, 1.0, v20
	v_rcp_f32_e32 v0, v0
	v_rcp_f32_e32 v1, v1
	v_add_f32_e32 v16, 1.0, v16
	v_add_f32_e32 v17, 1.0, v17
	v_rcp_f32_e32 v16, v16
	v_rcp_f32_e32 v17, v17
	v_pk_mul_f32 v[0:1], v[12:13], v[0:1]
	s_nop 0
	v_pk_mul_f32 v[0:1], v[4:5], v[0:1]
	v_pk_mul_f32 v[4:5], v[14:15], v[16:17]
	v_cvt_pk_bf16_f32 v0, v0, v1
	v_mul_f32_e32 v1, 0xbfb8aa3b, v8
	v_pk_mul_f32 v[4:5], v[6:7], v[4:5]
	v_exp_f32_e32 v6, v1
	v_mul_f32_e32 v1, 0xbfb8aa3b, v9
	v_exp_f32_e32 v7, v1
	v_cvt_pk_bf16_f32 v1, v4, v5
	v_add_f32_e32 v4, 1.0, v6
	v_mul_f32_e32 v6, 0xbfb8aa3b, v10
	v_add_f32_e32 v5, 1.0, v7
	v_mul_f32_e32 v7, 0xbfb8aa3b, v11
	v_exp_f32_e32 v6, v6
	v_exp_f32_e32 v7, v7
	v_rcp_f32_e32 v4, v4
	v_rcp_f32_e32 v5, v5
	v_add_f32_e32 v6, 1.0, v6
	v_add_f32_e32 v7, 1.0, v7
	v_rcp_f32_e32 v6, v6
	v_rcp_f32_e32 v7, v7
	v_pk_mul_f32 v[4:5], v[8:9], v[4:5]
	s_nop 0
	v_pk_mul_f32 v[2:3], v[2:3], v[4:5]
	v_pk_mul_f32 v[4:5], v[10:11], v[6:7]
	v_cvt_pk_bf16_f32 v2, v2, v3
	v_pk_mul_f32 v[4:5], v[18:19], v[4:5]
	s_nop 0
	v_cvt_pk_bf16_f32 v3, v4, v5
	v_lshlrev_b64 v[4:5], 7, v[148:149]
	v_lshl_add_u64 v[4:5], s[22:23], 0, v[4:5]
	v_lshl_add_u64 v[4:5], v[4:5], 0, v[136:137]
	v_add_co_u32_e32 v4, vcc, 0x5000, v4
	s_nop 1
	v_addc_co_u32_e32 v5, vcc, 0, v5, vcc
	s_andn2_b64 vcc, exec, s[6:7]
	s_mov_b64 s[6:7], -1
	global_store_dwordx4 v[4:5], v[0:3], off offset:2048
	s_cbranch_vccnz .LBB0_1040
	s_andn2_b64 vcc, exec, s[0:1]
	s_cbranch_vccnz .LBB0_1039
	s_branch .LBB0_1039

; #define PG8_STAGE(bufoff, gbase, voff) do { _Pragma("unroll") for (int _i = 0; _i < 2; ++_i) \
;         __builtin_amdgcn_global_load_lds((const unsigned*)((const char*)(gbase) + (voff)[_i]), (LAS unsigned*)(lds + (bufoff) + ldsw + _i * 8192), 16, 0, 0); } while (0)
; #define PG8_WAIT_V(n) asm volatile("s_waitcnt vmcnt(" #n ")" ::: "memory")
; #define PG8_BAR __builtin_amdgcn_s_barrier()
;     __device__ bool next(int i, Unit& u) const { if (i > 0 || c >= 32 || c < 0) return false; u.pm = c & 1; u.pn = c >> 1; u.z = 0; u.o = 0; u.a = A + (size_t)u.pm * 256 * D * 2; u.b = B + (size_t)u.pn * 256 * D * 2; return true; }
; template <bool ALIGN_EPI, class Epi, class Sched>
; __device__ __forceinline__ void gemm_phase(LAS unsigned char* lds, const int lda, const int ldb, const int K, const Sched& S, const Epi& E, const size_t kstepA = (size_t)(BK * 2), const size_t kstepB = (size_t)(BK * 2)) {
;     ...
;     for (int i = 0; i < 2; ++i) { int R, C; stage_rc(tid * 16 + i * 8192, R, C); const int Rb = (R & ~31) + perm32(R & 31);
;         voffA[i] = (unsigned)(R * lda + C) * 2u; voffB[i] = (unsigned)(Rb * ldb + C) * 2u; }
;     const size_t kstep = kstepB;
;     const size_t hstepA = (size_t)HALF * lda * 2, hstepB = (size_t)HALF * ldb * 2;
;     const unsigned ldsw = (unsigned)wid * 1024u;
;     const int aoff = lds_byte(wr * 64 + fr, fq * 8), boff = lds_byte(wc * 32 + fr, fq * 8);
;     ...
;     Unit cur, nxt; int ui = 0;
;     if (!S.next(0, cur)) return;
;     f32x4 acc[2][2][4][2];
; #pragma unroll
;     for (int a = 0; a < 2; ++a)
; #pragma unroll
;         for (int b = 0; b < 2; ++b)
; #pragma unroll
;             for (int m = 0; m < 4; ++m)
; #pragma unroll
;                 for (int n = 0; n < 2; ++n) acc[a][b][m][n] = (f32x4){0.f, 0.f, 0.f, 0.f};
;     bf16x8 At[4][2], B0[2][2], B1[2][2];
;     const char* cA = cur.a; const char* cB = cur.b;
;     PG8_STAGE(PG8_SB(0, 0), cB, voffB); PG8_STAGE(PG8_SB(0, 1), cB + hstepB, voffB); PG8_STAGE(PG8_SA(0, 0), cA, voffA); PG8_STAGE(PG8_SA(0, 1), cA + hstepA, voffA);
;     if (wr == 1) PG8_BAR;
;     PG8_WAIT_V(2); PG8_BAR;
;     PG8_STAGE(PG8_SB(1, 0), cB + kstep, voffB); PG8_STAGE(PG8_SA(1, 0), cA + kstepA, voffA); PG8_STAGE(PG8_SB(1, 1), cB + hstepB + kstep, voffB);
;     PG8_WAIT_V(6); PG8_BAR;
.LBB0_1142:
	v_bfe_i32 v2, v0, 27, 1
	v_lshlrev_b32_e32 v4, 4, v0
	v_lshrrev_b32_e32 v2, 22, v2
	v_ashrrev_i32_e32 v1, 31, v0
	v_add_u32_e32 v2, v4, v2
	v_lshrrev_b32_e32 v1, 26, v1
	v_and_b32_e32 v2, 0xfffffc00, v2
	v_add_u32_e32 v1, v0, v1
	v_sub_u32_e32 v2, v4, v2
	v_ashrrev_i32_e32 v1, 6, v1
	v_lshrrev_b32_e32 v3, 4, v2
	v_bitop3_b32 v3, v3, v2, 32 bitop3:0x6c
	v_lshlrev_b32_e32 v2, 3, v1
	v_and_b32_e32 v5, -16, v2
	v_ashrrev_i32_e32 v2, 31, v3
	v_lshrrev_b32_e32 v2, 26, v2
	v_add_u32_e32 v6, v3, v2
	v_ashrrev_i32_e32 v2, 6, v6
	v_and_b32_e32 v6, 0xc0, v6
	v_sub_u32_e32 v3, v3, v6
	v_mov_b32_e32 v6, 1
	v_lshlrev_b32_e32 v7, 5, v1
	v_ashrrev_i16_sdwa v3, v6, sext(v3) dst_sel:DWORD dst_unused:UNUSED_PAD src0_sel:DWORD src1_sel:BYTE_0
	v_and_b32_e32 v7, 32, v7
	v_bfe_i32 v3, v3, 0, 16
	v_add_u32_e32 v5, v2, v5
	v_and_b32_e32 v10, 3, v2
	s_mov_b32 s1, 0x1ffffe0
	v_add_lshl_u32 v7, v7, v3, 1
	v_lshlrev_b32_e32 v8, 1, v5
	v_lshrrev_b32_e32 v9, 2, v5
	v_and_or_b32 v10, v5, s1, v10
	v_lshl_add_u32 v168, v5, 7, v7
	v_add_u32_e32 v5, 0x2000, v4
	v_ashrrev_i32_e32 v4, 31, v5
	v_lshrrev_b32_e32 v4, 22, v4
	v_and_b32_e32 v8, 24, v8
	v_and_b32_e32 v9, 4, v9
	v_add_u32_e32 v4, v5, v4
	v_or3_b32 v8, v10, v9, v8
	v_ashrrev_i32_e32 v4, 10, v4
	v_lshl_add_u32 v170, v8, 7, v7
	v_mul_i32_i24_e32 v7, 0x400, v4
	v_sub_u32_e32 v5, v5, v7
	v_lshrrev_b32_e32 v7, 4, v5
	v_bitop3_b32 v7, v7, v5, 32 bitop3:0x6c
	v_lshlrev_b32_e32 v5, 3, v4
	v_and_b32_e32 v8, -16, v5
	v_ashrrev_i32_e32 v5, 31, v7
	v_lshrrev_b32_e32 v5, 26, v5
	v_add_u32_e32 v9, v7, v5
	s_ashr_i32 s0, s6, 6
	v_ashrrev_i32_e32 v5, 6, v9
	v_and_b32_e32 v9, 0xc0, v9
	v_add_u32_e32 v8, v5, v8
	v_sub_u32_e32 v7, v7, v9
	s_lshl_b32 s18, s0, 10
	v_lshlrev_b32_e32 v10, 5, v4
	v_ashrrev_i16_sdwa v6, v6, sext(v7) dst_sel:DWORD dst_unused:UNUSED_PAD src0_sel:DWORD src1_sel:BYTE_0
	v_lshlrev_b32_e32 v7, 1, v8
	v_lshrrev_b32_e32 v9, 2, v8
	v_and_b32_e32 v11, 3, v5
	s_add_i32 s19, s18, 0
	v_and_b32_e32 v10, 32, v10
	v_bfe_i32 v6, v6, 0, 16
	v_and_b32_e32 v7, 24, v7
	v_and_b32_e32 v9, 4, v9
	v_and_or_b32 v11, v8, s1, v11
	s_add_i32 m0, s19, 0x10000
	v_or3_b32 v7, v11, v9, v7
	v_add_lshl_u32 v9, v10, v6, 1
	s_ashr_i32 s1, s6, 8
	global_load_lds_dwordx4 v170, s[12:13]
	s_add_i32 m0, s19, 0x12000
	v_lshl_add_u32 v174, v7, 7, v9
	s_add_u32 s4, s12, 0x4000
	global_load_lds_dwordx4 v174, s[12:13]
	s_addc_u32 s5, s13, 0
	s_add_i32 m0, s19, 0x14000
	s_add_i32 s29, s19, 0x2000
	global_load_lds_dwordx4 v170, s[4:5]
	s_add_i32 m0, s19, 0x16000
	v_lshl_add_u32 v172, v8, 7, v9
	global_load_lds_dwordx4 v174, s[4:5]
	s_mov_b32 m0, s19
	s_add_u32 s4, s10, 0x4000
	global_load_lds_dwordx4 v168, s[10:11]
	s_mov_b32 m0, s29
	s_addc_u32 s5, s11, 0
	s_add_i32 s30, s19, 0x4000
	global_load_lds_dwordx4 v172, s[10:11]
	s_mov_b32 m0, s30
	s_add_i32 s31, s19, 0x6000
	global_load_lds_dwordx4 v168, s[4:5]
	s_mov_b32 m0, s31
	v_mov_b32_e32 v177, 0
	global_load_lds_dwordx4 v172, s[4:5]
	s_cmp_eq_u32 s1, 1
	s_mov_b32 s23, 0
	v_mov_b32_e32 v171, v177
	v_mov_b32_e32 v175, v177
	s_mov_b64 s[40:41], 0x4000
	v_mov_b32_e32 v169, v177
	s_cselect_b64 s[44:45], -1, 0
	s_cmp_lg_u32 s1, 1
	v_mov_b32_e32 v173, v177
	s_cbranch_scc1 .LBB0_1144
.LBB0_1144:
	s_and_b32 s33, s0, 3
	s_lshl_b32 s0, s1, 13
	s_lshl_b32 s42, s33, 5
	s_lshl_b32 s7, s33, 12
	s_add_u32 s4, s12, 0x40000
	s_addc_u32 s5, s13, 0
	s_add_i32 m0, s19, 0x18000
	v_lshl_add_u64 v[8:9], s[4:5], 0, v[170:171]
	s_waitcnt vmcnt(2)
	s_barrier
	global_load_lds_dwordx4 v[8:9], off
	s_add_i32 m0, s19, 0x1a000
	v_lshl_add_u64 v[8:9], s[4:5], 0, v[174:175]
	s_add_u32 s4, s10, 0x200000
	s_addc_u32 s5, s11, 0
	s_add_i32 s43, s19, 0x8000
	global_load_lds_dwordx4 v[8:9], off
	v_lshl_add_u64 v[8:9], s[4:5], 0, v[168:169]
	s_mov_b32 m0, s43
	s_add_i32 s50, s19, 0xa000
	global_load_lds_dwordx4 v[8:9], off
	v_lshl_add_u64 v[8:9], s[4:5], 0, v[172:173]
	s_add_u32 s4, s12, 0x44000
	s_mov_b32 m0, s50
	s_addc_u32 s5, s13, 0
	global_load_lds_dwordx4 v[8:9], off
	s_add_i32 m0, s19, 0x1c000
	v_lshl_add_u64 v[8:9], s[4:5], 0, v[170:171]
	global_load_lds_dwordx4 v[8:9], off
	v_lshl_add_u64 v[8:9], s[4:5], 0, v[174:175]
	s_add_i32 m0, s19, 0x1e000
	v_bfe_u32 v7, v0, 4, 2
	global_load_lds_dwordx4 v[8:9], off
	v_and_b32_e32 v8, 15, v0
	v_lshlrev_b32_e32 v9, 4, v7
	v_lshlrev_b32_e32 v0, 2, v0
	v_lshl_or_b32 v216, s1, 6, v8
	v_lshl_or_b32 v8, v8, 6, v9
	v_and_b32_e32 v0, 32, v0
	v_bitop3_b32 v9, v8, s0, v0 bitop3:0xde
	v_bitop3_b32 v218, v8, s7, v0 bitop3:0xde
	v_lshlrev_b32_e32 v0, 10, v1
	v_and_b32_e32 v0, 0xfffff800, v0
	v_lshl_add_u32 v0, v2, 7, v0
	v_and_b32_e32 v1, 1, v1
	v_lshl_or_b32 v0, v1, 6, v0
	v_lshl_add_u32 v178, v3, 1, v0
	v_lshlrev_b32_e32 v0, 10, v4
	v_and_b32_e32 v0, 0xfffff800, v0
	s_waitcnt vmcnt(6)
	s_cmpk_lt_u32 s6, 0x100
	v_lshl_add_u32 v0, v5, 7, v0
	v_and_b32_e32 v1, 1, v4
	s_cselect_b64 s[46:47], -1, 0
	v_lshl_or_b32 v0, v1, 6, v0
	s_add_i32 s51, 0, 0x10000
	s_add_i32 s64, 0, 0x14000
	v_lshlrev_b32_e32 v217, 3, v7
	v_cmp_eq_u32_e64 s[4:5], 0, v7
	v_mov_b32_e32 v179, v177
	v_lshl_add_u32 v180, v6, 1, v0
	v_mov_b32_e32 v181, v177
	v_mov_b64_e32 v[182:183], 0x200
	v_mov_b64_e32 v[186:187], 0x1ff
	v_add_u32_e32 v219, s51, v218
	v_add_u32_e32 v220, s64, v218
	v_add_u32_e32 v221, 0, v9
	v_mbcnt_hi_u32_b32 v222, -1, v185
	s_mov_b64 s[48:49], 0x4800
	s_mov_b64 s[52:53], 0x5000
	s_mov_b64 s[54:55], 0x5800
	s_mov_b32 s65, 0
	s_barrier
	s_branch .LBB0_1147

; #define PG8_STAGE(bufoff, gbase, voff) do { _Pragma("unroll") for (int _i = 0; _i < 2; ++_i) \
;         __builtin_amdgcn_global_load_lds((const unsigned*)((const char*)(gbase) + (voff)[_i]), (LAS unsigned*)(lds + (bufoff) + ldsw + _i * 8192), 16, 0, 0); } while (0)
; #define PG8_LDA(dst, b, h) do { _Pragma("unroll") for (int m = 0; m < 4; ++m) _Pragma("unroll") for (int k = 0; k < 2; ++k) dst[m][k] = *(const LAS bf16x8*)(lds + PG8_SA(b, h) + aoff + m * 2048 + k * 1024); } while (0)
; #define PG8_LDB(dst, b, h) do { _Pragma("unroll") for (int n = 0; n < 2; ++n) _Pragma("unroll") for (int k = 0; k < 2; ++k) dst[n][k] = *(const LAS bf16x8*)(lds + PG8_SB(b, h) + boff + n * 2048 + k * 1024); } while (0)
; #define PG8_MMA(ai, bj, At, Bt) do { __builtin_amdgcn_s_setprio(1); _Pragma("unroll") for (int m = 0; m < 4; ++m) _Pragma("unroll") for (int n = 0; n < 2; ++n) _Pragma("unroll") for (int k = 0; k < 2; ++k) \
;         acc[ai][bj][m][n] = __builtin_amdgcn_mfma_f32_16x16x32_bf16(Bt[n][k], At[m][k], acc[ai][bj][m][n], 0, 0, 0); __builtin_amdgcn_s_setprio(0); } while (0)
; #define PG8_WAIT_V(n) asm volatile("s_waitcnt vmcnt(" #n ")" ::: "memory")
; template <bool ALIGN_EPI, class Epi, class Sched>
; __device__ __forceinline__ void gemm_phase(LAS unsigned char* lds, const int lda, const int ldb, const int K, const Sched& S, const Epi& E, const size_t kstepA = (size_t)(BK * 2), const size_t kstepB = (size_t)(BK * 2)) {
;     ...
;         for (int t = 0; t < nt; t += 2) {
;             const bool last = (t == nt - 2);
;             const char* a1 = cA + (size_t)(t + 1) * kstepA;
;             const char* a2 = last ? nA : cA + (size_t)(t + 2) * kstepA; const char* b2 = last ? nB : cB + (size_t)(t + 2) * kstep;
;             const char* a3 = a2 + kstepA; const char* b3 = b2 + kstep;
;             PG8_LDB(B0, 0, 0); PG8_LDB(B1, 0, 1); PG8_SCHED; PG8_LDA(At, 0, 0); PG8_STAGE(PG8_SA(1, 1), a1 + hstepA, voffA);
;             PG8_WAIT_V(8); PG8_WAIT_L(0); PG8_BAR; PG8_MMA(0, 0, At, B0); PG8_MMA(0, 1, At, B1); PG8_BAR; PG8_SCHED;
;     ...
; #pragma unroll
;         for (int a = 0; a < 2; ++a)
; #pragma unroll
;             for (int b = 0; b < 2; ++b)
; #pragma unroll
;                 for (int m = 0; m < 4; ++m)
; #pragma unroll
;                     for (int n = 0; n < 2; ++n) acc[a][b][m][n] = (f32x4){0.f, 0.f, 0.f, 0.f};
;         cur = nxt; cA = nA; cB = nB; ++ui;
.LBB0_1153:
	s_add_u32 s57, s12, 0x80000
	s_addc_u32 s59, s13, 0
	s_add_u32 s10, s10, 0x204000
	v_mov_b32_e32 v0, 0
	s_addc_u32 s11, s11, 0
	s_mov_b32 s67, -2
	s_waitcnt lgkmcnt(0)
	v_mov_b32_e32 v1, v0
	v_mov_b32_e32 v2, v0
	v_mov_b32_e32 v3, v0
	v_mov_b32_e32 v4, v0
	v_mov_b32_e32 v5, v0
	v_mov_b32_e32 v6, v0
	v_mov_b32_e32 v7, v0
	v_mov_b32_e32 v16, v0
	v_mov_b32_e32 v17, v0
	v_mov_b32_e32 v18, v0
	v_mov_b32_e32 v19, v0
	v_mov_b32_e32 v20, v0
	v_mov_b32_e32 v21, v0
	v_mov_b32_e32 v22, v0
	v_mov_b32_e32 v23, v0
	v_mov_b32_e32 v32, v0
	v_mov_b32_e32 v33, v0
	v_mov_b32_e32 v34, v0
	v_mov_b32_e32 v35, v0
	v_mov_b32_e32 v36, v0
	v_mov_b32_e32 v37, v0
	v_mov_b32_e32 v38, v0
	v_mov_b32_e32 v39, v0
	v_mov_b32_e32 v48, v0
	v_mov_b32_e32 v49, v0
	v_mov_b32_e32 v50, v0
	v_mov_b32_e32 v51, v0
	v_mov_b32_e32 v52, v0
	v_mov_b32_e32 v53, v0
	v_mov_b32_e32 v54, v0
	v_mov_b32_e32 v55, v0
	v_mov_b32_e32 v8, v0
	v_mov_b32_e32 v9, v0
	v_mov_b32_e32 v10, v0
	v_mov_b32_e32 v11, v0
	v_mov_b32_e32 v12, v0
	v_mov_b32_e32 v13, v0
	v_mov_b32_e32 v14, v0
	v_mov_b32_e32 v15, v0
	v_mov_b32_e32 v24, v0
	v_mov_b32_e32 v25, v0
	v_mov_b32_e32 v26, v0
	v_mov_b32_e32 v27, v0
	v_mov_b32_e32 v28, v0
	v_mov_b32_e32 v29, v0
	v_mov_b32_e32 v30, v0
	v_mov_b32_e32 v31, v0
	v_mov_b32_e32 v40, v0
	v_mov_b32_e32 v41, v0
	v_mov_b32_e32 v42, v0
	v_mov_b32_e32 v43, v0
	v_mov_b32_e32 v44, v0
	v_mov_b32_e32 v45, v0
	v_mov_b32_e32 v46, v0
	v_mov_b32_e32 v47, v0
	v_mov_b32_e32 v56, v0
	v_mov_b32_e32 v57, v0
	v_mov_b32_e32 v58, v0
	v_mov_b32_e32 v59, v0
	v_mov_b32_e32 v60, v0
	v_mov_b32_e32 v61, v0
	v_mov_b32_e32 v62, v0
	v_mov_b32_e32 v63, v0
	v_mov_b32_e32 v64, v0
	v_mov_b32_e32 v65, v0
	v_mov_b32_e32 v66, v0
	v_mov_b32_e32 v67, v0
	v_mov_b32_e32 v68, v0
	v_mov_b32_e32 v69, v0
	v_mov_b32_e32 v70, v0
	v_mov_b32_e32 v71, v0
	v_mov_b32_e32 v88, v0
	v_mov_b32_e32 v89, v0
	v_mov_b32_e32 v90, v0
	v_mov_b32_e32 v91, v0
	v_mov_b32_e32 v92, v0
	v_mov_b32_e32 v93, v0
	v_mov_b32_e32 v94, v0
	v_mov_b32_e32 v95, v0
	v_mov_b32_e32 v112, v0
	v_mov_b32_e32 v113, v0
	v_mov_b32_e32 v114, v0
	v_mov_b32_e32 v115, v0
	v_mov_b32_e32 v116, v0
	v_mov_b32_e32 v117, v0
	v_mov_b32_e32 v118, v0
	v_mov_b32_e32 v119, v0
	v_mov_b32_e32 v128, v0
	v_mov_b32_e32 v129, v0
	v_mov_b32_e32 v130, v0
	v_mov_b32_e32 v131, v0
	v_mov_b32_e32 v132, v0
	v_mov_b32_e32 v133, v0
	v_mov_b32_e32 v134, v0
	v_mov_b32_e32 v135, v0
	v_mov_b32_e32 v72, v0
	v_mov_b32_e32 v73, v0
	v_mov_b32_e32 v74, v0
	v_mov_b32_e32 v75, v0
	v_mov_b32_e32 v76, v0
	v_mov_b32_e32 v77, v0
	v_mov_b32_e32 v78, v0
	v_mov_b32_e32 v79, v0
	v_mov_b32_e32 v96, v0
	v_mov_b32_e32 v97, v0
	v_mov_b32_e32 v98, v0
	v_mov_b32_e32 v99, v0
	v_mov_b32_e32 v100, v0
	v_mov_b32_e32 v101, v0
	v_mov_b32_e32 v102, v0
	v_mov_b32_e32 v103, v0
	v_mov_b32_e32 v120, v0
	v_mov_b32_e32 v121, v0
	v_mov_b32_e32 v122, v0
	v_mov_b32_e32 v123, v0
	v_mov_b32_e32 v124, v0
	v_mov_b32_e32 v125, v0
	v_mov_b32_e32 v126, v0
	v_mov_b32_e32 v127, v0
	v_mov_b32_e32 v136, v0
	v_mov_b32_e32 v137, v0
	v_mov_b32_e32 v138, v0
	v_mov_b32_e32 v139, v0
	v_mov_b32_e32 v140, v0
	v_mov_b32_e32 v141, v0
	v_mov_b32_e32 v142, v0
	v_mov_b32_e32 v143, v0
	s_cmp_lg_u64 s[46:47], 0
	s_cbranch_scc0 .Lp13_kloop_y
.LBB0_1154:
	ds_read_b128 v[80:83], v219
	ds_read_b128 v[84:87], v219 offset:1024
	ds_read_b128 v[104:107], v219 offset:2048
	ds_read_b128 v[108:111], v219 offset:3072
	ds_read_b128 v[144:147], v220
	ds_read_b128 v[148:151], v220 offset:1024
	ds_read_b128 v[152:155], v220 offset:2048
	ds_read_b128 v[156:159], v220 offset:3072
	s_add_u32 s12, s10, 0x1fc000
	s_addc_u32 s13, s11, 0
	s_cmpk_eq_i32 s67, 0x54
	s_cselect_b32 s16, s0, s12
	s_cselect_b32 s17, s1, s13
	s_cselect_b32 s14, s8, s57
	s_cselect_b32 s15, s9, s59
	s_add_u32 s12, s16, 0x200000
	s_addc_u32 s13, s17, 0
	v_lshl_add_u64 v[212:213], s[10:11], 0, v[178:179]
	s_add_i32 m0, s19, 0xc000
	ds_read_b128 v[160:163], v221
	ds_read_b128 v[164:167], v221 offset:1024
	ds_read_b128 v[188:191], v221 offset:2048
	ds_read_b128 v[192:195], v221 offset:3072
	ds_read_b128 v[196:199], v221 offset:4096
	ds_read_b128 v[200:203], v221 offset:5120
	ds_read_b128 v[204:207], v221 offset:6144
	ds_read_b128 v[208:211], v221 offset:7168
	global_load_lds_dwordx4 v[212:213], off
	v_lshl_add_u64 v[212:213], s[10:11], 0, v[180:181]
	s_add_i32 m0, s19, 0xe000
	s_nop 0
	global_load_lds_dwordx4 v[212:213], off
	s_waitcnt vmcnt(8)
	s_waitcnt lgkmcnt(0)
	s_setprio 1
	s_waitcnt lgkmcnt(0)
	v_mfma_f32_16x16x32_bf16 v[140:143], v[80:83], v[160:163], v[140:143]
	v_mfma_f32_16x16x32_bf16 v[140:143], v[84:87], v[164:167], v[140:143]
	v_mfma_f32_16x16x32_bf16 v[136:139], v[104:107], v[160:163], v[136:139]
	v_mfma_f32_16x16x32_bf16 v[136:139], v[108:111], v[164:167], v[136:139]
	v_mfma_f32_16x16x32_bf16 v[124:127], v[80:83], v[188:191], v[124:127]
	v_mfma_f32_16x16x32_bf16 v[124:127], v[84:87], v[192:195], v[124:127]
	v_mfma_f32_16x16x32_bf16 v[120:123], v[104:107], v[188:191], v[120:123]
	v_mfma_f32_16x16x32_bf16 v[120:123], v[108:111], v[192:195], v[120:123]
	v_mfma_f32_16x16x32_bf16 v[100:103], v[80:83], v[196:199], v[100:103]
	v_mfma_f32_16x16x32_bf16 v[100:103], v[84:87], v[200:203], v[100:103]
	v_mfma_f32_16x16x32_bf16 v[96:99], v[104:107], v[196:199], v[96:99]
	v_mfma_f32_16x16x32_bf16 v[96:99], v[108:111], v[200:203], v[96:99]
	v_mfma_f32_16x16x32_bf16 v[76:79], v[80:83], v[204:207], v[76:79]
	v_mfma_f32_16x16x32_bf16 v[76:79], v[84:87], v[208:211], v[76:79]
	v_mfma_f32_16x16x32_bf16 v[72:75], v[104:107], v[204:207], v[72:75]
	v_mfma_f32_16x16x32_bf16 v[72:75], v[108:111], v[208:211], v[72:75]
	s_setprio 0
	s_setprio 1
	v_mfma_f32_16x16x32_bf16 v[132:135], v[144:147], v[160:163], v[132:135]
	v_mfma_f32_16x16x32_bf16 v[132:135], v[148:151], v[164:167], v[132:135]
	v_mfma_f32_16x16x32_bf16 v[128:131], v[152:155], v[160:163], v[128:131]
	v_mfma_f32_16x16x32_bf16 v[128:131], v[156:159], v[164:167], v[128:131]
	v_mfma_f32_16x16x32_bf16 v[116:119], v[144:147], v[188:191], v[116:119]
	v_mfma_f32_16x16x32_bf16 v[116:119], v[148:151], v[192:195], v[116:119]
	v_mfma_f32_16x16x32_bf16 v[112:115], v[152:155], v[188:191], v[112:115]
	v_mfma_f32_16x16x32_bf16 v[112:115], v[156:159], v[192:195], v[112:115]
	v_mfma_f32_16x16x32_bf16 v[92:95], v[144:147], v[196:199], v[92:95]
	v_mfma_f32_16x16x32_bf16 v[92:95], v[148:151], v[200:203], v[92:95]
	v_mfma_f32_16x16x32_bf16 v[88:91], v[152:155], v[196:199], v[88:91]
	v_mfma_f32_16x16x32_bf16 v[88:91], v[156:159], v[200:203], v[88:91]
	v_mfma_f32_16x16x32_bf16 v[68:71], v[144:147], v[204:207], v[68:71]
	v_mfma_f32_16x16x32_bf16 v[68:71], v[148:151], v[208:211], v[68:71]
	v_mfma_f32_16x16x32_bf16 v[64:67], v[152:155], v[204:207], v[64:67]
	v_mfma_f32_16x16x32_bf16 v[64:67], v[156:159], v[208:211], v[64:67]
	s_setprio 0
	s_barrier
; #define PG8_STAGE(bufoff, gbase, voff) do { _Pragma("unroll") for (int _i = 0; _i < 2; ++_i) \
;         __builtin_amdgcn_global_load_lds((const unsigned*)((const char*)(gbase) + (voff)[_i]), (LAS unsigned*)(lds + (bufoff) + ldsw + _i * 8192), 16, 0, 0); } while (0)
; #define PG8_LDA(dst, b, h) do { _Pragma("unroll") for (int m = 0; m < 4; ++m) _Pragma("unroll") for (int k = 0; k < 2; ++k) dst[m][k] = *(const LAS bf16x8*)(lds + PG8_SA(b, h) + aoff + m * 2048 + k * 1024); } while (0)
; #define PG8_LDB(dst, b, h) do { _Pragma("unroll") for (int n = 0; n < 2; ++n) _Pragma("unroll") for (int k = 0; k < 2; ++k) dst[n][k] = *(const LAS bf16x8*)(lds + PG8_SB(b, h) + boff + n * 2048 + k * 1024); } while (0)
; #define PG8_MMA(ai, bj, At, Bt) do { __builtin_amdgcn_s_setprio(1); _Pragma("unroll") for (int m = 0; m < 4; ++m) _Pragma("unroll") for (int n = 0; n < 2; ++n) _Pragma("unroll") for (int k = 0; k < 2; ++k) \
;         acc[ai][bj][m][n] = __builtin_amdgcn_mfma_f32_16x16x32_bf16(Bt[n][k], At[m][k], acc[ai][bj][m][n], 0, 0, 0); __builtin_amdgcn_s_setprio(0); } while (0)
; #define PG8_WAIT_V(n) asm volatile("s_waitcnt vmcnt(" #n ")" ::: "memory")
; #define PG8_WAIT_L(n) asm volatile("s_waitcnt lgkmcnt(" #n ")" ::: "memory")
; #define PG8_BAR __builtin_amdgcn_s_barrier()
; #define PG8_SCHED __builtin_amdgcn_sched_barrier(0)
; template <bool ALIGN_EPI, class Epi, class Sched>
; __device__ __forceinline__ void gemm_phase(LAS unsigned char* lds, const int lda, const int ldb, const int K, const Sched& S, const Epi& E, const size_t kstepA = (size_t)(BK * 2), const size_t kstepB = (size_t)(BK * 2)) {
;     ...
;             PG8_LDA(At, 0, 1); PG8_STAGE(PG8_SB(0, 0), b2, voffB); PG8_STAGE(PG8_SB(0, 1), b2 + hstepB, voffB); PG8_STAGE(PG8_SA(0, 0), a2, voffA);
;             PG8_WAIT_V(8); PG8_WAIT_L(0); PG8_BAR; PG8_MMA(1, 0, At, B0); PG8_MMA(1, 1, At, B1); PG8_BAR; PG8_SCHED;
;             PG8_LDB(B0, 1, 0); PG8_LDB(B1, 1, 1); PG8_SCHED; PG8_LDA(At, 1, 0); PG8_STAGE(PG8_SA(0, 1), a2 + hstepA, voffA);
;             PG8_WAIT_V(8); PG8_WAIT_L(0); PG8_BAR; PG8_MMA(0, 0, At, B0); PG8_MMA(0, 1, At, B1); PG8_BAR; PG8_SCHED;
	s_add_i32 s68, s51, s18
	v_lshl_add_u64 v[212:213], s[14:15], 0, v[170:171]
	s_mov_b32 m0, s68
	ds_read_b128 v[160:163], v221 offset:16384
	ds_read_b128 v[164:167], v221 offset:17408
	ds_read_b128 v[188:191], v221 offset:18432
	ds_read_b128 v[192:195], v221 offset:19456
	ds_read_b128 v[196:199], v221 offset:20480
	ds_read_b128 v[200:203], v221 offset:21504
	ds_read_b128 v[204:207], v221 offset:22528
	ds_read_b128 v[208:211], v221 offset:23552
	global_load_lds_dwordx4 v[212:213], off
	s_add_i32 m0, s68, 0x2000
	s_add_u32 s68, s14, 0x4000
	v_lshl_add_u64 v[212:213], s[14:15], 0, v[174:175]
	s_addc_u32 s69, s15, 0
	s_add_i32 s70, s64, s18
	global_load_lds_dwordx4 v[212:213], off
	v_lshl_add_u64 v[212:213], s[68:69], 0, v[170:171]
	s_mov_b32 m0, s70
	s_nop 0
	global_load_lds_dwordx4 v[212:213], off
	v_lshl_add_u64 v[212:213], s[68:69], 0, v[174:175]
	s_add_i32 m0, s70, 0x2000
	s_nop 0
	global_load_lds_dwordx4 v[212:213], off
	v_lshl_add_u64 v[212:213], s[16:17], 0, v[168:169]
	s_mov_b32 m0, s19
	s_nop 0
	global_load_lds_dwordx4 v[212:213], off
	v_lshl_add_u64 v[212:213], s[16:17], 0, v[172:173]
	s_mov_b32 m0, s29
	s_nop 0
	global_load_lds_dwordx4 v[212:213], off
	s_waitcnt vmcnt(8)
	s_waitcnt lgkmcnt(0)
	s_setprio 1
	s_waitcnt lgkmcnt(0)
	v_mfma_f32_16x16x32_bf16 v[60:63], v[80:83], v[160:163], v[60:63]
	v_mfma_f32_16x16x32_bf16 v[60:63], v[84:87], v[164:167], v[60:63]
	v_mfma_f32_16x16x32_bf16 v[56:59], v[104:107], v[160:163], v[56:59]
	v_mfma_f32_16x16x32_bf16 v[56:59], v[108:111], v[164:167], v[56:59]
	v_mfma_f32_16x16x32_bf16 v[44:47], v[80:83], v[188:191], v[44:47]
	v_mfma_f32_16x16x32_bf16 v[44:47], v[84:87], v[192:195], v[44:47]
	v_mfma_f32_16x16x32_bf16 v[40:43], v[104:107], v[188:191], v[40:43]
	v_mfma_f32_16x16x32_bf16 v[40:43], v[108:111], v[192:195], v[40:43]
	v_mfma_f32_16x16x32_bf16 v[28:31], v[80:83], v[196:199], v[28:31]
	v_mfma_f32_16x16x32_bf16 v[28:31], v[84:87], v[200:203], v[28:31]
	v_mfma_f32_16x16x32_bf16 v[24:27], v[104:107], v[196:199], v[24:27]
	v_mfma_f32_16x16x32_bf16 v[24:27], v[108:111], v[200:203], v[24:27]
	v_mfma_f32_16x16x32_bf16 v[12:15], v[80:83], v[204:207], v[12:15]
	v_mfma_f32_16x16x32_bf16 v[12:15], v[84:87], v[208:211], v[12:15]
	v_mfma_f32_16x16x32_bf16 v[8:11], v[104:107], v[204:207], v[8:11]
	v_mfma_f32_16x16x32_bf16 v[8:11], v[108:111], v[208:211], v[8:11]
	s_setprio 0
	s_setprio 1
	v_mfma_f32_16x16x32_bf16 v[52:55], v[144:147], v[160:163], v[52:55]
	v_mfma_f32_16x16x32_bf16 v[52:55], v[148:151], v[164:167], v[52:55]
	v_mfma_f32_16x16x32_bf16 v[48:51], v[152:155], v[160:163], v[48:51]
	v_mfma_f32_16x16x32_bf16 v[48:51], v[156:159], v[164:167], v[48:51]
	v_mfma_f32_16x16x32_bf16 v[36:39], v[144:147], v[188:191], v[36:39]
	v_mfma_f32_16x16x32_bf16 v[36:39], v[148:151], v[192:195], v[36:39]
	v_mfma_f32_16x16x32_bf16 v[32:35], v[152:155], v[188:191], v[32:35]
	v_mfma_f32_16x16x32_bf16 v[32:35], v[156:159], v[192:195], v[32:35]
	v_mfma_f32_16x16x32_bf16 v[20:23], v[144:147], v[196:199], v[20:23]
	v_mfma_f32_16x16x32_bf16 v[20:23], v[148:151], v[200:203], v[20:23]
	v_mfma_f32_16x16x32_bf16 v[16:19], v[152:155], v[196:199], v[16:19]
	v_mfma_f32_16x16x32_bf16 v[16:19], v[156:159], v[200:203], v[16:19]
	v_mfma_f32_16x16x32_bf16 v[4:7], v[144:147], v[204:207], v[4:7]
	v_mfma_f32_16x16x32_bf16 v[4:7], v[148:151], v[208:211], v[4:7]
	v_mfma_f32_16x16x32_bf16 v[0:3], v[152:155], v[204:207], v[0:3]
	v_mfma_f32_16x16x32_bf16 v[0:3], v[156:159], v[208:211], v[0:3]
	s_setprio 0
	s_barrier
	s_add_i32 s68, 0, 0x18000
	s_add_i32 s69, 0, 0x1c000
	v_add_u32_e32 v108, s68, v218
	v_add_u32_e32 v156, s69, v218
	ds_read_b128 v[80:83], v108
	ds_read_b128 v[84:87], v108 offset:1024
	ds_read_b128 v[104:107], v108 offset:2048
	ds_read_b128 v[108:111], v108 offset:3072
	ds_read_b128 v[144:147], v156
	ds_read_b128 v[148:151], v156 offset:1024
	ds_read_b128 v[152:155], v156 offset:2048
	ds_read_b128 v[156:159], v156 offset:3072
	s_add_u32 s16, s16, 0x4000
	s_addc_u32 s17, s17, 0
	s_mov_b32 m0, s30
	v_lshl_add_u64 v[212:213], s[16:17], 0, v[168:169]
	ds_read_b128 v[160:163], v221 offset:32768
	ds_read_b128 v[164:167], v221 offset:33792
	ds_read_b128 v[188:191], v221 offset:34816
	ds_read_b128 v[192:195], v221 offset:35840
	ds_read_b128 v[196:199], v221 offset:36864
	ds_read_b128 v[200:203], v221 offset:37888
	ds_read_b128 v[204:207], v221 offset:38912
	ds_read_b128 v[208:211], v221 offset:39936
	global_load_lds_dwordx4 v[212:213], off
	v_lshl_add_u64 v[212:213], s[16:17], 0, v[172:173]
	s_mov_b32 m0, s31
	s_nop 0
	global_load_lds_dwordx4 v[212:213], off
	s_waitcnt vmcnt(8)
	s_waitcnt lgkmcnt(0)
	s_setprio 1
	s_waitcnt lgkmcnt(0)
	v_mfma_f32_16x16x32_bf16 v[140:143], v[80:83], v[160:163], v[140:143]
	v_mfma_f32_16x16x32_bf16 v[140:143], v[84:87], v[164:167], v[140:143]
	v_mfma_f32_16x16x32_bf16 v[136:139], v[104:107], v[160:163], v[136:139]
	v_mfma_f32_16x16x32_bf16 v[136:139], v[108:111], v[164:167], v[136:139]
	v_mfma_f32_16x16x32_bf16 v[124:127], v[80:83], v[188:191], v[124:127]
	v_mfma_f32_16x16x32_bf16 v[124:127], v[84:87], v[192:195], v[124:127]
	v_mfma_f32_16x16x32_bf16 v[120:123], v[104:107], v[188:191], v[120:123]
	v_mfma_f32_16x16x32_bf16 v[120:123], v[108:111], v[192:195], v[120:123]
	v_mfma_f32_16x16x32_bf16 v[100:103], v[80:83], v[196:199], v[100:103]
	v_mfma_f32_16x16x32_bf16 v[100:103], v[84:87], v[200:203], v[100:103]
	v_mfma_f32_16x16x32_bf16 v[96:99], v[104:107], v[196:199], v[96:99]
	v_mfma_f32_16x16x32_bf16 v[96:99], v[108:111], v[200:203], v[96:99]
	v_mfma_f32_16x16x32_bf16 v[76:79], v[80:83], v[204:207], v[76:79]
	v_mfma_f32_16x16x32_bf16 v[76:79], v[84:87], v[208:211], v[76:79]
	v_mfma_f32_16x16x32_bf16 v[72:75], v[104:107], v[204:207], v[72:75]
	v_mfma_f32_16x16x32_bf16 v[72:75], v[108:111], v[208:211], v[72:75]
	s_setprio 0
	s_setprio 1
	v_mfma_f32_16x16x32_bf16 v[132:135], v[144:147], v[160:163], v[132:135]
	v_mfma_f32_16x16x32_bf16 v[132:135], v[148:151], v[164:167], v[132:135]
	v_mfma_f32_16x16x32_bf16 v[128:131], v[152:155], v[160:163], v[128:131]
	v_mfma_f32_16x16x32_bf16 v[128:131], v[156:159], v[164:167], v[128:131]
	v_mfma_f32_16x16x32_bf16 v[116:119], v[144:147], v[188:191], v[116:119]
	v_mfma_f32_16x16x32_bf16 v[116:119], v[148:151], v[192:195], v[116:119]
	v_mfma_f32_16x16x32_bf16 v[112:115], v[152:155], v[188:191], v[112:115]
	v_mfma_f32_16x16x32_bf16 v[112:115], v[156:159], v[192:195], v[112:115]
	v_mfma_f32_16x16x32_bf16 v[92:95], v[144:147], v[196:199], v[92:95]
	v_mfma_f32_16x16x32_bf16 v[92:95], v[148:151], v[200:203], v[92:95]
	v_mfma_f32_16x16x32_bf16 v[88:91], v[152:155], v[196:199], v[88:91]
	v_mfma_f32_16x16x32_bf16 v[88:91], v[156:159], v[200:203], v[88:91]
	v_mfma_f32_16x16x32_bf16 v[68:71], v[144:147], v[204:207], v[68:71]
	v_mfma_f32_16x16x32_bf16 v[68:71], v[148:151], v[208:211], v[68:71]
	v_mfma_f32_16x16x32_bf16 v[64:67], v[152:155], v[204:207], v[64:67]
	v_mfma_f32_16x16x32_bf16 v[64:67], v[156:159], v[208:211], v[64:67]
	s_setprio 0
	s_barrier
; #define PG8_STAGE(bufoff, gbase, voff) do { _Pragma("unroll") for (int _i = 0; _i < 2; ++_i) \
;         __builtin_amdgcn_global_load_lds((const unsigned*)((const char*)(gbase) + (voff)[_i]), (LAS unsigned*)(lds + (bufoff) + ldsw + _i * 8192), 16, 0, 0); } while (0)
; #define PG8_LDA(dst, b, h) do { _Pragma("unroll") for (int m = 0; m < 4; ++m) _Pragma("unroll") for (int k = 0; k < 2; ++k) dst[m][k] = *(const LAS bf16x8*)(lds + PG8_SA(b, h) + aoff + m * 2048 + k * 1024); } while (0)
; #define PG8_LDB(dst, b, h) do { _Pragma("unroll") for (int n = 0; n < 2; ++n) _Pragma("unroll") for (int k = 0; k < 2; ++k) dst[n][k] = *(const LAS bf16x8*)(lds + PG8_SB(b, h) + boff + n * 2048 + k * 1024); } while (0)
; template <bool ALIGN_EPI, class Epi, class Sched>
; __device__ __forceinline__ void gemm_phase(LAS unsigned char* lds, const int lda, const int ldb, const int K, const Sched& S, const Epi& E, const size_t kstepA = (size_t)(BK * 2), const size_t kstepB = (size_t)(BK * 2)) {
;     ...
;         for (int t = 0; t < nt; t += 2) {
;             const bool last = (t == nt - 2);
;             const char* a1 = cA + (size_t)(t + 1) * kstepA;
;             const char* a2 = last ? nA : cA + (size_t)(t + 2) * kstepA; const char* b2 = last ? nB : cB + (size_t)(t + 2) * kstep;
;             const char* a3 = a2 + kstepA; const char* b3 = b2 + kstep;
;             PG8_LDB(B0, 0, 0); PG8_LDB(B1, 0, 1); PG8_SCHED; PG8_LDA(At, 0, 0); PG8_STAGE(PG8_SA(1, 1), a1 + hstepA, voffA);
;             PG8_WAIT_V(8); PG8_WAIT_L(0); PG8_BAR; PG8_MMA(0, 0, At, B0); PG8_MMA(0, 1, At, B1); PG8_BAR; PG8_SCHED;
;             PG8_LDA(At, 0, 1); PG8_STAGE(PG8_SB(0, 0), b2, voffB); PG8_STAGE(PG8_SB(0, 1), b2 + hstepB, voffB); PG8_STAGE(PG8_SA(0, 0), a2, voffA);
;             PG8_WAIT_V(8); PG8_WAIT_L(0); PG8_BAR; PG8_MMA(1, 0, At, B0); PG8_MMA(1, 1, At, B1); PG8_BAR; PG8_SCHED;
;             PG8_LDB(B0, 1, 0); PG8_LDB(B1, 1, 1); PG8_SCHED; PG8_LDA(At, 1, 0); PG8_STAGE(PG8_SA(0, 1), a2 + hstepA, voffA);
;             PG8_WAIT_V(8); PG8_WAIT_L(0); PG8_BAR; PG8_MMA(0, 0, At, B0); PG8_MMA(0, 1, At, B1); PG8_BAR; PG8_SCHED;
;             PG8_LDA(At, 1, 1); PG8_STAGE(PG8_SB(1, 0), b3, voffB); PG8_STAGE(PG8_SB(1, 1), b3 + hstepB, voffB); PG8_STAGE(PG8_SA(1, 0), a3, voffA);
;             PG8_WAIT_V(8); PG8_WAIT_L(0); PG8_BAR; PG8_MMA(1, 0, At, B0); PG8_MMA(1, 1, At, B1); PG8_BAR; PG8_SCHED;
	s_add_u32 s16, s14, 0x40000
	s_addc_u32 s17, s15, 0
	s_add_i32 s68, s68, s18
	v_lshl_add_u64 v[212:213], s[16:17], 0, v[170:171]
	s_mov_b32 m0, s68
	ds_read_b128 v[160:163], v221 offset:49152
	ds_read_b128 v[164:167], v221 offset:50176
	ds_read_b128 v[188:191], v221 offset:51200
	ds_read_b128 v[192:195], v221 offset:52224
	ds_read_b128 v[196:199], v221 offset:53248
	ds_read_b128 v[200:203], v221 offset:54272
	ds_read_b128 v[204:207], v221 offset:55296
	ds_read_b128 v[208:211], v221 offset:56320
	global_load_lds_dwordx4 v[212:213], off
	s_add_i32 m0, s68, 0x2000
	s_add_u32 s14, s14, 0x44000
	v_lshl_add_u64 v[212:213], s[16:17], 0, v[174:175]
	s_addc_u32 s15, s15, 0
	s_add_i32 s16, s69, s18
	global_load_lds_dwordx4 v[212:213], off
	v_lshl_add_u64 v[212:213], s[14:15], 0, v[170:171]
	s_mov_b32 m0, s16
	s_nop 0
	global_load_lds_dwordx4 v[212:213], off
	v_lshl_add_u64 v[212:213], s[14:15], 0, v[174:175]
	s_add_i32 m0, s16, 0x2000
	s_nop 0
	global_load_lds_dwordx4 v[212:213], off
	v_lshl_add_u64 v[212:213], s[12:13], 0, v[168:169]
	s_mov_b32 m0, s43
	s_nop 0
	global_load_lds_dwordx4 v[212:213], off
	v_lshl_add_u64 v[212:213], s[12:13], 0, v[172:173]
	s_mov_b32 m0, s50
	s_nop 0
	global_load_lds_dwordx4 v[212:213], off
	s_waitcnt vmcnt(8)
	s_waitcnt lgkmcnt(0)
	s_setprio 1
	s_waitcnt lgkmcnt(0)
	v_mfma_f32_16x16x32_bf16 v[60:63], v[80:83], v[160:163], v[60:63]
	v_mfma_f32_16x16x32_bf16 v[60:63], v[84:87], v[164:167], v[60:63]
	v_mfma_f32_16x16x32_bf16 v[56:59], v[104:107], v[160:163], v[56:59]
	v_mfma_f32_16x16x32_bf16 v[56:59], v[108:111], v[164:167], v[56:59]
	v_mfma_f32_16x16x32_bf16 v[44:47], v[80:83], v[188:191], v[44:47]
	v_mfma_f32_16x16x32_bf16 v[44:47], v[84:87], v[192:195], v[44:47]
	v_mfma_f32_16x16x32_bf16 v[40:43], v[104:107], v[188:191], v[40:43]
	v_mfma_f32_16x16x32_bf16 v[40:43], v[108:111], v[192:195], v[40:43]
	v_mfma_f32_16x16x32_bf16 v[28:31], v[80:83], v[196:199], v[28:31]
	v_mfma_f32_16x16x32_bf16 v[28:31], v[84:87], v[200:203], v[28:31]
	v_mfma_f32_16x16x32_bf16 v[24:27], v[104:107], v[196:199], v[24:27]
	v_mfma_f32_16x16x32_bf16 v[24:27], v[108:111], v[200:203], v[24:27]
	v_mfma_f32_16x16x32_bf16 v[12:15], v[80:83], v[204:207], v[12:15]
	v_mfma_f32_16x16x32_bf16 v[12:15], v[84:87], v[208:211], v[12:15]
	v_mfma_f32_16x16x32_bf16 v[8:11], v[104:107], v[204:207], v[8:11]
	v_mfma_f32_16x16x32_bf16 v[8:11], v[108:111], v[208:211], v[8:11]
	s_setprio 0
	s_setprio 1
	v_mfma_f32_16x16x32_bf16 v[52:55], v[144:147], v[160:163], v[52:55]
	v_mfma_f32_16x16x32_bf16 v[52:55], v[148:151], v[164:167], v[52:55]
	v_mfma_f32_16x16x32_bf16 v[48:51], v[152:155], v[160:163], v[48:51]
	v_mfma_f32_16x16x32_bf16 v[48:51], v[156:159], v[164:167], v[48:51]
	v_mfma_f32_16x16x32_bf16 v[36:39], v[144:147], v[188:191], v[36:39]
	v_mfma_f32_16x16x32_bf16 v[36:39], v[148:151], v[192:195], v[36:39]
	v_mfma_f32_16x16x32_bf16 v[32:35], v[152:155], v[188:191], v[32:35]
	v_mfma_f32_16x16x32_bf16 v[32:35], v[156:159], v[192:195], v[32:35]
	v_mfma_f32_16x16x32_bf16 v[20:23], v[144:147], v[196:199], v[20:23]
	v_mfma_f32_16x16x32_bf16 v[20:23], v[148:151], v[200:203], v[20:23]
	v_mfma_f32_16x16x32_bf16 v[16:19], v[152:155], v[196:199], v[16:19]
	v_mfma_f32_16x16x32_bf16 v[16:19], v[156:159], v[200:203], v[16:19]
	v_mfma_f32_16x16x32_bf16 v[4:7], v[144:147], v[204:207], v[4:7]
	v_mfma_f32_16x16x32_bf16 v[4:7], v[148:151], v[208:211], v[4:7]
	v_mfma_f32_16x16x32_bf16 v[0:3], v[152:155], v[204:207], v[0:3]
	v_mfma_f32_16x16x32_bf16 v[0:3], v[156:159], v[208:211], v[0:3]
	s_setprio 0
	s_barrier
	s_add_i32 s67, s67, 2
	s_add_u32 s57, s57, 0x80000
	s_addc_u32 s59, s59, 0
	s_add_u32 s10, s10, 0x400000
	s_addc_u32 s11, s11, 0
	s_cmpk_gt_u32 s67, 0x55
	s_cbranch_scc0 .LBB0_1154
	s_branch .Lp13_kloop_done
.Lp13_kloop_y:
	ds_read_b128 v[80:83], v219
	ds_read_b128 v[84:87], v219 offset:1024
	ds_read_b128 v[104:107], v219 offset:2048
	ds_read_b128 v[108:111], v219 offset:3072
	ds_read_b128 v[144:147], v220
	ds_read_b128 v[148:151], v220 offset:1024
	ds_read_b128 v[152:155], v220 offset:2048
	ds_read_b128 v[156:159], v220 offset:3072
	s_add_u32 s12, s10, 0x1fc000
	s_addc_u32 s13, s11, 0
	s_cmpk_eq_i32 s67, 0x54
	s_cselect_b32 s16, s0, s12
	s_cselect_b32 s17, s1, s13
	s_cselect_b32 s14, s8, s57
	s_cselect_b32 s15, s9, s59
	s_add_u32 s12, s16, 0x200000
	s_addc_u32 s13, s17, 0
	v_lshl_add_u64 v[212:213], s[10:11], 0, v[178:179]
	s_add_i32 m0, s19, 0xc000
	ds_read_b128 v[160:163], v221
	ds_read_b128 v[164:167], v221 offset:1024
	ds_read_b128 v[188:191], v221 offset:2048
	ds_read_b128 v[192:195], v221 offset:3072
	ds_read_b128 v[196:199], v221 offset:4096
	ds_read_b128 v[200:203], v221 offset:5120
	ds_read_b128 v[204:207], v221 offset:6144
	ds_read_b128 v[208:211], v221 offset:7168
	global_load_lds_dwordx4 v[212:213], off
	v_lshl_add_u64 v[212:213], s[10:11], 0, v[180:181]
	s_add_i32 m0, s19, 0xe000
	s_nop 0
	global_load_lds_dwordx4 v[212:213], off
	s_waitcnt vmcnt(8)
	s_waitcnt lgkmcnt(0)
	s_barrier
; #define PG8_STAGE(bufoff, gbase, voff) do { _Pragma("unroll") for (int _i = 0; _i < 2; ++_i) \
;         __builtin_amdgcn_global_load_lds((const unsigned*)((const char*)(gbase) + (voff)[_i]), (LAS unsigned*)(lds + (bufoff) + ldsw + _i * 8192), 16, 0, 0); } while (0)
; #define PG8_LDA(dst, b, h) do { _Pragma("unroll") for (int m = 0; m < 4; ++m) _Pragma("unroll") for (int k = 0; k < 2; ++k) dst[m][k] = *(const LAS bf16x8*)(lds + PG8_SA(b, h) + aoff + m * 2048 + k * 1024); } while (0)
; #define PG8_LDB(dst, b, h) do { _Pragma("unroll") for (int n = 0; n < 2; ++n) _Pragma("unroll") for (int k = 0; k < 2; ++k) dst[n][k] = *(const LAS bf16x8*)(lds + PG8_SB(b, h) + boff + n * 2048 + k * 1024); } while (0)
; #define PG8_MMA(ai, bj, At, Bt) do { __builtin_amdgcn_s_setprio(1); _Pragma("unroll") for (int m = 0; m < 4; ++m) _Pragma("unroll") for (int n = 0; n < 2; ++n) _Pragma("unroll") for (int k = 0; k < 2; ++k) \
;         acc[ai][bj][m][n] = __builtin_amdgcn_mfma_f32_16x16x32_bf16(Bt[n][k], At[m][k], acc[ai][bj][m][n], 0, 0, 0); __builtin_amdgcn_s_setprio(0); } while (0)
; template <bool ALIGN_EPI, class Epi, class Sched>
; __device__ __forceinline__ void gemm_phase(LAS unsigned char* lds, const int lda, const int ldb, const int K, const Sched& S, const Epi& E, const size_t kstepA = (size_t)(BK * 2), const size_t kstepB = (size_t)(BK * 2)) {
;     ...
;             PG8_LDB(B0, 0, 0); PG8_LDB(B1, 0, 1); PG8_SCHED; PG8_LDA(At, 0, 0); PG8_STAGE(PG8_SA(1, 1), a1 + hstepA, voffA);
;             PG8_WAIT_V(8); PG8_WAIT_L(0); PG8_BAR; PG8_MMA(0, 0, At, B0); PG8_MMA(0, 1, At, B1); PG8_BAR; PG8_SCHED;
;             PG8_LDA(At, 0, 1); PG8_STAGE(PG8_SB(0, 0), b2, voffB); PG8_STAGE(PG8_SB(0, 1), b2 + hstepB, voffB); PG8_STAGE(PG8_SA(0, 0), a2, voffA);
;             PG8_WAIT_V(8); PG8_WAIT_L(0); PG8_BAR; PG8_MMA(1, 0, At, B0); PG8_MMA(1, 1, At, B1); PG8_BAR; PG8_SCHED;
;             PG8_LDB(B0, 1, 0); PG8_LDB(B1, 1, 1); PG8_SCHED; PG8_LDA(At, 1, 0); PG8_STAGE(PG8_SA(0, 1), a2 + hstepA, voffA);
;             PG8_WAIT_V(8); PG8_WAIT_L(0); PG8_BAR; PG8_MMA(0, 0, At, B0); PG8_MMA(0, 1, At, B1); PG8_BAR; PG8_SCHED;
;             PG8_LDA(At, 1, 1); PG8_STAGE(PG8_SB(1, 0), b3, voffB); PG8_STAGE(PG8_SB(1, 1), b3 + hstepB, voffB); PG8_STAGE(PG8_SA(1, 0), a3, voffA);
;             PG8_WAIT_V(8); PG8_WAIT_L(0); PG8_BAR; PG8_MMA(1, 0, At, B0); PG8_MMA(1, 1, At, B1); PG8_BAR; PG8_SCHED;
	s_setprio 2
	s_waitcnt lgkmcnt(0)
	v_mfma_f32_16x16x32_bf16 v[140:143], v[80:83], v[160:163], v[140:143]
	v_mfma_f32_16x16x32_bf16 v[140:143], v[84:87], v[164:167], v[140:143]
	v_mfma_f32_16x16x32_bf16 v[136:139], v[104:107], v[160:163], v[136:139]
	v_mfma_f32_16x16x32_bf16 v[136:139], v[108:111], v[164:167], v[136:139]
	v_mfma_f32_16x16x32_bf16 v[124:127], v[80:83], v[188:191], v[124:127]
	v_mfma_f32_16x16x32_bf16 v[124:127], v[84:87], v[192:195], v[124:127]
	v_mfma_f32_16x16x32_bf16 v[120:123], v[104:107], v[188:191], v[120:123]
	v_mfma_f32_16x16x32_bf16 v[120:123], v[108:111], v[192:195], v[120:123]
	v_mfma_f32_16x16x32_bf16 v[100:103], v[80:83], v[196:199], v[100:103]
	v_mfma_f32_16x16x32_bf16 v[100:103], v[84:87], v[200:203], v[100:103]
	v_mfma_f32_16x16x32_bf16 v[96:99], v[104:107], v[196:199], v[96:99]
	v_mfma_f32_16x16x32_bf16 v[96:99], v[108:111], v[200:203], v[96:99]
	v_mfma_f32_16x16x32_bf16 v[76:79], v[80:83], v[204:207], v[76:79]
	v_mfma_f32_16x16x32_bf16 v[76:79], v[84:87], v[208:211], v[76:79]
	v_mfma_f32_16x16x32_bf16 v[72:75], v[104:107], v[204:207], v[72:75]
	v_mfma_f32_16x16x32_bf16 v[72:75], v[108:111], v[208:211], v[72:75]
	s_setprio 0
	s_setprio 2
	v_mfma_f32_16x16x32_bf16 v[132:135], v[144:147], v[160:163], v[132:135]
	v_mfma_f32_16x16x32_bf16 v[132:135], v[148:151], v[164:167], v[132:135]
	v_mfma_f32_16x16x32_bf16 v[128:131], v[152:155], v[160:163], v[128:131]
	v_mfma_f32_16x16x32_bf16 v[128:131], v[156:159], v[164:167], v[128:131]
	v_mfma_f32_16x16x32_bf16 v[116:119], v[144:147], v[188:191], v[116:119]
	v_mfma_f32_16x16x32_bf16 v[116:119], v[148:151], v[192:195], v[116:119]
	v_mfma_f32_16x16x32_bf16 v[112:115], v[152:155], v[188:191], v[112:115]
	v_mfma_f32_16x16x32_bf16 v[112:115], v[156:159], v[192:195], v[112:115]
	v_mfma_f32_16x16x32_bf16 v[92:95], v[144:147], v[196:199], v[92:95]
	v_mfma_f32_16x16x32_bf16 v[92:95], v[148:151], v[200:203], v[92:95]
	v_mfma_f32_16x16x32_bf16 v[88:91], v[152:155], v[196:199], v[88:91]
	v_mfma_f32_16x16x32_bf16 v[88:91], v[156:159], v[200:203], v[88:91]
	v_mfma_f32_16x16x32_bf16 v[68:71], v[144:147], v[204:207], v[68:71]
	v_mfma_f32_16x16x32_bf16 v[68:71], v[148:151], v[208:211], v[68:71]
	v_mfma_f32_16x16x32_bf16 v[64:67], v[152:155], v[204:207], v[64:67]
	v_mfma_f32_16x16x32_bf16 v[64:67], v[156:159], v[208:211], v[64:67]
	s_setprio 0
	s_add_i32 s68, s51, s18
	v_lshl_add_u64 v[212:213], s[14:15], 0, v[170:171]
	s_mov_b32 m0, s68
	ds_read_b128 v[160:163], v221 offset:16384
	ds_read_b128 v[164:167], v221 offset:17408
	ds_read_b128 v[188:191], v221 offset:18432
	ds_read_b128 v[192:195], v221 offset:19456
	ds_read_b128 v[196:199], v221 offset:20480
	ds_read_b128 v[200:203], v221 offset:21504
	ds_read_b128 v[204:207], v221 offset:22528
	ds_read_b128 v[208:211], v221 offset:23552
	global_load_lds_dwordx4 v[212:213], off
	s_add_i32 m0, s68, 0x2000
	s_add_u32 s68, s14, 0x4000
	v_lshl_add_u64 v[212:213], s[14:15], 0, v[174:175]
	s_addc_u32 s69, s15, 0
	s_add_i32 s70, s64, s18
	global_load_lds_dwordx4 v[212:213], off
	v_lshl_add_u64 v[212:213], s[68:69], 0, v[170:171]
	s_mov_b32 m0, s70
	s_nop 0
	global_load_lds_dwordx4 v[212:213], off
	v_lshl_add_u64 v[212:213], s[68:69], 0, v[174:175]
	s_add_i32 m0, s70, 0x2000
	s_nop 0
	global_load_lds_dwordx4 v[212:213], off
	v_lshl_add_u64 v[212:213], s[16:17], 0, v[168:169]
	s_mov_b32 m0, s19
	s_nop 0
	global_load_lds_dwordx4 v[212:213], off
	v_lshl_add_u64 v[212:213], s[16:17], 0, v[172:173]
	s_mov_b32 m0, s29
	s_nop 0
	global_load_lds_dwordx4 v[212:213], off
	s_waitcnt vmcnt(8)
	s_waitcnt lgkmcnt(0)
	s_barrier
	s_setprio 2
	s_waitcnt lgkmcnt(0)
	v_mfma_f32_16x16x32_bf16 v[60:63], v[80:83], v[160:163], v[60:63]
	v_mfma_f32_16x16x32_bf16 v[60:63], v[84:87], v[164:167], v[60:63]
	v_mfma_f32_16x16x32_bf16 v[56:59], v[104:107], v[160:163], v[56:59]
	v_mfma_f32_16x16x32_bf16 v[56:59], v[108:111], v[164:167], v[56:59]
	v_mfma_f32_16x16x32_bf16 v[44:47], v[80:83], v[188:191], v[44:47]
	v_mfma_f32_16x16x32_bf16 v[44:47], v[84:87], v[192:195], v[44:47]
	v_mfma_f32_16x16x32_bf16 v[40:43], v[104:107], v[188:191], v[40:43]
	v_mfma_f32_16x16x32_bf16 v[40:43], v[108:111], v[192:195], v[40:43]
	v_mfma_f32_16x16x32_bf16 v[28:31], v[80:83], v[196:199], v[28:31]
	v_mfma_f32_16x16x32_bf16 v[28:31], v[84:87], v[200:203], v[28:31]
	v_mfma_f32_16x16x32_bf16 v[24:27], v[104:107], v[196:199], v[24:27]
	v_mfma_f32_16x16x32_bf16 v[24:27], v[108:111], v[200:203], v[24:27]
	v_mfma_f32_16x16x32_bf16 v[12:15], v[80:83], v[204:207], v[12:15]
	v_mfma_f32_16x16x32_bf16 v[12:15], v[84:87], v[208:211], v[12:15]
	v_mfma_f32_16x16x32_bf16 v[8:11], v[104:107], v[204:207], v[8:11]
	v_mfma_f32_16x16x32_bf16 v[8:11], v[108:111], v[208:211], v[8:11]
	s_setprio 0
	s_setprio 2
	v_mfma_f32_16x16x32_bf16 v[52:55], v[144:147], v[160:163], v[52:55]
	v_mfma_f32_16x16x32_bf16 v[52:55], v[148:151], v[164:167], v[52:55]
	v_mfma_f32_16x16x32_bf16 v[48:51], v[152:155], v[160:163], v[48:51]
	v_mfma_f32_16x16x32_bf16 v[48:51], v[156:159], v[164:167], v[48:51]
	v_mfma_f32_16x16x32_bf16 v[36:39], v[144:147], v[188:191], v[36:39]
	v_mfma_f32_16x16x32_bf16 v[36:39], v[148:151], v[192:195], v[36:39]
	v_mfma_f32_16x16x32_bf16 v[32:35], v[152:155], v[188:191], v[32:35]
	v_mfma_f32_16x16x32_bf16 v[32:35], v[156:159], v[192:195], v[32:35]
	v_mfma_f32_16x16x32_bf16 v[20:23], v[144:147], v[196:199], v[20:23]
	v_mfma_f32_16x16x32_bf16 v[20:23], v[148:151], v[200:203], v[20:23]
	v_mfma_f32_16x16x32_bf16 v[16:19], v[152:155], v[196:199], v[16:19]
	v_mfma_f32_16x16x32_bf16 v[16:19], v[156:159], v[200:203], v[16:19]
	v_mfma_f32_16x16x32_bf16 v[4:7], v[144:147], v[204:207], v[4:7]
	v_mfma_f32_16x16x32_bf16 v[4:7], v[148:151], v[208:211], v[4:7]
	v_mfma_f32_16x16x32_bf16 v[0:3], v[152:155], v[204:207], v[0:3]
	v_mfma_f32_16x16x32_bf16 v[0:3], v[156:159], v[208:211], v[0:3]
	s_setprio 0
	s_add_i32 s68, 0, 0x18000
	s_add_i32 s69, 0, 0x1c000
	v_add_u32_e32 v108, s68, v218
	v_add_u32_e32 v156, s69, v218
	ds_read_b128 v[80:83], v108
	ds_read_b128 v[84:87], v108 offset:1024
	ds_read_b128 v[104:107], v108 offset:2048
	ds_read_b128 v[108:111], v108 offset:3072
	ds_read_b128 v[144:147], v156
	ds_read_b128 v[148:151], v156 offset:1024
	ds_read_b128 v[152:155], v156 offset:2048
	ds_read_b128 v[156:159], v156 offset:3072
	s_add_u32 s16, s16, 0x4000
	s_addc_u32 s17, s17, 0
	s_mov_b32 m0, s30
	v_lshl_add_u64 v[212:213], s[16:17], 0, v[168:169]
	ds_read_b128 v[160:163], v221 offset:32768
	ds_read_b128 v[164:167], v221 offset:33792
	ds_read_b128 v[188:191], v221 offset:34816
	ds_read_b128 v[192:195], v221 offset:35840
	ds_read_b128 v[196:199], v221 offset:36864
	ds_read_b128 v[200:203], v221 offset:37888
	ds_read_b128 v[204:207], v221 offset:38912
	ds_read_b128 v[208:211], v221 offset:39936
	global_load_lds_dwordx4 v[212:213], off
	v_lshl_add_u64 v[212:213], s[16:17], 0, v[172:173]
	s_mov_b32 m0, s31
	s_nop 0
	global_load_lds_dwordx4 v[212:213], off
	s_waitcnt vmcnt(8)
	s_waitcnt lgkmcnt(0)
	s_barrier
; #define PG8_STAGE(bufoff, gbase, voff) do { _Pragma("unroll") for (int _i = 0; _i < 2; ++_i) \
;         __builtin_amdgcn_global_load_lds((const unsigned*)((const char*)(gbase) + (voff)[_i]), (LAS unsigned*)(lds + (bufoff) + ldsw + _i * 8192), 16, 0, 0); } while (0)
; #define PG8_LDA(dst, b, h) do { _Pragma("unroll") for (int m = 0; m < 4; ++m) _Pragma("unroll") for (int k = 0; k < 2; ++k) dst[m][k] = *(const LAS bf16x8*)(lds + PG8_SA(b, h) + aoff + m * 2048 + k * 1024); } while (0)
; #define PG8_LDB(dst, b, h) do { _Pragma("unroll") for (int n = 0; n < 2; ++n) _Pragma("unroll") for (int k = 0; k < 2; ++k) dst[n][k] = *(const LAS bf16x8*)(lds + PG8_SB(b, h) + boff + n * 2048 + k * 1024); } while (0)
; #define PG8_WAIT_V(n) asm volatile("s_waitcnt vmcnt(" #n ")" ::: "memory")
; #define PG8_WAIT_L(n) asm volatile("s_waitcnt lgkmcnt(" #n ")" ::: "memory")
; #define PG8_BAR __builtin_amdgcn_s_barrier()
; #define PG8_SCHED __builtin_amdgcn_sched_barrier(0)
; template <bool ALIGN_EPI, class Epi, class Sched>
; __device__ __forceinline__ void gemm_phase(LAS unsigned char* lds, const int lda, const int ldb, const int K, const Sched& S, const Epi& E, const size_t kstepA = (size_t)(BK * 2), const size_t kstepB = (size_t)(BK * 2)) {
;     ...
;             PG8_LDB(B0, 0, 0); PG8_LDB(B1, 0, 1); PG8_SCHED; PG8_LDA(At, 0, 0); PG8_STAGE(PG8_SA(1, 1), a1 + hstepA, voffA);
;             PG8_WAIT_V(8); PG8_WAIT_L(0); PG8_BAR; PG8_MMA(0, 0, At, B0); PG8_MMA(0, 1, At, B1); PG8_BAR; PG8_SCHED;
;             PG8_LDA(At, 0, 1); PG8_STAGE(PG8_SB(0, 0), b2, voffB); PG8_STAGE(PG8_SB(0, 1), b2 + hstepB, voffB); PG8_STAGE(PG8_SA(0, 0), a2, voffA);
;             PG8_WAIT_V(8); PG8_WAIT_L(0); PG8_BAR; PG8_MMA(1, 0, At, B0); PG8_MMA(1, 1, At, B1); PG8_BAR; PG8_SCHED;
;             PG8_LDB(B0, 1, 0); PG8_LDB(B1, 1, 1); PG8_SCHED; PG8_LDA(At, 1, 0); PG8_STAGE(PG8_SA(0, 1), a2 + hstepA, voffA);
;             PG8_WAIT_V(8); PG8_WAIT_L(0); PG8_BAR; PG8_MMA(0, 0, At, B0); PG8_MMA(0, 1, At, B1); PG8_BAR; PG8_SCHED;
;             PG8_LDA(At, 1, 1); PG8_STAGE(PG8_SB(1, 0), b3, voffB); PG8_STAGE(PG8_SB(1, 1), b3 + hstepB, voffB); PG8_STAGE(PG8_SA(1, 0), a3, voffA);
;             PG8_WAIT_V(8); PG8_WAIT_L(0); PG8_BAR; PG8_MMA(1, 0, At, B0); PG8_MMA(1, 1, At, B1); PG8_BAR; PG8_SCHED;
;         }
;         if constexpr (ALIGN_EPI) { if (wr == 0) PG8_BAR; }
	s_setprio 2
	s_waitcnt lgkmcnt(0)
	v_mfma_f32_16x16x32_bf16 v[140:143], v[80:83], v[160:163], v[140:143]
	v_mfma_f32_16x16x32_bf16 v[140:143], v[84:87], v[164:167], v[140:143]
	v_mfma_f32_16x16x32_bf16 v[136:139], v[104:107], v[160:163], v[136:139]
	v_mfma_f32_16x16x32_bf16 v[136:139], v[108:111], v[164:167], v[136:139]
	v_mfma_f32_16x16x32_bf16 v[124:127], v[80:83], v[188:191], v[124:127]
	v_mfma_f32_16x16x32_bf16 v[124:127], v[84:87], v[192:195], v[124:127]
	v_mfma_f32_16x16x32_bf16 v[120:123], v[104:107], v[188:191], v[120:123]
	v_mfma_f32_16x16x32_bf16 v[120:123], v[108:111], v[192:195], v[120:123]
	v_mfma_f32_16x16x32_bf16 v[100:103], v[80:83], v[196:199], v[100:103]
	v_mfma_f32_16x16x32_bf16 v[100:103], v[84:87], v[200:203], v[100:103]
	v_mfma_f32_16x16x32_bf16 v[96:99], v[104:107], v[196:199], v[96:99]
	v_mfma_f32_16x16x32_bf16 v[96:99], v[108:111], v[200:203], v[96:99]
	v_mfma_f32_16x16x32_bf16 v[76:79], v[80:83], v[204:207], v[76:79]
	v_mfma_f32_16x16x32_bf16 v[76:79], v[84:87], v[208:211], v[76:79]
	v_mfma_f32_16x16x32_bf16 v[72:75], v[104:107], v[204:207], v[72:75]
	v_mfma_f32_16x16x32_bf16 v[72:75], v[108:111], v[208:211], v[72:75]
	s_setprio 0
	s_setprio 2
	v_mfma_f32_16x16x32_bf16 v[132:135], v[144:147], v[160:163], v[132:135]
	v_mfma_f32_16x16x32_bf16 v[132:135], v[148:151], v[164:167], v[132:135]
	v_mfma_f32_16x16x32_bf16 v[128:131], v[152:155], v[160:163], v[128:131]
	v_mfma_f32_16x16x32_bf16 v[128:131], v[156:159], v[164:167], v[128:131]
	v_mfma_f32_16x16x32_bf16 v[116:119], v[144:147], v[188:191], v[116:119]
	v_mfma_f32_16x16x32_bf16 v[116:119], v[148:151], v[192:195], v[116:119]
	v_mfma_f32_16x16x32_bf16 v[112:115], v[152:155], v[188:191], v[112:115]
	v_mfma_f32_16x16x32_bf16 v[112:115], v[156:159], v[192:195], v[112:115]
	v_mfma_f32_16x16x32_bf16 v[92:95], v[144:147], v[196:199], v[92:95]
	v_mfma_f32_16x16x32_bf16 v[92:95], v[148:151], v[200:203], v[92:95]
	v_mfma_f32_16x16x32_bf16 v[88:91], v[152:155], v[196:199], v[88:91]
	v_mfma_f32_16x16x32_bf16 v[88:91], v[156:159], v[200:203], v[88:91]
	v_mfma_f32_16x16x32_bf16 v[68:71], v[144:147], v[204:207], v[68:71]
	v_mfma_f32_16x16x32_bf16 v[68:71], v[148:151], v[208:211], v[68:71]
	v_mfma_f32_16x16x32_bf16 v[64:67], v[152:155], v[204:207], v[64:67]
	v_mfma_f32_16x16x32_bf16 v[64:67], v[156:159], v[208:211], v[64:67]
	s_setprio 0
	s_add_u32 s16, s14, 0x40000
	s_addc_u32 s17, s15, 0
	s_add_i32 s68, s68, s18
	v_lshl_add_u64 v[212:213], s[16:17], 0, v[170:171]
	s_mov_b32 m0, s68
	ds_read_b128 v[160:163], v221 offset:49152
	ds_read_b128 v[164:167], v221 offset:50176
	ds_read_b128 v[188:191], v221 offset:51200
	ds_read_b128 v[192:195], v221 offset:52224
	ds_read_b128 v[196:199], v221 offset:53248
	ds_read_b128 v[200:203], v221 offset:54272
	ds_read_b128 v[204:207], v221 offset:55296
	ds_read_b128 v[208:211], v221 offset:56320
	global_load_lds_dwordx4 v[212:213], off
	s_add_i32 m0, s68, 0x2000
	s_add_u32 s14, s14, 0x44000
	v_lshl_add_u64 v[212:213], s[16:17], 0, v[174:175]
	s_addc_u32 s15, s15, 0
	s_add_i32 s16, s69, s18
	global_load_lds_dwordx4 v[212:213], off
	v_lshl_add_u64 v[212:213], s[14:15], 0, v[170:171]
	s_mov_b32 m0, s16
	s_nop 0
	global_load_lds_dwordx4 v[212:213], off
	v_lshl_add_u64 v[212:213], s[14:15], 0, v[174:175]
	s_add_i32 m0, s16, 0x2000
	s_nop 0
	global_load_lds_dwordx4 v[212:213], off
	v_lshl_add_u64 v[212:213], s[12:13], 0, v[168:169]
	s_mov_b32 m0, s43
	s_nop 0
	global_load_lds_dwordx4 v[212:213], off
	v_lshl_add_u64 v[212:213], s[12:13], 0, v[172:173]
	s_mov_b32 m0, s50
	s_nop 0
	global_load_lds_dwordx4 v[212:213], off
	s_waitcnt vmcnt(8)
	s_waitcnt lgkmcnt(0)
	s_barrier
	s_setprio 2
	s_waitcnt lgkmcnt(0)
	v_mfma_f32_16x16x32_bf16 v[60:63], v[80:83], v[160:163], v[60:63]
	v_mfma_f32_16x16x32_bf16 v[60:63], v[84:87], v[164:167], v[60:63]
	v_mfma_f32_16x16x32_bf16 v[56:59], v[104:107], v[160:163], v[56:59]
	v_mfma_f32_16x16x32_bf16 v[56:59], v[108:111], v[164:167], v[56:59]
	v_mfma_f32_16x16x32_bf16 v[44:47], v[80:83], v[188:191], v[44:47]
	v_mfma_f32_16x16x32_bf16 v[44:47], v[84:87], v[192:195], v[44:47]
	v_mfma_f32_16x16x32_bf16 v[40:43], v[104:107], v[188:191], v[40:43]
	v_mfma_f32_16x16x32_bf16 v[40:43], v[108:111], v[192:195], v[40:43]
	v_mfma_f32_16x16x32_bf16 v[28:31], v[80:83], v[196:199], v[28:31]
	v_mfma_f32_16x16x32_bf16 v[28:31], v[84:87], v[200:203], v[28:31]
	v_mfma_f32_16x16x32_bf16 v[24:27], v[104:107], v[196:199], v[24:27]
	v_mfma_f32_16x16x32_bf16 v[24:27], v[108:111], v[200:203], v[24:27]
	v_mfma_f32_16x16x32_bf16 v[12:15], v[80:83], v[204:207], v[12:15]
	v_mfma_f32_16x16x32_bf16 v[12:15], v[84:87], v[208:211], v[12:15]
	v_mfma_f32_16x16x32_bf16 v[8:11], v[104:107], v[204:207], v[8:11]
	v_mfma_f32_16x16x32_bf16 v[8:11], v[108:111], v[208:211], v[8:11]
	s_setprio 0
	s_setprio 2
	v_mfma_f32_16x16x32_bf16 v[52:55], v[144:147], v[160:163], v[52:55]
	v_mfma_f32_16x16x32_bf16 v[52:55], v[148:151], v[164:167], v[52:55]
	v_mfma_f32_16x16x32_bf16 v[48:51], v[152:155], v[160:163], v[48:51]
	v_mfma_f32_16x16x32_bf16 v[48:51], v[156:159], v[164:167], v[48:51]
	v_mfma_f32_16x16x32_bf16 v[36:39], v[144:147], v[188:191], v[36:39]
	v_mfma_f32_16x16x32_bf16 v[36:39], v[148:151], v[192:195], v[36:39]
	v_mfma_f32_16x16x32_bf16 v[32:35], v[152:155], v[188:191], v[32:35]
	v_mfma_f32_16x16x32_bf16 v[32:35], v[156:159], v[192:195], v[32:35]
	v_mfma_f32_16x16x32_bf16 v[20:23], v[144:147], v[196:199], v[20:23]
	v_mfma_f32_16x16x32_bf16 v[20:23], v[148:151], v[200:203], v[20:23]
	v_mfma_f32_16x16x32_bf16 v[16:19], v[152:155], v[196:199], v[16:19]
	v_mfma_f32_16x16x32_bf16 v[16:19], v[156:159], v[200:203], v[16:19]
	v_mfma_f32_16x16x32_bf16 v[4:7], v[144:147], v[204:207], v[4:7]
	v_mfma_f32_16x16x32_bf16 v[4:7], v[148:151], v[208:211], v[4:7]
	v_mfma_f32_16x16x32_bf16 v[0:3], v[152:155], v[204:207], v[0:3]
	v_mfma_f32_16x16x32_bf16 v[0:3], v[156:159], v[208:211], v[0:3]
	s_setprio 0
	s_add_i32 s67, s67, 2
	s_add_u32 s57, s57, 0x80000
	s_addc_u32 s59, s59, 0
	s_add_u32 s10, s10, 0x400000
	s_addc_u32 s11, s11, 0
	s_cmpk_gt_u32 s67, 0x55
	s_cbranch_scc0 .Lp13_kloop_y
.Lp13_kloop_done:
	s_and_b64 vcc, exec, s[46:47]
	s_cbranch_vccz .LBB0_1157

; #define PG8_BAR __builtin_amdgcn_s_barrier()
; template <bool ALIGN_EPI, class Epi, class Sched>
; __device__ __forceinline__ void gemm_phase(LAS unsigned char* lds, const int lda, const int ldb, const int K, const Sched& S, const Epi& E, const size_t kstepA = (size_t)(BK * 2), const size_t kstepB = (size_t)(BK * 2)) {
;     ...
;         if (!has_next) break;
; #pragma unroll
;         for (int a = 0; a < 2; ++a)
; #pragma unroll
;             for (int b = 0; b < 2; ++b)
; #pragma unroll
;                 for (int m = 0; m < 4; ++m)
; #pragma unroll
;                     for (int n = 0; n < 2; ++n) acc[a][b][m][n] = (f32x4){0.f, 0.f, 0.f, 0.f};
;         cur = nxt; cA = nA; cB = nB; ++ui;
;         if constexpr (ALIGN_EPI) { if (wr == 1) PG8_BAR; }
;     }
.LBB0_1173:
	s_or_b64 exec, exec, s[8:9]
	s_andn2_b64 vcc, exec, s[6:7]
	s_mov_b64 s[0:1], -1
	s_cbranch_vccnz .LBB0_1146
	s_andn2_b64 vcc, exec, s[44:45]
	s_cbranch_vccnz .LBB0_1145
	s_branch .LBB0_1145
